# FFT code: pairs of identical packed ops combined lane-wise by v_mov merged into one packed op with per-lane modifiers (152 sites, 94 duplicate ops removed)
# speedup vs baseline: 1.0077x; 1.0077x over previous
.LBB0_275:
	s_or_b64 exec, exec, s[10:11]
	v_mov_b32_e32 v40, v1
	s_mov_b32 s73, s50
	v_ashrrev_i32_e32 v42, 31, v40
	v_lshrrev_b32_e32 v42, 23, v42
	v_add_u32_e32 v42, v40, v42
	v_ashrrev_i32_e32 v42, 9, v42
	v_mul_i32_i24_e32 v44, 0x200, v42
	v_sub_u32_e32 v70, v40, v44
	v_lshlrev_b32_e32 v40, 14, v42
	v_lshlrev_b32_e32 v42, 1, v70
	v_bfrev_b32_e32 v42, v42
	v_lshrrev_b32_e32 v42, 22, v42
	v_sub_u32_e32 v42, 0x400, v42
	v_bfrev_b32_e32 v42, v42
	v_lshrrev_b32_e32 v42, 18, v42
	v_and_b32_e32 v42, 0x3ff0, v42
	v_cmp_eq_u32_e64 s[10:11], 0, v70
	v_lshl_add_u32 v44, v70, 5, v40
	v_lshlrev_b32_e32 v45, 3, v44
	v_cndmask_b32_e64 v42, v42, 16, s[10:11]
	v_or_b32_e32 v40, v42, v40
	v_ashrrev_i32_e32 v44, 2, v44
	v_ashrrev_i32_e32 v42, 5, v40
	v_add3_u32 v44, 0, v45, v44
	v_lshlrev_b32_e32 v40, 3, v40
	v_lshlrev_b32_e32 v42, 3, v42
	v_add3_u32 v40, 0, v40, v42
	ds_read2_b64 v[46:49], v44 offset1:1
	ds_read2_b64 v[50:53], v44 offset0:2 offset1:3
	ds_read2_b64 v[76:79], v40 offset1:1
	ds_read2_b64 v[80:83], v40 offset0:2 offset1:3
	ds_read2_b64 v[54:57], v44 offset0:4 offset1:5
	ds_read2_b64 v[58:61], v44 offset0:6 offset1:7
	ds_read2_b64 v[84:87], v40 offset0:4 offset1:5
	ds_read2_b64 v[88:91], v40 offset0:6 offset1:7
	ds_read2_b64 v[62:65], v44 offset0:8 offset1:9
	ds_read2_b64 v[66:69], v44 offset0:10 offset1:11
	ds_read2_b64 v[100:103], v40 offset0:8 offset1:9
	ds_read2_b64 v[104:107], v40 offset0:10 offset1:11
	ds_read2_b64 v[72:75], v44 offset0:12 offset1:13
	ds_read2_b64 v[92:95], v44 offset0:14 offset1:15
	ds_read2_b64 v[108:111], v40 offset0:12 offset1:13
	ds_read2_b64 v[112:115], v40 offset0:14 offset1:15
	s_waitcnt lgkmcnt(7)
	v_pk_add_f32 v[96:97], v[46:47], v[62:63]
	v_pk_add_f32 v[46:47], v[46:47], v[62:63] neg_lo:[0,1] neg_hi:[0,1]
	v_pk_add_f32 v[62:63], v[48:49], v[64:65]
	v_pk_add_f32 v[48:49], v[48:49], v[64:65] neg_lo:[0,1] neg_hi:[0,1]
	s_waitcnt lgkmcnt(3)
	v_pk_add_f32 v[98:99], v[56:57], v[74:75]
	v_pk_mul_f32 v[64:65], v[48:49], s[62:63]
	v_pk_add_f32 v[56:57], v[56:57], v[74:75] neg_lo:[0,1] neg_hi:[0,1]
	v_pk_fma_f32 v[48:49], v[48:49], s[50:51], v[64:65] op_sel:[0,0,1] op_sel_hi:[1,0,0]
	v_pk_add_f32 v[64:65], v[50:51], v[66:67]
	v_pk_add_f32 v[50:51], v[50:51], v[66:67] neg_lo:[0,1] neg_hi:[0,1]
	s_mov_b32 s80, s63
	v_pk_mul_f32 v[74:75], v[56:57], s[72:73]
	s_mov_b32 s78, s69
	v_pk_mul_f32 v[66:67], v[50:51], s[68:69]
	v_pk_fma_f32 v[56:57], v[56:57], s[80:81], v[74:75] op_sel:[0,0,1] op_sel_hi:[1,0,0] neg_lo:[1,0,0] neg_hi:[1,0,0]
	s_waitcnt lgkmcnt(2)
	v_pk_add_f32 v[74:75], v[58:59], v[92:93]
	v_pk_add_f32 v[58:59], v[58:59], v[92:93] neg_lo:[0,1] neg_hi:[0,1]
	v_pk_fma_f32 v[50:51], v[50:51], s[78:79], v[66:67] op_sel:[0,0,1] op_sel_hi:[1,0,0]
	v_pk_add_f32 v[66:67], v[52:53], v[68:69]
	v_pk_add_f32 v[52:53], v[52:53], v[68:69] neg_lo:[0,1] neg_hi:[0,1]
	v_pk_mul_f32 v[92:93], v[58:59], s[68:69]
	v_pk_mul_f32 v[68:69], v[52:53], s[72:73]
	v_pk_fma_f32 v[58:59], v[58:59], s[78:79], v[92:93] op_sel:[0,0,1] op_sel_hi:[1,0,0] neg_lo:[1,0,0] neg_hi:[1,0,0]
	v_pk_add_f32 v[92:93], v[60:61], v[94:95]
	v_pk_add_f32 v[60:61], v[60:61], v[94:95] neg_lo:[0,1] neg_hi:[0,1]
	v_pk_fma_f32 v[52:53], v[52:53], s[80:81], v[68:69] op_sel:[0,0,1] op_sel_hi:[1,0,0]
	v_pk_add_f32 v[68:69], v[54:55], v[72:73]
	v_pk_add_f32 v[54:55], v[54:55], v[72:73] neg_lo:[0,1] neg_hi:[0,1]
	v_pk_mul_f32 v[94:95], v[60:61], s[62:63]
	v_pk_add_f32 v[116:117], v[66:67], v[92:93]
	v_pk_add_f32 v[66:67], v[66:67], v[92:93] neg_lo:[0,1] neg_hi:[0,1]
	v_xor_b32_e32 v73, 0x80000000, v54
	v_pk_fma_f32 v[60:61], v[60:61], s[50:51], v[94:95] op_sel:[0,0,1] op_sel_hi:[1,0,0] neg_lo:[1,0,0] neg_hi:[1,0,0]
	v_pk_add_f32 v[94:95], v[96:97], v[68:69]
	v_pk_add_f32 v[68:69], v[96:97], v[68:69] neg_lo:[0,1] neg_hi:[0,1]
	v_pk_add_f32 v[96:97], v[62:63], v[98:99]
	v_pk_add_f32 v[62:63], v[62:63], v[98:99] neg_lo:[0,1] neg_hi:[0,1]
	v_pk_mul_f32 v[92:93], v[66:67], s[68:69]
	v_mov_b32_e32 v72, v55
	v_pk_mul_f32 v[98:99], v[62:63], s[68:69]
	v_pk_fma_f32 v[66:67], v[66:67], s[78:79], v[92:93] op_sel:[0,0,1] op_sel_hi:[1,0,0] neg_lo:[1,0,0] neg_hi:[1,0,0]
	v_pk_add_f32 v[54:55], v[46:47], v[72:73]
	v_pk_add_f32 v[46:47], v[46:47], v[72:73] neg_lo:[0,1] neg_hi:[0,1]
	v_pk_add_f32 v[72:73], v[48:49], v[56:57]
	v_pk_add_f32 v[48:49], v[48:49], v[56:57] neg_lo:[0,1] neg_hi:[0,1]
	v_pk_add_f32 v[92:93], v[52:53], v[60:61]
	v_pk_add_f32 v[52:53], v[52:53], v[60:61] neg_lo:[0,1] neg_hi:[0,1]
	v_pk_fma_f32 v[62:63], v[62:63], s[78:79], v[98:99] op_sel:[0,0,1] op_sel_hi:[1,0,0]
	v_pk_add_f32 v[98:99], v[64:65], v[74:75]
	v_pk_mul_f32 v[56:57], v[48:49], s[68:69]
	v_pk_mul_f32 v[60:61], v[52:53], s[68:69]
	v_pk_fma_f32 v[48:49], v[48:49], s[78:79], v[56:57] op_sel:[0,0,1] op_sel_hi:[1,0,0]
	v_pk_add_f32 v[56:57], v[50:51], v[58:59]
	v_pk_fma_f32 v[52:53], v[52:53], s[78:79], v[60:61] op_sel:[0,0,1] op_sel_hi:[1,0,0] neg_lo:[1,0,0] neg_hi:[1,0,0]
	v_pk_add_f32 v[60:61], v[94:95], v[98:99]
	v_pk_add_f32 v[118:119], v[94:95], v[98:99] neg_lo:[0,1] neg_hi:[0,1]
	v_pk_add_f32 v[94:95], v[96:97], v[116:117]
	v_pk_add_f32 v[116:117], v[96:97], v[116:117] neg_lo:[0,1] neg_hi:[0,1]
	v_pk_add_f32 v[128:129], v[54:55], v[56:57]
	v_pk_add_f32 v[54:55], v[54:55], v[56:57] neg_lo:[0,1] neg_hi:[0,1]
	v_pk_add_f32 v[56:57], v[72:73], v[92:93]
	v_pk_add_f32 v[92:93], v[72:73], v[92:93] neg_lo:[0,1] neg_hi:[0,1]
	v_pk_add_f32 v[96:97], v[78:79], v[102:103]
	v_pk_add_f32 v[78:79], v[78:79], v[102:103] neg_lo:[0,1] neg_hi:[0,1]
	v_xor_b32_e32 v131, 0x80000000, v92
	v_mov_b32_e32 v130, v93
	v_pk_add_f32 v[92:93], v[76:77], v[100:101]
	v_pk_add_f32 v[76:77], v[76:77], v[100:101] neg_lo:[0,1] neg_hi:[0,1]
	v_pk_mul_f32 v[100:101], v[78:79], s[62:63]
	v_bfrev_b32_e32 v40, v70
	v_pk_fma_f32 v[78:79], v[78:79], s[50:51], v[100:101] op_sel:[0,0,1] op_sel_hi:[1,0,0]
	v_pk_add_f32 v[100:101], v[80:81], v[104:105]
	v_pk_add_f32 v[80:81], v[80:81], v[104:105] neg_lo:[0,1] neg_hi:[0,1]
	v_lshrrev_b32_e32 v40, 23, v40
	v_pk_mul_f32 v[102:103], v[80:81], s[68:69]
	v_cvt_f32_u32_e32 v40, v40
	v_pk_fma_f32 v[80:81], v[80:81], s[78:79], v[102:103] op_sel:[0,0,1] op_sel_hi:[1,0,0]
	v_pk_add_f32 v[102:103], v[82:83], v[106:107]
	v_pk_add_f32 v[82:83], v[82:83], v[106:107] neg_lo:[0,1] neg_hi:[0,1]
	v_mul_f32_e32 v40, 0x38000000, v40
	v_pk_mul_f32 v[104:105], v[82:83], s[72:73]
	v_ashrrev_i32_e32 v71, 31, v70
	v_pk_fma_f32 v[82:83], v[82:83], s[80:81], v[104:105] op_sel:[0,0,1] op_sel_hi:[1,0,0]
	s_waitcnt lgkmcnt(1)
	v_pk_add_f32 v[104:105], v[84:85], v[108:109]
	v_pk_add_f32 v[106:107], v[84:85], v[108:109] neg_lo:[0,1] neg_hi:[0,1]
	v_pk_add_f32 v[74:75], v[64:65], v[74:75] neg_lo:[0,1] neg_hi:[0,1]
	v_pk_add_f32 v[84:85], v[86:87], v[110:111]
	v_pk_add_f32 v[86:87], v[86:87], v[110:111] neg_lo:[0,1] neg_hi:[0,1]
	v_cndmask_b32_e64 v40, v40, v154, s[10:11]
	v_pk_mul_f32 v[108:109], v[86:87], s[72:73]
	v_lshl_add_u64 v[44:45], v[70:71], 3, s[26:27]
	v_pk_fma_f32 v[86:87], v[86:87], s[80:81], v[108:109] op_sel:[0,0,1] op_sel_hi:[1,0,0] neg_lo:[1,0,0] neg_hi:[1,0,0]
	s_waitcnt lgkmcnt(0)
	v_pk_add_f32 v[108:109], v[88:89], v[112:113]
	v_pk_add_f32 v[88:89], v[88:89], v[112:113] neg_lo:[0,1] neg_hi:[0,1]
	v_pk_mul_f32 v[110:111], v[88:89], s[68:69]
	v_pk_add_f32 v[50:51], v[50:51], v[58:59] neg_lo:[0,1] neg_hi:[0,1]
	v_pk_fma_f32 v[88:89], v[88:89], s[78:79], v[110:111] op_sel:[0,0,1] op_sel_hi:[1,0,0] neg_lo:[1,0,0] neg_hi:[1,0,0]
	v_pk_add_f32 v[110:111], v[90:91], v[114:115]
	v_pk_add_f32 v[90:91], v[90:91], v[114:115] neg_lo:[0,1] neg_hi:[0,1]
	v_pk_mul_f32 v[112:113], v[90:91], s[62:63]
	v_pk_add_f32 v[124:125], v[62:63], v[66:67]
	v_pk_fma_f32 v[90:91], v[90:91], s[50:51], v[112:113] op_sel:[0,0,1] op_sel_hi:[1,0,0] neg_lo:[1,0,0] neg_hi:[1,0,0]
	v_pk_add_f32 v[112:113], v[92:93], v[104:105]
	v_pk_add_f32 v[92:93], v[92:93], v[104:105] neg_lo:[0,1] neg_hi:[0,1]
	v_pk_add_f32 v[104:105], v[96:97], v[84:85]
	v_pk_add_f32 v[84:85], v[96:97], v[84:85] neg_lo:[0,1] neg_hi:[0,1]
	v_pk_add_f32 v[66:67], v[62:63], v[66:67] neg_lo:[0,1] neg_hi:[0,1]
	v_pk_mul_f32 v[96:97], v[84:85], s[68:69]
	v_cos_f32_e32 v71, v40
	v_pk_fma_f32 v[84:85], v[84:85], s[78:79], v[96:97] op_sel:[0,0,1] op_sel_hi:[1,0,0]
	v_pk_add_f32 v[96:97], v[100:101], v[108:109]
	v_pk_add_f32 v[108:109], v[100:101], v[108:109] neg_lo:[0,1] neg_hi:[0,1]
	v_cmp_ne_u32_e32 vcc, 0, v70
	s_nop 0
	s_nop 0
	v_pk_add_f32 v[100:101], v[102:103], v[110:111]
	v_pk_add_f32 v[102:103], v[102:103], v[110:111] neg_lo:[0,1] neg_hi:[0,1]
	v_xor_b32_e32 v59, 0x80000000, v50
	v_pk_mul_f32 v[110:111], v[102:103], s[68:69]
	v_pk_add_f32 v[64:65], v[68:69], v[74:75] op_sel:[0,1] op_sel_hi:[1,0] neg_hi:[0,1]
	v_pk_fma_f32 v[102:103], v[102:103], s[78:79], v[110:111] op_sel:[0,0,1] op_sel_hi:[1,0,0] neg_lo:[1,0,0] neg_hi:[1,0,0]
	v_pk_add_f32 v[110:111], v[76:77], v[106:107] op_sel:[0,1] op_sel_hi:[1,0] neg_hi:[0,1]
	v_pk_add_f32 v[76:77], v[76:77], v[106:107] op_sel:[0,1] op_sel_hi:[1,0] neg_lo:[0,1]
	v_pk_add_f32 v[106:107], v[78:79], v[86:87]
	v_pk_add_f32 v[78:79], v[78:79], v[86:87] neg_lo:[0,1] neg_hi:[0,1]
	v_pk_add_f32 v[122:123], v[68:69], v[74:75] op_sel:[0,1] op_sel_hi:[1,0] neg_lo:[0,1]
	v_pk_mul_f32 v[86:87], v[78:79], s[68:69]
	v_xor_b32_e32 v127, 0x80000000, v66
	v_pk_fma_f32 v[78:79], v[78:79], s[78:79], v[86:87] op_sel:[0,0,1] op_sel_hi:[1,0,0]
	v_pk_add_f32 v[86:87], v[80:81], v[88:89]
	v_pk_add_f32 v[88:89], v[80:81], v[88:89] neg_lo:[0,1] neg_hi:[0,1]
	v_mov_b32_e32 v58, v51
	v_pk_add_f32 v[80:81], v[82:83], v[90:91]
	v_pk_add_f32 v[82:83], v[82:83], v[90:91] neg_lo:[0,1] neg_hi:[0,1]
	v_mov_b32_e32 v126, v67
	v_pk_mul_f32 v[90:91], v[82:83], s[68:69]
	v_sin_f32_e32 v70, v40
	v_pk_fma_f32 v[82:83], v[82:83], s[78:79], v[90:91] op_sel:[0,0,1] op_sel_hi:[1,0,0] neg_lo:[1,0,0] neg_hi:[1,0,0]
	v_pk_add_f32 v[132:133], v[46:47], v[58:59]
	v_pk_add_f32 v[156:157], v[46:47], v[58:59] neg_lo:[0,1] neg_hi:[0,1]
	v_pk_add_f32 v[46:47], v[48:49], v[52:53]
	v_pk_add_f32 v[52:53], v[48:49], v[52:53] neg_lo:[0,1] neg_hi:[0,1]
	v_pk_add_f32 v[98:99], v[60:61], v[94:95]
	v_pk_add_f32 v[94:95], v[60:61], v[94:95] neg_lo:[0,1] neg_hi:[0,1]
	v_pk_add_f32 v[74:75], v[118:119], v[116:117] op_sel:[0,1] op_sel_hi:[1,0] neg_hi:[0,1]
	v_pk_add_f32 v[68:69], v[118:119], v[116:117] op_sel:[0,1] op_sel_hi:[1,0] neg_lo:[0,1]
	v_pk_add_f32 v[72:73], v[64:65], v[124:125]
	v_pk_add_f32 v[62:63], v[64:65], v[124:125] neg_lo:[0,1] neg_hi:[0,1]
	v_pk_add_f32 v[60:61], v[122:123], v[126:127]
	v_pk_add_f32 v[66:67], v[122:123], v[126:127] neg_lo:[0,1] neg_hi:[0,1]
	v_pk_add_f32 v[114:115], v[112:113], v[96:97]
	v_pk_add_f32 v[96:97], v[112:113], v[96:97] neg_lo:[0,1] neg_hi:[0,1]
	v_pk_add_f32 v[112:113], v[104:105], v[100:101]
	v_pk_add_f32 v[100:101], v[104:105], v[100:101] neg_lo:[0,1] neg_hi:[0,1]
	v_pk_add_f32 v[104:105], v[92:93], v[108:109] op_sel:[0,1] op_sel_hi:[1,0] neg_hi:[0,1]
	v_pk_add_f32 v[92:93], v[92:93], v[108:109] op_sel:[0,1] op_sel_hi:[1,0] neg_lo:[0,1]
	v_pk_add_f32 v[108:109], v[84:85], v[102:103]
	v_pk_add_f32 v[102:103], v[84:85], v[102:103] neg_lo:[0,1] neg_hi:[0,1]
	v_pk_add_f32 v[118:119], v[106:107], v[80:81]
	v_pk_add_f32 v[106:107], v[106:107], v[80:81] neg_lo:[0,1] neg_hi:[0,1]
	v_pk_add_f32 v[122:123], v[76:77], v[88:89] op_sel:[0,1] op_sel_hi:[1,0] neg_hi:[0,1]
	v_pk_add_f32 v[124:125], v[76:77], v[88:89] op_sel:[0,1] op_sel_hi:[1,0] neg_lo:[0,1]
	v_pk_add_f32 v[76:77], v[78:79], v[82:83] neg_lo:[0,1] neg_hi:[0,1]
	v_xor_b32_e32 v159, 0x80000000, v52
	v_pk_add_f32 v[64:65], v[128:129], v[56:57]
	v_pk_add_f32 v[50:51], v[128:129], v[56:57] neg_lo:[0,1] neg_hi:[0,1]
	v_mov_b32_e32 v158, v53
	v_pk_add_f32 v[116:117], v[110:111], v[86:87]
	v_pk_add_f32 v[110:111], v[110:111], v[86:87] neg_lo:[0,1] neg_hi:[0,1]
	v_pk_add_f32 v[126:127], v[78:79], v[82:83]
	v_xor_b32_e32 v129, 0x80000000, v76
	v_mov_b32_e32 v128, v77
	v_pk_add_f32 v[56:57], v[54:55], v[130:131]
	v_pk_add_f32 v[58:59], v[54:55], v[130:131] neg_lo:[0,1] neg_hi:[0,1]
	v_pk_add_f32 v[54:55], v[132:133], v[46:47]
	v_pk_add_f32 v[48:49], v[132:133], v[46:47] neg_lo:[0,1] neg_hi:[0,1]
	v_pk_add_f32 v[46:47], v[156:157], v[158:159]
	v_pk_add_f32 v[52:53], v[156:157], v[158:159] neg_lo:[0,1] neg_hi:[0,1]
	v_pk_add_f32 v[90:91], v[114:115], v[112:113]
	v_pk_add_f32 v[86:87], v[114:115], v[112:113] neg_lo:[0,1] neg_hi:[0,1]
	v_pk_add_f32 v[80:81], v[96:97], v[100:101] op_sel:[0,1] op_sel_hi:[1,0] neg_hi:[0,1]
	v_pk_add_f32 v[84:85], v[96:97], v[100:101] op_sel:[0,1] op_sel_hi:[1,0] neg_lo:[0,1]
	v_pk_add_f32 v[76:77], v[104:105], v[108:109]
	v_pk_add_f32 v[78:79], v[104:105], v[108:109] neg_lo:[0,1] neg_hi:[0,1]
	v_pk_add_f32 v[82:83], v[92:93], v[102:103] op_sel:[0,1] op_sel_hi:[1,0] neg_hi:[0,1]
	v_pk_add_f32 v[88:89], v[92:93], v[102:103] op_sel:[0,1] op_sel_hi:[1,0] neg_lo:[0,1]
	v_pk_add_f32 v[92:93], v[116:117], v[118:119]
	v_pk_add_f32 v[100:101], v[116:117], v[118:119] neg_lo:[0,1] neg_hi:[0,1]
	v_pk_add_f32 v[102:103], v[110:111], v[106:107] op_sel:[0,1] op_sel_hi:[1,0] neg_hi:[0,1]
	v_pk_add_f32 v[106:107], v[110:111], v[106:107] op_sel:[0,1] op_sel_hi:[1,0] neg_lo:[0,1]
	v_pk_add_f32 v[108:109], v[122:123], v[126:127]
	v_pk_add_f32 v[110:111], v[122:123], v[126:127] neg_lo:[0,1] neg_hi:[0,1]
	v_pk_add_f32 v[112:113], v[124:125], v[128:129]
	v_pk_add_f32 v[118:119], v[124:125], v[128:129] neg_lo:[0,1] neg_hi:[0,1]
	v_mul_f32_e32 v40, 0x3f3504f3, v71
	v_mul_f32_e32 v104, 0xbec3ef15, v71
	v_mul_f32_e32 v96, 0xbf6c835e, v71
	s_and_saveexec_b64 s[10:11], vcc
	s_xor_b64 s[10:11], exec, s[10:11]
	s_cbranch_execz .LBB0_277
	v_pk_add_f32 v[114:115], v[98:99], v[118:119]
	v_pk_add_f32 v[98:99], v[98:99], v[118:119] neg_lo:[0,1] neg_hi:[0,1]
	v_mul_f32_e32 v42, 0.5, v114
	v_pk_fma_f32 v[116:117], v[70:71], 0, v[70:71] op_sel:[0,0,1] op_sel_hi:[1,0,0] neg_lo:[1,0,0]
	v_mov_b32_e32 v114, v98
	v_pk_mul_f32 v[114:115], v[114:115], s[74:75]
	s_mov_b32 s78, s63
	v_pk_mul_f32 v[118:119], v[116:117], v[114:115] op_sel:[0,1] op_sel_hi:[1,0]
	v_pk_mul_f32 v[114:115], v[116:117], v[114:115]
	s_mov_b32 s79, s50
	v_sub_f32_e32 v97, v114, v115
	v_fma_mixlo_f16 v105, v99, s75, v97
	v_fma_f32 v97, v99, 0.5, -v97
	v_cvt_f16_f32_sdwa v97, -v97 dst_sel:WORD_1 dst_unused:UNUSED_PAD src0_sel:DWORD
	v_pk_add_f32 v[98:99], v[118:119], v[118:119] op_sel:[0,1] op_sel_hi:[0,1]
	s_waitcnt vmcnt(0)
	v_pk_add_f32 v[114:115], v[42:43], v[98:99]
	v_pk_add_f32 v[98:99], v[42:43], v[98:99] op_sel_hi:[0,1] neg_lo:[0,1] neg_hi:[0,1]
	v_cvt_pk_f16_f32 v42, v114, v99
	v_lshlrev_b32_e32 v98, 16, v105
	v_or_b32_sdwa v99, v97, v42 dst_sel:DWORD dst_unused:UNUSED_PAD src0_sel:DWORD src1_sel:WORD_1
	v_or_b32_sdwa v98, v98, v42 dst_sel:DWORD dst_unused:UNUSED_PAD src0_sel:DWORD src1_sel:WORD_0
	global_store_dwordx2 v[44:45], v[98:99], off
	v_pk_add_f32 v[98:99], v[94:95], v[112:113]
	v_pk_add_f32 v[94:95], v[94:95], v[112:113] neg_lo:[0,1] neg_hi:[0,1]
	v_mul_f32_e32 v42, 0.5, v98
	v_mov_b32_e32 v98, v71
	v_mov_b32_e32 v112, v71
	v_mov_b32_e32 v113, v70
	v_pk_fma_f32 v[114:115], v[70:71], 0, v[112:113] op_sel_hi:[1,0,1] neg_lo:[0,0,1] neg_hi:[0,0,1]
	v_pk_fma_f32 v[116:117], v[70:71], 0, v[98:99] op_sel_hi:[1,0,1]
	v_mov_b32_e32 v98, v94
	v_pk_mov_b32 v[114:115], v[114:115], v[116:117] op_sel:[1,0]
	v_pk_mul_f32 v[98:99], v[98:99], s[74:75]
	s_mov_b32 s51, s63
	v_pk_mul_f32 v[116:117], v[114:115], v[98:99] op_sel:[0,1] op_sel_hi:[1,0]
	v_pk_mul_f32 v[98:99], v[114:115], v[98:99]
	v_pk_add_f32 v[114:115], v[74:75], v[110:111]
	v_sub_f32_e32 v94, v98, v99
	v_fma_mixlo_f16 v97, v95, s75, v94
	v_fma_f32 v94, v95, 0.5, -v94
	v_cvt_f16_f32_sdwa v105, -v94 dst_sel:WORD_1 dst_unused:UNUSED_PAD src0_sel:DWORD
	v_pk_add_f32 v[94:95], v[116:117], v[116:117] op_sel:[0,1] op_sel_hi:[0,1]
	v_pk_add_f32 v[98:99], v[42:43], v[94:95]
	v_pk_add_f32 v[94:95], v[42:43], v[94:95] op_sel_hi:[0,1] neg_lo:[0,1] neg_hi:[0,1]
	v_cvt_pk_f16_f32 v42, v98, v95
	v_lshlrev_b32_e32 v94, 16, v97
	v_add_co_u32_e32 v98, vcc, s31, v44
	v_or_b32_sdwa v95, v105, v42 dst_sel:DWORD dst_unused:UNUSED_PAD src0_sel:DWORD src1_sel:WORD_1
	v_or_b32_sdwa v94, v94, v42 dst_sel:DWORD dst_unused:UNUSED_PAD src0_sel:DWORD src1_sel:WORD_0
	v_addc_co_u32_e32 v99, vcc, 0, v45, vcc
	global_store_dwordx2 v[98:99], v[94:95], off offset:-4096
	v_pk_mul_f32 v[94:95], v[112:113], s[68:69]
	v_pk_add_f32 v[74:75], v[74:75], v[110:111] neg_lo:[0,1] neg_hi:[0,1]
	v_mul_f32_e32 v42, 0.5, v114
	v_pk_add_f32 v[110:111], v[40:41], v[94:95] op_sel:[0,1] op_sel_hi:[0,1] neg_lo:[0,1] neg_hi:[0,1]
	v_pk_fma_f32 v[116:117], v[112:113], s[68:69], v[40:41] op_sel_hi:[1,1,0]
	v_mov_b32_e32 v114, v74
	v_mov_b32_e32 v111, v117
	v_pk_mul_f32 v[114:115], v[114:115], s[74:75]
	s_mov_b32 s45, s41
	v_pk_mul_f32 v[116:117], v[110:111], v[114:115] op_sel:[0,1] op_sel_hi:[1,0]
	v_pk_mul_f32 v[114:115], v[110:111], v[114:115]
	s_mov_b32 s65, s67
	v_sub_f32_e32 v40, v114, v115
	v_fma_mixlo_f16 v97, v75, s75, v40
	v_fma_f32 v40, v75, 0.5, -v40
	v_cvt_f16_f32_sdwa v40, -v40 dst_sel:WORD_1 dst_unused:UNUSED_PAD src0_sel:DWORD
	v_pk_add_f32 v[74:75], v[116:117], v[116:117] op_sel:[0,1] op_sel_hi:[0,1]
	v_pk_add_f32 v[114:115], v[42:43], v[74:75]
	v_pk_add_f32 v[74:75], v[42:43], v[74:75] op_sel_hi:[0,1] neg_lo:[0,1] neg_hi:[0,1]
	v_cvt_pk_f16_f32 v42, v114, v75
	v_lshlrev_b32_e32 v74, 16, v97
	v_or_b32_sdwa v75, v40, v42 dst_sel:DWORD dst_unused:UNUSED_PAD src0_sel:DWORD src1_sel:WORD_1
	v_or_b32_sdwa v74, v74, v42 dst_sel:DWORD dst_unused:UNUSED_PAD src0_sel:DWORD src1_sel:WORD_0
	global_store_dwordx2 v[98:99], v[74:75], off
	v_pk_fma_f32 v[74:75], v[112:113], s[68:69], v[94:95] op_sel:[0,0,1] op_sel_hi:[1,1,0] neg_lo:[0,0,1] neg_hi:[0,0,1]
	v_pk_add_f32 v[94:95], v[68:69], v[108:109]
	v_pk_add_f32 v[68:69], v[68:69], v[108:109] neg_lo:[0,1] neg_hi:[0,1]
	v_mul_f32_e32 v40, 0.5, v94
	v_mov_b32_e32 v94, v68
	v_pk_mul_f32 v[94:95], v[94:95], s[74:75]
	v_mov_b32_e32 v75, v110
	v_mov_b32_e32 v111, v74
	v_pk_mul_f32 v[74:75], v[74:75], v[94:95]
	v_pk_mul_f32 v[98:99], v[110:111], v[94:95]
	v_sub_f32_e32 v42, v74, v75
	v_fma_mixlo_f16 v94, v69, s75, v42
	v_fma_f32 v42, v69, 0.5, -v42
	v_cvt_f16_f32_sdwa v42, -v42 dst_sel:WORD_1 dst_unused:UNUSED_PAD src0_sel:DWORD
	v_pk_add_f32 v[68:69], v[98:99], v[98:99] op_sel:[1,0] op_sel_hi:[1,0]
	s_nop 0
	v_pk_add_f32 v[74:75], v[40:41], v[68:69]
	v_pk_add_f32 v[68:69], v[40:41], v[68:69] op_sel_hi:[0,1] neg_lo:[0,1] neg_hi:[0,1]
	v_cvt_pk_f16_f32 v40, v74, v69
	v_lshlrev_b32_e32 v68, 16, v94
	v_add_co_u32_e32 v74, vcc, s30, v44
	v_or_b32_sdwa v69, v42, v40 dst_sel:DWORD dst_unused:UNUSED_PAD src0_sel:DWORD src1_sel:WORD_1
	v_or_b32_sdwa v68, v68, v40 dst_sel:DWORD dst_unused:UNUSED_PAD src0_sel:DWORD src1_sel:WORD_0
	v_addc_co_u32_e32 v75, vcc, 0, v45, vcc
	global_store_dwordx2 v[74:75], v[68:69], off offset:-4096
	v_mov_b32_e32 v42, v71
	v_pk_mul_f32 v[68:69], v[70:71], s[78:79] op_sel_hi:[0,1]
	v_pk_add_f32 v[94:95], v[72:73], v[106:107]
	v_pk_add_f32 v[72:73], v[72:73], v[106:107] neg_lo:[0,1] neg_hi:[0,1]
	v_mul_f32_e32 v40, 0.5, v94
	v_pk_fma_f32 v[98:99], v[42:43], s[50:51], v[68:69] op_sel_hi:[0,1,1] neg_lo:[0,0,1] neg_hi:[0,0,1]
	v_pk_fma_f32 v[106:107], v[42:43], s[50:51], v[68:69] op_sel_hi:[0,1,1]
	v_mov_b32_e32 v94, v72
	v_mov_b32_e32 v108, v98
	v_mov_b32_e32 v109, v107
	v_pk_mul_f32 v[94:95], v[94:95], s[74:75]
	s_mov_b32 s78, s41
	v_pk_mul_f32 v[110:111], v[108:109], v[94:95] op_sel:[0,1] op_sel_hi:[1,0]
	v_pk_mul_f32 v[94:95], v[108:109], v[94:95]
	s_mov_b32 s79, s44
	v_sub_f32_e32 v72, v94, v95
	v_fma_mixlo_f16 v97, v73, s75, v72
	v_fma_f32 v72, v73, 0.5, -v72
	v_cvt_f16_f32_sdwa v105, -v72 dst_sel:WORD_1 dst_unused:UNUSED_PAD src0_sel:DWORD
	v_pk_add_f32 v[72:73], v[110:111], v[110:111] op_sel:[0,1] op_sel_hi:[0,1]
	v_pk_add_f32 v[94:95], v[40:41], v[72:73]
	v_pk_add_f32 v[72:73], v[40:41], v[72:73] op_sel_hi:[0,1] neg_lo:[0,1] neg_hi:[0,1]
	v_cvt_pk_f16_f32 v40, v94, v73
	v_lshlrev_b32_e32 v72, 16, v97
	v_or_b32_sdwa v73, v105, v40 dst_sel:DWORD dst_unused:UNUSED_PAD src0_sel:DWORD src1_sel:WORD_1
	v_or_b32_sdwa v72, v72, v40 dst_sel:DWORD dst_unused:UNUSED_PAD src0_sel:DWORD src1_sel:WORD_0
	global_store_dwordx2 v[74:75], v[72:73], off
	v_pk_add_f32 v[72:73], v[62:63], v[102:103]
	v_sub_f32_e32 v75, v63, v103
	v_mov_b32_e32 v105, v62
	v_pk_mov_b32 v[62:63], v[68:69], v[102:103] op_sel:[1,0]
	v_mul_f32_e32 v40, 0.5, v73
	v_pk_add_f32 v[62:63], v[104:105], v[62:63] neg_lo:[0,1] neg_hi:[0,1]
	v_mul_f32_e32 v74, 0.5, v72
	v_pk_mul_f32 v[94:95], v[62:63], v[40:41]
	s_nop 0
	v_mul_f32_e32 v62, v62, v95
	v_fma_f32 v40, -v98, v40, v62
	v_fma_mixlo_f16 v69, v75, s75, v40
	v_fma_f32 v40, v75, 0.5, -v40
	v_pk_fma_f32 v[102:103], v[98:99], v[94:95], v[94:95] op_sel:[0,1,0] op_sel_hi:[1,0,1]
	v_cvt_f16_f32_sdwa v40, -v40 dst_sel:WORD_1 dst_unused:UNUSED_PAD src0_sel:DWORD
	v_pk_add_f32 v[62:63], v[74:75], v[102:103]
	v_lshlrev_b32_e32 v69, 16, v69
	v_fma_f32 v63, v72, 0.5, -v102
	v_cvt_pk_f16_f32 v62, v62, v63
	v_add_co_u32_e32 v72, vcc, s33, v44
	v_or_b32_sdwa v63, v40, v62 dst_sel:DWORD dst_unused:UNUSED_PAD src0_sel:DWORD src1_sel:WORD_1
	v_or_b32_sdwa v62, v69, v62 dst_sel:DWORD dst_unused:UNUSED_PAD src0_sel:DWORD src1_sel:WORD_0
	v_addc_co_u32_e32 v73, vcc, 0, v45, vcc
	global_store_dwordx2 v[72:73], v[62:63], off offset:-4096
	v_pk_add_f32 v[62:63], v[100:101], v[60:61]
	v_pk_add_f32 v[60:61], v[60:61], v[100:101] neg_lo:[0,1] neg_hi:[0,1]
	v_mul_f32_e32 v40, 0.5, v62
	v_mov_b32_e32 v62, v60
	v_pk_mov_b32 v[74:75], v[98:99], v[106:107] op_sel:[1,0]
	v_pk_mul_f32 v[62:63], v[62:63], s[74:75]
	s_nop 0
	v_pk_mul_f32 v[94:95], v[74:75], v[62:63] op_sel:[0,1] op_sel_hi:[1,0]
	v_pk_mul_f32 v[62:63], v[74:75], v[62:63]
	s_nop 0
	v_sub_f32_e32 v60, v62, v63
	v_fma_mixlo_f16 v69, v61, s75, v60
	v_fma_f32 v60, v61, 0.5, -v60
	v_cvt_f16_f32_sdwa v97, -v60 dst_sel:WORD_1 dst_unused:UNUSED_PAD src0_sel:DWORD
	v_pk_add_f32 v[60:61], v[94:95], v[94:95] op_sel:[0,1] op_sel_hi:[0,1]
	v_pk_add_f32 v[62:63], v[40:41], v[60:61]
	v_pk_add_f32 v[60:61], v[40:41], v[60:61] op_sel_hi:[0,1] neg_lo:[0,1] neg_hi:[0,1]
	v_cvt_pk_f16_f32 v40, v62, v61
	v_lshlrev_b32_e32 v60, 16, v69
	v_or_b32_sdwa v61, v97, v40 dst_sel:DWORD dst_unused:UNUSED_PAD src0_sel:DWORD src1_sel:WORD_1
	v_or_b32_sdwa v60, v60, v40 dst_sel:DWORD dst_unused:UNUSED_PAD src0_sel:DWORD src1_sel:WORD_0
	global_store_dwordx2 v[72:73], v[60:61], off
	v_pk_add_f32 v[60:61], v[92:93], v[66:67]
	v_mov_b32_e32 v97, v66
	v_mov_b32_e32 v69, v92
	v_sub_f32_e32 v63, v67, v93
	v_mul_f32_e32 v40, 0.5, v61
	v_pk_add_f32 v[66:67], v[96:97], v[68:69] neg_lo:[0,1] neg_hi:[0,1]
	v_mul_f32_e32 v62, 0.5, v60
	v_pk_mul_f32 v[68:69], v[66:67], v[40:41]
	s_nop 0
	v_mul_f32_e32 v61, v66, v69
	v_fma_f32 v40, -v99, v40, v61
	v_fma_mixlo_f16 v61, v63, s75, v40
	v_fma_f32 v40, v63, 0.5, -v40
	v_cvt_f16_f32_sdwa v40, -v40 dst_sel:WORD_1 dst_unused:UNUSED_PAD src0_sel:DWORD
	v_pk_fma_f32 v[72:73], v[74:75], v[68:69], v[68:69] op_sel:[0,1,0] op_sel_hi:[1,0,1]
	v_pk_add_f32 v[66:67], v[64:65], v[88:89]
	v_pk_add_f32 v[62:63], v[62:63], v[72:73]
	v_fma_f32 v60, v60, 0.5, -v72
	v_cvt_pk_f16_f32 v60, v62, v60
	v_lshlrev_b32_e32 v62, 16, v61
	v_or_b32_sdwa v61, v40, v60 dst_sel:DWORD dst_unused:UNUSED_PAD src0_sel:DWORD src1_sel:WORD_1
	v_or_b32_sdwa v60, v62, v60 dst_sel:DWORD dst_unused:UNUSED_PAD src0_sel:DWORD src1_sel:WORD_0
	v_add_co_u32_e32 v62, vcc, s34, v44
	v_pk_add_f32 v[64:65], v[64:65], v[88:89] neg_lo:[0,1] neg_hi:[0,1]
	s_nop 0
	v_addc_co_u32_e32 v63, vcc, 0, v45, vcc
	global_store_dwordx2 v[62:63], v[60:61], off offset:-4096
	v_pk_mul_f32 v[60:61], v[70:71], s[44:45] op_sel_hi:[0,1]
	v_mul_f32_e32 v40, 0.5, v66
	v_pk_fma_f32 v[68:69], v[42:43], s[78:79], v[60:61] op_sel_hi:[0,1,1] neg_lo:[0,0,1] neg_hi:[0,0,1]
	v_pk_fma_f32 v[72:73], v[42:43], s[78:79], v[60:61] op_sel_hi:[0,1,1]
	v_mov_b32_e32 v66, v64
	v_mov_b32_e32 v74, v68
	v_mov_b32_e32 v75, v73
	v_pk_mul_f32 v[66:67], v[66:67], s[74:75]
	s_mov_b32 s78, s67
	v_pk_mul_f32 v[88:89], v[74:75], v[66:67] op_sel:[0,1] op_sel_hi:[1,0]
	v_pk_mul_f32 v[66:67], v[74:75], v[66:67]
	s_mov_b32 s79, s64
	v_sub_f32_e32 v64, v66, v67
	v_fma_mixlo_f16 v74, v65, s75, v64
	v_fma_f32 v64, v65, 0.5, -v64
	v_cvt_f16_f32_sdwa v75, -v64 dst_sel:WORD_1 dst_unused:UNUSED_PAD src0_sel:DWORD
	v_pk_add_f32 v[64:65], v[88:89], v[88:89] op_sel:[0,1] op_sel_hi:[0,1]
	v_pk_add_f32 v[66:67], v[40:41], v[64:65]
	v_pk_add_f32 v[64:65], v[40:41], v[64:65] op_sel_hi:[0,1] neg_lo:[0,1] neg_hi:[0,1]
	v_cvt_pk_f16_f32 v40, v66, v65
	v_lshlrev_b32_e32 v64, 16, v74
	v_or_b32_sdwa v65, v75, v40 dst_sel:DWORD dst_unused:UNUSED_PAD src0_sel:DWORD src1_sel:WORD_1
	v_or_b32_sdwa v64, v64, v40 dst_sel:DWORD dst_unused:UNUSED_PAD src0_sel:DWORD src1_sel:WORD_0
	global_store_dwordx2 v[62:63], v[64:65], off
	v_mul_f32_e32 v62, 0xbe47c5c2, v71
	v_pk_add_f32 v[64:65], v[50:51], v[82:83]
	v_sub_f32_e32 v67, v51, v83
	v_mov_b32_e32 v63, v50
	v_pk_mov_b32 v[50:51], v[60:61], v[82:83] op_sel:[1,0]
	v_mul_f32_e32 v40, 0.5, v65
	v_pk_add_f32 v[50:51], v[62:63], v[50:51] neg_lo:[0,1] neg_hi:[0,1]
	v_mul_f32_e32 v66, 0.5, v64
	v_pk_mul_f32 v[62:63], v[50:51], v[40:41]
	s_nop 0
	v_mul_f32_e32 v50, v50, v63
	v_fma_f32 v40, -v68, v40, v50
	v_fma_mixlo_f16 v61, v67, s75, v40
	v_fma_f32 v40, v67, 0.5, -v40
	v_pk_fma_f32 v[74:75], v[68:69], v[62:63], v[62:63] op_sel:[0,1,0] op_sel_hi:[1,0,1]
	v_cvt_f16_f32_sdwa v40, -v40 dst_sel:WORD_1 dst_unused:UNUSED_PAD src0_sel:DWORD
	v_pk_add_f32 v[50:51], v[66:67], v[74:75]
	v_lshlrev_b32_e32 v61, 16, v61
	v_fma_f32 v51, v64, 0.5, -v74
	v_cvt_pk_f16_f32 v50, v50, v51
	v_add_co_u32_e32 v62, vcc, s35, v44
	v_or_b32_sdwa v51, v40, v50 dst_sel:DWORD dst_unused:UNUSED_PAD src0_sel:DWORD src1_sel:WORD_1
	v_or_b32_sdwa v50, v61, v50 dst_sel:DWORD dst_unused:UNUSED_PAD src0_sel:DWORD src1_sel:WORD_0
	v_addc_co_u32_e32 v63, vcc, 0, v45, vcc
	global_store_dwordx2 v[62:63], v[50:51], off offset:-4096
	v_pk_mul_f32 v[50:51], v[70:71], s[64:65] op_sel_hi:[0,1]
	v_pk_add_f32 v[64:65], v[78:79], v[56:57]
	v_pk_add_f32 v[56:57], v[56:57], v[78:79] neg_lo:[0,1] neg_hi:[0,1]
	v_mul_f32_e32 v40, 0.5, v64
	v_pk_fma_f32 v[66:67], v[42:43], s[78:79], v[50:51] op_sel_hi:[0,1,1] neg_lo:[0,0,1] neg_hi:[0,0,1]
	v_pk_fma_f32 v[74:75], v[42:43], s[78:79], v[50:51] op_sel_hi:[0,1,1]
	v_mov_b32_e32 v64, v56
	v_mov_b32_e32 v78, v66
	v_mov_b32_e32 v79, v75
	v_pk_mul_f32 v[64:65], v[64:65], s[74:75]
	s_nop 0
	v_pk_mul_f32 v[82:83], v[78:79], v[64:65] op_sel:[0,1] op_sel_hi:[1,0]
	v_pk_mul_f32 v[64:65], v[78:79], v[64:65]
	s_nop 0
	v_sub_f32_e32 v42, v64, v65
	v_fma_mixlo_f16 v61, v57, s75, v42
	v_fma_f32 v42, v57, 0.5, -v42
	v_cvt_f16_f32_sdwa v42, -v42 dst_sel:WORD_1 dst_unused:UNUSED_PAD src0_sel:DWORD
	v_pk_add_f32 v[56:57], v[82:83], v[82:83] op_sel:[0,1] op_sel_hi:[0,1]
	v_pk_add_f32 v[64:65], v[40:41], v[56:57]
	v_pk_add_f32 v[56:57], v[40:41], v[56:57] op_sel_hi:[0,1] neg_lo:[0,1] neg_hi:[0,1]
	v_cvt_pk_f16_f32 v40, v64, v57
	v_lshlrev_b32_e32 v56, 16, v61
	v_or_b32_sdwa v57, v42, v40 dst_sel:DWORD dst_unused:UNUSED_PAD src0_sel:DWORD src1_sel:WORD_1
	v_or_b32_sdwa v56, v56, v40 dst_sel:DWORD dst_unused:UNUSED_PAD src0_sel:DWORD src1_sel:WORD_0
	global_store_dwordx2 v[62:63], v[56:57], off
	v_mul_f32_e32 v56, 0xbf54db31, v71
	v_pk_add_f32 v[62:63], v[76:77], v[58:59]
	v_sub_f32_e32 v61, v59, v77
	v_mov_b32_e32 v57, v58
	v_pk_mov_b32 v[58:59], v[50:51], v[76:77] op_sel:[1,0]
	v_mul_f32_e32 v40, 0.5, v63
	v_pk_add_f32 v[56:57], v[56:57], v[58:59] neg_lo:[0,1] neg_hi:[0,1]
	v_mul_f32_e32 v42, 0.5, v62
	v_pk_mul_f32 v[58:59], v[56:57], v[40:41]
	s_nop 0
	v_mul_f32_e32 v51, v56, v59
	v_fma_f32 v40, -v66, v40, v51
	v_fma_mixlo_f16 v51, v61, s75, v40
	v_fma_f32 v40, v61, 0.5, -v40
	v_cvt_f16_f32_sdwa v40, -v40 dst_sel:WORD_1 dst_unused:UNUSED_PAD src0_sel:DWORD
	v_pk_fma_f32 v[64:65], v[66:67], v[58:59], v[58:59] op_sel:[0,1,0] op_sel_hi:[1,0,1]
	v_lshlrev_b32_e32 v51, 16, v51
	v_pk_add_f32 v[56:57], v[42:43], v[64:65]
	v_fma_f32 v42, v62, 0.5, -v64
	v_cvt_pk_f16_f32 v42, v56, v42
	v_add_co_u32_e32 v58, vcc, s39, v44
	v_or_b32_sdwa v57, v40, v42 dst_sel:DWORD dst_unused:UNUSED_PAD src0_sel:DWORD src1_sel:WORD_1
	v_or_b32_sdwa v56, v51, v42 dst_sel:DWORD dst_unused:UNUSED_PAD src0_sel:DWORD src1_sel:WORD_0
	v_addc_co_u32_e32 v59, vcc, 0, v45, vcc
	global_store_dwordx2 v[58:59], v[56:57], off offset:-4096
	v_pk_add_f32 v[56:57], v[84:85], v[54:55]
	v_pk_add_f32 v[54:55], v[54:55], v[84:85] neg_lo:[0,1] neg_hi:[0,1]
	v_mul_f32_e32 v40, 0.5, v56
	v_mov_b32_e32 v56, v54
	v_pk_mov_b32 v[62:63], v[66:67], v[74:75] op_sel:[1,0]
	v_pk_mul_f32 v[56:57], v[56:57], s[74:75]
	s_nop 0
	v_pk_mul_f32 v[64:65], v[62:63], v[56:57] op_sel:[0,1] op_sel_hi:[1,0]
	v_pk_mul_f32 v[56:57], v[62:63], v[56:57]
	s_nop 0
	v_sub_f32_e32 v42, v56, v57
	v_fma_mixlo_f16 v51, v55, s75, v42
	v_fma_f32 v42, v55, 0.5, -v42
	v_cvt_f16_f32_sdwa v42, -v42 dst_sel:WORD_1 dst_unused:UNUSED_PAD src0_sel:DWORD
	v_pk_add_f32 v[54:55], v[64:65], v[64:65] op_sel:[0,1] op_sel_hi:[0,1]
	v_pk_add_f32 v[56:57], v[40:41], v[54:55]
	v_pk_add_f32 v[54:55], v[40:41], v[54:55] op_sel_hi:[0,1] neg_lo:[0,1] neg_hi:[0,1]
	v_cvt_pk_f16_f32 v40, v56, v55
	v_lshlrev_b32_e32 v51, 16, v51
	v_or_b32_sdwa v55, v42, v40 dst_sel:DWORD dst_unused:UNUSED_PAD src0_sel:DWORD src1_sel:WORD_1
	v_or_b32_sdwa v54, v51, v40 dst_sel:DWORD dst_unused:UNUSED_PAD src0_sel:DWORD src1_sel:WORD_0
	global_store_dwordx2 v[58:59], v[54:55], off
	v_mul_f32_e32 v54, 0xbf0e39da, v71
	v_pk_add_f32 v[56:57], v[80:81], v[48:49]
	v_mov_b32_e32 v55, v48
	v_mov_b32_e32 v51, v80
	v_sub_f32_e32 v58, v49, v81
	v_mul_f32_e32 v40, 0.5, v57
	v_pk_add_f32 v[48:49], v[54:55], v[50:51] neg_lo:[0,1] neg_hi:[0,1]
	v_mul_f32_e32 v42, 0.5, v56
	v_pk_mul_f32 v[50:51], v[48:49], v[40:41]
	s_nop 0
	v_mul_f32_e32 v48, v48, v51
	v_fma_f32 v40, -v67, v40, v48
	v_pk_fma_f32 v[54:55], v[62:63], v[50:51], v[50:51] op_sel:[0,1,0] op_sel_hi:[1,0,1]
	v_fma_mixlo_f16 v50, v58, s75, v40
	v_fma_f32 v40, v58, 0.5, -v40
	v_cvt_f16_f32_sdwa v40, -v40 dst_sel:WORD_1 dst_unused:UNUSED_PAD src0_sel:DWORD
	v_pk_add_f32 v[48:49], v[42:43], v[54:55]
	v_fma_f32 v42, v56, 0.5, -v54
	v_cvt_pk_f16_f32 v42, v48, v42
	v_lshlrev_b32_e32 v48, 16, v50
	v_add_co_u32_e32 v50, vcc, s43, v44
	v_or_b32_sdwa v49, v40, v42 dst_sel:DWORD dst_unused:UNUSED_PAD src0_sel:DWORD src1_sel:WORD_1
	v_or_b32_sdwa v48, v48, v42 dst_sel:DWORD dst_unused:UNUSED_PAD src0_sel:DWORD src1_sel:WORD_0
	v_addc_co_u32_e32 v51, vcc, 0, v45, vcc
	global_store_dwordx2 v[50:51], v[48:49], off offset:-4096
	v_pk_add_f32 v[48:49], v[86:87], v[46:47]
	v_pk_add_f32 v[46:47], v[46:47], v[86:87] neg_lo:[0,1] neg_hi:[0,1]
	v_mul_f32_e32 v40, 0.5, v48
	v_mov_b32_e32 v48, v46
	v_pk_mov_b32 v[54:55], v[68:69], v[72:73] op_sel:[1,0]
	v_pk_mul_f32 v[48:49], v[48:49], s[74:75]
	s_nop 0
	v_pk_mul_f32 v[56:57], v[54:55], v[48:49] op_sel:[0,1] op_sel_hi:[1,0]
	v_pk_mul_f32 v[48:49], v[54:55], v[48:49]
	s_nop 0
	v_sub_f32_e32 v42, v48, v49
	v_fma_mixlo_f16 v54, v47, s75, v42
	v_fma_f32 v42, v47, 0.5, -v42
	v_pk_add_f32 v[46:47], v[56:57], v[56:57] op_sel:[0,1] op_sel_hi:[0,1]
	v_pk_add_f32 v[48:49], v[40:41], v[46:47]
	v_pk_add_f32 v[46:47], v[40:41], v[46:47] op_sel_hi:[0,1] neg_lo:[0,1] neg_hi:[0,1]
	v_cvt_pk_f16_f32 v56, v48, v47
	v_pk_add_f32 v[46:47], v[52:53], v[90:91]
	v_pk_add_f32 v[48:49], v[52:53], v[90:91] neg_lo:[0,1] neg_hi:[0,1]
	v_mov_b32_e32 v52, v46
	v_mov_b32_e32 v53, v49
	v_mov_b32_e32 v49, v47
	v_pk_mul_f32 v[46:47], v[48:49], s[74:75]
	v_fma_f32 v40, v71, s40, -v60
	v_pk_mul_f32 v[48:49], v[68:69], v[46:47] op_sel:[1,0]
	v_lshlrev_b32_e32 v57, 16, v54
	v_pk_fma_f32 v[54:55], v[40:41], v[46:47], v[48:49] op_sel:[0,1,0] op_sel_hi:[0,0,1] neg_hi:[0,0,1]
	s_nop 0
	s_nop 0
	v_pk_fma_f32 v[46:47], v[52:53], 0.5, v[54:55] op_sel_hi:[1,0,1]
	v_cvt_f16_f32_sdwa v42, -v42 dst_sel:WORD_1 dst_unused:UNUSED_PAD src0_sel:DWORD
	v_cvt_f16_f32_e32 v40, v46
	v_cvt_f16_f32_sdwa v48, v47 dst_sel:WORD_1 dst_unused:UNUSED_PAD src0_sel:DWORD
	v_or_b32_sdwa v46, v57, v56 dst_sel:DWORD dst_unused:UNUSED_PAD src0_sel:DWORD src1_sel:WORD_0
	v_or_b32_sdwa v47, v42, v56 dst_sel:DWORD dst_unused:UNUSED_PAD src0_sel:DWORD src1_sel:WORD_1
	v_pk_fma_f32 v[116:117], v[52:53], 0.5, v[54:55] op_sel_hi:[1,0,1] neg_lo:[0,0,1] neg_hi:[0,0,1]
	v_or_b32_e32 v114, v48, v40
	global_store_dwordx2 v[50:51], v[46:47], off
.LBB0_277:
	s_andn2_saveexec_b64 s[10:11], s[10:11]
	s_cbranch_execz .LBB0_270
	v_pk_add_f32 v[114:115], v[90:91], v[118:119]
	v_pk_add_f32 v[90:91], v[90:91], v[118:119] neg_lo:[0,1] neg_hi:[0,1]
	v_mul_f32_e32 v42, 0.5, v114
	v_pk_fma_f32 v[116:117], v[70:71], 0, v[70:71] op_sel:[0,0,1] op_sel_hi:[1,0,0] neg_lo:[1,0,0]
	v_mov_b32_e32 v114, v90
	v_pk_mul_f32 v[114:115], v[114:115], s[74:75]
	s_mov_b32 s78, s63
	v_pk_mul_f32 v[118:119], v[116:117], v[114:115] op_sel:[0,1] op_sel_hi:[1,0]
	v_pk_mul_f32 v[114:115], v[116:117], v[114:115]
	s_mov_b32 s79, s50
	v_sub_f32_e32 v90, v114, v115
	v_fma_mixlo_f16 v97, v91, s75, v90
	v_fma_f32 v90, v91, 0.5, -v90
	v_cvt_f16_f32_sdwa v105, -v90 dst_sel:WORD_1 dst_unused:UNUSED_PAD src0_sel:DWORD
	v_pk_add_f32 v[90:91], v[118:119], v[118:119] op_sel:[0,1] op_sel_hi:[0,1]
	s_waitcnt vmcnt(0)
	v_pk_add_f32 v[114:115], v[42:43], v[90:91]
	v_pk_add_f32 v[90:91], v[42:43], v[90:91] op_sel_hi:[0,1] neg_lo:[0,1] neg_hi:[0,1]
	v_cvt_pk_f16_f32 v42, v114, v91
	v_lshlrev_b32_e32 v90, 16, v97
	v_or_b32_sdwa v91, v105, v42 dst_sel:DWORD dst_unused:UNUSED_PAD src0_sel:DWORD src1_sel:WORD_1
	v_or_b32_sdwa v90, v90, v42 dst_sel:DWORD dst_unused:UNUSED_PAD src0_sel:DWORD src1_sel:WORD_0
	global_store_dwordx2 v[44:45], v[90:91], off
	v_pk_add_f32 v[90:91], v[86:87], v[112:113]
	v_pk_add_f32 v[86:87], v[86:87], v[112:113] neg_lo:[0,1] neg_hi:[0,1]
	v_mul_f32_e32 v42, 0.5, v90
	v_mov_b32_e32 v90, v71
	v_mov_b32_e32 v112, v71
	v_mov_b32_e32 v113, v70
	v_pk_fma_f32 v[114:115], v[70:71], 0, v[112:113] op_sel_hi:[1,0,1] neg_lo:[0,0,1] neg_hi:[0,0,1]
	v_pk_fma_f32 v[116:117], v[70:71], 0, v[90:91] op_sel_hi:[1,0,1]
	v_mov_b32_e32 v90, v86
	v_pk_mov_b32 v[114:115], v[114:115], v[116:117] op_sel:[1,0]
	v_pk_mul_f32 v[90:91], v[90:91], s[74:75]
	s_mov_b32 s51, s63
	v_pk_mul_f32 v[116:117], v[114:115], v[90:91] op_sel:[0,1] op_sel_hi:[1,0]
	v_pk_mul_f32 v[90:91], v[114:115], v[90:91]
	v_pk_add_f32 v[114:115], v[80:81], v[110:111]
	v_sub_f32_e32 v86, v90, v91
	v_fma_mixlo_f16 v97, v87, s75, v86
	v_fma_f32 v86, v87, 0.5, -v86
	v_cvt_f16_f32_sdwa v105, -v86 dst_sel:WORD_1 dst_unused:UNUSED_PAD src0_sel:DWORD
	v_pk_add_f32 v[86:87], v[116:117], v[116:117] op_sel:[0,1] op_sel_hi:[0,1]
	v_pk_add_f32 v[90:91], v[42:43], v[86:87]
	v_pk_add_f32 v[86:87], v[42:43], v[86:87] op_sel_hi:[0,1] neg_lo:[0,1] neg_hi:[0,1]
	v_cvt_pk_f16_f32 v42, v90, v87
	v_lshlrev_b32_e32 v86, 16, v97
	v_add_co_u32_e32 v90, vcc, s31, v44
	v_or_b32_sdwa v87, v105, v42 dst_sel:DWORD dst_unused:UNUSED_PAD src0_sel:DWORD src1_sel:WORD_1
	v_or_b32_sdwa v86, v86, v42 dst_sel:DWORD dst_unused:UNUSED_PAD src0_sel:DWORD src1_sel:WORD_0
	v_addc_co_u32_e32 v91, vcc, 0, v45, vcc
	global_store_dwordx2 v[90:91], v[86:87], off offset:-4096
	v_pk_mul_f32 v[86:87], v[112:113], s[68:69]
	v_pk_add_f32 v[80:81], v[80:81], v[110:111] neg_lo:[0,1] neg_hi:[0,1]
	v_mul_f32_e32 v42, 0.5, v114
	v_pk_add_f32 v[110:111], v[40:41], v[86:87] op_sel:[0,1] op_sel_hi:[0,1] neg_lo:[0,1] neg_hi:[0,1]
	v_pk_fma_f32 v[116:117], v[112:113], s[68:69], v[40:41] op_sel_hi:[1,1,0]
	v_mov_b32_e32 v114, v80
	v_mov_b32_e32 v111, v117
	v_pk_mul_f32 v[114:115], v[114:115], s[74:75]
	v_mov_b32_e32 v105, v78
	v_pk_mul_f32 v[116:117], v[110:111], v[114:115] op_sel:[0,1] op_sel_hi:[1,0]
	v_pk_mul_f32 v[114:115], v[110:111], v[114:115]
	s_mov_b32 s45, s41
	v_sub_f32_e32 v40, v114, v115
	v_fma_mixlo_f16 v97, v81, s75, v40
	v_fma_f32 v40, v81, 0.5, -v40
	v_cvt_f16_f32_sdwa v40, -v40 dst_sel:WORD_1 dst_unused:UNUSED_PAD src0_sel:DWORD
	v_pk_add_f32 v[80:81], v[116:117], v[116:117] op_sel:[0,1] op_sel_hi:[0,1]
	v_pk_add_f32 v[114:115], v[42:43], v[80:81]
	v_pk_add_f32 v[80:81], v[42:43], v[80:81] op_sel_hi:[0,1] neg_lo:[0,1] neg_hi:[0,1]
	v_cvt_pk_f16_f32 v42, v114, v81
	v_lshlrev_b32_e32 v80, 16, v97
	v_or_b32_sdwa v81, v40, v42 dst_sel:DWORD dst_unused:UNUSED_PAD src0_sel:DWORD src1_sel:WORD_1
	v_or_b32_sdwa v80, v80, v42 dst_sel:DWORD dst_unused:UNUSED_PAD src0_sel:DWORD src1_sel:WORD_0
	global_store_dwordx2 v[90:91], v[80:81], off
	v_pk_fma_f32 v[80:81], v[112:113], s[68:69], v[86:87] op_sel:[0,0,1] op_sel_hi:[1,1,0] neg_lo:[0,0,1] neg_hi:[0,0,1]
	v_pk_add_f32 v[86:87], v[84:85], v[108:109]
	v_pk_add_f32 v[84:85], v[84:85], v[108:109] neg_lo:[0,1] neg_hi:[0,1]
	v_mul_f32_e32 v40, 0.5, v86
	v_mov_b32_e32 v86, v84
	v_pk_mul_f32 v[86:87], v[86:87], s[74:75]
	v_mov_b32_e32 v81, v110
	v_mov_b32_e32 v111, v80
	v_pk_mul_f32 v[80:81], v[80:81], v[86:87]
	v_pk_mul_f32 v[90:91], v[110:111], v[86:87]
	v_sub_f32_e32 v42, v80, v81
	v_fma_mixlo_f16 v86, v85, s75, v42
	v_fma_f32 v42, v85, 0.5, -v42
	v_cvt_f16_f32_sdwa v42, -v42 dst_sel:WORD_1 dst_unused:UNUSED_PAD src0_sel:DWORD
	v_pk_add_f32 v[80:81], v[90:91], v[90:91] op_sel:[1,0] op_sel_hi:[1,0]
	s_mov_b32 s80, s41
	v_pk_add_f32 v[84:85], v[40:41], v[80:81]
	v_pk_add_f32 v[80:81], v[40:41], v[80:81] op_sel_hi:[0,1] neg_lo:[0,1] neg_hi:[0,1]
	v_cvt_pk_f16_f32 v40, v84, v81
	v_lshlrev_b32_e32 v80, 16, v86
	v_add_co_u32_e32 v84, vcc, s30, v44
	v_or_b32_sdwa v81, v42, v40 dst_sel:DWORD dst_unused:UNUSED_PAD src0_sel:DWORD src1_sel:WORD_1
	v_or_b32_sdwa v80, v80, v40 dst_sel:DWORD dst_unused:UNUSED_PAD src0_sel:DWORD src1_sel:WORD_0
	v_addc_co_u32_e32 v85, vcc, 0, v45, vcc
	global_store_dwordx2 v[84:85], v[80:81], off offset:-4096
	v_mov_b32_e32 v40, v71
	v_pk_mul_f32 v[70:71], v[70:71], s[78:79] op_sel_hi:[0,1]
	v_pk_add_f32 v[80:81], v[76:77], v[106:107]
	v_pk_add_f32 v[76:77], v[76:77], v[106:107] neg_lo:[0,1] neg_hi:[0,1]
	v_mul_f32_e32 v42, 0.5, v80
	v_pk_fma_f32 v[86:87], v[40:41], s[50:51], v[70:71] op_sel_hi:[0,1,1] neg_lo:[0,0,1] neg_hi:[0,0,1]
	v_pk_fma_f32 v[90:91], v[40:41], s[50:51], v[70:71] op_sel_hi:[0,1,1]
	v_mov_b32_e32 v80, v76
	v_mov_b32_e32 v106, v86
	v_mov_b32_e32 v107, v91
	v_pk_mul_f32 v[80:81], v[80:81], s[74:75]
	s_mov_b32 s81, s44
	v_pk_mul_f32 v[108:109], v[106:107], v[80:81] op_sel:[0,1] op_sel_hi:[1,0]
	v_pk_mul_f32 v[80:81], v[106:107], v[80:81]
	s_mov_b32 s65, s67
	v_sub_f32_e32 v40, v80, v81
	v_fma_mixlo_f16 v97, v77, s75, v40
	v_fma_f32 v40, v77, 0.5, -v40
	v_cvt_f16_f32_sdwa v40, -v40 dst_sel:WORD_1 dst_unused:UNUSED_PAD src0_sel:DWORD
	v_pk_add_f32 v[76:77], v[108:109], v[108:109] op_sel:[0,1] op_sel_hi:[0,1]
	v_pk_add_f32 v[80:81], v[42:43], v[76:77]
	v_pk_add_f32 v[76:77], v[42:43], v[76:77] op_sel_hi:[0,1] neg_lo:[0,1] neg_hi:[0,1]
	v_cvt_pk_f16_f32 v42, v80, v77
	v_lshlrev_b32_e32 v76, 16, v97
	v_or_b32_sdwa v77, v40, v42 dst_sel:DWORD dst_unused:UNUSED_PAD src0_sel:DWORD src1_sel:WORD_1
	v_or_b32_sdwa v76, v76, v42 dst_sel:DWORD dst_unused:UNUSED_PAD src0_sel:DWORD src1_sel:WORD_0
	global_store_dwordx2 v[84:85], v[76:77], off
	v_pk_add_f32 v[76:77], v[78:79], v[102:103]
	v_sub_f32_e32 v97, v79, v103
	v_pk_mov_b32 v[78:79], v[70:71], v[102:103] op_sel:[1,0]
	v_mul_f32_e32 v40, 0.5, v77
	v_pk_add_f32 v[78:79], v[104:105], v[78:79] neg_lo:[0,1] neg_hi:[0,1]
	v_mul_f32_e32 v42, 0.5, v76
	v_pk_mul_f32 v[80:81], v[78:79], v[40:41]
	s_mov_b32 s82, s69
	v_mul_f32_e32 v71, v78, v81
	v_fma_f32 v40, -v86, v40, v71
	v_fma_mixlo_f16 v71, v97, s75, v40
	v_fma_f32 v40, v97, 0.5, -v40
	v_cvt_f16_f32_sdwa v40, -v40 dst_sel:WORD_1 dst_unused:UNUSED_PAD src0_sel:DWORD
	v_pk_fma_f32 v[84:85], v[86:87], v[80:81], v[80:81] op_sel:[0,1,0] op_sel_hi:[1,0,1]
	v_lshlrev_b32_e32 v71, 16, v71
	v_pk_add_f32 v[78:79], v[42:43], v[84:85]
	v_fma_f32 v42, v76, 0.5, -v84
	v_cvt_pk_f16_f32 v42, v78, v42
	v_add_co_u32_e32 v78, vcc, s33, v44
	v_or_b32_sdwa v77, v40, v42 dst_sel:DWORD dst_unused:UNUSED_PAD src0_sel:DWORD src1_sel:WORD_1
	v_or_b32_sdwa v76, v71, v42 dst_sel:DWORD dst_unused:UNUSED_PAD src0_sel:DWORD src1_sel:WORD_0
	v_addc_co_u32_e32 v79, vcc, 0, v45, vcc
	global_store_dwordx2 v[78:79], v[76:77], off offset:-4096
	v_pk_add_f32 v[76:77], v[100:101], v[82:83]
	v_pk_add_f32 v[80:81], v[82:83], v[100:101] neg_lo:[0,1] neg_hi:[0,1]
	v_mul_f32_e32 v40, 0.5, v76
	v_mov_b32_e32 v76, v80
	v_pk_mov_b32 v[82:83], v[86:87], v[90:91] op_sel:[1,0]
	v_pk_mul_f32 v[76:77], v[76:77], s[74:75]
	v_mov_b32_e32 v97, v88
	v_pk_mul_f32 v[84:85], v[82:83], v[76:77] op_sel:[0,1] op_sel_hi:[1,0]
	v_pk_mul_f32 v[76:77], v[82:83], v[76:77]
	s_nop 0
	v_sub_f32_e32 v42, v76, v77
	v_fma_mixlo_f16 v71, v81, s75, v42
	v_fma_f32 v42, v81, 0.5, -v42
	v_cvt_f16_f32_sdwa v42, -v42 dst_sel:WORD_1 dst_unused:UNUSED_PAD src0_sel:DWORD
	v_pk_add_f32 v[76:77], v[84:85], v[84:85] op_sel:[0,1] op_sel_hi:[0,1]
	v_pk_add_f32 v[80:81], v[40:41], v[76:77]
	v_pk_add_f32 v[76:77], v[40:41], v[76:77] op_sel_hi:[0,1] neg_lo:[0,1] neg_hi:[0,1]
	v_cvt_pk_f16_f32 v40, v80, v77
	v_lshlrev_b32_e32 v71, 16, v71
	v_or_b32_sdwa v77, v42, v40 dst_sel:DWORD dst_unused:UNUSED_PAD src0_sel:DWORD src1_sel:WORD_1
	v_or_b32_sdwa v76, v71, v40 dst_sel:DWORD dst_unused:UNUSED_PAD src0_sel:DWORD src1_sel:WORD_0
	global_store_dwordx2 v[78:79], v[76:77], off
	v_pk_add_f32 v[76:77], v[92:93], v[88:89]
	v_mov_b32_e32 v71, v92
	v_mul_f32_e32 v40, 0.5, v77
	v_pk_add_f32 v[70:71], v[96:97], v[70:71] neg_lo:[0,1] neg_hi:[0,1]
	v_sub_f32_e32 v84, v89, v93
	v_pk_mul_f32 v[78:79], v[70:71], v[40:41]
	v_mul_f32_e32 v42, 0.5, v76
	v_mul_f32_e32 v70, v70, v79
	v_fma_f32 v40, -v87, v40, v70
	v_fma_mixlo_f16 v77, v84, s75, v40
	v_fma_f32 v40, v84, 0.5, -v40
	v_cvt_f16_f32_sdwa v40, -v40 dst_sel:WORD_1 dst_unused:UNUSED_PAD src0_sel:DWORD
	v_pk_fma_f32 v[80:81], v[82:83], v[78:79], v[78:79] op_sel:[0,1,0] op_sel_hi:[1,0,1]
	s_nop 0
	v_pk_add_f32 v[70:71], v[42:43], v[80:81]
	v_fma_f32 v42, v76, 0.5, -v80
	v_cvt_pk_f16_f32 v42, v70, v42
	v_lshlrev_b32_e32 v70, 16, v77
	v_or_b32_sdwa v71, v40, v42 dst_sel:DWORD dst_unused:UNUSED_PAD src0_sel:DWORD src1_sel:WORD_1
	v_sub_f32_e32 v40, v98, v99
	v_or_b32_sdwa v70, v70, v42 dst_sel:DWORD dst_unused:UNUSED_PAD src0_sel:DWORD src1_sel:WORD_0
	v_add_co_u32_e32 v76, vcc, s34, v44
	v_cvt_f16_f32_sdwa v42, -v95 dst_sel:WORD_1 dst_unused:UNUSED_PAD src0_sel:DWORD
	v_cvt_f16_f32_sdwa v40, v40 dst_sel:WORD_1 dst_unused:UNUSED_PAD src0_sel:DWORD
	v_addc_co_u32_e32 v77, vcc, 0, v45, vcc
	global_store_dwordx2 v[76:77], v[70:71], off offset:-4096
	v_pk_add_f32 v[70:71], v[98:99], v[98:99] op_sel:[0,1] op_sel_hi:[1,0]
	s_nop 0
	v_cvt_pk_f16_f32 v70, v70, v94
	v_or_b32_sdwa v71, v42, v70 dst_sel:DWORD dst_unused:UNUSED_PAD src0_sel:DWORD src1_sel:WORD_1
	v_or_b32_sdwa v70, v40, v70 dst_sel:DWORD dst_unused:UNUSED_PAD src0_sel:DWORD src1_sel:WORD_0
	global_store_dwordx2 v[76:77], v[70:71], off
	v_pk_add_f32 v[70:71], v[64:65], v[52:53]
	v_pk_add_f32 v[52:53], v[64:65], v[52:53] neg_lo:[0,1] neg_hi:[0,1]
	v_mul_f32_e32 v40, 0.5, v70
	v_mov_b32_e32 v70, v52
	v_pk_mul_f32 v[64:65], v[70:71], s[74:75]
	s_nop 0
	v_pk_mul_f32 v[70:71], v[64:65], s[44:45]
	v_pk_mul_f32 v[64:65], v[64:65], s[80:81]
	s_mov_b32 s80, s67
	v_sub_f32_e32 v42, v64, v65
	v_fma_mixlo_f16 v76, v53, s75, v42
	v_fma_f32 v42, v53, 0.5, -v42
	v_cvt_f16_f32_sdwa v42, -v42 dst_sel:WORD_1 dst_unused:UNUSED_PAD src0_sel:DWORD
	v_pk_add_f32 v[52:53], v[70:71], v[70:71] op_sel:[1,0] op_sel_hi:[1,0]
	s_mov_b32 s81, s64
	v_pk_add_f32 v[64:65], v[40:41], v[52:53]
	v_pk_add_f32 v[52:53], v[40:41], v[52:53] op_sel_hi:[0,1] neg_lo:[0,1] neg_hi:[0,1]
	v_cvt_pk_f16_f32 v40, v64, v53
	v_lshlrev_b32_e32 v52, 16, v76
	v_add_co_u32_e32 v64, vcc, s35, v44
	v_or_b32_sdwa v53, v42, v40 dst_sel:DWORD dst_unused:UNUSED_PAD src0_sel:DWORD src1_sel:WORD_1
	v_or_b32_sdwa v52, v52, v40 dst_sel:DWORD dst_unused:UNUSED_PAD src0_sel:DWORD src1_sel:WORD_0
	v_addc_co_u32_e32 v65, vcc, 0, v45, vcc
	global_store_dwordx2 v[64:65], v[52:53], off offset:-4096
	v_pk_add_f32 v[52:53], v[72:73], v[66:67]
	v_pk_add_f32 v[66:67], v[72:73], v[66:67] neg_lo:[0,1] neg_hi:[0,1]
	v_mul_f32_e32 v40, 0.5, v52
	v_mov_b32_e32 v52, v66
	v_pk_mul_f32 v[52:53], v[52:53], s[74:75]
	s_nop 0
	v_pk_mul_f32 v[70:71], v[52:53], s[78:79]
	v_pk_mul_f32 v[52:53], v[52:53], s[50:51]
	s_nop 0
	v_sub_f32_e32 v42, v52, v53
	v_fma_mixlo_f16 v72, v67, s75, v42
	v_fma_f32 v42, v67, 0.5, -v42
	v_cvt_f16_f32_sdwa v42, -v42 dst_sel:WORD_1 dst_unused:UNUSED_PAD src0_sel:DWORD
	v_pk_add_f32 v[52:53], v[70:71], v[70:71] op_sel:[1,0] op_sel_hi:[1,0]
	s_nop 0
	v_pk_add_f32 v[66:67], v[40:41], v[52:53]
	v_pk_add_f32 v[52:53], v[40:41], v[52:53] op_sel_hi:[0,1] neg_lo:[0,1] neg_hi:[0,1]
	v_cvt_pk_f16_f32 v40, v66, v53
	v_lshlrev_b32_e32 v52, 16, v72
	v_or_b32_sdwa v53, v42, v40 dst_sel:DWORD dst_unused:UNUSED_PAD src0_sel:DWORD src1_sel:WORD_1
	v_or_b32_sdwa v52, v52, v40 dst_sel:DWORD dst_unused:UNUSED_PAD src0_sel:DWORD src1_sel:WORD_0
	global_store_dwordx2 v[64:65], v[52:53], off
	v_pk_add_f32 v[52:53], v[54:55], v[58:59]
	v_pk_add_f32 v[54:55], v[54:55], v[58:59] neg_lo:[0,1] neg_hi:[0,1]
	v_mul_f32_e32 v40, 0.5, v52
	v_mov_b32_e32 v52, v54
	v_pk_mul_f32 v[52:53], v[52:53], s[74:75]
	s_nop 0
	v_pk_mul_f32 v[58:59], v[52:53], s[80:81]
	v_pk_mul_f32 v[52:53], v[52:53], s[64:65]
	s_nop 0
	v_sub_f32_e32 v42, v52, v53
	v_fma_mixlo_f16 v64, v55, s75, v42
	v_fma_f32 v42, v55, 0.5, -v42
	v_cvt_f16_f32_sdwa v42, -v42 dst_sel:WORD_1 dst_unused:UNUSED_PAD src0_sel:DWORD
	v_pk_add_f32 v[52:53], v[58:59], v[58:59] op_sel:[1,0] op_sel_hi:[1,0]
	v_pk_add_f32 v[58:59], v[74:75], v[68:69] neg_lo:[0,1] neg_hi:[0,1]
	v_pk_add_f32 v[54:55], v[40:41], v[52:53]
	v_pk_add_f32 v[52:53], v[40:41], v[52:53] op_sel_hi:[0,1] neg_lo:[0,1] neg_hi:[0,1]
	v_cvt_pk_f16_f32 v40, v54, v53
	v_lshlrev_b32_e32 v52, 16, v64
	v_add_co_u32_e32 v54, vcc, s39, v44
	v_or_b32_sdwa v53, v42, v40 dst_sel:DWORD dst_unused:UNUSED_PAD src0_sel:DWORD src1_sel:WORD_1
	v_or_b32_sdwa v52, v52, v40 dst_sel:DWORD dst_unused:UNUSED_PAD src0_sel:DWORD src1_sel:WORD_0
	v_addc_co_u32_e32 v55, vcc, 0, v45, vcc
	global_store_dwordx2 v[54:55], v[52:53], off offset:-4096
	v_pk_add_f32 v[52:53], v[74:75], v[68:69]
	s_nop 0
	v_mul_f32_e32 v40, 0.5, v52
	v_mov_b32_e32 v52, v58
	v_pk_mul_f32 v[52:53], v[52:53], s[74:75]
	s_nop 0
	v_pk_mul_f32 v[52:53], v[52:53], s[82:83] op_sel_hi:[1,0]
	s_nop 0
	v_sub_f32_e32 v42, v52, v53
	v_fma_mixlo_f16 v64, v59, s75, v42
	v_fma_f32 v42, v59, 0.5, -v42
	v_cvt_f16_f32_sdwa v42, -v42 dst_sel:WORD_1 dst_unused:UNUSED_PAD src0_sel:DWORD
	v_pk_add_f32 v[52:53], v[52:53], v[52:53] op_sel:[1,0] op_sel_hi:[1,0]
	s_nop 0
	v_pk_add_f32 v[58:59], v[40:41], v[52:53]
	v_pk_add_f32 v[52:53], v[40:41], v[52:53] op_sel_hi:[0,1] neg_lo:[0,1] neg_hi:[0,1]
	v_cvt_pk_f16_f32 v40, v58, v53
	v_lshlrev_b32_e32 v52, 16, v64
	v_or_b32_sdwa v53, v42, v40 dst_sel:DWORD dst_unused:UNUSED_PAD src0_sel:DWORD src1_sel:WORD_1
	v_or_b32_sdwa v52, v52, v40 dst_sel:DWORD dst_unused:UNUSED_PAD src0_sel:DWORD src1_sel:WORD_0
	global_store_dwordx2 v[54:55], v[52:53], off
	v_pk_add_f32 v[52:53], v[56:57], v[48:49]
	v_pk_add_f32 v[48:49], v[56:57], v[48:49] neg_lo:[0,1] neg_hi:[0,1]
	v_mul_f32_e32 v40, 0.5, v52
	v_mov_b32_e32 v52, v48
	v_pk_mul_f32 v[52:53], v[52:53], s[74:75]
	s_nop 0
	v_pk_mul_f32 v[54:55], v[52:53], s[64:65]
	v_pk_mul_f32 v[52:53], v[52:53], s[80:81]
	s_nop 0
	v_sub_f32_e32 v42, v52, v53
	v_fma_mixlo_f16 v56, v49, s75, v42
	v_fma_f32 v42, v49, 0.5, -v42
	v_cvt_f16_f32_sdwa v42, -v42 dst_sel:WORD_1 dst_unused:UNUSED_PAD src0_sel:DWORD
	v_pk_add_f32 v[48:49], v[54:55], v[54:55] op_sel:[1,0] op_sel_hi:[1,0]
	v_pk_add_f32 v[54:55], v[60:61], v[62:63] neg_lo:[0,1] neg_hi:[0,1]
	v_pk_add_f32 v[52:53], v[40:41], v[48:49]
	v_pk_add_f32 v[48:49], v[40:41], v[48:49] op_sel_hi:[0,1] neg_lo:[0,1] neg_hi:[0,1]
	v_cvt_pk_f16_f32 v40, v52, v49
	v_lshlrev_b32_e32 v48, 16, v56
	v_add_co_u32_e32 v52, vcc, s43, v44
	v_or_b32_sdwa v49, v42, v40 dst_sel:DWORD dst_unused:UNUSED_PAD src0_sel:DWORD src1_sel:WORD_1
	v_or_b32_sdwa v48, v48, v40 dst_sel:DWORD dst_unused:UNUSED_PAD src0_sel:DWORD src1_sel:WORD_0
	v_addc_co_u32_e32 v53, vcc, 0, v45, vcc
	global_store_dwordx2 v[52:53], v[48:49], off offset:-4096
	v_pk_add_f32 v[48:49], v[62:63], v[60:61]
	s_nop 0
	v_mul_f32_e32 v40, 0.5, v48
	v_mov_b32_e32 v48, v54
	v_pk_mul_f32 v[48:49], v[48:49], s[74:75]
	s_nop 0
	v_pk_mul_f32 v[56:57], v[48:49], s[50:51]
	v_pk_mul_f32 v[48:49], v[48:49], s[78:79]
	s_mov_b32 s78, s41
	v_sub_f32_e32 v42, v48, v49
	v_pk_add_f32 v[48:49], v[56:57], v[56:57] op_sel:[1,0] op_sel_hi:[1,0]
	v_fma_mixlo_f16 v58, v55, s75, v42
	v_fma_f32 v42, v55, 0.5, -v42
	v_pk_add_f32 v[54:55], v[40:41], v[48:49]
	v_pk_add_f32 v[48:49], v[40:41], v[48:49] op_sel_hi:[0,1] neg_lo:[0,1] neg_hi:[0,1]
	v_cvt_pk_f16_f32 v40, v54, v49
	v_pk_add_f32 v[48:49], v[46:47], v[50:51]
	v_pk_add_f32 v[46:47], v[46:47], v[50:51] neg_lo:[0,1] neg_hi:[0,1]
	v_mov_b32_e32 v50, v48
	v_mov_b32_e32 v51, v47
	v_mov_b32_e32 v47, v49
	v_pk_mul_f32 v[46:47], v[46:47], s[74:75]
	v_cvt_f16_f32_sdwa v42, -v42 dst_sel:WORD_1 dst_unused:UNUSED_PAD src0_sel:DWORD
	v_pk_mul_f32 v[48:49], v[46:47], s[44:45] op_sel_hi:[1,0]
	v_lshlrev_b32_e32 v56, 16, v58
	v_pk_fma_f32 v[54:55], v[46:47], s[78:79], v[48:49] op_sel:[0,0,1] op_sel_hi:[1,0,0] neg_hi:[1,0,0]
	s_nop 0
	s_nop 0
	s_nop 0
	v_pk_fma_f32 v[46:47], v[50:51], 0.5, v[54:55] op_sel_hi:[1,0,1]
	v_pk_fma_f32 v[116:117], v[50:51], 0.5, v[54:55] op_sel_hi:[1,0,1] neg_lo:[0,0,1] neg_hi:[0,0,1]
	v_cvt_f16_f32_e32 v48, v46
	v_cvt_f16_f32_sdwa v49, v47 dst_sel:WORD_1 dst_unused:UNUSED_PAD src0_sel:DWORD
	v_or_b32_sdwa v47, v42, v40 dst_sel:DWORD dst_unused:UNUSED_PAD src0_sel:DWORD src1_sel:WORD_1
	v_or_b32_sdwa v46, v56, v40 dst_sel:DWORD dst_unused:UNUSED_PAD src0_sel:DWORD src1_sel:WORD_0
	global_store_dwordx2 v[52:53], v[46:47], off
	v_or_b32_e32 v114, v49, v48
	s_branch .LBB0_270

.LBB0_432:
	s_or_b64 exec, exec, s[6:7]
	v_mov_b32_e32 v36, v130
	s_mov_b32 s75, s42
	v_ashrrev_i32_e32 v40, 31, v36
	v_add_u32_sdwa v40, v36, v40 dst_sel:DWORD dst_unused:UNUSED_PAD src0_sel:DWORD src1_sel:BYTE_3
	v_ashrrev_i32_e32 v40, 8, v40
	v_mul_i32_i24_e32 v41, 0x100, v40
	v_sub_u32_e32 v66, v36, v41
	v_lshlrev_b32_e32 v41, 1, v66
	v_bfrev_b32_e32 v41, v41
	v_lshrrev_b32_e32 v41, 23, v41
	v_sub_u32_e32 v41, 0x200, v41
	v_bfrev_b32_e32 v41, v41
	v_lshrrev_b32_e32 v41, 19, v41
	v_and_b32_e32 v41, 0x1ff0, v41
	v_cmp_eq_u32_e64 s[6:7], 0, v66
	v_lshlrev_b32_e32 v40, 13, v40
	v_lshl_add_u32 v42, v66, 5, v40
	v_cndmask_b32_e64 v41, v41, 16, s[6:7]
	v_or_b32_e32 v40, v41, v40
	v_lshlrev_b32_e32 v43, 3, v42
	v_ashrrev_i32_e32 v42, 2, v42
	v_ashrrev_i32_e32 v41, 5, v40
	v_add3_u32 v88, 0, v43, v42
	v_lshlrev_b32_e32 v40, 3, v40
	v_lshlrev_b32_e32 v41, 3, v41
	v_add_u32_e32 v36, 0xffffff00, v36
	v_add3_u32 v40, 0, v40, v41
	ds_read2_b64 v[42:45], v88 offset1:1
	ds_read2_b64 v[46:49], v88 offset0:2 offset1:3
	ds_read2_b64 v[72:75], v40 offset1:1
	ds_read2_b64 v[76:79], v40 offset0:2 offset1:3
	ds_read2_b64 v[50:53], v88 offset0:4 offset1:5
	ds_read2_b64 v[54:57], v88 offset0:6 offset1:7
	ds_read2_b64 v[80:83], v40 offset0:4 offset1:5
	ds_read2_b64 v[84:87], v40 offset0:6 offset1:7
	ds_read2_b64 v[58:61], v88 offset0:8 offset1:9
	ds_read2_b64 v[62:65], v88 offset0:10 offset1:11
	ds_read2_b64 v[96:99], v40 offset0:8 offset1:9
	ds_read2_b64 v[100:103], v40 offset0:10 offset1:11
	ds_read2_b64 v[68:71], v88 offset0:12 offset1:13
	ds_read2_b64 v[88:91], v88 offset0:14 offset1:15
	ds_read2_b64 v[104:107], v40 offset0:12 offset1:13
	ds_read2_b64 v[108:111], v40 offset0:14 offset1:15
	v_mov_b32_e32 v40, s16
	v_cmp_gt_u32_e64 s[8:9], s33, v36
	s_waitcnt lgkmcnt(7)
	v_pk_add_f32 v[92:93], v[42:43], v[58:59]
	v_pk_add_f32 v[42:43], v[42:43], v[58:59] neg_lo:[0,1] neg_hi:[0,1]
	v_pk_add_f32 v[58:59], v[44:45], v[60:61]
	v_pk_add_f32 v[44:45], v[44:45], v[60:61] neg_lo:[0,1] neg_hi:[0,1]
	v_addc_co_u32_e64 v40, s[8:9], 0, v40, s[8:9]
	v_pk_mul_f32 v[60:61], v[44:45], s[44:45]
	s_waitcnt lgkmcnt(3)
	v_pk_add_f32 v[94:95], v[52:53], v[70:71]
	v_pk_add_f32 v[52:53], v[52:53], v[70:71] neg_lo:[0,1] neg_hi:[0,1]
	v_pk_fma_f32 v[44:45], v[44:45], s[42:43], v[60:61] op_sel:[0,0,1] op_sel_hi:[1,0,0]
	v_pk_add_f32 v[60:61], v[46:47], v[62:63]
	v_pk_add_f32 v[46:47], v[46:47], v[62:63] neg_lo:[0,1] neg_hi:[0,1]
	s_mov_b32 s67, s64
	s_mov_b32 s8, s45
	v_pk_mul_f32 v[70:71], v[52:53], s[74:75]
	v_pk_mul_f32 v[62:63], v[46:47], s[66:67]
	v_pk_fma_f32 v[52:53], v[52:53], s[8:9], v[70:71] op_sel:[0,0,1] op_sel_hi:[1,0,0] neg_lo:[1,0,0] neg_hi:[1,0,0]
	s_waitcnt lgkmcnt(2)
	v_pk_add_f32 v[70:71], v[54:55], v[88:89]
	v_pk_add_f32 v[54:55], v[54:55], v[88:89] neg_lo:[0,1] neg_hi:[0,1]
	v_pk_fma_f32 v[46:47], v[46:47], s[64:65], v[62:63] op_sel:[0,0,1] op_sel_hi:[1,0,0]
	v_pk_add_f32 v[62:63], v[48:49], v[64:65]
	v_pk_add_f32 v[48:49], v[48:49], v[64:65] neg_lo:[0,1] neg_hi:[0,1]
	v_pk_mul_f32 v[88:89], v[54:55], s[66:67]
	v_pk_mul_f32 v[64:65], v[48:49], s[74:75]
	v_pk_fma_f32 v[54:55], v[54:55], s[64:65], v[88:89] op_sel:[0,0,1] op_sel_hi:[1,0,0] neg_lo:[1,0,0] neg_hi:[1,0,0]
	v_pk_add_f32 v[88:89], v[56:57], v[90:91]
	v_pk_add_f32 v[56:57], v[56:57], v[90:91] neg_lo:[0,1] neg_hi:[0,1]
	v_pk_fma_f32 v[48:49], v[48:49], s[8:9], v[64:65] op_sel:[0,0,1] op_sel_hi:[1,0,0]
	v_pk_add_f32 v[64:65], v[50:51], v[68:69]
	v_pk_add_f32 v[50:51], v[50:51], v[68:69] neg_lo:[0,1] neg_hi:[0,1]
	v_pk_mul_f32 v[90:91], v[56:57], s[44:45]
	v_pk_add_f32 v[112:113], v[62:63], v[88:89]
	v_pk_add_f32 v[62:63], v[62:63], v[88:89] neg_lo:[0,1] neg_hi:[0,1]
	v_xor_b32_e32 v69, 0x80000000, v50
	v_pk_fma_f32 v[56:57], v[56:57], s[42:43], v[90:91] op_sel:[0,0,1] op_sel_hi:[1,0,0] neg_lo:[1,0,0] neg_hi:[1,0,0]
	v_pk_add_f32 v[90:91], v[92:93], v[64:65]
	v_pk_add_f32 v[64:65], v[92:93], v[64:65] neg_lo:[0,1] neg_hi:[0,1]
	v_pk_add_f32 v[92:93], v[58:59], v[94:95]
	v_pk_add_f32 v[58:59], v[58:59], v[94:95] neg_lo:[0,1] neg_hi:[0,1]
	v_pk_mul_f32 v[88:89], v[62:63], s[66:67]
	v_mov_b32_e32 v68, v51
	v_pk_mul_f32 v[94:95], v[58:59], s[66:67]
	v_pk_fma_f32 v[62:63], v[62:63], s[64:65], v[88:89] op_sel:[0,0,1] op_sel_hi:[1,0,0] neg_lo:[1,0,0] neg_hi:[1,0,0]
	v_pk_add_f32 v[50:51], v[42:43], v[68:69]
	v_pk_add_f32 v[42:43], v[42:43], v[68:69] neg_lo:[0,1] neg_hi:[0,1]
	v_pk_add_f32 v[68:69], v[44:45], v[52:53]
	v_pk_add_f32 v[44:45], v[44:45], v[52:53] neg_lo:[0,1] neg_hi:[0,1]
	v_pk_add_f32 v[88:89], v[48:49], v[56:57]
	v_pk_add_f32 v[48:49], v[48:49], v[56:57] neg_lo:[0,1] neg_hi:[0,1]
	v_pk_fma_f32 v[58:59], v[58:59], s[64:65], v[94:95] op_sel:[0,0,1] op_sel_hi:[1,0,0]
	v_pk_add_f32 v[94:95], v[60:61], v[70:71]
	v_pk_mul_f32 v[52:53], v[44:45], s[66:67]
	v_pk_mul_f32 v[56:57], v[48:49], s[66:67]
	v_pk_fma_f32 v[44:45], v[44:45], s[64:65], v[52:53] op_sel:[0,0,1] op_sel_hi:[1,0,0]
	v_pk_add_f32 v[52:53], v[46:47], v[54:55]
	v_pk_fma_f32 v[48:49], v[48:49], s[64:65], v[56:57] op_sel:[0,0,1] op_sel_hi:[1,0,0] neg_lo:[1,0,0] neg_hi:[1,0,0]
	v_pk_add_f32 v[56:57], v[90:91], v[94:95]
	v_pk_add_f32 v[114:115], v[90:91], v[94:95] neg_lo:[0,1] neg_hi:[0,1]
	v_pk_add_f32 v[90:91], v[92:93], v[112:113]
	v_pk_add_f32 v[112:113], v[92:93], v[112:113] neg_lo:[0,1] neg_hi:[0,1]
	v_pk_add_f32 v[122:123], v[50:51], v[52:53]
	v_pk_add_f32 v[50:51], v[50:51], v[52:53] neg_lo:[0,1] neg_hi:[0,1]
	v_pk_add_f32 v[52:53], v[68:69], v[88:89]
	v_pk_add_f32 v[88:89], v[68:69], v[88:89] neg_lo:[0,1] neg_hi:[0,1]
	v_pk_add_f32 v[92:93], v[74:75], v[98:99]
	v_pk_add_f32 v[74:75], v[74:75], v[98:99] neg_lo:[0,1] neg_hi:[0,1]
	v_xor_b32_e32 v125, 0x80000000, v88
	v_mov_b32_e32 v124, v89
	v_pk_add_f32 v[88:89], v[72:73], v[96:97]
	v_pk_add_f32 v[72:73], v[72:73], v[96:97] neg_lo:[0,1] neg_hi:[0,1]
	v_pk_mul_f32 v[96:97], v[74:75], s[44:45]
	v_bfrev_b32_e32 v36, v66
	v_pk_fma_f32 v[74:75], v[74:75], s[42:43], v[96:97] op_sel:[0,0,1] op_sel_hi:[1,0,0]
	v_pk_add_f32 v[96:97], v[76:77], v[100:101]
	v_pk_add_f32 v[76:77], v[76:77], v[100:101] neg_lo:[0,1] neg_hi:[0,1]
	v_ashrrev_i32_e32 v41, 31, v40
	v_pk_mul_f32 v[98:99], v[76:77], s[66:67]
	v_cvt_f32_ubyte3_e32 v36, v36
	v_pk_fma_f32 v[76:77], v[76:77], s[64:65], v[98:99] op_sel:[0,0,1] op_sel_hi:[1,0,0]
	v_pk_add_f32 v[98:99], v[78:79], v[102:103]
	v_pk_add_f32 v[78:79], v[78:79], v[102:103] neg_lo:[0,1] neg_hi:[0,1]
	v_lshlrev_b64 v[40:41], 15, v[40:41]
	v_pk_mul_f32 v[100:101], v[78:79], s[74:75]
	v_mul_f32_e32 v36, 0x38800000, v36
	v_pk_fma_f32 v[78:79], v[78:79], s[8:9], v[100:101] op_sel:[0,0,1] op_sel_hi:[1,0,0]
	s_waitcnt lgkmcnt(1)
	v_pk_add_f32 v[100:101], v[80:81], v[104:105]
	v_pk_add_f32 v[102:103], v[80:81], v[104:105] neg_lo:[0,1] neg_hi:[0,1]
	v_ashrrev_i32_e32 v67, 31, v66
	v_pk_add_f32 v[80:81], v[82:83], v[106:107]
	v_pk_add_f32 v[82:83], v[82:83], v[106:107] neg_lo:[0,1] neg_hi:[0,1]
	v_lshl_add_u64 v[40:41], s[18:19], 0, v[40:41]
	v_pk_mul_f32 v[104:105], v[82:83], s[74:75]
	v_pk_add_f32 v[60:61], v[60:61], v[70:71] neg_lo:[0,1] neg_hi:[0,1]
	v_pk_fma_f32 v[82:83], v[82:83], s[8:9], v[104:105] op_sel:[0,0,1] op_sel_hi:[1,0,0] neg_lo:[1,0,0] neg_hi:[1,0,0]
	s_waitcnt lgkmcnt(0)
	v_pk_add_f32 v[104:105], v[84:85], v[108:109]
	v_pk_add_f32 v[84:85], v[84:85], v[108:109] neg_lo:[0,1] neg_hi:[0,1]
	v_cndmask_b32_e64 v36, v36, v152, s[6:7]
	v_pk_mul_f32 v[106:107], v[84:85], s[66:67]
	v_lshl_add_u64 v[40:41], v[66:67], 3, v[40:41]
	v_pk_fma_f32 v[84:85], v[84:85], s[64:65], v[106:107] op_sel:[0,0,1] op_sel_hi:[1,0,0] neg_lo:[1,0,0] neg_hi:[1,0,0]
	v_pk_add_f32 v[106:107], v[86:87], v[110:111]
	v_pk_add_f32 v[86:87], v[86:87], v[110:111] neg_lo:[0,1] neg_hi:[0,1]
	v_xor_b32_e32 v71, 0x80000000, v60
	v_pk_mul_f32 v[108:109], v[86:87], s[44:45]
	v_pk_add_f32 v[46:47], v[46:47], v[54:55] neg_lo:[0,1] neg_hi:[0,1]
	v_pk_fma_f32 v[86:87], v[86:87], s[42:43], v[108:109] op_sel:[0,0,1] op_sel_hi:[1,0,0] neg_lo:[1,0,0] neg_hi:[1,0,0]
	v_pk_add_f32 v[108:109], v[88:89], v[100:101]
	v_pk_add_f32 v[88:89], v[88:89], v[100:101] neg_lo:[0,1] neg_hi:[0,1]
	v_pk_add_f32 v[100:101], v[92:93], v[80:81]
	v_pk_add_f32 v[80:81], v[92:93], v[80:81] neg_lo:[0,1] neg_hi:[0,1]
	v_mov_b32_e32 v70, v61
	v_pk_mul_f32 v[92:93], v[80:81], s[66:67]
	v_pk_add_f32 v[118:119], v[58:59], v[62:63]
	v_pk_fma_f32 v[80:81], v[80:81], s[64:65], v[92:93] op_sel:[0,0,1] op_sel_hi:[1,0,0]
	v_pk_add_f32 v[92:93], v[96:97], v[104:105]
	v_pk_add_f32 v[104:105], v[96:97], v[104:105] neg_lo:[0,1] neg_hi:[0,1]
	v_pk_add_f32 v[62:63], v[58:59], v[62:63] neg_lo:[0,1] neg_hi:[0,1]
	v_pk_add_f32 v[96:97], v[98:99], v[106:107]
	v_pk_add_f32 v[98:99], v[98:99], v[106:107] neg_lo:[0,1] neg_hi:[0,1]
	v_cos_f32_e32 v67, v36
	v_pk_mul_f32 v[106:107], v[98:99], s[66:67]
	v_cmp_ne_u32_e32 vcc, 0, v66
	v_pk_fma_f32 v[98:99], v[98:99], s[64:65], v[106:107] op_sel:[0,0,1] op_sel_hi:[1,0,0] neg_lo:[1,0,0] neg_hi:[1,0,0]
	v_pk_add_f32 v[106:107], v[72:73], v[102:103] op_sel:[0,1] op_sel_hi:[1,0] neg_hi:[0,1]
	v_pk_add_f32 v[72:73], v[72:73], v[102:103] op_sel:[0,1] op_sel_hi:[1,0] neg_lo:[0,1]
	v_pk_add_f32 v[102:103], v[74:75], v[82:83]
	v_pk_add_f32 v[74:75], v[74:75], v[82:83] neg_lo:[0,1] neg_hi:[0,1]
	v_xor_b32_e32 v55, 0x80000000, v46
	v_pk_mul_f32 v[82:83], v[74:75], s[66:67]
	v_pk_add_f32 v[116:117], v[64:65], v[70:71] neg_lo:[0,1] neg_hi:[0,1]
	v_pk_fma_f32 v[74:75], v[74:75], s[64:65], v[82:83] op_sel:[0,0,1] op_sel_hi:[1,0,0]
	v_pk_add_f32 v[82:83], v[76:77], v[84:85]
	v_pk_add_f32 v[84:85], v[76:77], v[84:85] neg_lo:[0,1] neg_hi:[0,1]
	v_xor_b32_e32 v121, 0x80000000, v62
	v_pk_add_f32 v[76:77], v[78:79], v[86:87]
	v_pk_add_f32 v[78:79], v[78:79], v[86:87] neg_lo:[0,1] neg_hi:[0,1]
	v_mov_b32_e32 v54, v47
	v_pk_mul_f32 v[86:87], v[78:79], s[66:67]
	v_mov_b32_e32 v120, v63
	v_pk_fma_f32 v[78:79], v[78:79], s[64:65], v[86:87] op_sel:[0,0,1] op_sel_hi:[1,0,0] neg_lo:[1,0,0] neg_hi:[1,0,0]
	v_pk_add_f32 v[86:87], v[108:109], v[92:93]
	v_pk_add_f32 v[92:93], v[108:109], v[92:93] neg_lo:[0,1] neg_hi:[0,1]
	v_pk_add_f32 v[108:109], v[100:101], v[96:97]
	v_pk_add_f32 v[96:97], v[100:101], v[96:97] neg_lo:[0,1] neg_hi:[0,1]
	v_sin_f32_e32 v66, v36
	v_pk_add_f32 v[60:61], v[64:65], v[70:71]
	v_pk_add_f32 v[126:127], v[42:43], v[54:55]
	v_pk_add_f32 v[128:129], v[42:43], v[54:55] neg_lo:[0,1] neg_hi:[0,1]
	v_pk_add_f32 v[42:43], v[44:45], v[48:49]
	v_pk_add_f32 v[48:49], v[44:45], v[48:49] neg_lo:[0,1] neg_hi:[0,1]
	v_pk_add_f32 v[94:95], v[56:57], v[90:91]
	v_pk_add_f32 v[90:91], v[56:57], v[90:91] neg_lo:[0,1] neg_hi:[0,1]
	v_pk_add_f32 v[70:71], v[114:115], v[112:113] op_sel:[0,1] op_sel_hi:[1,0] neg_hi:[0,1]
	v_pk_add_f32 v[64:65], v[114:115], v[112:113] op_sel:[0,1] op_sel_hi:[1,0] neg_lo:[0,1]
	v_pk_add_f32 v[56:57], v[116:117], v[120:121]
	v_pk_add_f32 v[62:63], v[116:117], v[120:121] neg_lo:[0,1] neg_hi:[0,1]
	v_xor_b32_e32 v101, 0x80000000, v96
	v_mov_b32_e32 v100, v97
	v_pk_add_f32 v[96:97], v[88:89], v[104:105] op_sel:[0,1] op_sel_hi:[1,0] neg_hi:[0,1]
	v_pk_add_f32 v[88:89], v[88:89], v[104:105] op_sel:[0,1] op_sel_hi:[1,0] neg_lo:[0,1]
	v_pk_add_f32 v[104:105], v[80:81], v[98:99]
	v_pk_add_f32 v[98:99], v[80:81], v[98:99] neg_lo:[0,1] neg_hi:[0,1]
	v_pk_add_f32 v[112:113], v[102:103], v[76:77]
	v_pk_add_f32 v[102:103], v[102:103], v[76:77] neg_lo:[0,1] neg_hi:[0,1]
	v_pk_add_f32 v[114:115], v[72:73], v[84:85] op_sel:[0,1] op_sel_hi:[1,0] neg_hi:[0,1]
	v_pk_add_f32 v[116:117], v[72:73], v[84:85] op_sel:[0,1] op_sel_hi:[1,0] neg_lo:[0,1]
	v_pk_add_f32 v[72:73], v[74:75], v[78:79] neg_lo:[0,1] neg_hi:[0,1]
	v_xor_b32_e32 v155, 0x80000000, v48
	v_pk_add_f32 v[68:69], v[60:61], v[118:119]
	v_pk_add_f32 v[58:59], v[60:61], v[118:119] neg_lo:[0,1] neg_hi:[0,1]
	v_mov_b32_e32 v154, v49
	v_pk_add_f32 v[110:111], v[106:107], v[82:83]
	v_pk_add_f32 v[106:107], v[106:107], v[82:83] neg_lo:[0,1] neg_hi:[0,1]
	v_pk_add_f32 v[118:119], v[74:75], v[78:79]
	v_xor_b32_e32 v121, 0x80000000, v72
	v_mov_b32_e32 v120, v73
	v_pk_add_f32 v[60:61], v[122:123], v[52:53]
	v_pk_add_f32 v[46:47], v[122:123], v[52:53] neg_lo:[0,1] neg_hi:[0,1]
	v_pk_add_f32 v[52:53], v[50:51], v[124:125]
	v_pk_add_f32 v[54:55], v[50:51], v[124:125] neg_lo:[0,1] neg_hi:[0,1]
	v_pk_add_f32 v[50:51], v[126:127], v[42:43]
	v_pk_add_f32 v[44:45], v[126:127], v[42:43] neg_lo:[0,1] neg_hi:[0,1]
	v_pk_add_f32 v[42:43], v[128:129], v[154:155]
	v_pk_add_f32 v[48:49], v[128:129], v[154:155] neg_lo:[0,1] neg_hi:[0,1]
	v_pk_add_f32 v[84:85], v[86:87], v[108:109]
	v_pk_add_f32 v[86:87], v[86:87], v[108:109] neg_lo:[0,1] neg_hi:[0,1]
	v_pk_add_f32 v[78:79], v[92:93], v[100:101]
	v_pk_add_f32 v[74:75], v[92:93], v[100:101] neg_lo:[0,1] neg_hi:[0,1]
	v_pk_add_f32 v[72:73], v[96:97], v[104:105]
	v_pk_add_f32 v[76:77], v[96:97], v[104:105] neg_lo:[0,1] neg_hi:[0,1]
	v_pk_add_f32 v[82:83], v[88:89], v[98:99] op_sel:[0,1] op_sel_hi:[1,0] neg_hi:[0,1]
	v_pk_add_f32 v[80:81], v[88:89], v[98:99] op_sel:[0,1] op_sel_hi:[1,0] neg_lo:[0,1]
	v_pk_add_f32 v[88:89], v[110:111], v[112:113]
	v_pk_add_f32 v[96:97], v[110:111], v[112:113] neg_lo:[0,1] neg_hi:[0,1]
	v_pk_add_f32 v[98:99], v[106:107], v[102:103] op_sel:[0,1] op_sel_hi:[1,0] neg_hi:[0,1]
	v_pk_add_f32 v[102:103], v[106:107], v[102:103] op_sel:[0,1] op_sel_hi:[1,0] neg_lo:[0,1]
	v_pk_add_f32 v[104:105], v[114:115], v[118:119]
	v_pk_add_f32 v[106:107], v[114:115], v[118:119] neg_lo:[0,1] neg_hi:[0,1]
	v_pk_add_f32 v[108:109], v[116:117], v[120:121]
	v_pk_add_f32 v[114:115], v[116:117], v[120:121] neg_lo:[0,1] neg_hi:[0,1]
	v_mul_f32_e32 v36, 0x3f3504f3, v67
	v_mul_f32_e32 v100, 0xbec3ef15, v67
	v_mul_f32_e32 v92, 0xbf6c835e, v67
	s_and_saveexec_b64 s[6:7], vcc
	s_xor_b64 s[6:7], exec, s[6:7]
	s_cbranch_execz .LBB0_434
	v_pk_add_f32 v[110:111], v[94:95], v[114:115]
	v_pk_add_f32 v[94:95], v[94:95], v[114:115] neg_lo:[0,1] neg_hi:[0,1]
	v_mul_f32_e32 v112, 0.5, v110
	v_pk_fma_f32 v[114:115], v[66:67], 0, v[66:67] op_sel:[0,0,1] op_sel_hi:[1,0,0] neg_lo:[1,0,0]
	v_mov_b32_e32 v110, v94
	v_pk_mul_f32 v[110:111], v[110:111], s[78:79]
	s_mov_b32 s8, s45
	v_pk_mul_f32 v[116:117], v[114:115], v[110:111] op_sel:[0,1] op_sel_hi:[1,0]
	v_pk_mul_f32 v[110:111], v[114:115], v[110:111]
	s_mov_b32 s9, s42
	v_sub_f32_e32 v93, v110, v111
	v_fma_mixlo_f16 v101, v95, s79, v93
	v_fma_f32 v93, v95, 0.5, -v93
	v_cvt_f16_f32_sdwa v93, -v93 dst_sel:WORD_1 dst_unused:UNUSED_PAD src0_sel:DWORD
	v_pk_add_f32 v[94:95], v[116:117], v[116:117] op_sel:[0,1] op_sel_hi:[0,1]
	v_pk_add_f32 v[110:111], v[112:113], v[94:95]
	v_pk_add_f32 v[94:95], v[112:113], v[94:95] op_sel_hi:[0,1] neg_lo:[0,1] neg_hi:[0,1]
	v_cvt_pk_f16_f32 v94, v110, v95
	v_lshlrev_b32_e32 v101, 16, v101
	v_or_b32_sdwa v95, v93, v94 dst_sel:DWORD dst_unused:UNUSED_PAD src0_sel:DWORD src1_sel:WORD_1
	v_or_b32_sdwa v94, v101, v94 dst_sel:DWORD dst_unused:UNUSED_PAD src0_sel:DWORD src1_sel:WORD_0
	global_store_dwordx2 v[40:41], v[94:95], off
	v_pk_add_f32 v[94:95], v[90:91], v[108:109]
	v_pk_add_f32 v[90:91], v[90:91], v[108:109] neg_lo:[0,1] neg_hi:[0,1]
	v_mul_f32_e32 v110, 0.5, v94
	v_mov_b32_e32 v94, v67
	v_mov_b32_e32 v108, v67
	v_mov_b32_e32 v109, v66
	v_pk_fma_f32 v[112:113], v[66:67], 0, v[108:109] op_sel_hi:[1,0,1] neg_lo:[0,0,1] neg_hi:[0,0,1]
	v_pk_fma_f32 v[114:115], v[66:67], 0, v[94:95] op_sel_hi:[1,0,1]
	v_mov_b32_e32 v94, v90
	v_pk_mov_b32 v[112:113], v[112:113], v[114:115] op_sel:[1,0]
	v_pk_mul_f32 v[94:95], v[94:95], s[78:79]
	s_mov_b32 s43, s45
	v_pk_mul_f32 v[114:115], v[112:113], v[94:95] op_sel:[0,1] op_sel_hi:[1,0]
	v_pk_mul_f32 v[94:95], v[112:113], v[94:95]
	v_pk_fma_f32 v[112:113], v[108:109], s[68:69], v[36:37] op_sel_hi:[1,1,0]
	v_sub_f32_e32 v90, v94, v95
	v_fma_mixlo_f16 v93, v91, s79, v90
	v_fma_f32 v90, v91, 0.5, -v90
	v_cvt_f16_f32_sdwa v101, -v90 dst_sel:WORD_1 dst_unused:UNUSED_PAD src0_sel:DWORD
	v_pk_add_f32 v[90:91], v[114:115], v[114:115] op_sel:[0,1] op_sel_hi:[0,1]
	v_pk_add_f32 v[94:95], v[110:111], v[90:91]
	v_pk_add_f32 v[90:91], v[110:111], v[90:91] op_sel_hi:[0,1] neg_lo:[0,1] neg_hi:[0,1]
	v_cvt_pk_f16_f32 v90, v94, v91
	v_lshlrev_b32_e32 v93, 16, v93
	v_or_b32_sdwa v91, v101, v90 dst_sel:DWORD dst_unused:UNUSED_PAD src0_sel:DWORD src1_sel:WORD_1
	v_or_b32_sdwa v90, v93, v90 dst_sel:DWORD dst_unused:UNUSED_PAD src0_sel:DWORD src1_sel:WORD_0
	global_store_dwordx2 v[40:41], v[90:91], off offset:2048
	v_pk_mul_f32 v[90:91], v[108:109], s[68:69]
	v_pk_add_f32 v[94:95], v[70:71], v[106:107]
	v_pk_add_f32 v[70:71], v[70:71], v[106:107] neg_lo:[0,1] neg_hi:[0,1]
	v_mul_f32_e32 v110, 0.5, v94
	v_pk_add_f32 v[106:107], v[36:37], v[90:91] op_sel:[0,1] op_sel_hi:[0,1] neg_lo:[0,1] neg_hi:[0,1]
	v_mov_b32_e32 v94, v70
	v_mov_b32_e32 v107, v113
	v_pk_mul_f32 v[94:95], v[94:95], s[78:79]
	v_mov_b32_e32 v101, v58
	v_pk_mul_f32 v[112:113], v[106:107], v[94:95] op_sel:[0,1] op_sel_hi:[1,0]
	v_pk_mul_f32 v[94:95], v[106:107], v[94:95]
	s_mov_b32 s39, s27
	v_sub_f32_e32 v36, v94, v95
	v_fma_mixlo_f16 v93, v71, s79, v36
	v_fma_f32 v36, v71, 0.5, -v36
	v_pk_add_f32 v[70:71], v[112:113], v[112:113] op_sel:[0,1] op_sel_hi:[0,1]
	v_cvt_f16_f32_sdwa v36, -v36 dst_sel:WORD_1 dst_unused:UNUSED_PAD src0_sel:DWORD
	v_pk_add_f32 v[94:95], v[110:111], v[70:71]
	v_pk_add_f32 v[70:71], v[110:111], v[70:71] op_sel_hi:[0,1] neg_lo:[0,1] neg_hi:[0,1]
	v_cvt_pk_f16_f32 v70, v94, v71
	v_add_co_u32_e32 v94, vcc, s34, v40
	v_lshlrev_b32_e32 v93, 16, v93
	s_nop 0
	v_addc_co_u32_e32 v95, vcc, 0, v41, vcc
	v_add_co_u32_e32 v110, vcc, s3, v40
	v_or_b32_sdwa v71, v36, v70 dst_sel:DWORD dst_unused:UNUSED_PAD src0_sel:DWORD src1_sel:WORD_1
	v_or_b32_sdwa v70, v93, v70 dst_sel:DWORD dst_unused:UNUSED_PAD src0_sel:DWORD src1_sel:WORD_0
	v_addc_co_u32_e32 v111, vcc, 0, v41, vcc
	global_store_dwordx2 v[110:111], v[70:71], off offset:-4096
	v_pk_fma_f32 v[70:71], v[108:109], s[68:69], v[90:91] op_sel:[0,0,1] op_sel_hi:[1,1,0] neg_lo:[0,0,1] neg_hi:[0,0,1]
	v_pk_add_f32 v[90:91], v[64:65], v[104:105]
	v_pk_add_f32 v[64:65], v[64:65], v[104:105] neg_lo:[0,1] neg_hi:[0,1]
	v_mul_f32_e32 v36, 0.5, v90
	v_mov_b32_e32 v90, v64
	v_pk_mul_f32 v[90:91], v[90:91], s[78:79]
	v_mov_b32_e32 v71, v106
	v_mov_b32_e32 v107, v70
	v_pk_mul_f32 v[70:71], v[70:71], v[90:91]
	v_pk_mul_f32 v[104:105], v[106:107], v[90:91]
	v_sub_f32_e32 v64, v70, v71
	v_fma_mixlo_f16 v90, v65, s79, v64
	v_fma_f32 v64, v65, 0.5, -v64
	v_cvt_f16_f32_sdwa v91, -v64 dst_sel:WORD_1 dst_unused:UNUSED_PAD src0_sel:DWORD
	v_pk_add_f32 v[64:65], v[104:105], v[104:105] op_sel:[1,0] op_sel_hi:[1,0]
	s_nop 0
	v_pk_add_f32 v[70:71], v[36:37], v[64:65]
	v_pk_add_f32 v[64:65], v[36:37], v[64:65] op_sel_hi:[0,1] neg_lo:[0,1] neg_hi:[0,1]
	v_cvt_pk_f16_f32 v36, v70, v65
	v_lshlrev_b32_e32 v64, 16, v90
	v_or_b32_sdwa v65, v91, v36 dst_sel:DWORD dst_unused:UNUSED_PAD src0_sel:DWORD src1_sel:WORD_1
	v_or_b32_sdwa v64, v64, v36 dst_sel:DWORD dst_unused:UNUSED_PAD src0_sel:DWORD src1_sel:WORD_0
	global_store_dwordx2 v[94:95], v[64:65], off offset:2048
	v_mov_b32_e32 v64, v67
	v_pk_mul_f32 v[70:71], v[66:67], s[8:9] op_sel_hi:[0,1]
	v_pk_add_f32 v[90:91], v[68:69], v[102:103]
	v_pk_add_f32 v[68:69], v[68:69], v[102:103] neg_lo:[0,1] neg_hi:[0,1]
	v_mul_f32_e32 v36, 0.5, v90
	v_pk_fma_f32 v[94:95], v[64:65], s[42:43], v[70:71] op_sel_hi:[0,1,1] neg_lo:[0,0,1] neg_hi:[0,0,1]
	v_pk_fma_f32 v[102:103], v[64:65], s[42:43], v[70:71] op_sel_hi:[0,1,1]
	v_mov_b32_e32 v90, v68
	v_mov_b32_e32 v104, v94
	v_mov_b32_e32 v105, v103
	v_pk_mul_f32 v[90:91], v[90:91], s[78:79]
	s_mov_b32 s8, s27
	v_pk_mul_f32 v[106:107], v[104:105], v[90:91] op_sel:[0,1] op_sel_hi:[1,0]
	v_pk_mul_f32 v[90:91], v[104:105], v[90:91]
	s_mov_b32 s9, s38
	v_sub_f32_e32 v65, v90, v91
	v_fma_mixlo_f16 v93, v69, s79, v65
	v_fma_f32 v65, v69, 0.5, -v65
	v_cvt_f16_f32_sdwa v65, -v65 dst_sel:WORD_1 dst_unused:UNUSED_PAD src0_sel:DWORD
	v_pk_add_f32 v[68:69], v[106:107], v[106:107] op_sel:[0,1] op_sel_hi:[0,1]
	v_pk_add_f32 v[90:91], v[36:37], v[68:69]
	v_pk_add_f32 v[68:69], v[36:37], v[68:69] op_sel_hi:[0,1] neg_lo:[0,1] neg_hi:[0,1]
	v_cvt_pk_f16_f32 v36, v90, v69
	v_lshlrev_b32_e32 v68, 16, v93
	v_or_b32_sdwa v69, v65, v36 dst_sel:DWORD dst_unused:UNUSED_PAD src0_sel:DWORD src1_sel:WORD_1
	v_or_b32_sdwa v68, v68, v36 dst_sel:DWORD dst_unused:UNUSED_PAD src0_sel:DWORD src1_sel:WORD_0
	global_store_dwordx2 v[110:111], v[68:69], off
	v_pk_add_f32 v[68:69], v[58:59], v[98:99]
	v_sub_f32_e32 v65, v59, v99
	v_pk_mov_b32 v[58:59], v[70:71], v[98:99] op_sel:[1,0]
	v_mul_f32_e32 v36, 0.5, v69
	v_pk_add_f32 v[58:59], v[100:101], v[58:59] neg_lo:[0,1] neg_hi:[0,1]
	v_mul_f32_e32 v90, 0.5, v68
	v_pk_mul_f32 v[98:99], v[58:59], v[36:37]
	v_mov_b32_e32 v93, v62
	v_mul_f32_e32 v58, v58, v99
	v_fma_f32 v36, -v94, v36, v58
	v_fma_mixlo_f16 v69, v65, s79, v36
	v_fma_f32 v36, v65, 0.5, -v36
	v_pk_fma_f32 v[100:101], v[94:95], v[98:99], v[98:99] op_sel:[0,1,0] op_sel_hi:[1,0,1]
	v_cvt_f16_f32_sdwa v36, -v36 dst_sel:WORD_1 dst_unused:UNUSED_PAD src0_sel:DWORD
	v_pk_add_f32 v[58:59], v[90:91], v[100:101]
	v_lshlrev_b32_e32 v65, 16, v69
	v_fma_f32 v59, v68, 0.5, -v100
	v_cvt_pk_f16_f32 v58, v58, v59
	v_or_b32_sdwa v59, v36, v58 dst_sel:DWORD dst_unused:UNUSED_PAD src0_sel:DWORD src1_sel:WORD_1
	v_or_b32_sdwa v58, v65, v58 dst_sel:DWORD dst_unused:UNUSED_PAD src0_sel:DWORD src1_sel:WORD_0
	global_store_dwordx2 v[110:111], v[58:59], off offset:2048
	v_pk_add_f32 v[58:59], v[96:97], v[56:57]
	v_pk_add_f32 v[56:57], v[56:57], v[96:97] neg_lo:[0,1] neg_hi:[0,1]
	v_mul_f32_e32 v36, 0.5, v58
	v_mov_b32_e32 v58, v56
	v_pk_mov_b32 v[68:69], v[94:95], v[102:103] op_sel:[1,0]
	v_pk_mul_f32 v[58:59], v[58:59], s[78:79]
	s_nop 0
	v_pk_mul_f32 v[90:91], v[68:69], v[58:59] op_sel:[0,1] op_sel_hi:[1,0]
	v_pk_mul_f32 v[58:59], v[68:69], v[58:59]
	s_nop 0
	v_sub_f32_e32 v56, v58, v59
	v_fma_mixlo_f16 v65, v57, s79, v56
	v_fma_f32 v56, v57, 0.5, -v56
	v_cvt_f16_f32_sdwa v71, -v56 dst_sel:WORD_1 dst_unused:UNUSED_PAD src0_sel:DWORD
	v_pk_add_f32 v[56:57], v[90:91], v[90:91] op_sel:[0,1] op_sel_hi:[0,1]
	v_pk_add_f32 v[58:59], v[36:37], v[56:57]
	v_pk_add_f32 v[56:57], v[36:37], v[56:57] op_sel_hi:[0,1] neg_lo:[0,1] neg_hi:[0,1]
	v_cvt_pk_f16_f32 v36, v58, v57
	v_add_co_u32_e32 v58, vcc, s35, v40
	v_lshlrev_b32_e32 v56, 16, v65
	s_nop 0
	v_addc_co_u32_e32 v59, vcc, 0, v41, vcc
	v_add_co_u32_e32 v90, vcc, s37, v40
	v_or_b32_sdwa v57, v71, v36 dst_sel:DWORD dst_unused:UNUSED_PAD src0_sel:DWORD src1_sel:WORD_1
	v_or_b32_sdwa v56, v56, v36 dst_sel:DWORD dst_unused:UNUSED_PAD src0_sel:DWORD src1_sel:WORD_0
	v_addc_co_u32_e32 v91, vcc, 0, v41, vcc
	global_store_dwordx2 v[90:91], v[56:57], off offset:-4096
	v_pk_add_f32 v[56:57], v[88:89], v[62:63]
	v_mov_b32_e32 v71, v88
	v_sub_f32_e32 v65, v63, v89
	v_mul_f32_e32 v36, 0.5, v57
	v_pk_add_f32 v[62:63], v[92:93], v[70:71] neg_lo:[0,1] neg_hi:[0,1]
	v_mul_f32_e32 v94, 0.5, v56
	v_pk_mul_f32 v[70:71], v[62:63], v[36:37]
	s_nop 0
	v_mul_f32_e32 v57, v62, v71
	v_fma_f32 v36, -v95, v36, v57
	v_fma_mixlo_f16 v57, v65, s79, v36
	v_fma_f32 v36, v65, 0.5, -v36
	v_cvt_f16_f32_sdwa v36, -v36 dst_sel:WORD_1 dst_unused:UNUSED_PAD src0_sel:DWORD
	v_pk_fma_f32 v[68:69], v[68:69], v[70:71], v[70:71] op_sel:[0,1,0] op_sel_hi:[1,0,1]
	s_nop 0
	v_pk_add_f32 v[62:63], v[94:95], v[68:69]
	v_fma_f32 v56, v56, 0.5, -v68
	v_cvt_pk_f16_f32 v56, v62, v56
	v_lshlrev_b32_e32 v62, 16, v57
	v_or_b32_sdwa v57, v36, v56 dst_sel:DWORD dst_unused:UNUSED_PAD src0_sel:DWORD src1_sel:WORD_1
	v_or_b32_sdwa v56, v62, v56 dst_sel:DWORD dst_unused:UNUSED_PAD src0_sel:DWORD src1_sel:WORD_0
	global_store_dwordx2 v[58:59], v[56:57], off offset:2048
	v_pk_mul_f32 v[56:57], v[66:67], s[38:39] op_sel_hi:[0,1]
	v_pk_add_f32 v[58:59], v[60:61], v[80:81]
	v_pk_add_f32 v[60:61], v[60:61], v[80:81] neg_lo:[0,1] neg_hi:[0,1]
	v_mul_f32_e32 v36, 0.5, v58
	v_pk_fma_f32 v[62:63], v[64:65], s[8:9], v[56:57] op_sel_hi:[0,1,1] neg_lo:[0,0,1] neg_hi:[0,0,1]
	v_pk_fma_f32 v[68:69], v[64:65], s[8:9], v[56:57] op_sel_hi:[0,1,1]
	v_mov_b32_e32 v58, v60
	v_mov_b32_e32 v70, v62
	v_mov_b32_e32 v71, v69
	v_pk_mul_f32 v[58:59], v[58:59], s[78:79]
	s_mov_b32 s8, s47
	v_pk_mul_f32 v[80:81], v[70:71], v[58:59] op_sel:[0,1] op_sel_hi:[1,0]
	v_pk_mul_f32 v[58:59], v[70:71], v[58:59]
	s_mov_b32 s9, s46
	v_sub_f32_e32 v58, v58, v59
	v_fma_mixlo_f16 v65, v61, s79, v58
	v_fma_f32 v58, v61, 0.5, -v58
	v_cvt_f16_f32_sdwa v70, -v58 dst_sel:WORD_1 dst_unused:UNUSED_PAD src0_sel:DWORD
	v_pk_add_f32 v[58:59], v[80:81], v[80:81] op_sel:[0,1] op_sel_hi:[0,1]
	v_pk_add_f32 v[60:61], v[36:37], v[58:59]
	v_pk_add_f32 v[58:59], v[36:37], v[58:59] op_sel_hi:[0,1] neg_lo:[0,1] neg_hi:[0,1]
	v_cvt_pk_f16_f32 v36, v60, v59
	v_lshlrev_b32_e32 v58, 16, v65
	v_or_b32_sdwa v59, v70, v36 dst_sel:DWORD dst_unused:UNUSED_PAD src0_sel:DWORD src1_sel:WORD_1
	v_or_b32_sdwa v58, v58, v36 dst_sel:DWORD dst_unused:UNUSED_PAD src0_sel:DWORD src1_sel:WORD_0
	global_store_dwordx2 v[90:91], v[58:59], off
	v_mul_f32_e32 v58, 0xbe47c5c2, v67
	v_pk_add_f32 v[60:61], v[46:47], v[82:83]
	v_sub_f32_e32 v65, v47, v83
	v_mov_b32_e32 v59, v46
	v_pk_mov_b32 v[46:47], v[56:57], v[82:83] op_sel:[1,0]
	v_mul_f32_e32 v36, 0.5, v61
	v_pk_add_f32 v[46:47], v[58:59], v[46:47] neg_lo:[0,1] neg_hi:[0,1]
	v_mul_f32_e32 v70, 0.5, v60
	v_pk_mul_f32 v[58:59], v[46:47], v[36:37]
	s_nop 0
	v_mul_f32_e32 v46, v46, v59
	v_fma_f32 v36, -v62, v36, v46
	v_fma_mixlo_f16 v57, v65, s79, v36
	v_fma_f32 v36, v65, 0.5, -v36
	v_pk_fma_f32 v[80:81], v[62:63], v[58:59], v[58:59] op_sel:[0,1,0] op_sel_hi:[1,0,1]
	v_cvt_f16_f32_sdwa v36, -v36 dst_sel:WORD_1 dst_unused:UNUSED_PAD src0_sel:DWORD
	v_pk_add_f32 v[46:47], v[70:71], v[80:81]
	v_lshlrev_b32_e32 v57, 16, v57
	v_fma_f32 v47, v60, 0.5, -v80
	v_cvt_pk_f16_f32 v46, v46, v47
	v_or_b32_sdwa v47, v36, v46 dst_sel:DWORD dst_unused:UNUSED_PAD src0_sel:DWORD src1_sel:WORD_1
	v_or_b32_sdwa v46, v57, v46 dst_sel:DWORD dst_unused:UNUSED_PAD src0_sel:DWORD src1_sel:WORD_0
	global_store_dwordx2 v[90:91], v[46:47], off offset:2048
	v_pk_mul_f32 v[46:47], v[66:67], s[8:9] op_sel_hi:[0,1]
	v_pk_add_f32 v[58:59], v[76:77], v[52:53]
	v_pk_add_f32 v[52:53], v[52:53], v[76:77] neg_lo:[0,1] neg_hi:[0,1]
	v_mul_f32_e32 v36, 0.5, v58
	v_pk_fma_f32 v[60:61], v[64:65], s[46:47], v[46:47] op_sel_hi:[0,1,1] neg_lo:[0,0,1] neg_hi:[0,0,1]
	v_pk_fma_f32 v[64:65], v[64:65], s[46:47], v[46:47] op_sel_hi:[0,1,1]
	v_mov_b32_e32 v58, v52
	v_mov_b32_e32 v70, v60
	v_mov_b32_e32 v71, v65
	v_pk_mul_f32 v[58:59], v[58:59], s[78:79]
	s_nop 0
	v_pk_mul_f32 v[76:77], v[70:71], v[58:59] op_sel:[0,1] op_sel_hi:[1,0]
	v_pk_mul_f32 v[58:59], v[70:71], v[58:59]
	s_nop 0
	v_sub_f32_e32 v52, v58, v59
	v_fma_mixlo_f16 v57, v53, s79, v52
	v_fma_f32 v52, v53, 0.5, -v52
	v_cvt_f16_f32_sdwa v66, -v52 dst_sel:WORD_1 dst_unused:UNUSED_PAD src0_sel:DWORD
	v_pk_add_f32 v[52:53], v[76:77], v[76:77] op_sel:[0,1] op_sel_hi:[0,1]
	v_pk_add_f32 v[58:59], v[36:37], v[52:53]
	v_pk_add_f32 v[52:53], v[36:37], v[52:53] op_sel_hi:[0,1] neg_lo:[0,1] neg_hi:[0,1]
	v_cvt_pk_f16_f32 v36, v58, v53
	v_add_co_u32_e32 v58, vcc, s51, v40
	v_lshlrev_b32_e32 v52, 16, v57
	s_nop 0
	v_addc_co_u32_e32 v59, vcc, 0, v41, vcc
	v_add_co_u32_e32 v70, vcc, s60, v40
	v_or_b32_sdwa v53, v66, v36 dst_sel:DWORD dst_unused:UNUSED_PAD src0_sel:DWORD src1_sel:WORD_1
	v_or_b32_sdwa v52, v52, v36 dst_sel:DWORD dst_unused:UNUSED_PAD src0_sel:DWORD src1_sel:WORD_0
	v_addc_co_u32_e32 v71, vcc, 0, v41, vcc
	global_store_dwordx2 v[70:71], v[52:53], off offset:-4096
	v_mul_f32_e32 v52, 0xbf54db31, v67
	v_pk_add_f32 v[76:77], v[72:73], v[54:55]
	v_sub_f32_e32 v57, v55, v73
	v_mov_b32_e32 v53, v54
	v_pk_mov_b32 v[54:55], v[46:47], v[72:73] op_sel:[1,0]
	v_mul_f32_e32 v36, 0.5, v77
	v_pk_add_f32 v[52:53], v[52:53], v[54:55] neg_lo:[0,1] neg_hi:[0,1]
	v_mul_f32_e32 v66, 0.5, v76
	v_pk_mul_f32 v[54:55], v[52:53], v[36:37]
	s_nop 0
	v_mul_f32_e32 v47, v52, v55
	v_fma_f32 v36, -v60, v36, v47
	v_fma_mixlo_f16 v47, v57, s79, v36
	v_fma_f32 v36, v57, 0.5, -v36
	v_pk_fma_f32 v[72:73], v[60:61], v[54:55], v[54:55] op_sel:[0,1,0] op_sel_hi:[1,0,1]
	v_cvt_f16_f32_sdwa v36, -v36 dst_sel:WORD_1 dst_unused:UNUSED_PAD src0_sel:DWORD
	v_pk_add_f32 v[52:53], v[66:67], v[72:73]
	v_lshlrev_b32_e32 v47, 16, v47
	v_fma_f32 v53, v76, 0.5, -v72
	v_cvt_pk_f16_f32 v52, v52, v53
	v_or_b32_sdwa v53, v36, v52 dst_sel:DWORD dst_unused:UNUSED_PAD src0_sel:DWORD src1_sel:WORD_1
	v_or_b32_sdwa v52, v47, v52 dst_sel:DWORD dst_unused:UNUSED_PAD src0_sel:DWORD src1_sel:WORD_0
	global_store_dwordx2 v[58:59], v[52:53], off offset:2048
	v_pk_add_f32 v[52:53], v[74:75], v[50:51]
	v_pk_add_f32 v[50:51], v[50:51], v[74:75] neg_lo:[0,1] neg_hi:[0,1]
	v_mul_f32_e32 v36, 0.5, v52
	v_mov_b32_e32 v52, v50
	v_pk_mov_b32 v[54:55], v[60:61], v[64:65] op_sel:[1,0]
	v_pk_mul_f32 v[52:53], v[52:53], s[78:79]
	s_nop 0
	v_pk_mul_f32 v[58:59], v[54:55], v[52:53] op_sel:[0,1] op_sel_hi:[1,0]
	v_pk_mul_f32 v[52:53], v[54:55], v[52:53]
	s_nop 0
	v_sub_f32_e32 v47, v52, v53
	v_fma_mixlo_f16 v57, v51, s79, v47
	v_fma_f32 v47, v51, 0.5, -v47
	v_cvt_f16_f32_sdwa v47, -v47 dst_sel:WORD_1 dst_unused:UNUSED_PAD src0_sel:DWORD
	v_pk_add_f32 v[50:51], v[58:59], v[58:59] op_sel:[0,1] op_sel_hi:[0,1]
	v_pk_add_f32 v[52:53], v[36:37], v[50:51]
	v_pk_add_f32 v[50:51], v[36:37], v[50:51] op_sel_hi:[0,1] neg_lo:[0,1] neg_hi:[0,1]
	v_cvt_pk_f16_f32 v36, v52, v51
	v_lshlrev_b32_e32 v50, 16, v57
	v_or_b32_sdwa v51, v47, v36 dst_sel:DWORD dst_unused:UNUSED_PAD src0_sel:DWORD src1_sel:WORD_1
	v_or_b32_sdwa v50, v50, v36 dst_sel:DWORD dst_unused:UNUSED_PAD src0_sel:DWORD src1_sel:WORD_0
	global_store_dwordx2 v[70:71], v[50:51], off
	v_mul_f32_e32 v50, 0xbf0e39da, v67
	v_pk_add_f32 v[52:53], v[78:79], v[44:45]
	v_mov_b32_e32 v51, v44
	v_mov_b32_e32 v47, v78
	v_sub_f32_e32 v57, v45, v79
	v_mul_f32_e32 v36, 0.5, v53
	v_pk_add_f32 v[44:45], v[50:51], v[46:47] neg_lo:[0,1] neg_hi:[0,1]
	v_mul_f32_e32 v58, 0.5, v52
	v_pk_mul_f32 v[46:47], v[44:45], v[36:37]
	s_nop 0
	v_mul_f32_e32 v44, v44, v47
	v_fma_f32 v36, -v61, v36, v44
	v_pk_fma_f32 v[50:51], v[54:55], v[46:47], v[46:47] op_sel:[0,1,0] op_sel_hi:[1,0,1]
	v_fma_mixlo_f16 v46, v57, s79, v36
	v_fma_f32 v36, v57, 0.5, -v36
	v_cvt_f16_f32_sdwa v36, -v36 dst_sel:WORD_1 dst_unused:UNUSED_PAD src0_sel:DWORD
	v_pk_add_f32 v[44:45], v[58:59], v[50:51]
	v_lshlrev_b32_e32 v46, 16, v46
	v_fma_f32 v45, v52, 0.5, -v50
	v_cvt_pk_f16_f32 v44, v44, v45
	v_or_b32_sdwa v45, v36, v44 dst_sel:DWORD dst_unused:UNUSED_PAD src0_sel:DWORD src1_sel:WORD_1
	v_or_b32_sdwa v44, v46, v44 dst_sel:DWORD dst_unused:UNUSED_PAD src0_sel:DWORD src1_sel:WORD_0
	global_store_dwordx2 v[70:71], v[44:45], off offset:2048
	v_pk_add_f32 v[44:45], v[86:87], v[42:43]
	v_pk_add_f32 v[42:43], v[42:43], v[86:87] neg_lo:[0,1] neg_hi:[0,1]
	v_mul_f32_e32 v36, 0.5, v44
	v_mov_b32_e32 v44, v42
	v_pk_mov_b32 v[46:47], v[62:63], v[68:69] op_sel:[1,0]
	v_pk_mul_f32 v[44:45], v[44:45], s[78:79]
	s_nop 0
	v_pk_mul_f32 v[50:51], v[46:47], v[44:45] op_sel:[0,1] op_sel_hi:[1,0]
	v_pk_mul_f32 v[44:45], v[46:47], v[44:45]
	s_nop 0
	v_sub_f32_e32 v42, v44, v45
	v_fma_mixlo_f16 v46, v43, s79, v42
	v_fma_f32 v42, v43, 0.5, -v42
	v_cvt_f16_f32_sdwa v47, -v42 dst_sel:WORD_1 dst_unused:UNUSED_PAD src0_sel:DWORD
	v_pk_add_f32 v[42:43], v[50:51], v[50:51] op_sel:[0,1] op_sel_hi:[0,1]
	v_pk_add_f32 v[44:45], v[36:37], v[42:43]
	v_pk_add_f32 v[42:43], v[36:37], v[42:43] op_sel_hi:[0,1] neg_lo:[0,1] neg_hi:[0,1]
	v_cvt_pk_f16_f32 v36, v44, v43
	v_lshlrev_b32_e32 v42, 16, v46
	v_or_b32_sdwa v43, v47, v36 dst_sel:DWORD dst_unused:UNUSED_PAD src0_sel:DWORD src1_sel:WORD_1
	v_pk_add_f32 v[44:45], v[48:49], v[84:85]
	v_pk_add_f32 v[46:47], v[48:49], v[84:85] neg_lo:[0,1] neg_hi:[0,1]
	v_mov_b32_e32 v48, v44
	v_mov_b32_e32 v49, v47
	v_mov_b32_e32 v47, v45
	v_pk_mul_f32 v[44:45], v[46:47], s[78:79]
	v_or_b32_sdwa v42, v42, v36 dst_sel:DWORD dst_unused:UNUSED_PAD src0_sel:DWORD src1_sel:WORD_0
	v_fma_f32 v36, v67, s26, -v56
	v_pk_mul_f32 v[46:47], v[62:63], v[44:45] op_sel:[1,0]
	s_nop 0
	v_pk_fma_f32 v[50:51], v[36:37], v[44:45], v[46:47] op_sel:[0,1,0] op_sel_hi:[0,0,1] neg_hi:[0,0,1]
	s_nop 0
	v_pk_fma_f32 v[44:45], v[48:49], 0.5, v[50:51] op_sel_hi:[1,0,1]
	v_pk_fma_f32 v[112:113], v[48:49], 0.5, v[50:51] op_sel_hi:[1,0,1] neg_lo:[0,0,1] neg_hi:[0,0,1]
	v_cvt_f16_f32_e32 v36, v44
	v_cvt_f16_f32_sdwa v46, v45 dst_sel:WORD_1 dst_unused:UNUSED_PAD src0_sel:DWORD
	v_add_co_u32_e32 v44, vcc, s61, v40
	v_or_b32_e32 v110, v46, v36
	s_nop 0
	v_addc_co_u32_e32 v45, vcc, 0, v41, vcc
	global_store_dwordx2 v[44:45], v[42:43], off
.LBB0_434:
	s_andn2_saveexec_b64 s[6:7], s[6:7]
	s_cbranch_execz .LBB0_427
	v_pk_add_f32 v[110:111], v[84:85], v[114:115]
	v_pk_add_f32 v[84:85], v[84:85], v[114:115] neg_lo:[0,1] neg_hi:[0,1]
	v_mul_f32_e32 v112, 0.5, v110
	v_pk_fma_f32 v[114:115], v[66:67], 0, v[66:67] op_sel:[0,0,1] op_sel_hi:[1,0,0] neg_lo:[1,0,0]
	v_mov_b32_e32 v110, v84
	v_pk_mul_f32 v[110:111], v[110:111], s[78:79]
	s_mov_b32 s8, s45
	v_pk_mul_f32 v[116:117], v[114:115], v[110:111] op_sel:[0,1] op_sel_hi:[1,0]
	v_pk_mul_f32 v[110:111], v[114:115], v[110:111]
	s_mov_b32 s9, s42
	v_sub_f32_e32 v84, v110, v111
	v_fma_mixlo_f16 v93, v85, s79, v84
	v_fma_f32 v84, v85, 0.5, -v84
	v_cvt_f16_f32_sdwa v101, -v84 dst_sel:WORD_1 dst_unused:UNUSED_PAD src0_sel:DWORD
	v_pk_add_f32 v[84:85], v[116:117], v[116:117] op_sel:[0,1] op_sel_hi:[0,1]
	v_pk_add_f32 v[110:111], v[112:113], v[84:85]
	v_pk_add_f32 v[84:85], v[112:113], v[84:85] op_sel_hi:[0,1] neg_lo:[0,1] neg_hi:[0,1]
	v_cvt_pk_f16_f32 v84, v110, v85
	v_lshlrev_b32_e32 v93, 16, v93
	v_or_b32_sdwa v85, v101, v84 dst_sel:DWORD dst_unused:UNUSED_PAD src0_sel:DWORD src1_sel:WORD_1
	v_or_b32_sdwa v84, v93, v84 dst_sel:DWORD dst_unused:UNUSED_PAD src0_sel:DWORD src1_sel:WORD_0
	global_store_dwordx2 v[40:41], v[84:85], off
	v_pk_add_f32 v[84:85], v[86:87], v[108:109]
	v_pk_add_f32 v[86:87], v[86:87], v[108:109] neg_lo:[0,1] neg_hi:[0,1]
	v_mul_f32_e32 v110, 0.5, v84
	v_mov_b32_e32 v84, v67
	v_mov_b32_e32 v108, v67
	v_mov_b32_e32 v109, v66
	v_pk_fma_f32 v[112:113], v[66:67], 0, v[108:109] op_sel_hi:[1,0,1] neg_lo:[0,0,1] neg_hi:[0,0,1]
	v_pk_fma_f32 v[114:115], v[66:67], 0, v[84:85] op_sel_hi:[1,0,1]
	v_mov_b32_e32 v84, v86
	v_pk_mov_b32 v[112:113], v[112:113], v[114:115] op_sel:[1,0]
	v_pk_mul_f32 v[84:85], v[84:85], s[78:79]
	s_mov_b32 s43, s45
	v_pk_mul_f32 v[114:115], v[112:113], v[84:85] op_sel:[0,1] op_sel_hi:[1,0]
	v_pk_mul_f32 v[84:85], v[112:113], v[84:85]
	v_pk_fma_f32 v[112:113], v[108:109], s[68:69], v[36:37] op_sel_hi:[1,1,0]
	v_sub_f32_e32 v84, v84, v85
	v_fma_mixlo_f16 v93, v87, s79, v84
	v_fma_f32 v84, v87, 0.5, -v84
	v_cvt_f16_f32_sdwa v101, -v84 dst_sel:WORD_1 dst_unused:UNUSED_PAD src0_sel:DWORD
	v_pk_add_f32 v[84:85], v[114:115], v[114:115] op_sel:[0,1] op_sel_hi:[0,1]
	v_pk_add_f32 v[86:87], v[110:111], v[84:85]
	v_pk_add_f32 v[84:85], v[110:111], v[84:85] op_sel_hi:[0,1] neg_lo:[0,1] neg_hi:[0,1]
	v_cvt_pk_f16_f32 v84, v86, v85
	v_lshlrev_b32_e32 v86, 16, v93
	v_or_b32_sdwa v85, v101, v84 dst_sel:DWORD dst_unused:UNUSED_PAD src0_sel:DWORD src1_sel:WORD_1
	v_or_b32_sdwa v84, v86, v84 dst_sel:DWORD dst_unused:UNUSED_PAD src0_sel:DWORD src1_sel:WORD_0
	global_store_dwordx2 v[40:41], v[84:85], off offset:2048
	v_pk_mul_f32 v[84:85], v[108:109], s[68:69]
	v_pk_add_f32 v[86:87], v[78:79], v[106:107]
	v_pk_add_f32 v[78:79], v[78:79], v[106:107] neg_lo:[0,1] neg_hi:[0,1]
	v_mul_f32_e32 v110, 0.5, v86
	v_pk_add_f32 v[106:107], v[36:37], v[84:85] op_sel:[0,1] op_sel_hi:[0,1] neg_lo:[0,1] neg_hi:[0,1]
	v_mov_b32_e32 v86, v78
	v_mov_b32_e32 v107, v113
	v_pk_mul_f32 v[86:87], v[86:87], s[78:79]
	v_mov_b32_e32 v101, v76
	v_pk_mul_f32 v[112:113], v[106:107], v[86:87] op_sel:[0,1] op_sel_hi:[1,0]
	v_pk_mul_f32 v[86:87], v[106:107], v[86:87]
	s_mov_b32 s39, s27
	v_sub_f32_e32 v36, v86, v87
	v_fma_mixlo_f16 v93, v79, s79, v36
	v_fma_f32 v36, v79, 0.5, -v36
	v_cvt_f16_f32_sdwa v36, -v36 dst_sel:WORD_1 dst_unused:UNUSED_PAD src0_sel:DWORD
	v_pk_add_f32 v[78:79], v[112:113], v[112:113] op_sel:[0,1] op_sel_hi:[0,1]
	v_pk_add_f32 v[86:87], v[110:111], v[78:79]
	v_pk_add_f32 v[78:79], v[110:111], v[78:79] op_sel_hi:[0,1] neg_lo:[0,1] neg_hi:[0,1]
	v_cvt_pk_f16_f32 v78, v86, v79
	v_lshlrev_b32_e32 v86, 16, v93
	v_or_b32_sdwa v79, v36, v78 dst_sel:DWORD dst_unused:UNUSED_PAD src0_sel:DWORD src1_sel:WORD_1
	v_or_b32_sdwa v78, v86, v78 dst_sel:DWORD dst_unused:UNUSED_PAD src0_sel:DWORD src1_sel:WORD_0
	v_add_co_u32_e32 v86, vcc, s34, v40
	v_mov_b32_e32 v93, v80
	s_nop 0
	v_addc_co_u32_e32 v87, vcc, 0, v41, vcc
	v_add_co_u32_e32 v110, vcc, s3, v40
	s_mov_b32 s82, s27
	s_nop 0
	v_addc_co_u32_e32 v111, vcc, 0, v41, vcc
	global_store_dwordx2 v[110:111], v[78:79], off offset:-4096
	v_pk_fma_f32 v[78:79], v[108:109], s[68:69], v[84:85] op_sel:[0,0,1] op_sel_hi:[1,1,0] neg_lo:[0,0,1] neg_hi:[0,0,1]
	v_pk_add_f32 v[84:85], v[74:75], v[104:105]
	v_pk_add_f32 v[74:75], v[74:75], v[104:105] neg_lo:[0,1] neg_hi:[0,1]
	v_mul_f32_e32 v36, 0.5, v84
	v_mov_b32_e32 v84, v74
	v_pk_mul_f32 v[84:85], v[84:85], s[78:79]
	v_mov_b32_e32 v79, v106
	v_mov_b32_e32 v107, v78
	v_pk_mul_f32 v[78:79], v[78:79], v[84:85]
	v_pk_mul_f32 v[104:105], v[106:107], v[84:85]
	v_sub_f32_e32 v74, v78, v79
	v_fma_mixlo_f16 v84, v75, s79, v74
	v_fma_f32 v74, v75, 0.5, -v74
	v_cvt_f16_f32_sdwa v85, -v74 dst_sel:WORD_1 dst_unused:UNUSED_PAD src0_sel:DWORD
	v_pk_add_f32 v[74:75], v[104:105], v[104:105] op_sel:[1,0] op_sel_hi:[1,0]
	s_mov_b32 s83, s38
	v_pk_add_f32 v[78:79], v[36:37], v[74:75]
	v_pk_add_f32 v[74:75], v[36:37], v[74:75] op_sel_hi:[0,1] neg_lo:[0,1] neg_hi:[0,1]
	v_cvt_pk_f16_f32 v36, v78, v75
	v_lshlrev_b32_e32 v74, 16, v84
	v_or_b32_sdwa v75, v85, v36 dst_sel:DWORD dst_unused:UNUSED_PAD src0_sel:DWORD src1_sel:WORD_1
	v_or_b32_sdwa v74, v74, v36 dst_sel:DWORD dst_unused:UNUSED_PAD src0_sel:DWORD src1_sel:WORD_0
	global_store_dwordx2 v[86:87], v[74:75], off offset:2048
	v_mov_b32_e32 v36, v67
	v_pk_mul_f32 v[66:67], v[66:67], s[8:9] op_sel_hi:[0,1]
	v_pk_add_f32 v[74:75], v[72:73], v[102:103]
	v_pk_add_f32 v[72:73], v[72:73], v[102:103] neg_lo:[0,1] neg_hi:[0,1]
	v_mul_f32_e32 v78, 0.5, v74
	v_pk_fma_f32 v[84:85], v[36:37], s[42:43], v[66:67] op_sel_hi:[0,1,1] neg_lo:[0,0,1] neg_hi:[0,0,1]
	v_pk_fma_f32 v[86:87], v[36:37], s[42:43], v[66:67] op_sel_hi:[0,1,1]
	v_mov_b32_e32 v74, v72
	v_mov_b32_e32 v102, v84
	v_mov_b32_e32 v103, v87
	v_pk_mul_f32 v[74:75], v[74:75], s[78:79]
	s_nop 0
	v_pk_mul_f32 v[104:105], v[102:103], v[74:75] op_sel:[0,1] op_sel_hi:[1,0]
	v_pk_mul_f32 v[74:75], v[102:103], v[74:75]
	s_nop 0
	v_sub_f32_e32 v36, v74, v75
	v_fma_mixlo_f16 v79, v73, s79, v36
	v_fma_f32 v36, v73, 0.5, -v36
	v_cvt_f16_f32_sdwa v36, -v36 dst_sel:WORD_1 dst_unused:UNUSED_PAD src0_sel:DWORD
	v_pk_add_f32 v[72:73], v[104:105], v[104:105] op_sel:[0,1] op_sel_hi:[0,1]
	v_pk_add_f32 v[74:75], v[78:79], v[72:73]
	v_pk_add_f32 v[72:73], v[78:79], v[72:73] op_sel_hi:[0,1] neg_lo:[0,1] neg_hi:[0,1]
	v_cvt_pk_f16_f32 v72, v74, v73
	v_lshlrev_b32_e32 v74, 16, v79
	v_or_b32_sdwa v73, v36, v72 dst_sel:DWORD dst_unused:UNUSED_PAD src0_sel:DWORD src1_sel:WORD_1
	v_or_b32_sdwa v72, v74, v72 dst_sel:DWORD dst_unused:UNUSED_PAD src0_sel:DWORD src1_sel:WORD_0
	global_store_dwordx2 v[110:111], v[72:73], off
	v_pk_add_f32 v[72:73], v[76:77], v[98:99]
	v_sub_f32_e32 v75, v77, v99
	v_pk_mov_b32 v[76:77], v[66:67], v[98:99] op_sel:[1,0]
	v_mul_f32_e32 v36, 0.5, v73
	v_pk_add_f32 v[76:77], v[100:101], v[76:77] neg_lo:[0,1] neg_hi:[0,1]
	v_mul_f32_e32 v74, 0.5, v72
	v_pk_mul_f32 v[78:79], v[76:77], v[36:37]
	s_nop 0
	v_mul_f32_e32 v67, v76, v79
	v_fma_f32 v36, -v84, v36, v67
	v_fma_mixlo_f16 v67, v75, s79, v36
	v_fma_f32 v36, v75, 0.5, -v36
	v_cvt_f16_f32_sdwa v36, -v36 dst_sel:WORD_1 dst_unused:UNUSED_PAD src0_sel:DWORD
	v_pk_fma_f32 v[98:99], v[84:85], v[78:79], v[78:79] op_sel:[0,1,0] op_sel_hi:[1,0,1]
	v_lshlrev_b32_e32 v67, 16, v67
	v_pk_add_f32 v[74:75], v[74:75], v[98:99]
	v_fma_f32 v72, v72, 0.5, -v98
	v_cvt_pk_f16_f32 v72, v74, v72
	v_or_b32_sdwa v73, v36, v72 dst_sel:DWORD dst_unused:UNUSED_PAD src0_sel:DWORD src1_sel:WORD_1
	v_or_b32_sdwa v72, v67, v72 dst_sel:DWORD dst_unused:UNUSED_PAD src0_sel:DWORD src1_sel:WORD_0
	global_store_dwordx2 v[110:111], v[72:73], off offset:2048
	v_pk_add_f32 v[72:73], v[96:97], v[82:83]
	v_pk_add_f32 v[74:75], v[82:83], v[96:97] neg_lo:[0,1] neg_hi:[0,1]
	v_mul_f32_e32 v36, 0.5, v72
	v_mov_b32_e32 v72, v74
	v_pk_mov_b32 v[76:77], v[84:85], v[86:87] op_sel:[1,0]
	v_pk_mul_f32 v[72:73], v[72:73], s[78:79]
	v_sub_f32_e32 v83, v81, v89
	v_pk_mul_f32 v[78:79], v[76:77], v[72:73] op_sel:[0,1] op_sel_hi:[1,0]
	v_pk_mul_f32 v[72:73], v[76:77], v[72:73]
	s_nop 0
	v_sub_f32_e32 v67, v72, v73
	v_fma_mixlo_f16 v82, v75, s79, v67
	v_fma_f32 v67, v75, 0.5, -v67
	v_pk_add_f32 v[72:73], v[78:79], v[78:79] op_sel:[0,1] op_sel_hi:[0,1]
	v_cvt_f16_f32_sdwa v67, -v67 dst_sel:WORD_1 dst_unused:UNUSED_PAD src0_sel:DWORD
	v_pk_add_f32 v[74:75], v[36:37], v[72:73]
	v_pk_add_f32 v[72:73], v[36:37], v[72:73] op_sel_hi:[0,1] neg_lo:[0,1] neg_hi:[0,1]
	v_cvt_pk_f16_f32 v36, v74, v73
	v_add_co_u32_e32 v74, vcc, s35, v40
	v_lshlrev_b32_e32 v72, 16, v82
	s_nop 0
	v_addc_co_u32_e32 v75, vcc, 0, v41, vcc
	v_add_co_u32_e32 v78, vcc, s37, v40
	v_or_b32_sdwa v73, v67, v36 dst_sel:DWORD dst_unused:UNUSED_PAD src0_sel:DWORD src1_sel:WORD_1
	v_or_b32_sdwa v72, v72, v36 dst_sel:DWORD dst_unused:UNUSED_PAD src0_sel:DWORD src1_sel:WORD_0
	v_addc_co_u32_e32 v79, vcc, 0, v41, vcc
	global_store_dwordx2 v[78:79], v[72:73], off offset:-4096
	v_pk_add_f32 v[72:73], v[88:89], v[80:81]
	v_mov_b32_e32 v67, v88
	v_mul_f32_e32 v36, 0.5, v73
	v_pk_add_f32 v[66:67], v[92:93], v[66:67] neg_lo:[0,1] neg_hi:[0,1]
	v_mul_f32_e32 v82, 0.5, v72
	v_pk_mul_f32 v[80:81], v[66:67], v[36:37]
	s_nop 0
	v_mul_f32_e32 v66, v66, v81
	v_fma_f32 v36, -v85, v36, v66
	v_fma_mixlo_f16 v73, v83, s79, v36
	v_fma_f32 v36, v83, 0.5, -v36
	v_pk_fma_f32 v[76:77], v[76:77], v[80:81], v[80:81] op_sel:[0,1,0] op_sel_hi:[1,0,1]
	v_cvt_f16_f32_sdwa v36, -v36 dst_sel:WORD_1 dst_unused:UNUSED_PAD src0_sel:DWORD
	v_pk_add_f32 v[66:67], v[82:83], v[76:77]
	s_nop 0
	v_fma_f32 v67, v72, 0.5, -v76
	v_cvt_pk_f16_f32 v66, v66, v67
	v_lshlrev_b32_e32 v72, 16, v73
	v_or_b32_sdwa v67, v36, v66 dst_sel:DWORD dst_unused:UNUSED_PAD src0_sel:DWORD src1_sel:WORD_1
	v_sub_f32_e32 v36, v94, v95
	v_or_b32_sdwa v66, v72, v66 dst_sel:DWORD dst_unused:UNUSED_PAD src0_sel:DWORD src1_sel:WORD_0
	v_cvt_f16_f32_sdwa v72, -v91 dst_sel:WORD_1 dst_unused:UNUSED_PAD src0_sel:DWORD
	v_cvt_f16_f32_sdwa v36, v36 dst_sel:WORD_1 dst_unused:UNUSED_PAD src0_sel:DWORD
	global_store_dwordx2 v[74:75], v[66:67], off offset:2048
	v_pk_add_f32 v[66:67], v[94:95], v[94:95] op_sel:[0,1] op_sel_hi:[1,0]
	s_nop 0
	v_cvt_pk_f16_f32 v66, v66, v90
	v_or_b32_sdwa v67, v72, v66 dst_sel:DWORD dst_unused:UNUSED_PAD src0_sel:DWORD src1_sel:WORD_1
	v_or_b32_sdwa v66, v36, v66 dst_sel:DWORD dst_unused:UNUSED_PAD src0_sel:DWORD src1_sel:WORD_0
	global_store_dwordx2 v[78:79], v[66:67], off
	v_pk_add_f32 v[66:67], v[60:61], v[48:49]
	v_pk_add_f32 v[48:49], v[60:61], v[48:49] neg_lo:[0,1] neg_hi:[0,1]
	v_mul_f32_e32 v36, 0.5, v66
	v_mov_b32_e32 v66, v48
	v_pk_mul_f32 v[60:61], v[66:67], s[78:79]
	s_nop 0
	v_pk_mul_f32 v[66:67], v[60:61], s[38:39]
	v_pk_mul_f32 v[60:61], v[60:61], s[82:83]
	s_mov_b32 s82, s47
	v_sub_f32_e32 v48, v60, v61
	v_fma_mixlo_f16 v72, v49, s79, v48
	v_fma_f32 v48, v49, 0.5, -v48
	v_cvt_f16_f32_sdwa v73, -v48 dst_sel:WORD_1 dst_unused:UNUSED_PAD src0_sel:DWORD
	v_pk_add_f32 v[48:49], v[66:67], v[66:67] op_sel:[1,0] op_sel_hi:[1,0]
	s_mov_b32 s83, s46
	v_pk_add_f32 v[60:61], v[36:37], v[48:49]
	v_pk_add_f32 v[48:49], v[36:37], v[48:49] op_sel_hi:[0,1] neg_lo:[0,1] neg_hi:[0,1]
	v_cvt_pk_f16_f32 v36, v60, v49
	v_lshlrev_b32_e32 v48, 16, v72
	v_or_b32_sdwa v49, v73, v36 dst_sel:DWORD dst_unused:UNUSED_PAD src0_sel:DWORD src1_sel:WORD_1
	v_or_b32_sdwa v48, v48, v36 dst_sel:DWORD dst_unused:UNUSED_PAD src0_sel:DWORD src1_sel:WORD_0
	global_store_dwordx2 v[78:79], v[48:49], off offset:2048
	v_pk_add_f32 v[48:49], v[68:69], v[62:63]
	v_pk_add_f32 v[60:61], v[68:69], v[62:63] neg_lo:[0,1] neg_hi:[0,1]
	v_mul_f32_e32 v36, 0.5, v48
	v_mov_b32_e32 v48, v60
	v_pk_mul_f32 v[48:49], v[48:49], s[78:79]
	s_nop 0
	v_pk_mul_f32 v[62:63], v[48:49], s[8:9]
	v_pk_mul_f32 v[48:49], v[48:49], s[42:43]
	s_nop 0
	v_sub_f32_e32 v48, v48, v49
	v_fma_mixlo_f16 v66, v61, s79, v48
	v_fma_f32 v48, v61, 0.5, -v48
	v_cvt_f16_f32_sdwa v67, -v48 dst_sel:WORD_1 dst_unused:UNUSED_PAD src0_sel:DWORD
	v_pk_add_f32 v[48:49], v[62:63], v[62:63] op_sel:[1,0] op_sel_hi:[1,0]
	s_nop 0
	v_pk_add_f32 v[60:61], v[36:37], v[48:49]
	v_pk_add_f32 v[48:49], v[36:37], v[48:49] op_sel_hi:[0,1] neg_lo:[0,1] neg_hi:[0,1]
	v_cvt_pk_f16_f32 v36, v60, v49
	v_add_co_u32_e32 v60, vcc, s51, v40
	v_lshlrev_b32_e32 v48, 16, v66
	s_nop 0
	v_addc_co_u32_e32 v61, vcc, 0, v41, vcc
	v_add_co_u32_e32 v62, vcc, s60, v40
	v_or_b32_sdwa v49, v67, v36 dst_sel:DWORD dst_unused:UNUSED_PAD src0_sel:DWORD src1_sel:WORD_1
	v_or_b32_sdwa v48, v48, v36 dst_sel:DWORD dst_unused:UNUSED_PAD src0_sel:DWORD src1_sel:WORD_0
	v_addc_co_u32_e32 v63, vcc, 0, v41, vcc
	global_store_dwordx2 v[62:63], v[48:49], off offset:-4096
	v_pk_add_f32 v[48:49], v[50:51], v[54:55]
	v_pk_add_f32 v[50:51], v[50:51], v[54:55] neg_lo:[0,1] neg_hi:[0,1]
	v_mul_f32_e32 v36, 0.5, v48
	v_mov_b32_e32 v48, v50
	v_pk_mul_f32 v[48:49], v[48:49], s[78:79]
	s_nop 0
	v_pk_mul_f32 v[54:55], v[48:49], s[46:47]
	v_pk_mul_f32 v[48:49], v[48:49], s[82:83]
	s_nop 0
	v_sub_f32_e32 v48, v48, v49
	v_fma_mixlo_f16 v66, v51, s79, v48
	v_fma_f32 v48, v51, 0.5, -v48
	v_cvt_f16_f32_sdwa v67, -v48 dst_sel:WORD_1 dst_unused:UNUSED_PAD src0_sel:DWORD
	v_pk_add_f32 v[48:49], v[54:55], v[54:55] op_sel:[1,0] op_sel_hi:[1,0]
	s_nop 0
	v_pk_add_f32 v[50:51], v[36:37], v[48:49]
	v_pk_add_f32 v[48:49], v[36:37], v[48:49] op_sel_hi:[0,1] neg_lo:[0,1] neg_hi:[0,1]
	v_cvt_pk_f16_f32 v36, v50, v49
	v_lshlrev_b32_e32 v48, 16, v66
	v_or_b32_sdwa v49, v67, v36 dst_sel:DWORD dst_unused:UNUSED_PAD src0_sel:DWORD src1_sel:WORD_1
	v_or_b32_sdwa v48, v48, v36 dst_sel:DWORD dst_unused:UNUSED_PAD src0_sel:DWORD src1_sel:WORD_0
	global_store_dwordx2 v[60:61], v[48:49], off offset:2048
	v_pk_add_f32 v[48:49], v[70:71], v[64:65]
	v_pk_add_f32 v[50:51], v[70:71], v[64:65] neg_lo:[0,1] neg_hi:[0,1]
	v_mul_f32_e32 v36, 0.5, v48
	v_mov_b32_e32 v48, v50
	v_pk_mul_f32 v[48:49], v[48:49], s[78:79]
	s_nop 0
	v_pk_mul_f32 v[48:49], v[48:49], s[64:65] op_sel_hi:[1,0]
	s_nop 0
	v_sub_f32_e32 v50, v48, v49
	v_fma_mixlo_f16 v54, v51, s79, v50
	v_fma_f32 v50, v51, 0.5, -v50
	v_cvt_f16_f32_sdwa v55, -v50 dst_sel:WORD_1 dst_unused:UNUSED_PAD src0_sel:DWORD
	v_pk_add_f32 v[48:49], v[48:49], v[48:49] op_sel:[1,0] op_sel_hi:[1,0]
	s_nop 0
	v_pk_add_f32 v[50:51], v[36:37], v[48:49]
	v_pk_add_f32 v[48:49], v[36:37], v[48:49] op_sel_hi:[0,1] neg_lo:[0,1] neg_hi:[0,1]
	v_cvt_pk_f16_f32 v36, v50, v49
	v_lshlrev_b32_e32 v48, 16, v54
	v_or_b32_sdwa v49, v55, v36 dst_sel:DWORD dst_unused:UNUSED_PAD src0_sel:DWORD src1_sel:WORD_1
	v_or_b32_sdwa v48, v48, v36 dst_sel:DWORD dst_unused:UNUSED_PAD src0_sel:DWORD src1_sel:WORD_0
	global_store_dwordx2 v[62:63], v[48:49], off
	v_pk_add_f32 v[48:49], v[52:53], v[44:45]
	v_pk_add_f32 v[44:45], v[52:53], v[44:45] neg_lo:[0,1] neg_hi:[0,1]
	v_mul_f32_e32 v36, 0.5, v48
	v_mov_b32_e32 v48, v44
	v_pk_mul_f32 v[48:49], v[48:49], s[78:79]
	s_nop 0
	v_pk_mul_f32 v[50:51], v[48:49], s[82:83]
	v_pk_mul_f32 v[48:49], v[48:49], s[46:47]
	s_nop 0
	v_sub_f32_e32 v44, v48, v49
	v_fma_mixlo_f16 v52, v45, s79, v44
	v_fma_f32 v44, v45, 0.5, -v44
	v_cvt_f16_f32_sdwa v53, -v44 dst_sel:WORD_1 dst_unused:UNUSED_PAD src0_sel:DWORD
	v_pk_add_f32 v[44:45], v[50:51], v[50:51] op_sel:[1,0] op_sel_hi:[1,0]
	s_nop 0
	v_pk_add_f32 v[48:49], v[36:37], v[44:45]
	v_pk_add_f32 v[44:45], v[36:37], v[44:45] op_sel_hi:[0,1] neg_lo:[0,1] neg_hi:[0,1]
	v_cvt_pk_f16_f32 v36, v48, v45
	v_lshlrev_b32_e32 v44, 16, v52
	v_or_b32_sdwa v45, v53, v36 dst_sel:DWORD dst_unused:UNUSED_PAD src0_sel:DWORD src1_sel:WORD_1
	v_or_b32_sdwa v44, v44, v36 dst_sel:DWORD dst_unused:UNUSED_PAD src0_sel:DWORD src1_sel:WORD_0
	global_store_dwordx2 v[62:63], v[44:45], off offset:2048
	v_pk_add_f32 v[44:45], v[58:59], v[56:57]
	v_pk_add_f32 v[48:49], v[56:57], v[58:59] neg_lo:[0,1] neg_hi:[0,1]
	v_mul_f32_e32 v36, 0.5, v44
	v_mov_b32_e32 v44, v48
	v_pk_mul_f32 v[44:45], v[44:45], s[78:79]
	s_nop 0
	v_pk_mul_f32 v[50:51], v[44:45], s[42:43]
	v_pk_mul_f32 v[44:45], v[44:45], s[8:9]
	s_mov_b32 s8, s27
	v_sub_f32_e32 v44, v44, v45
	v_fma_mixlo_f16 v52, v49, s79, v44
	v_fma_f32 v44, v49, 0.5, -v44
	v_cvt_f16_f32_sdwa v53, -v44 dst_sel:WORD_1 dst_unused:UNUSED_PAD src0_sel:DWORD
	v_pk_add_f32 v[44:45], v[50:51], v[50:51] op_sel:[1,0] op_sel_hi:[1,0]
	s_nop 0
	v_pk_add_f32 v[48:49], v[36:37], v[44:45]
	v_pk_add_f32 v[44:45], v[36:37], v[44:45] op_sel_hi:[0,1] neg_lo:[0,1] neg_hi:[0,1]
	v_cvt_pk_f16_f32 v36, v48, v45
	v_pk_add_f32 v[48:49], v[42:43], v[46:47]
	v_pk_add_f32 v[42:43], v[42:43], v[46:47] neg_lo:[0,1] neg_hi:[0,1]
	v_mov_b32_e32 v46, v48
	v_mov_b32_e32 v47, v43
	v_mov_b32_e32 v43, v49
	v_pk_mul_f32 v[42:43], v[42:43], s[78:79]
	v_lshlrev_b32_e32 v44, 16, v52
	v_pk_mul_f32 v[48:49], v[42:43], s[38:39] op_sel_hi:[1,0]
	v_or_b32_sdwa v45, v53, v36 dst_sel:DWORD dst_unused:UNUSED_PAD src0_sel:DWORD src1_sel:WORD_1
	v_pk_fma_f32 v[50:51], v[42:43], s[8:9], v[48:49] op_sel:[0,0,1] op_sel_hi:[1,0,0] neg_hi:[1,0,0]
	s_nop 0
	v_or_b32_sdwa v44, v44, v36 dst_sel:DWORD dst_unused:UNUSED_PAD src0_sel:DWORD src1_sel:WORD_0
	s_nop 0
	v_pk_fma_f32 v[42:43], v[46:47], 0.5, v[50:51] op_sel_hi:[1,0,1]
	v_pk_fma_f32 v[112:113], v[46:47], 0.5, v[50:51] op_sel_hi:[1,0,1] neg_lo:[0,0,1] neg_hi:[0,0,1]
	v_cvt_f16_f32_e32 v36, v42
	v_cvt_f16_f32_sdwa v48, v43 dst_sel:WORD_1 dst_unused:UNUSED_PAD src0_sel:DWORD
	v_add_co_u32_e32 v42, vcc, s61, v40
	v_or_b32_e32 v110, v48, v36
	s_nop 0
	v_addc_co_u32_e32 v43, vcc, 0, v41, vcc
	global_store_dwordx2 v[42:43], v[44:45], off
	s_branch .LBB0_427

.LBB0_499:
	v_mov_b32_e32 v2, v210
	s_mov_b32 s43, s8
	v_and_b32_e32 v3, 0x1ff, v2
	v_lshlrev_b32_e32 v2, 5, v2
	v_and_or_b32 v2, v2, s94, v3
	v_ashrrev_i32_e32 v4, 5, v2
	v_lshlrev_b32_e32 v2, 3, v2
	v_lshlrev_b32_e32 v4, 3, v4
	v_add3_u32 v18, 0, v2, v4
	ds_read_b64 v[128:129], v18
	ds_read_b64 v[134:135], v18 offset:4224
	ds_read_b64 v[136:137], v18 offset:8448
	ds_read_b64 v[138:139], v18 offset:12672
	ds_read_b64 v[140:141], v18 offset:16896
	ds_read_b64 v[142:143], v18 offset:21120
	ds_read_b64 v[132:133], v18 offset:25344
	ds_read_b64 v[130:131], v18 offset:29568
	ds_read_b64 v[144:145], v18 offset:33792
	ds_read_b64 v[148:149], v18 offset:38016
	ds_read_b64 v[150:151], v18 offset:42240
	ds_read_b64 v[152:153], v18 offset:46464
	s_waitcnt lgkmcnt(10)
	v_pk_mul_f32 v[162:163], v[134:135], s[10:11]
	s_mov_b32 s74, s11
	v_pk_fma_f32 v[162:163], v[134:135], s[8:9], v[162:163] op_sel:[0,0,1] op_sel_hi:[1,0,0]
	s_waitcnt lgkmcnt(2)
	v_pk_mul_f32 v[178:179], v[148:149], s[42:43]
	v_pk_add_f32 v[194:195], v[134:135], v[148:149]
	v_pk_add_f32 v[134:135], v[134:135], v[148:149] neg_lo:[0,1] neg_hi:[0,1]
	v_pk_mul_f32 v[164:165], v[136:137], s[18:19]
	s_mov_b32 s41, s16
	v_pk_fma_f32 v[178:179], v[148:149], s[74:75], v[178:179] op_sel:[0,0,1] op_sel_hi:[1,0,0] neg_lo:[1,0,0] neg_hi:[1,0,0]
	v_pk_mul_f32 v[148:149], v[134:135], s[18:19]
	v_pk_fma_f32 v[164:165], v[136:137], s[16:17], v[164:165] op_sel:[0,0,1] op_sel_hi:[1,0,0]
	s_mov_b32 s80, s19
	s_waitcnt lgkmcnt(1)
	v_pk_mul_f32 v[180:181], v[150:151], s[40:41]
	v_pk_fma_f32 v[134:135], v[134:135], s[16:17], v[148:149] op_sel:[0,0,1] op_sel_hi:[1,0,0]
	v_pk_add_f32 v[148:149], v[136:137], v[150:151]
	v_pk_add_f32 v[136:137], v[136:137], v[150:151] neg_lo:[0,1] neg_hi:[0,1]
	v_pk_mul_f32 v[166:167], v[138:139], s[26:27]
	s_mov_b32 s78, s37
	s_mov_b32 s39, s24
	v_pk_fma_f32 v[180:181], v[150:151], s[80:81], v[180:181] op_sel:[0,0,1] op_sel_hi:[1,0,0] neg_lo:[1,0,0] neg_hi:[1,0,0]
	v_pk_mul_f32 v[150:151], v[136:137], s[36:37]
	ds_read_b64 v[154:155], v18 offset:50688
	ds_read_b64 v[156:157], v18 offset:54912
	ds_read_b64 v[158:159], v18 offset:59136
	ds_read_b64 v[160:161], v18 offset:63360
	v_pk_fma_f32 v[166:167], v[138:139], s[24:25], v[166:167] op_sel:[0,0,1] op_sel_hi:[1,0,0]
	s_mov_b32 s0, s27
	s_waitcnt lgkmcnt(4)
	v_pk_mul_f32 v[182:183], v[152:153], s[38:39]
	v_pk_fma_f32 v[136:137], v[136:137], s[78:79], v[150:151] op_sel:[0,0,1] op_sel_hi:[1,0,0]
	v_pk_add_f32 v[150:151], v[138:139], v[152:153]
	v_pk_add_f32 v[138:139], v[138:139], v[152:153] neg_lo:[0,1] neg_hi:[0,1]
	v_pk_mul_f32 v[168:169], v[140:141], s[36:37]
	v_pk_fma_f32 v[182:183], v[152:153], s[0:1], v[182:183] op_sel:[0,0,1] op_sel_hi:[1,0,0] neg_lo:[1,0,0] neg_hi:[1,0,0]
	v_pk_mul_f32 v[152:153], v[138:139], s[40:41]
	v_pk_fma_f32 v[168:169], v[140:141], s[78:79], v[168:169] op_sel:[0,0,1] op_sel_hi:[1,0,0]
	v_pk_mul_f32 v[170:171], v[142:143], s[38:39]
	s_waitcnt lgkmcnt(3)
	v_pk_mul_f32 v[184:185], v[154:155], s[36:37]
	v_pk_fma_f32 v[138:139], v[138:139], s[80:81], v[152:153] op_sel:[0,0,1] op_sel_hi:[1,0,0]
	v_pk_add_f32 v[152:153], v[140:141], v[154:155]
	v_pk_add_f32 v[140:141], v[140:141], v[154:155] neg_lo:[0,1] neg_hi:[0,1]
	v_pk_fma_f32 v[170:171], v[142:143], s[0:1], v[170:171] op_sel:[0,0,1] op_sel_hi:[1,0,0]
	v_pk_fma_f32 v[184:185], v[154:155], s[78:79], v[184:185] op_sel:[0,0,1] op_sel_hi:[1,0,0] neg_lo:[1,0,0] neg_hi:[1,0,0]
	s_waitcnt lgkmcnt(2)
	v_pk_mul_f32 v[186:187], v[156:157], s[26:27]
	v_xor_b32_e32 v155, 0x80000000, v140
	v_mov_b32_e32 v154, v141
	v_pk_add_f32 v[140:141], v[142:143], v[156:157]
	v_pk_add_f32 v[142:143], v[142:143], v[156:157] neg_lo:[0,1] neg_hi:[0,1]
	v_pk_mul_f32 v[172:173], v[132:133], s[40:41]
	v_pk_fma_f32 v[186:187], v[156:157], s[24:25], v[186:187] op_sel:[0,0,1] op_sel_hi:[1,0,0] neg_lo:[1,0,0] neg_hi:[1,0,0]
	v_pk_mul_f32 v[156:157], v[142:143], s[40:41]
	v_pk_fma_f32 v[172:173], v[132:133], s[80:81], v[172:173] op_sel:[0,0,1] op_sel_hi:[1,0,0]
	s_waitcnt lgkmcnt(1)
	v_pk_mul_f32 v[188:189], v[158:159], s[18:19]
	v_pk_fma_f32 v[142:143], v[142:143], s[80:81], v[156:157] op_sel:[0,0,1] op_sel_hi:[1,0,0] neg_lo:[1,0,0] neg_hi:[1,0,0]
	v_pk_add_f32 v[156:157], v[132:133], v[158:159]
	v_pk_add_f32 v[132:133], v[132:133], v[158:159] neg_lo:[0,1] neg_hi:[0,1]
	v_pk_mul_f32 v[174:175], v[130:131], s[42:43]
	v_pk_fma_f32 v[188:189], v[158:159], s[16:17], v[188:189] op_sel:[0,0,1] op_sel_hi:[1,0,0] neg_lo:[1,0,0] neg_hi:[1,0,0]
	v_pk_mul_f32 v[158:159], v[132:133], s[36:37]
	v_pk_fma_f32 v[174:175], v[130:131], s[74:75], v[174:175] op_sel:[0,0,1] op_sel_hi:[1,0,0]
	s_waitcnt lgkmcnt(0)
	v_pk_mul_f32 v[190:191], v[160:161], s[10:11]
	v_pk_fma_f32 v[132:133], v[132:133], s[78:79], v[158:159] op_sel:[0,0,1] op_sel_hi:[1,0,0] neg_lo:[1,0,0] neg_hi:[1,0,0]
	v_pk_add_f32 v[158:159], v[130:131], v[160:161]
	v_pk_add_f32 v[130:131], v[130:131], v[160:161] neg_lo:[0,1] neg_hi:[0,1]
	v_xor_b32_e32 v177, 0x80000000, v144
	v_mov_b32_e32 v176, v145
	v_pk_fma_f32 v[190:191], v[160:161], s[8:9], v[190:191] op_sel:[0,0,1] op_sel_hi:[1,0,0] neg_lo:[1,0,0] neg_hi:[1,0,0]
	v_pk_mul_f32 v[160:161], v[130:131], s[18:19]
	v_pk_add_f32 v[192:193], v[128:129], v[144:145]
	v_pk_add_f32 v[144:145], v[128:129], v[144:145] neg_lo:[0,1] neg_hi:[0,1]
	v_pk_fma_f32 v[130:131], v[130:131], s[16:17], v[160:161] op_sel:[0,0,1] op_sel_hi:[1,0,0] neg_lo:[1,0,0] neg_hi:[1,0,0]
	v_pk_add_f32 v[160:161], v[128:129], v[176:177]
	v_pk_add_f32 v[128:129], v[128:129], v[176:177] neg_lo:[0,1] neg_hi:[0,1]
	v_pk_add_f32 v[176:177], v[162:163], v[178:179]
	v_pk_add_f32 v[162:163], v[162:163], v[178:179] neg_lo:[0,1] neg_hi:[0,1]
	v_cvt_f32_u32_e32 v2, v3
	v_pk_mul_f32 v[178:179], v[162:163], s[18:19]
	s_add_i32 s76, s72, s48
	v_pk_fma_f32 v[162:163], v[162:163], s[16:17], v[178:179] op_sel:[0,0,1] op_sel_hi:[1,0,0]
	v_pk_add_f32 v[178:179], v[164:165], v[180:181]
	v_pk_add_f32 v[164:165], v[164:165], v[180:181] neg_lo:[0,1] neg_hi:[0,1]
	v_mul_f32_e32 v2, 0x38800000, v2
	v_pk_mul_f32 v[180:181], v[164:165], s[36:37]
	v_sin_f32_e32 v34, v2
	v_pk_fma_f32 v[164:165], v[164:165], s[78:79], v[180:181] op_sel:[0,0,1] op_sel_hi:[1,0,0]
	v_pk_add_f32 v[180:181], v[166:167], v[182:183]
	v_pk_add_f32 v[166:167], v[166:167], v[182:183] neg_lo:[0,1] neg_hi:[0,1]
	v_cos_f32_e32 v30, v2
	v_pk_mul_f32 v[182:183], v[166:167], s[40:41]
	v_xor_b32_e32 v31, 0x80000000, v34
	v_pk_fma_f32 v[166:167], v[166:167], s[80:81], v[182:183] op_sel:[0,0,1] op_sel_hi:[1,0,0]
	v_pk_add_f32 v[182:183], v[168:169], v[184:185]
	v_pk_add_f32 v[184:185], v[168:169], v[184:185] neg_lo:[0,1] neg_hi:[0,1]
	v_mov_b32_e32 v35, v31
	v_pk_add_f32 v[168:169], v[170:171], v[186:187]
	v_pk_add_f32 v[170:171], v[170:171], v[186:187] neg_lo:[0,1] neg_hi:[0,1]
	v_pk_mul_f32 v[2:3], v[30:31], v[34:35] op_sel:[1,0] op_sel_hi:[0,1]
	v_pk_mul_f32 v[186:187], v[170:171], s[40:41]
	v_pk_fma_f32 v[44:45], v[30:31], v[30:31], v[2:3] op_sel_hi:[1,0,1]
	v_pk_fma_f32 v[170:171], v[170:171], s[80:81], v[186:187] op_sel:[0,0,1] op_sel_hi:[1,0,0] neg_lo:[1,0,0] neg_hi:[1,0,0]
	v_pk_add_f32 v[186:187], v[172:173], v[188:189]
	v_pk_add_f32 v[172:173], v[172:173], v[188:189] neg_lo:[0,1] neg_hi:[0,1]
	v_pk_mul_f32 v[2:3], v[34:35], v[44:45] op_sel:[0,1] op_sel_hi:[1,0]
	v_pk_mul_f32 v[188:189], v[172:173], s[36:37]
	v_xor_b32_e32 v54, 0x80000000, v45
	v_pk_fma_f32 v[172:173], v[172:173], s[78:79], v[188:189] op_sel:[0,0,1] op_sel_hi:[1,0,0] neg_lo:[1,0,0] neg_hi:[1,0,0]
	v_pk_add_f32 v[188:189], v[174:175], v[190:191]
	v_pk_add_f32 v[174:175], v[174:175], v[190:191] neg_lo:[0,1] neg_hi:[0,1]
	v_mov_b32_e32 v55, v45
	v_pk_mul_f32 v[190:191], v[174:175], s[18:19]
	v_pk_fma_f32 v[46:47], v[30:31], v[44:45], v[2:3] op_sel_hi:[0,1,1]
	v_pk_fma_f32 v[174:175], v[174:175], s[16:17], v[190:191] op_sel:[0,0,1] op_sel_hi:[1,0,0] neg_lo:[1,0,0] neg_hi:[1,0,0]
	v_pk_add_f32 v[190:191], v[192:193], v[152:153]
	v_pk_add_f32 v[152:153], v[192:193], v[152:153] neg_lo:[0,1] neg_hi:[0,1]
	v_pk_add_f32 v[192:193], v[194:195], v[140:141]
	v_pk_add_f32 v[140:141], v[194:195], v[140:141] neg_lo:[0,1] neg_hi:[0,1]
	v_pk_mul_f32 v[2:3], v[44:45], v[54:55] op_sel:[1,0] op_sel_hi:[0,1]
	v_pk_mul_f32 v[194:195], v[140:141], s[36:37]
	v_pk_fma_f32 v[52:53], v[44:45], v[44:45], v[2:3] op_sel_hi:[1,0,1]
	v_pk_fma_f32 v[140:141], v[140:141], s[78:79], v[194:195] op_sel:[0,0,1] op_sel_hi:[1,0,0]
	v_pk_add_f32 v[194:195], v[148:149], v[156:157]
	v_pk_add_f32 v[156:157], v[148:149], v[156:157] neg_lo:[0,1] neg_hi:[0,1]
	v_xor_b32_e32 v58, 0x80000000, v53
	v_pk_add_f32 v[148:149], v[150:151], v[158:159]
	v_pk_add_f32 v[150:151], v[150:151], v[158:159] neg_lo:[0,1] neg_hi:[0,1]
	v_mov_b32_e32 v59, v53
	v_pk_mul_f32 v[158:159], v[150:151], s[36:37]
	v_pk_mul_f32 v[2:3], v[52:53], v[58:59] op_sel:[1,0] op_sel_hi:[0,1]
	v_pk_fma_f32 v[150:151], v[150:151], s[78:79], v[158:159] op_sel:[0,0,1] op_sel_hi:[1,0,0] neg_lo:[1,0,0] neg_hi:[1,0,0]
	v_pk_add_f32 v[158:159], v[144:145], v[154:155]
	v_pk_add_f32 v[144:145], v[144:145], v[154:155] neg_lo:[0,1] neg_hi:[0,1]
	v_pk_add_f32 v[154:155], v[134:135], v[142:143]
	v_pk_add_f32 v[134:135], v[134:135], v[142:143] neg_lo:[0,1] neg_hi:[0,1]
	v_pk_fma_f32 v[48:49], v[52:53], v[52:53], v[2:3] op_sel_hi:[1,0,1]
	v_pk_mul_f32 v[142:143], v[134:135], s[36:37]
	v_pk_mul_f32 v[2:3], v[58:59], v[48:49] op_sel:[0,1] op_sel_hi:[1,0]
	v_pk_fma_f32 v[134:135], v[134:135], s[78:79], v[142:143] op_sel:[0,0,1] op_sel_hi:[1,0,0]
	v_pk_add_f32 v[142:143], v[136:137], v[132:133]
	v_pk_add_f32 v[136:137], v[136:137], v[132:133] neg_lo:[0,1] neg_hi:[0,1]
	v_pk_fma_f32 v[36:37], v[52:53], v[48:49], v[2:3] op_sel_hi:[0,1,1]
	v_pk_add_f32 v[132:133], v[138:139], v[130:131]
	v_pk_add_f32 v[130:131], v[138:139], v[130:131] neg_lo:[0,1] neg_hi:[0,1]
	v_pk_mul_f32 v[2:3], v[58:59], v[36:37] op_sel:[0,1] op_sel_hi:[1,0]
	v_pk_mul_f32 v[138:139], v[130:131], s[36:37]
	v_pk_fma_f32 v[26:27], v[52:53], v[36:37], v[2:3] op_sel_hi:[0,1,1]
	v_pk_fma_f32 v[130:131], v[130:131], s[78:79], v[138:139] op_sel:[0,0,1] op_sel_hi:[1,0,0] neg_lo:[1,0,0] neg_hi:[1,0,0]
	v_pk_add_f32 v[138:139], v[160:161], v[182:183]
	v_pk_add_f32 v[160:161], v[160:161], v[182:183] neg_lo:[0,1] neg_hi:[0,1]
	v_pk_add_f32 v[182:183], v[176:177], v[168:169]
	v_pk_add_f32 v[168:169], v[176:177], v[168:169] neg_lo:[0,1] neg_hi:[0,1]
	v_pk_mul_f32 v[2:3], v[58:59], v[26:27] op_sel:[0,1] op_sel_hi:[1,0]
	v_pk_mul_f32 v[176:177], v[168:169], s[36:37]
	v_pk_fma_f32 v[20:21], v[52:53], v[26:27], v[2:3] op_sel_hi:[0,1,1]
	v_pk_fma_f32 v[168:169], v[168:169], s[78:79], v[176:177] op_sel:[0,0,1] op_sel_hi:[1,0,0]
	v_pk_add_f32 v[176:177], v[178:179], v[186:187]
	v_pk_add_f32 v[186:187], v[178:179], v[186:187] neg_lo:[0,1] neg_hi:[0,1]
	v_pk_mul_f32 v[2:3], v[58:59], v[20:21] op_sel:[0,1] op_sel_hi:[1,0]
	v_pk_add_f32 v[178:179], v[180:181], v[188:189]
	v_pk_add_f32 v[180:181], v[180:181], v[188:189] neg_lo:[0,1] neg_hi:[0,1]
	v_pk_fma_f32 v[10:11], v[52:53], v[20:21], v[2:3] op_sel_hi:[0,1,1]
	v_pk_mul_f32 v[188:189], v[180:181], s[36:37]
	v_pk_mul_f32 v[2:3], v[58:59], v[10:11] op_sel:[0,1] op_sel_hi:[1,0]
	v_pk_fma_f32 v[180:181], v[180:181], s[78:79], v[188:189] op_sel:[0,0,1] op_sel_hi:[1,0,0] neg_lo:[1,0,0] neg_hi:[1,0,0]
	v_pk_add_f32 v[188:189], v[128:129], v[184:185] op_sel:[0,1] op_sel_hi:[1,0] neg_hi:[0,1]
	v_pk_add_f32 v[128:129], v[128:129], v[184:185] op_sel:[0,1] op_sel_hi:[1,0] neg_lo:[0,1]
	v_pk_add_f32 v[184:185], v[162:163], v[170:171]
	v_pk_add_f32 v[162:163], v[162:163], v[170:171] neg_lo:[0,1] neg_hi:[0,1]
	v_pk_fma_f32 v[4:5], v[52:53], v[10:11], v[2:3] op_sel_hi:[0,1,1]
	v_pk_mul_f32 v[170:171], v[162:163], s[36:37]
	v_pk_mul_f32 v[8:9], v[54:55], v[4:5] op_sel:[0,1] op_sel_hi:[1,0]
	v_pk_fma_f32 v[162:163], v[162:163], s[78:79], v[170:171] op_sel:[0,0,1] op_sel_hi:[1,0,0]
	v_pk_add_f32 v[170:171], v[164:165], v[172:173]
	v_pk_add_f32 v[172:173], v[164:165], v[172:173] neg_lo:[0,1] neg_hi:[0,1]
	v_pk_mul_f32 v[14:15], v[34:35], v[4:5] op_sel:[0,1] op_sel_hi:[1,0]
	v_pk_add_f32 v[164:165], v[166:167], v[174:175]
	v_pk_add_f32 v[166:167], v[166:167], v[174:175] neg_lo:[0,1] neg_hi:[0,1]
	v_pk_mul_f32 v[32:33], v[54:55], v[10:11] op_sel:[0,1] op_sel_hi:[1,0]
	v_pk_mul_f32 v[174:175], v[166:167], s[36:37]
	v_pk_mul_f32 v[40:41], v[34:35], v[10:11] op_sel:[0,1] op_sel_hi:[1,0]
	v_pk_fma_f32 v[166:167], v[166:167], s[78:79], v[174:175] op_sel:[0,0,1] op_sel_hi:[1,0,0] neg_lo:[1,0,0] neg_hi:[1,0,0]
	v_pk_add_f32 v[174:175], v[190:191], v[194:195]
	v_pk_add_f32 v[190:191], v[190:191], v[194:195] neg_lo:[0,1] neg_hi:[0,1]
	v_pk_add_f32 v[194:195], v[192:193], v[148:149]
	v_pk_add_f32 v[192:193], v[192:193], v[148:149] neg_lo:[0,1] neg_hi:[0,1]
	v_pk_mul_f32 v[62:63], v[54:55], v[20:21] op_sel:[0,1] op_sel_hi:[1,0]
	v_pk_add_f32 v[148:149], v[152:153], v[156:157] op_sel:[0,1] op_sel_hi:[1,0] neg_hi:[0,1]
	v_pk_add_f32 v[152:153], v[152:153], v[156:157] op_sel:[0,1] op_sel_hi:[1,0] neg_lo:[0,1]
	v_pk_add_f32 v[156:157], v[140:141], v[150:151]
	v_pk_add_f32 v[150:151], v[140:141], v[150:151] neg_lo:[0,1] neg_hi:[0,1]
	v_pk_mul_f32 v[66:67], v[34:35], v[20:21] op_sel:[0,1] op_sel_hi:[1,0]
	v_pk_add_f32 v[140:141], v[158:159], v[142:143]
	v_pk_add_f32 v[142:143], v[158:159], v[142:143] neg_lo:[0,1] neg_hi:[0,1]
	v_pk_add_f32 v[158:159], v[154:155], v[132:133]
	v_pk_add_f32 v[154:155], v[154:155], v[132:133] neg_lo:[0,1] neg_hi:[0,1]
	v_pk_mul_f32 v[78:79], v[54:55], v[26:27] op_sel:[0,1] op_sel_hi:[1,0]
	v_pk_add_f32 v[132:133], v[144:145], v[136:137] op_sel:[0,1] op_sel_hi:[1,0] neg_hi:[0,1]
	v_pk_add_f32 v[136:137], v[144:145], v[136:137] op_sel:[0,1] op_sel_hi:[1,0] neg_lo:[0,1]
	v_pk_add_f32 v[144:145], v[134:135], v[130:131]
	v_pk_add_f32 v[134:135], v[134:135], v[130:131] neg_lo:[0,1] neg_hi:[0,1]
	v_pk_mul_f32 v[82:83], v[34:35], v[26:27] op_sel:[0,1] op_sel_hi:[1,0]
	v_pk_add_f32 v[130:131], v[138:139], v[176:177]
	v_pk_add_f32 v[138:139], v[138:139], v[176:177] neg_lo:[0,1] neg_hi:[0,1]
	v_pk_add_f32 v[176:177], v[182:183], v[178:179]
	v_pk_add_f32 v[182:183], v[182:183], v[178:179] neg_lo:[0,1] neg_hi:[0,1]
	v_pk_mul_f32 v[92:93], v[54:55], v[36:37] op_sel:[0,1] op_sel_hi:[1,0]
	v_pk_add_f32 v[178:179], v[160:161], v[186:187] op_sel:[0,1] op_sel_hi:[1,0] neg_hi:[0,1]
	v_pk_add_f32 v[160:161], v[160:161], v[186:187] op_sel:[0,1] op_sel_hi:[1,0] neg_lo:[0,1]
	v_pk_add_f32 v[186:187], v[168:169], v[180:181]
	v_pk_add_f32 v[180:181], v[168:169], v[180:181] neg_lo:[0,1] neg_hi:[0,1]
	v_pk_mul_f32 v[96:97], v[34:35], v[36:37] op_sel:[0,1] op_sel_hi:[1,0]
	v_pk_add_f32 v[168:169], v[188:189], v[170:171]
	v_pk_add_f32 v[170:171], v[188:189], v[170:171] neg_lo:[0,1] neg_hi:[0,1]
	v_pk_add_f32 v[188:189], v[184:185], v[164:165]
	v_pk_add_f32 v[184:185], v[184:185], v[164:165] neg_lo:[0,1] neg_hi:[0,1]
	v_pk_mul_f32 v[106:107], v[54:55], v[48:49] op_sel:[0,1] op_sel_hi:[1,0]
	v_pk_add_f32 v[164:165], v[128:129], v[172:173] op_sel:[0,1] op_sel_hi:[1,0] neg_hi:[0,1]
	v_pk_add_f32 v[128:129], v[128:129], v[172:173] op_sel:[0,1] op_sel_hi:[1,0] neg_lo:[0,1]
	v_pk_add_f32 v[172:173], v[162:163], v[166:167]
	v_pk_add_f32 v[166:167], v[162:163], v[166:167] neg_lo:[0,1] neg_hi:[0,1]
	v_pk_mul_f32 v[110:111], v[34:35], v[48:49] op_sel:[0,1] op_sel_hi:[1,0]
	v_pk_add_f32 v[162:163], v[174:175], v[194:195]
	v_pk_add_f32 v[174:175], v[174:175], v[194:195] neg_lo:[0,1] neg_hi:[0,1]
	v_pk_add_f32 v[194:195], v[190:191], v[192:193] op_sel:[0,1] op_sel_hi:[1,0] neg_hi:[0,1]
	v_pk_add_f32 v[190:191], v[190:191], v[192:193] op_sel:[0,1] op_sel_hi:[1,0] neg_lo:[0,1]
	v_pk_add_f32 v[192:193], v[148:149], v[156:157]
	v_pk_add_f32 v[148:149], v[148:149], v[156:157] neg_lo:[0,1] neg_hi:[0,1]
	v_pk_add_f32 v[156:157], v[152:153], v[150:151] op_sel:[0,1] op_sel_hi:[1,0] neg_hi:[0,1]
	v_pk_add_f32 v[150:151], v[152:153], v[150:151] op_sel:[0,1] op_sel_hi:[1,0] neg_lo:[0,1]
	v_pk_add_f32 v[152:153], v[140:141], v[158:159]
	v_pk_add_f32 v[140:141], v[140:141], v[158:159] neg_lo:[0,1] neg_hi:[0,1]
	v_pk_add_f32 v[158:159], v[142:143], v[154:155] op_sel:[0,1] op_sel_hi:[1,0] neg_hi:[0,1]
	v_pk_add_f32 v[142:143], v[142:143], v[154:155] op_sel:[0,1] op_sel_hi:[1,0] neg_lo:[0,1]
	v_pk_add_f32 v[154:155], v[132:133], v[144:145]
	v_pk_add_f32 v[132:133], v[132:133], v[144:145] neg_lo:[0,1] neg_hi:[0,1]
	v_pk_add_f32 v[144:145], v[136:137], v[134:135] op_sel:[0,1] op_sel_hi:[1,0] neg_hi:[0,1]
	v_pk_add_f32 v[134:135], v[136:137], v[134:135] op_sel:[0,1] op_sel_hi:[1,0] neg_lo:[0,1]
	v_pk_add_f32 v[136:137], v[130:131], v[176:177]
	v_pk_mul_f32 v[120:121], v[54:55], v[52:53] op_sel:[0,1] op_sel_hi:[1,0]
	v_pk_mul_f32 v[124:125], v[34:35], v[52:53] op_sel:[0,1] op_sel_hi:[1,0]
	v_pk_mul_f32 v[34:35], v[34:35], v[136:137] op_sel:[0,1] op_sel_hi:[1,0]
	v_xor_b32_e32 v72, 0x80000000, v47
	v_mov_b32_e32 v73, v47
	v_pk_fma_f32 v[8:9], v[44:45], v[4:5], v[8:9] op_sel_hi:[0,1,1]
	v_pk_fma_f32 v[14:15], v[30:31], v[4:5], v[14:15] op_sel_hi:[0,1,1]
	v_xor_b32_e32 v22, 0x80000000, v5
	v_pk_fma_f32 v[32:33], v[44:45], v[10:11], v[32:33] op_sel_hi:[0,1,1]
	v_pk_fma_f32 v[40:41], v[30:31], v[10:11], v[40:41] op_sel_hi:[0,1,1]
	v_pk_fma_f32 v[62:63], v[44:45], v[20:21], v[62:63] op_sel_hi:[0,1,1]
	v_pk_fma_f32 v[66:67], v[30:31], v[20:21], v[66:67] op_sel_hi:[0,1,1]
	v_pk_fma_f32 v[78:79], v[44:45], v[26:27], v[78:79] op_sel_hi:[0,1,1]
	v_pk_fma_f32 v[82:83], v[30:31], v[26:27], v[82:83] op_sel_hi:[0,1,1]
	v_pk_fma_f32 v[92:93], v[44:45], v[36:37], v[92:93] op_sel_hi:[0,1,1]
	v_pk_fma_f32 v[96:97], v[30:31], v[36:37], v[96:97] op_sel_hi:[0,1,1]
	v_pk_fma_f32 v[106:107], v[44:45], v[48:49], v[106:107] op_sel_hi:[0,1,1]
	v_pk_fma_f32 v[110:111], v[30:31], v[48:49], v[110:111] op_sel_hi:[0,1,1]
	v_pk_fma_f32 v[120:121], v[44:45], v[52:53], v[120:121] op_sel_hi:[0,1,1]
	v_pk_fma_f32 v[124:125], v[30:31], v[52:53], v[124:125] op_sel_hi:[0,1,1]
	v_mov_b32_e32 v23, v5
	v_pk_add_f32 v[130:131], v[130:131], v[176:177] neg_lo:[0,1] neg_hi:[0,1]
	v_pk_add_f32 v[176:177], v[138:139], v[182:183] op_sel:[0,1] op_sel_hi:[1,0] neg_hi:[0,1]
	v_pk_add_f32 v[138:139], v[138:139], v[182:183] op_sel:[0,1] op_sel_hi:[1,0] neg_lo:[0,1]
	v_pk_add_f32 v[182:183], v[178:179], v[186:187]
	v_pk_add_f32 v[178:179], v[178:179], v[186:187] neg_lo:[0,1] neg_hi:[0,1]
	v_pk_add_f32 v[186:187], v[160:161], v[180:181] op_sel:[0,1] op_sel_hi:[1,0] neg_hi:[0,1]
	v_pk_add_f32 v[160:161], v[160:161], v[180:181] op_sel:[0,1] op_sel_hi:[1,0] neg_lo:[0,1]
	v_pk_add_f32 v[180:181], v[168:169], v[188:189]
	v_pk_fma_f32 v[30:31], v[30:31], v[136:137], v[34:35] op_sel_hi:[0,1,1]
	v_pk_mul_f32 v[34:35], v[54:55], v[152:153] op_sel:[0,1] op_sel_hi:[1,0]
	v_pk_mul_f32 v[2:3], v[72:73], v[4:5] op_sel:[0,1] op_sel_hi:[1,0]
	v_xor_b32_e32 v12, 0x80000000, v9
	v_pk_mul_f32 v[24:25], v[72:73], v[10:11] op_sel:[0,1] op_sel_hi:[1,0]
	v_xor_b32_e32 v38, 0x80000000, v33
	v_xor_b32_e32 v50, 0x80000000, v11
	v_pk_mul_f32 v[56:57], v[72:73], v[20:21] op_sel:[0,1] op_sel_hi:[1,0]
	v_xor_b32_e32 v64, 0x80000000, v63
	v_xor_b32_e32 v70, 0x80000000, v21
	v_pk_mul_f32 v[74:75], v[72:73], v[26:27] op_sel:[0,1] op_sel_hi:[1,0]
	v_xor_b32_e32 v80, 0x80000000, v79
	v_xor_b32_e32 v86, 0x80000000, v27
	v_pk_mul_f32 v[88:89], v[72:73], v[36:37] op_sel:[0,1] op_sel_hi:[1,0]
	v_xor_b32_e32 v94, 0x80000000, v93
	v_xor_b32_e32 v100, 0x80000000, v37
	v_pk_mul_f32 v[102:103], v[72:73], v[48:49] op_sel:[0,1] op_sel_hi:[1,0]
	v_xor_b32_e32 v108, 0x80000000, v107
	v_xor_b32_e32 v114, 0x80000000, v49
	v_pk_mul_f32 v[116:117], v[52:53], v[72:73] op_sel:[1,0] op_sel_hi:[0,1]
	v_xor_b32_e32 v122, 0x80000000, v121
	v_mov_b32_e32 v123, v121
	v_mov_b32_e32 v115, v49
	v_mov_b32_e32 v109, v107
	v_mov_b32_e32 v101, v37
	v_mov_b32_e32 v95, v93
	v_mov_b32_e32 v87, v27
	v_mov_b32_e32 v81, v79
	v_mov_b32_e32 v71, v21
	v_mov_b32_e32 v65, v63
	v_mov_b32_e32 v51, v11
	v_mov_b32_e32 v39, v33
	v_mov_b32_e32 v13, v9
	v_pk_fma_f32 v[34:35], v[44:45], v[152:153], v[34:35] op_sel_hi:[0,1,1]
	v_pk_mul_f32 v[44:45], v[72:73], v[180:181] op_sel:[0,1] op_sel_hi:[1,0]
	v_pk_mul_f32 v[22:23], v[150:151], v[22:23] op_sel:[1,0] op_sel_hi:[0,1]
	v_pk_fma_f32 v[2:3], v[46:47], v[4:5], v[2:3] op_sel_hi:[0,1,1]
	v_pk_fma_f32 v[24:25], v[46:47], v[10:11], v[24:25] op_sel_hi:[0,1,1]
	v_pk_fma_f32 v[56:57], v[46:47], v[20:21], v[56:57] op_sel_hi:[0,1,1]
	v_pk_fma_f32 v[74:75], v[46:47], v[26:27], v[74:75] op_sel_hi:[0,1,1]
	v_xor_b32_e32 v84, 0x80000000, v83
	v_pk_fma_f32 v[88:89], v[46:47], v[36:37], v[88:89] op_sel_hi:[0,1,1]
	v_pk_fma_f32 v[102:103], v[46:47], v[48:49], v[102:103] op_sel_hi:[0,1,1]
	v_pk_fma_f32 v[116:117], v[52:53], v[46:47], v[116:117] op_sel_hi:[1,0,1]
	v_mov_b32_e32 v85, v83
	v_pk_fma_f32 v[44:45], v[46:47], v[180:181], v[44:45] op_sel_hi:[0,1,1]
	v_pk_mul_f32 v[46:47], v[58:59], v[192:193] op_sel:[0,1] op_sel_hi:[1,0]
	v_pk_mul_f32 v[54:55], v[122:123], v[154:155] op_sel:[0,1] op_sel_hi:[1,0]
	v_pk_mul_f32 v[72:73], v[114:115], v[194:195] op_sel:[0,1] op_sel_hi:[1,0]
	v_pk_mul_f32 v[108:109], v[108:109], v[158:159] op_sel:[0,1] op_sel_hi:[1,0]
	v_pk_mul_f32 v[100:101], v[100:101], v[156:157] op_sel:[0,1] op_sel_hi:[1,0]
	v_pk_mul_f32 v[94:95], v[94:95], v[144:145] op_sel:[0,1] op_sel_hi:[1,0]
	v_pk_mul_f32 v[86:87], v[174:175], v[86:87] op_sel:[1,0] op_sel_hi:[0,1]
	v_pk_mul_f32 v[80:81], v[140:141], v[80:81] op_sel:[1,0] op_sel_hi:[0,1]
	v_pk_mul_f32 v[70:71], v[148:149], v[70:71] op_sel:[1,0] op_sel_hi:[0,1]
	v_pk_mul_f32 v[64:65], v[132:133], v[64:65] op_sel:[1,0] op_sel_hi:[0,1]
	v_pk_mul_f32 v[50:51], v[190:191], v[50:51] op_sel:[1,0] op_sel_hi:[0,1]
	v_pk_mul_f32 v[38:39], v[142:143], v[38:39] op_sel:[1,0] op_sel_hi:[0,1]
	v_pk_fma_f32 v[4:5], v[150:151], v[4:5], v[22:23] op_sel_hi:[1,0,1]
	v_pk_mul_f32 v[12:13], v[134:135], v[12:13] op_sel:[1,0] op_sel_hi:[0,1]
	v_xor_b32_e32 v112, 0x80000000, v111
	v_mov_b32_e32 v113, v111
	v_pk_fma_f32 v[46:47], v[52:53], v[192:193], v[46:47] op_sel_hi:[0,1,1]
	v_pk_fma_f32 v[54:55], v[120:121], v[154:155], v[54:55] op_sel_hi:[0,1,1]
	v_pk_fma_f32 v[48:49], v[48:49], v[194:195], v[72:73] op_sel_hi:[0,1,1]
	v_pk_fma_f32 v[106:107], v[106:107], v[158:159], v[108:109] op_sel_hi:[0,1,1]
	v_pk_fma_f32 v[36:37], v[36:37], v[156:157], v[100:101] op_sel_hi:[0,1,1]
	v_pk_fma_f32 v[92:93], v[92:93], v[144:145], v[94:95] op_sel_hi:[0,1,1]
	v_pk_fma_f32 v[26:27], v[174:175], v[26:27], v[86:87] op_sel_hi:[1,0,1]
	v_pk_mul_f32 v[84:85], v[130:131], v[84:85] op_sel:[1,0] op_sel_hi:[0,1]
	v_pk_fma_f32 v[78:79], v[140:141], v[78:79], v[80:81] op_sel_hi:[1,0,1]
	v_pk_fma_f32 v[20:21], v[148:149], v[20:21], v[70:71] op_sel_hi:[1,0,1]
	v_pk_fma_f32 v[62:63], v[132:133], v[62:63], v[64:65] op_sel_hi:[1,0,1]
	v_pk_fma_f32 v[10:11], v[190:191], v[10:11], v[50:51] op_sel_hi:[1,0,1]
	v_pk_fma_f32 v[32:33], v[142:143], v[32:33], v[38:39] op_sel_hi:[1,0,1]
	v_pk_fma_f32 v[8:9], v[134:135], v[8:9], v[12:13] op_sel_hi:[1,0,1]
	ds_write_b64 v18, v[162:163]
	ds_write_b64 v18, v[26:27] offset:4224
	ds_write_b64 v18, v[48:49] offset:8448
	ds_write_b64 v18, v[10:11] offset:12672
	ds_write_b64 v18, v[46:47] offset:16896
	ds_write_b64 v18, v[20:21] offset:21120
	ds_write_b64 v18, v[36:37] offset:25344
	ds_write_b64 v18, v[4:5] offset:29568
	ds_write_b64 v18, v[34:35] offset:33792
	ds_write_b64 v18, v[78:79] offset:38016
	ds_write_b64 v18, v[106:107] offset:42240
	ds_write_b64 v18, v[32:33] offset:46464
	ds_write_b64 v18, v[54:55] offset:50688
	ds_write_b64 v18, v[62:63] offset:54912
	ds_write_b64 v18, v[92:93] offset:59136
	ds_write_b64 v18, v[8:9] offset:63360
	v_add_u32_e32 v4, 0x10800, v18
	v_xor_b32_e32 v42, 0x80000000, v41
	v_mov_b32_e32 v43, v41
	v_pk_mul_f32 v[72:73], v[112:113], v[176:177] op_sel:[0,1] op_sel_hi:[1,0]
	v_pk_fma_f32 v[82:83], v[130:131], v[82:83], v[84:85] op_sel_hi:[1,0,1]
	ds_write_b64 v4, v[30:31]
	v_add_u32_e32 v4, 0x11880, v18
	v_xor_b32_e32 v126, 0x80000000, v125
	v_mov_b32_e32 v127, v125
	v_pk_fma_f32 v[72:73], v[110:111], v[176:177], v[72:73] op_sel_hi:[0,1,1]
	v_pk_mul_f32 v[42:43], v[138:139], v[42:43] op_sel:[1,0] op_sel_hi:[0,1]
	ds_write_b64 v4, v[82:83]
	v_add_u32_e32 v4, 0x12900, v18
	v_xor_b32_e32 v68, 0x80000000, v67
	v_mov_b32_e32 v69, v67
	v_pk_mul_f32 v[52:53], v[126:127], v[182:183] op_sel:[0,1] op_sel_hi:[1,0]
	v_pk_fma_f32 v[40:41], v[138:139], v[40:41], v[42:43] op_sel_hi:[1,0,1]
	ds_write_b64 v4, v[72:73]
	v_add_u32_e32 v4, 0x13980, v18
	v_xor_b32_e32 v98, 0x80000000, v97
	v_mov_b32_e32 v99, v97
	v_pk_fma_f32 v[52:53], v[124:125], v[182:183], v[52:53] op_sel_hi:[0,1,1]
	v_pk_mul_f32 v[68:69], v[178:179], v[68:69] op_sel:[1,0] op_sel_hi:[0,1]
	ds_write_b64 v4, v[40:41]
	v_add_u32_e32 v4, 0x14a00, v18
	v_xor_b32_e32 v16, 0x80000000, v15
	v_mov_b32_e32 v17, v15
	v_pk_mul_f32 v[98:99], v[98:99], v[186:187] op_sel:[0,1] op_sel_hi:[1,0]
	v_pk_fma_f32 v[66:67], v[178:179], v[66:67], v[68:69] op_sel_hi:[1,0,1]
	ds_write_b64 v4, v[52:53]
	v_add_u32_e32 v4, 0x15a80, v18
	v_pk_fma_f32 v[96:97], v[96:97], v[186:187], v[98:99] op_sel_hi:[0,1,1]
	v_pk_mul_f32 v[16:17], v[160:161], v[16:17] op_sel:[1,0] op_sel_hi:[0,1]
	ds_write_b64 v4, v[66:67]
	v_add_u32_e32 v4, 0x16b00, v18
	v_xor_b32_e32 v76, 0x80000000, v75
	v_mov_b32_e32 v77, v75
	v_pk_add_f32 v[168:169], v[168:169], v[188:189] neg_lo:[0,1] neg_hi:[0,1]
	v_pk_fma_f32 v[14:15], v[160:161], v[14:15], v[16:17] op_sel_hi:[1,0,1]
	ds_write_b64 v4, v[96:97]
	v_add_u32_e32 v4, 0x17b80, v18
	v_xor_b32_e32 v104, 0x80000000, v103
	v_mov_b32_e32 v105, v103
	v_pk_add_f32 v[188:189], v[170:171], v[184:185] op_sel:[0,1] op_sel_hi:[1,0] neg_hi:[0,1]
	v_pk_mul_f32 v[76:77], v[168:169], v[76:77] op_sel:[1,0] op_sel_hi:[0,1]
	ds_write_b64 v4, v[14:15]
	v_add_u32_e32 v4, 0x18c00, v18
	v_xor_b32_e32 v28, 0x80000000, v25
	v_mov_b32_e32 v29, v25
	v_pk_add_f32 v[170:171], v[170:171], v[184:185] op_sel:[0,1] op_sel_hi:[1,0] neg_lo:[0,1]
	v_pk_mul_f32 v[104:105], v[104:105], v[188:189] op_sel:[0,1] op_sel_hi:[1,0]
	v_pk_fma_f32 v[74:75], v[168:169], v[74:75], v[76:77] op_sel_hi:[1,0,1]
	ds_write_b64 v4, v[44:45]
	v_add_u32_e32 v4, 0x19c80, v18
	v_xor_b32_e32 v118, 0x80000000, v117
	v_mov_b32_e32 v119, v117
	v_pk_add_f32 v[184:185], v[164:165], v[172:173]
	v_pk_fma_f32 v[102:103], v[102:103], v[188:189], v[104:105] op_sel_hi:[0,1,1]
	v_pk_mul_f32 v[28:29], v[170:171], v[28:29] op_sel:[1,0] op_sel_hi:[0,1]
	ds_write_b64 v4, v[74:75]
	v_add_u32_e32 v4, 0x1ad00, v18
	v_xor_b32_e32 v60, 0x80000000, v57
	v_mov_b32_e32 v61, v57
	v_pk_add_f32 v[164:165], v[164:165], v[172:173] neg_lo:[0,1] neg_hi:[0,1]
	v_pk_mul_f32 v[58:59], v[118:119], v[184:185] op_sel:[0,1] op_sel_hi:[1,0]
	v_pk_fma_f32 v[24:25], v[170:171], v[24:25], v[28:29] op_sel_hi:[1,0,1]
	ds_write_b64 v4, v[102:103]
	v_add_u32_e32 v4, 0x1bd80, v18
	v_xor_b32_e32 v90, 0x80000000, v89
	v_mov_b32_e32 v91, v89
	v_pk_add_f32 v[172:173], v[128:129], v[166:167] op_sel:[0,1] op_sel_hi:[1,0] neg_hi:[0,1]
	v_pk_fma_f32 v[58:59], v[116:117], v[184:185], v[58:59] op_sel_hi:[0,1,1]
	v_pk_mul_f32 v[60:61], v[164:165], v[60:61] op_sel:[1,0] op_sel_hi:[0,1]
	ds_write_b64 v4, v[24:25]
	v_add_u32_e32 v4, 0x1ce00, v18
	v_xor_b32_e32 v6, 0x80000000, v3
	v_mov_b32_e32 v7, v3
	v_pk_add_f32 v[128:129], v[128:129], v[166:167] op_sel:[0,1] op_sel_hi:[1,0] neg_lo:[0,1]
	v_pk_mul_f32 v[90:91], v[90:91], v[172:173] op_sel:[0,1] op_sel_hi:[1,0]
	v_pk_fma_f32 v[56:57], v[164:165], v[56:57], v[60:61] op_sel_hi:[1,0,1]
	ds_write_b64 v4, v[58:59]
	v_add_u32_e32 v4, 0x1de80, v18
	v_pk_fma_f32 v[88:89], v[88:89], v[172:173], v[90:91] op_sel_hi:[0,1,1]
	v_pk_mul_f32 v[6:7], v[128:129], v[6:7] op_sel:[1,0] op_sel_hi:[0,1]
	ds_write_b64 v4, v[56:57]
	v_add_u32_e32 v4, 0x1ef00, v18
	v_pk_fma_f32 v[2:3], v[128:129], v[2:3], v[6:7] op_sel_hi:[1,0,1]
	ds_write_b64 v4, v[88:89]
	v_add_u32_e32 v4, 0x1ff80, v18
	ds_write_b64 v4, v[2:3]
	v_mov_b32_e32 v2, v210
	s_waitcnt lgkmcnt(0)
	s_barrier
	s_ashr_i32 s77, s76, 31
	v_and_b32_e32 v3, 15, v2
	v_lshlrev_b32_e32 v2, 5, v2
	v_and_b32_e32 v4, 0xfffffe00, v2
	v_lshl_add_u32 v5, v4, 3, 0
	v_lshlrev_b32_e32 v6, 3, v3
	v_ashrrev_i32_e32 v7, 2, v4
	v_add3_u32 v18, v5, v6, v7
	v_add_u32_e32 v196, 0x800, v18
	ds_read2_b64 v[128:131], v18 offset1:16
	ds_read2_b64 v[132:135], v18 offset0:33 offset1:49
	ds_read2_b64 v[136:139], v18 offset0:66 offset1:82
	ds_read2_b64 v[140:143], v18 offset0:99 offset1:115
	ds_read2_b64 v[148:151], v18 offset0:132 offset1:148
	ds_read2_b64 v[152:155], v18 offset0:165 offset1:181
	ds_read2_b64 v[156:159], v18 offset0:198 offset1:214
	ds_read2_b64 v[160:163], v18 offset0:231 offset1:247
	ds_read2_b64 v[164:167], v196 offset0:8 offset1:24
	ds_read2_b64 v[168:171], v196 offset0:41 offset1:57
	ds_read2_b64 v[172:175], v196 offset0:74 offset1:90
	ds_read2_b64 v[176:179], v196 offset0:107 offset1:123
	ds_read2_b64 v[180:183], v196 offset0:140 offset1:156
	ds_read2_b64 v[184:187], v196 offset0:173 offset1:189
	ds_read2_b64 v[188:191], v196 offset0:206 offset1:222
	ds_read2_b64 v[192:195], v196 offset0:239 offset1:255
	s_waitcnt lgkmcnt(7)
	v_pk_add_f32 v[144:145], v[128:129], v[164:165]
	v_pk_add_f32 v[128:129], v[128:129], v[164:165] neg_lo:[0,1] neg_hi:[0,1]
	v_pk_add_f32 v[164:165], v[130:131], v[166:167]
	v_pk_add_f32 v[130:131], v[130:131], v[166:167] neg_lo:[0,1] neg_hi:[0,1]
	v_cvt_f32_ubyte0_e32 v2, v3
	v_pk_mul_f32 v[166:167], v[130:131], s[10:11]
	v_mul_f32_e32 v3, 0x3b000000, v2
	v_pk_fma_f32 v[130:131], v[130:131], s[8:9], v[166:167] op_sel:[0,0,1] op_sel_hi:[1,0,0]
	s_waitcnt lgkmcnt(6)
	v_pk_add_f32 v[166:167], v[132:133], v[168:169]
	v_pk_add_f32 v[132:133], v[132:133], v[168:169] neg_lo:[0,1] neg_hi:[0,1]
	v_sin_f32_e32 v2, v3
	v_pk_mul_f32 v[168:169], v[132:133], s[18:19]
	v_cos_f32_e32 v4, v3
	v_pk_fma_f32 v[132:133], v[132:133], s[16:17], v[168:169] op_sel:[0,0,1] op_sel_hi:[1,0,0]
	v_pk_add_f32 v[168:169], v[134:135], v[170:171]
	v_pk_add_f32 v[134:135], v[134:135], v[170:171] neg_lo:[0,1] neg_hi:[0,1]
	v_xor_b32_e32 v5, 0x80000000, v2
	v_pk_mul_f32 v[170:171], v[134:135], s[26:27]
	v_mov_b32_e32 v3, v5
	v_pk_fma_f32 v[134:135], v[134:135], s[24:25], v[170:171] op_sel:[0,0,1] op_sel_hi:[1,0,0]
	s_waitcnt lgkmcnt(5)
	v_pk_add_f32 v[170:171], v[136:137], v[172:173]
	v_pk_add_f32 v[136:137], v[136:137], v[172:173] neg_lo:[0,1] neg_hi:[0,1]
	v_pk_mul_f32 v[6:7], v[4:5], v[2:3] op_sel:[1,0] op_sel_hi:[0,1]
	v_pk_mul_f32 v[172:173], v[136:137], s[36:37]
	v_pk_fma_f32 v[6:7], v[4:5], v[4:5], v[6:7] op_sel_hi:[1,0,1]
	v_pk_fma_f32 v[136:137], v[136:137], s[78:79], v[172:173] op_sel:[0,0,1] op_sel_hi:[1,0,0]
	v_pk_add_f32 v[172:173], v[138:139], v[174:175]
	v_pk_add_f32 v[138:139], v[138:139], v[174:175] neg_lo:[0,1] neg_hi:[0,1]
	v_xor_b32_e32 v12, 0x80000000, v7
	v_pk_mul_f32 v[174:175], v[138:139], s[38:39]
	v_mov_b32_e32 v13, v7
	v_pk_fma_f32 v[138:139], v[138:139], s[0:1], v[174:175] op_sel:[0,0,1] op_sel_hi:[1,0,0]
	s_waitcnt lgkmcnt(4)
	v_pk_add_f32 v[174:175], v[140:141], v[176:177]
	v_pk_add_f32 v[140:141], v[140:141], v[176:177] neg_lo:[0,1] neg_hi:[0,1]
	v_pk_mul_f32 v[10:11], v[6:7], v[12:13] op_sel:[1,0] op_sel_hi:[0,1]
	v_pk_mul_f32 v[176:177], v[140:141], s[40:41]
	v_pk_fma_f32 v[10:11], v[6:7], v[6:7], v[10:11] op_sel_hi:[1,0,1]
	v_pk_fma_f32 v[140:141], v[140:141], s[80:81], v[176:177] op_sel:[0,0,1] op_sel_hi:[1,0,0]
	v_pk_add_f32 v[176:177], v[142:143], v[178:179]
	v_pk_add_f32 v[142:143], v[142:143], v[178:179] neg_lo:[0,1] neg_hi:[0,1]
	v_xor_b32_e32 v14, 0x80000000, v11
	v_pk_mul_f32 v[178:179], v[142:143], s[42:43]
	v_mov_b32_e32 v15, v11
	v_pk_fma_f32 v[142:143], v[142:143], s[74:75], v[178:179] op_sel:[0,0,1] op_sel_hi:[1,0,0]
	s_waitcnt lgkmcnt(3)
	v_pk_add_f32 v[178:179], v[148:149], v[180:181]
	v_pk_add_f32 v[180:181], v[148:149], v[180:181] neg_lo:[0,1] neg_hi:[0,1]
	v_pk_mul_f32 v[28:29], v[10:11], v[14:15] op_sel:[1,0] op_sel_hi:[0,1]
	v_pk_add_f32 v[148:149], v[150:151], v[182:183]
	v_pk_add_f32 v[150:151], v[150:151], v[182:183] neg_lo:[0,1] neg_hi:[0,1]
	v_pk_fma_f32 v[28:29], v[10:11], v[10:11], v[28:29] op_sel_hi:[1,0,1]
	v_pk_mul_f32 v[182:183], v[150:151], s[42:43]
	v_pk_mul_f32 v[44:45], v[14:15], v[28:29] op_sel:[0,1] op_sel_hi:[1,0]
	v_pk_fma_f32 v[150:151], v[150:151], s[74:75], v[182:183] op_sel:[0,0,1] op_sel_hi:[1,0,0] neg_lo:[1,0,0] neg_hi:[1,0,0]
	s_waitcnt lgkmcnt(2)
	v_pk_add_f32 v[182:183], v[152:153], v[184:185]
	v_pk_add_f32 v[152:153], v[152:153], v[184:185] neg_lo:[0,1] neg_hi:[0,1]
	v_pk_fma_f32 v[44:45], v[10:11], v[28:29], v[44:45] op_sel_hi:[0,1,1]
	v_pk_mul_f32 v[184:185], v[152:153], s[40:41]
	v_pk_mul_f32 v[60:61], v[14:15], v[44:45] op_sel:[0,1] op_sel_hi:[1,0]
	v_pk_fma_f32 v[152:153], v[152:153], s[80:81], v[184:185] op_sel:[0,0,1] op_sel_hi:[1,0,0] neg_lo:[1,0,0] neg_hi:[1,0,0]
	v_pk_add_f32 v[184:185], v[154:155], v[186:187]
	v_pk_add_f32 v[154:155], v[154:155], v[186:187] neg_lo:[0,1] neg_hi:[0,1]
	v_pk_fma_f32 v[60:61], v[10:11], v[44:45], v[60:61] op_sel_hi:[0,1,1]
	v_pk_mul_f32 v[186:187], v[154:155], s[38:39]
	v_pk_mul_f32 v[76:77], v[14:15], v[60:61] op_sel:[0,1] op_sel_hi:[1,0]
	v_pk_fma_f32 v[154:155], v[154:155], s[0:1], v[186:187] op_sel:[0,0,1] op_sel_hi:[1,0,0] neg_lo:[1,0,0] neg_hi:[1,0,0]
	s_waitcnt lgkmcnt(1)
	v_pk_add_f32 v[186:187], v[156:157], v[188:189]
	v_pk_add_f32 v[156:157], v[156:157], v[188:189] neg_lo:[0,1] neg_hi:[0,1]
	v_pk_fma_f32 v[76:77], v[10:11], v[60:61], v[76:77] op_sel_hi:[0,1,1]
	v_pk_mul_f32 v[188:189], v[156:157], s[36:37]
	v_pk_mul_f32 v[92:93], v[14:15], v[76:77] op_sel:[0,1] op_sel_hi:[1,0]
	v_pk_fma_f32 v[156:157], v[156:157], s[78:79], v[188:189] op_sel:[0,0,1] op_sel_hi:[1,0,0] neg_lo:[1,0,0] neg_hi:[1,0,0]
	v_pk_add_f32 v[188:189], v[158:159], v[190:191]
	v_pk_add_f32 v[158:159], v[158:159], v[190:191] neg_lo:[0,1] neg_hi:[0,1]
	v_pk_fma_f32 v[92:93], v[10:11], v[76:77], v[92:93] op_sel_hi:[0,1,1]
	v_pk_mul_f32 v[190:191], v[158:159], s[26:27]
	v_pk_mul_f32 v[108:109], v[14:15], v[92:93] op_sel:[0,1] op_sel_hi:[1,0]
	v_pk_fma_f32 v[158:159], v[158:159], s[24:25], v[190:191] op_sel:[0,0,1] op_sel_hi:[1,0,0] neg_lo:[1,0,0] neg_hi:[1,0,0]
	s_waitcnt lgkmcnt(0)
	v_pk_add_f32 v[190:191], v[160:161], v[192:193]
	v_pk_add_f32 v[160:161], v[160:161], v[192:193] neg_lo:[0,1] neg_hi:[0,1]
	v_pk_mul_f32 v[8:9], v[2:3], v[6:7] op_sel:[0,1] op_sel_hi:[1,0]
	v_pk_mul_f32 v[192:193], v[160:161], s[18:19]
	v_pk_fma_f32 v[108:109], v[10:11], v[92:93], v[108:109] op_sel_hi:[0,1,1]
	v_pk_fma_f32 v[160:161], v[160:161], s[16:17], v[192:193] op_sel:[0,0,1] op_sel_hi:[1,0,0] neg_lo:[1,0,0] neg_hi:[1,0,0]
	v_pk_add_f32 v[192:193], v[162:163], v[194:195]
	v_pk_add_f32 v[162:163], v[162:163], v[194:195] neg_lo:[0,1] neg_hi:[0,1]
	v_pk_fma_f32 v[8:9], v[4:5], v[6:7], v[8:9] op_sel_hi:[0,1,1]
	v_pk_mul_f32 v[194:195], v[162:163], s[10:11]
	v_pk_mul_f32 v[16:17], v[2:3], v[10:11] op_sel:[0,1] op_sel_hi:[1,0]
	v_pk_fma_f32 v[162:163], v[162:163], s[8:9], v[194:195] op_sel:[0,0,1] op_sel_hi:[1,0,0] neg_lo:[1,0,0] neg_hi:[1,0,0]
	v_pk_add_f32 v[194:195], v[144:145], v[178:179]
	v_pk_add_f32 v[144:145], v[144:145], v[178:179] neg_lo:[0,1] neg_hi:[0,1]
	v_pk_add_f32 v[178:179], v[164:165], v[148:149]
	v_pk_add_f32 v[148:149], v[164:165], v[148:149] neg_lo:[0,1] neg_hi:[0,1]
	v_pk_mul_f32 v[32:33], v[2:3], v[28:29] op_sel:[0,1] op_sel_hi:[1,0]
	v_pk_mul_f32 v[164:165], v[148:149], s[18:19]
	v_pk_mul_f32 v[48:49], v[2:3], v[44:45] op_sel:[0,1] op_sel_hi:[1,0]
	v_pk_fma_f32 v[148:149], v[148:149], s[16:17], v[164:165] op_sel:[0,0,1] op_sel_hi:[1,0,0]
	v_pk_add_f32 v[164:165], v[166:167], v[182:183]
	v_pk_add_f32 v[166:167], v[166:167], v[182:183] neg_lo:[0,1] neg_hi:[0,1]
	v_pk_mul_f32 v[64:65], v[2:3], v[60:61] op_sel:[0,1] op_sel_hi:[1,0]
	v_pk_mul_f32 v[182:183], v[166:167], s[36:37]
	v_pk_mul_f32 v[80:81], v[2:3], v[76:77] op_sel:[0,1] op_sel_hi:[1,0]
	v_pk_fma_f32 v[166:167], v[166:167], s[78:79], v[182:183] op_sel:[0,0,1] op_sel_hi:[1,0,0]
	v_pk_add_f32 v[182:183], v[168:169], v[184:185]
	v_pk_add_f32 v[168:169], v[168:169], v[184:185] neg_lo:[0,1] neg_hi:[0,1]
	v_pk_mul_f32 v[96:97], v[2:3], v[92:93] op_sel:[0,1] op_sel_hi:[1,0]
	v_pk_mul_f32 v[184:185], v[168:169], s[40:41]
	v_pk_mul_f32 v[112:113], v[2:3], v[108:109] op_sel:[0,1] op_sel_hi:[1,0]
	v_pk_fma_f32 v[168:169], v[168:169], s[80:81], v[184:185] op_sel:[0,0,1] op_sel_hi:[1,0,0]
	v_pk_add_f32 v[184:185], v[170:171], v[186:187]
	v_pk_add_f32 v[186:187], v[170:171], v[186:187] neg_lo:[0,1] neg_hi:[0,1]
	v_xor_b32_e32 v22, 0x80000000, v9
	v_pk_add_f32 v[170:171], v[172:173], v[188:189]
	v_pk_add_f32 v[172:173], v[172:173], v[188:189] neg_lo:[0,1] neg_hi:[0,1]
	v_mov_b32_e32 v23, v9
	v_pk_mul_f32 v[188:189], v[172:173], s[40:41]
	v_pk_fma_f32 v[16:17], v[4:5], v[10:11], v[16:17] op_sel_hi:[0,1,1]
	v_pk_fma_f32 v[172:173], v[172:173], s[80:81], v[188:189] op_sel:[0,0,1] op_sel_hi:[1,0,0] neg_lo:[1,0,0] neg_hi:[1,0,0]
	v_pk_add_f32 v[188:189], v[174:175], v[190:191]
	v_pk_add_f32 v[174:175], v[174:175], v[190:191] neg_lo:[0,1] neg_hi:[0,1]
	v_pk_mul_f32 v[20:21], v[12:13], v[10:11] op_sel:[0,1] op_sel_hi:[1,0]
	v_pk_mul_f32 v[190:191], v[174:175], s[36:37]
	v_pk_fma_f32 v[32:33], v[4:5], v[28:29], v[32:33] op_sel_hi:[0,1,1]
	v_pk_fma_f32 v[174:175], v[174:175], s[78:79], v[190:191] op_sel:[0,0,1] op_sel_hi:[1,0,0] neg_lo:[1,0,0] neg_hi:[1,0,0]
	v_pk_add_f32 v[190:191], v[176:177], v[192:193]
	v_pk_add_f32 v[176:177], v[176:177], v[192:193] neg_lo:[0,1] neg_hi:[0,1]
	v_pk_mul_f32 v[36:37], v[12:13], v[28:29] op_sel:[0,1] op_sel_hi:[1,0]
	v_pk_mul_f32 v[192:193], v[176:177], s[18:19]
	v_pk_fma_f32 v[48:49], v[4:5], v[44:45], v[48:49] op_sel_hi:[0,1,1]
	v_pk_fma_f32 v[176:177], v[176:177], s[16:17], v[192:193] op_sel:[0,0,1] op_sel_hi:[1,0,0] neg_lo:[1,0,0] neg_hi:[1,0,0]
	v_pk_add_f32 v[192:193], v[128:129], v[180:181] op_sel:[0,1] op_sel_hi:[1,0] neg_hi:[0,1]
	v_pk_add_f32 v[128:129], v[128:129], v[180:181] op_sel:[0,1] op_sel_hi:[1,0] neg_lo:[0,1]
	v_pk_add_f32 v[180:181], v[130:131], v[150:151]
	v_pk_add_f32 v[130:131], v[130:131], v[150:151] neg_lo:[0,1] neg_hi:[0,1]
	v_pk_mul_f32 v[52:53], v[12:13], v[44:45] op_sel:[0,1] op_sel_hi:[1,0]
	v_pk_mul_f32 v[150:151], v[130:131], s[18:19]
	v_pk_fma_f32 v[64:65], v[4:5], v[60:61], v[64:65] op_sel_hi:[0,1,1]
	v_pk_fma_f32 v[130:131], v[130:131], s[16:17], v[150:151] op_sel:[0,0,1] op_sel_hi:[1,0,0]
	v_pk_add_f32 v[150:151], v[132:133], v[152:153]
	v_pk_add_f32 v[132:133], v[132:133], v[152:153] neg_lo:[0,1] neg_hi:[0,1]
	v_pk_mul_f32 v[68:69], v[12:13], v[60:61] op_sel:[0,1] op_sel_hi:[1,0]
	v_pk_mul_f32 v[152:153], v[132:133], s[36:37]
	v_pk_fma_f32 v[80:81], v[4:5], v[76:77], v[80:81] op_sel_hi:[0,1,1]
	v_pk_fma_f32 v[132:133], v[132:133], s[78:79], v[152:153] op_sel:[0,0,1] op_sel_hi:[1,0,0]
	v_pk_add_f32 v[152:153], v[134:135], v[154:155]
	v_pk_add_f32 v[134:135], v[134:135], v[154:155] neg_lo:[0,1] neg_hi:[0,1]
	v_pk_mul_f32 v[84:85], v[12:13], v[76:77] op_sel:[0,1] op_sel_hi:[1,0]
	v_pk_mul_f32 v[154:155], v[134:135], s[40:41]
	v_pk_fma_f32 v[96:97], v[4:5], v[92:93], v[96:97] op_sel_hi:[0,1,1]
	v_pk_fma_f32 v[134:135], v[134:135], s[80:81], v[154:155] op_sel:[0,0,1] op_sel_hi:[1,0,0]
	v_pk_add_f32 v[154:155], v[136:137], v[156:157]
	v_pk_add_f32 v[156:157], v[136:137], v[156:157] neg_lo:[0,1] neg_hi:[0,1]
	v_pk_mul_f32 v[100:101], v[12:13], v[92:93] op_sel:[0,1] op_sel_hi:[1,0]
	v_pk_add_f32 v[136:137], v[138:139], v[158:159]
	v_pk_add_f32 v[138:139], v[138:139], v[158:159] neg_lo:[0,1] neg_hi:[0,1]
	v_pk_fma_f32 v[112:113], v[4:5], v[108:109], v[112:113] op_sel_hi:[0,1,1]
	v_pk_mul_f32 v[158:159], v[138:139], s[40:41]
	v_pk_mul_f32 v[116:117], v[12:13], v[108:109] op_sel:[0,1] op_sel_hi:[1,0]
	v_pk_fma_f32 v[138:139], v[138:139], s[80:81], v[158:159] op_sel:[0,0,1] op_sel_hi:[1,0,0] neg_lo:[1,0,0] neg_hi:[1,0,0]
	v_pk_add_f32 v[158:159], v[140:141], v[160:161]
	v_pk_add_f32 v[140:141], v[140:141], v[160:161] neg_lo:[0,1] neg_hi:[0,1]
	v_pk_fma_f32 v[20:21], v[6:7], v[10:11], v[20:21] op_sel_hi:[0,1,1]
	v_pk_mul_f32 v[160:161], v[140:141], s[36:37]
	v_pk_mul_f32 v[24:25], v[10:11], v[22:23] op_sel:[1,0] op_sel_hi:[0,1]
	v_pk_fma_f32 v[140:141], v[140:141], s[78:79], v[160:161] op_sel:[0,0,1] op_sel_hi:[1,0,0] neg_lo:[1,0,0] neg_hi:[1,0,0]
	v_pk_add_f32 v[160:161], v[142:143], v[162:163]
	v_pk_add_f32 v[142:143], v[142:143], v[162:163] neg_lo:[0,1] neg_hi:[0,1]
	v_pk_fma_f32 v[36:37], v[6:7], v[28:29], v[36:37] op_sel_hi:[0,1,1]
	v_pk_mul_f32 v[162:163], v[142:143], s[18:19]
	v_pk_mul_f32 v[40:41], v[22:23], v[28:29] op_sel:[0,1] op_sel_hi:[1,0]
	v_pk_fma_f32 v[142:143], v[142:143], s[16:17], v[162:163] op_sel:[0,0,1] op_sel_hi:[1,0,0] neg_lo:[1,0,0] neg_hi:[1,0,0]
	v_pk_add_f32 v[162:163], v[194:195], v[184:185]
	v_pk_add_f32 v[184:185], v[194:195], v[184:185] neg_lo:[0,1] neg_hi:[0,1]
	v_pk_add_f32 v[194:195], v[178:179], v[170:171]
	v_pk_add_f32 v[170:171], v[178:179], v[170:171] neg_lo:[0,1] neg_hi:[0,1]
	v_pk_fma_f32 v[52:53], v[6:7], v[44:45], v[52:53] op_sel_hi:[0,1,1]
	v_pk_mul_f32 v[178:179], v[170:171], s[36:37]
	v_pk_mul_f32 v[56:57], v[22:23], v[44:45] op_sel:[0,1] op_sel_hi:[1,0]
	v_pk_fma_f32 v[170:171], v[170:171], s[78:79], v[178:179] op_sel:[0,0,1] op_sel_hi:[1,0,0]
	v_pk_add_f32 v[178:179], v[164:165], v[188:189]
	v_pk_add_f32 v[188:189], v[164:165], v[188:189] neg_lo:[0,1] neg_hi:[0,1]
	v_pk_fma_f32 v[68:69], v[6:7], v[60:61], v[68:69] op_sel_hi:[0,1,1]
	v_pk_add_f32 v[164:165], v[182:183], v[190:191]
	v_pk_add_f32 v[182:183], v[182:183], v[190:191] neg_lo:[0,1] neg_hi:[0,1]
	v_pk_mul_f32 v[72:73], v[22:23], v[60:61] op_sel:[0,1] op_sel_hi:[1,0]
	v_pk_mul_f32 v[190:191], v[182:183], s[36:37]
	v_pk_fma_f32 v[84:85], v[6:7], v[76:77], v[84:85] op_sel_hi:[0,1,1]
	v_pk_fma_f32 v[182:183], v[182:183], s[78:79], v[190:191] op_sel:[0,0,1] op_sel_hi:[1,0,0] neg_lo:[1,0,0] neg_hi:[1,0,0]
	v_pk_add_f32 v[190:191], v[144:145], v[186:187] op_sel:[0,1] op_sel_hi:[1,0] neg_hi:[0,1]
	v_pk_add_f32 v[144:145], v[144:145], v[186:187] op_sel:[0,1] op_sel_hi:[1,0] neg_lo:[0,1]
	v_pk_add_f32 v[186:187], v[148:149], v[172:173]
	v_pk_add_f32 v[148:149], v[148:149], v[172:173] neg_lo:[0,1] neg_hi:[0,1]
	v_pk_mul_f32 v[88:89], v[22:23], v[76:77] op_sel:[0,1] op_sel_hi:[1,0]
	v_pk_mul_f32 v[172:173], v[148:149], s[36:37]
	v_pk_fma_f32 v[100:101], v[6:7], v[92:93], v[100:101] op_sel_hi:[0,1,1]
	v_pk_fma_f32 v[148:149], v[148:149], s[78:79], v[172:173] op_sel:[0,0,1] op_sel_hi:[1,0,0]
	v_pk_add_f32 v[172:173], v[166:167], v[174:175]
	v_pk_add_f32 v[174:175], v[166:167], v[174:175] neg_lo:[0,1] neg_hi:[0,1]
	v_pk_mul_f32 v[104:105], v[22:23], v[92:93] op_sel:[0,1] op_sel_hi:[1,0]
	v_pk_add_f32 v[166:167], v[168:169], v[176:177]
	v_pk_add_f32 v[168:169], v[168:169], v[176:177] neg_lo:[0,1] neg_hi:[0,1]
	v_pk_fma_f32 v[116:117], v[6:7], v[108:109], v[116:117] op_sel_hi:[0,1,1]
	v_pk_mul_f32 v[176:177], v[168:169], s[36:37]
	v_pk_mul_f32 v[120:121], v[22:23], v[108:109] op_sel:[0,1] op_sel_hi:[1,0]
	v_pk_fma_f32 v[168:169], v[168:169], s[78:79], v[176:177] op_sel:[0,0,1] op_sel_hi:[1,0,0] neg_lo:[1,0,0] neg_hi:[1,0,0]
	v_pk_add_f32 v[176:177], v[192:193], v[154:155]
	v_pk_add_f32 v[154:155], v[192:193], v[154:155] neg_lo:[0,1] neg_hi:[0,1]
	v_pk_add_f32 v[192:193], v[180:181], v[136:137]
	v_pk_add_f32 v[136:137], v[180:181], v[136:137] neg_lo:[0,1] neg_hi:[0,1]
	v_xor_b32_e32 v26, 0x80000000, v17
	v_pk_mul_f32 v[180:181], v[136:137], s[36:37]
	v_xor_b32_e32 v30, 0x80000000, v21
	v_pk_fma_f32 v[136:137], v[136:137], s[78:79], v[180:181] op_sel:[0,0,1] op_sel_hi:[1,0,0]
	v_pk_add_f32 v[180:181], v[150:151], v[158:159]
	v_pk_add_f32 v[158:159], v[150:151], v[158:159] neg_lo:[0,1] neg_hi:[0,1]
	v_pk_fma_f32 v[24:25], v[10:11], v[8:9], v[24:25] op_sel_hi:[1,0,1]
	v_pk_add_f32 v[150:151], v[152:153], v[160:161]
	v_pk_add_f32 v[152:153], v[152:153], v[160:161] neg_lo:[0,1] neg_hi:[0,1]
	v_pk_fma_f32 v[40:41], v[8:9], v[28:29], v[40:41] op_sel_hi:[0,1,1]
	v_pk_mul_f32 v[160:161], v[152:153], s[36:37]
	v_pk_fma_f32 v[56:57], v[8:9], v[44:45], v[56:57] op_sel_hi:[0,1,1]
	v_pk_fma_f32 v[152:153], v[152:153], s[78:79], v[160:161] op_sel:[0,0,1] op_sel_hi:[1,0,0] neg_lo:[1,0,0] neg_hi:[1,0,0]
	v_pk_add_f32 v[160:161], v[128:129], v[156:157] op_sel:[0,1] op_sel_hi:[1,0] neg_hi:[0,1]
	v_pk_add_f32 v[128:129], v[128:129], v[156:157] op_sel:[0,1] op_sel_hi:[1,0] neg_lo:[0,1]
	v_pk_add_f32 v[156:157], v[130:131], v[138:139]
	v_pk_add_f32 v[130:131], v[130:131], v[138:139] neg_lo:[0,1] neg_hi:[0,1]
	v_pk_fma_f32 v[72:73], v[8:9], v[60:61], v[72:73] op_sel_hi:[0,1,1]
	v_pk_mul_f32 v[138:139], v[130:131], s[36:37]
	v_pk_fma_f32 v[88:89], v[8:9], v[76:77], v[88:89] op_sel_hi:[0,1,1]
	v_pk_fma_f32 v[130:131], v[130:131], s[78:79], v[138:139] op_sel:[0,0,1] op_sel_hi:[1,0,0]
	v_pk_add_f32 v[138:139], v[132:133], v[140:141]
	v_pk_add_f32 v[140:141], v[132:133], v[140:141] neg_lo:[0,1] neg_hi:[0,1]
	v_pk_fma_f32 v[104:105], v[8:9], v[92:93], v[104:105] op_sel_hi:[0,1,1]
	v_pk_add_f32 v[132:133], v[134:135], v[142:143]
	v_pk_add_f32 v[134:135], v[134:135], v[142:143] neg_lo:[0,1] neg_hi:[0,1]
	v_pk_fma_f32 v[120:121], v[8:9], v[108:109], v[120:121] op_sel_hi:[0,1,1]
	v_pk_mul_f32 v[142:143], v[134:135], s[36:37]
	v_mov_b32_e32 v27, v17
	v_pk_fma_f32 v[134:135], v[134:135], s[78:79], v[142:143] op_sel:[0,0,1] op_sel_hi:[1,0,0] neg_lo:[1,0,0] neg_hi:[1,0,0]
	v_pk_add_f32 v[142:143], v[162:163], v[178:179]
	v_pk_add_f32 v[162:163], v[162:163], v[178:179] neg_lo:[0,1] neg_hi:[0,1]
	v_pk_add_f32 v[178:179], v[194:195], v[164:165]
	v_pk_add_f32 v[194:195], v[194:195], v[164:165] neg_lo:[0,1] neg_hi:[0,1]
	v_mov_b32_e32 v31, v21
	v_pk_add_f32 v[164:165], v[184:185], v[188:189] op_sel:[0,1] op_sel_hi:[1,0] neg_hi:[0,1]
	v_pk_add_f32 v[184:185], v[184:185], v[188:189] op_sel:[0,1] op_sel_hi:[1,0] neg_lo:[0,1]
	v_pk_add_f32 v[188:189], v[170:171], v[182:183]
	v_pk_add_f32 v[182:183], v[170:171], v[182:183] neg_lo:[0,1] neg_hi:[0,1]
	v_xor_b32_e32 v34, 0x80000000, v25
	v_pk_add_f32 v[170:171], v[190:191], v[172:173]
	v_pk_add_f32 v[172:173], v[190:191], v[172:173] neg_lo:[0,1] neg_hi:[0,1]
	v_pk_add_f32 v[190:191], v[186:187], v[166:167]
	v_pk_add_f32 v[186:187], v[186:187], v[166:167] neg_lo:[0,1] neg_hi:[0,1]
	v_xor_b32_e32 v38, 0x80000000, v29
	v_pk_add_f32 v[166:167], v[144:145], v[174:175] op_sel:[0,1] op_sel_hi:[1,0] neg_hi:[0,1]
	v_pk_add_f32 v[144:145], v[144:145], v[174:175] op_sel:[0,1] op_sel_hi:[1,0] neg_lo:[0,1]
	v_pk_add_f32 v[174:175], v[148:149], v[168:169]
	v_pk_add_f32 v[168:169], v[148:149], v[168:169] neg_lo:[0,1] neg_hi:[0,1]
	v_xor_b32_e32 v42, 0x80000000, v33
	v_pk_add_f32 v[148:149], v[176:177], v[180:181]
	v_pk_add_f32 v[176:177], v[176:177], v[180:181] neg_lo:[0,1] neg_hi:[0,1]
	v_pk_add_f32 v[180:181], v[192:193], v[150:151]
	v_pk_add_f32 v[192:193], v[192:193], v[150:151] neg_lo:[0,1] neg_hi:[0,1]
	v_xor_b32_e32 v46, 0x80000000, v37
	v_pk_add_f32 v[150:151], v[154:155], v[158:159] op_sel:[0,1] op_sel_hi:[1,0] neg_hi:[0,1]
	v_pk_add_f32 v[154:155], v[154:155], v[158:159] op_sel:[0,1] op_sel_hi:[1,0] neg_lo:[0,1]
	v_pk_add_f32 v[158:159], v[136:137], v[152:153]
	v_pk_add_f32 v[152:153], v[136:137], v[152:153] neg_lo:[0,1] neg_hi:[0,1]
	v_mov_b32_e32 v35, v25
	v_pk_add_f32 v[136:137], v[160:161], v[138:139]
	v_pk_add_f32 v[138:139], v[160:161], v[138:139] neg_lo:[0,1] neg_hi:[0,1]
	v_pk_add_f32 v[160:161], v[156:157], v[132:133]
	v_pk_add_f32 v[156:157], v[156:157], v[132:133] neg_lo:[0,1] neg_hi:[0,1]
	v_mov_b32_e32 v39, v29
	v_pk_add_f32 v[132:133], v[128:129], v[140:141] op_sel:[0,1] op_sel_hi:[1,0] neg_hi:[0,1]
	v_pk_add_f32 v[128:129], v[128:129], v[140:141] op_sel:[0,1] op_sel_hi:[1,0] neg_lo:[0,1]
	v_pk_add_f32 v[140:141], v[130:131], v[134:135]
	v_pk_add_f32 v[134:135], v[130:131], v[134:135] neg_lo:[0,1] neg_hi:[0,1]
	v_mov_b32_e32 v43, v33
	v_pk_add_f32 v[130:131], v[142:143], v[178:179]
	v_pk_add_f32 v[142:143], v[142:143], v[178:179] neg_lo:[0,1] neg_hi:[0,1]
	v_pk_add_f32 v[178:179], v[162:163], v[194:195] op_sel:[0,1] op_sel_hi:[1,0] neg_hi:[0,1]
	v_pk_add_f32 v[162:163], v[162:163], v[194:195] op_sel:[0,1] op_sel_hi:[1,0] neg_lo:[0,1]
	v_pk_add_f32 v[194:195], v[164:165], v[188:189]
	v_pk_add_f32 v[164:165], v[164:165], v[188:189] neg_lo:[0,1] neg_hi:[0,1]
	v_pk_add_f32 v[188:189], v[184:185], v[182:183] op_sel:[0,1] op_sel_hi:[1,0] neg_hi:[0,1]
	v_pk_add_f32 v[182:183], v[184:185], v[182:183] op_sel:[0,1] op_sel_hi:[1,0] neg_lo:[0,1]
	v_pk_add_f32 v[184:185], v[170:171], v[190:191]
	v_pk_add_f32 v[170:171], v[170:171], v[190:191] neg_lo:[0,1] neg_hi:[0,1]
	v_pk_add_f32 v[190:191], v[172:173], v[186:187] op_sel:[0,1] op_sel_hi:[1,0] neg_hi:[0,1]
	v_pk_add_f32 v[172:173], v[172:173], v[186:187] op_sel:[0,1] op_sel_hi:[1,0] neg_lo:[0,1]
	v_pk_add_f32 v[186:187], v[166:167], v[174:175]
	v_pk_add_f32 v[166:167], v[166:167], v[174:175] neg_lo:[0,1] neg_hi:[0,1]
	v_pk_add_f32 v[174:175], v[144:145], v[168:169] op_sel:[0,1] op_sel_hi:[1,0] neg_hi:[0,1]
	v_pk_add_f32 v[144:145], v[144:145], v[168:169] op_sel:[0,1] op_sel_hi:[1,0] neg_lo:[0,1]
	v_pk_add_f32 v[168:169], v[148:149], v[180:181]
	v_pk_add_f32 v[148:149], v[148:149], v[180:181] neg_lo:[0,1] neg_hi:[0,1]
	v_pk_mul_f32 v[2:3], v[2:3], v[168:169] op_sel:[0,1] op_sel_hi:[1,0]
	v_pk_add_f32 v[180:181], v[176:177], v[192:193] op_sel:[0,1] op_sel_hi:[1,0] neg_hi:[0,1]
	v_pk_add_f32 v[176:177], v[176:177], v[192:193] op_sel:[0,1] op_sel_hi:[1,0] neg_lo:[0,1]
	v_pk_add_f32 v[192:193], v[150:151], v[158:159]
	v_pk_add_f32 v[150:151], v[150:151], v[158:159] neg_lo:[0,1] neg_hi:[0,1]
	v_pk_add_f32 v[158:159], v[154:155], v[152:153] op_sel:[0,1] op_sel_hi:[1,0] neg_hi:[0,1]
	v_pk_add_f32 v[152:153], v[154:155], v[152:153] op_sel:[0,1] op_sel_hi:[1,0] neg_lo:[0,1]
	v_pk_add_f32 v[154:155], v[136:137], v[160:161]
	v_pk_fma_f32 v[2:3], v[4:5], v[168:169], v[2:3] op_sel_hi:[0,1,1]
	v_pk_mul_f32 v[4:5], v[12:13], v[184:185] op_sel:[0,1] op_sel_hi:[1,0]
	v_mov_b32_e32 v47, v37
	v_pk_fma_f32 v[4:5], v[6:7], v[184:185], v[4:5] op_sel_hi:[0,1,1]
	v_pk_mul_f32 v[6:7], v[22:23], v[154:155] op_sel:[0,1] op_sel_hi:[1,0]
	v_pk_add_f32 v[136:137], v[136:137], v[160:161] neg_lo:[0,1] neg_hi:[0,1]
	v_pk_fma_f32 v[6:7], v[8:9], v[154:155], v[6:7] op_sel_hi:[0,1,1]
	v_pk_mul_f32 v[8:9], v[14:15], v[194:195] op_sel:[0,1] op_sel_hi:[1,0]
	v_pk_add_f32 v[160:161], v[138:139], v[156:157] op_sel:[0,1] op_sel_hi:[1,0] neg_hi:[0,1]
	v_pk_add_f32 v[138:139], v[138:139], v[156:157] op_sel:[0,1] op_sel_hi:[1,0] neg_lo:[0,1]
	v_pk_add_f32 v[156:157], v[132:133], v[140:141]
	v_pk_fma_f32 v[8:9], v[10:11], v[194:195], v[8:9] op_sel_hi:[0,1,1]
	v_pk_mul_f32 v[10:11], v[26:27], v[192:193] op_sel:[0,1] op_sel_hi:[1,0]
	v_pk_mul_f32 v[12:13], v[30:31], v[186:187] op_sel:[0,1] op_sel_hi:[1,0]
	v_xor_b32_e32 v50, 0x80000000, v41
	v_xor_b32_e32 v54, 0x80000000, v45
	v_xor_b32_e32 v58, 0x80000000, v49
	v_xor_b32_e32 v62, 0x80000000, v53
	v_xor_b32_e32 v66, 0x80000000, v57
	v_xor_b32_e32 v70, 0x80000000, v61
	v_xor_b32_e32 v74, 0x80000000, v65
	v_mov_b32_e32 v51, v41
	v_mov_b32_e32 v55, v45
	v_mov_b32_e32 v59, v49
	v_mov_b32_e32 v63, v53
	v_mov_b32_e32 v67, v57
	v_mov_b32_e32 v71, v61
	v_mov_b32_e32 v75, v65
	v_pk_add_f32 v[132:133], v[132:133], v[140:141] neg_lo:[0,1] neg_hi:[0,1]
	v_pk_add_f32 v[140:141], v[128:129], v[134:135] op_sel:[0,1] op_sel_hi:[1,0] neg_hi:[0,1]
	v_pk_fma_f32 v[10:11], v[16:17], v[192:193], v[10:11] op_sel_hi:[0,1,1]
	v_pk_fma_f32 v[12:13], v[20:21], v[186:187], v[12:13] op_sel_hi:[0,1,1]
	v_pk_mul_f32 v[14:15], v[34:35], v[156:157] op_sel:[0,1] op_sel_hi:[1,0]
	v_pk_mul_f32 v[16:17], v[38:39], v[178:179] op_sel:[0,1] op_sel_hi:[1,0]
	v_pk_mul_f32 v[20:21], v[42:43], v[180:181] op_sel:[0,1] op_sel_hi:[1,0]
	v_pk_mul_f32 v[22:23], v[46:47], v[190:191] op_sel:[0,1] op_sel_hi:[1,0]
	v_xor_b32_e32 v78, 0x80000000, v69
	v_xor_b32_e32 v82, 0x80000000, v73
	v_xor_b32_e32 v86, 0x80000000, v77
	v_xor_b32_e32 v90, 0x80000000, v81
	v_xor_b32_e32 v94, 0x80000000, v85
	v_xor_b32_e32 v98, 0x80000000, v89
	v_xor_b32_e32 v102, 0x80000000, v93
	v_xor_b32_e32 v106, 0x80000000, v97
	v_xor_b32_e32 v110, 0x80000000, v101
	v_xor_b32_e32 v114, 0x80000000, v105
	v_xor_b32_e32 v118, 0x80000000, v109
	v_xor_b32_e32 v122, 0x80000000, v113
	v_xor_b32_e32 v124, 0x80000000, v117
	v_xor_b32_e32 v126, 0x80000000, v121
	v_mov_b32_e32 v79, v69
	v_mov_b32_e32 v83, v73
	v_mov_b32_e32 v87, v77
	v_mov_b32_e32 v91, v81
	v_mov_b32_e32 v95, v85
	v_mov_b32_e32 v99, v89
	v_mov_b32_e32 v103, v93
	v_mov_b32_e32 v107, v97
	v_mov_b32_e32 v111, v101
	v_mov_b32_e32 v115, v105
	v_mov_b32_e32 v119, v109
	v_mov_b32_e32 v123, v113
	v_mov_b32_e32 v125, v117
	v_mov_b32_e32 v127, v121
	v_pk_add_f32 v[128:129], v[128:129], v[134:135] op_sel:[0,1] op_sel_hi:[1,0] neg_lo:[0,1]
	v_pk_fma_f32 v[14:15], v[24:25], v[156:157], v[14:15] op_sel_hi:[0,1,1]
	v_pk_fma_f32 v[16:17], v[28:29], v[178:179], v[16:17] op_sel_hi:[0,1,1]
	v_pk_fma_f32 v[20:21], v[32:33], v[180:181], v[20:21] op_sel_hi:[0,1,1]
	v_pk_fma_f32 v[22:23], v[36:37], v[190:191], v[22:23] op_sel_hi:[0,1,1]
	v_pk_mul_f32 v[24:25], v[50:51], v[160:161] op_sel:[0,1] op_sel_hi:[1,0]
	v_pk_mul_f32 v[26:27], v[54:55], v[188:189] op_sel:[0,1] op_sel_hi:[1,0]
	v_pk_mul_f32 v[28:29], v[58:59], v[158:159] op_sel:[0,1] op_sel_hi:[1,0]
	v_pk_mul_f32 v[30:31], v[62:63], v[174:175] op_sel:[0,1] op_sel_hi:[1,0]
	v_pk_mul_f32 v[32:33], v[66:67], v[140:141] op_sel:[0,1] op_sel_hi:[1,0]
	v_pk_mul_f32 v[34:35], v[70:71], v[142:143] op_sel:[0,1] op_sel_hi:[1,0]
	v_pk_mul_f32 v[36:37], v[74:75], v[148:149] op_sel:[0,1] op_sel_hi:[1,0]
	v_pk_fma_f32 v[24:25], v[40:41], v[160:161], v[24:25] op_sel_hi:[0,1,1]
	v_pk_fma_f32 v[26:27], v[44:45], v[188:189], v[26:27] op_sel_hi:[0,1,1]
	v_pk_fma_f32 v[28:29], v[48:49], v[158:159], v[28:29] op_sel_hi:[0,1,1]
	v_pk_fma_f32 v[30:31], v[52:53], v[174:175], v[30:31] op_sel_hi:[0,1,1]
	v_pk_fma_f32 v[32:33], v[56:57], v[140:141], v[32:33] op_sel_hi:[0,1,1]
	v_pk_fma_f32 v[34:35], v[60:61], v[142:143], v[34:35] op_sel_hi:[0,1,1]
	v_pk_fma_f32 v[36:37], v[64:65], v[148:149], v[36:37] op_sel_hi:[0,1,1]
	v_pk_mul_f32 v[38:39], v[78:79], v[170:171] op_sel:[0,1] op_sel_hi:[1,0]
	v_pk_mul_f32 v[40:41], v[82:83], v[136:137] op_sel:[0,1] op_sel_hi:[1,0]
	v_pk_mul_f32 v[42:43], v[86:87], v[164:165] op_sel:[0,1] op_sel_hi:[1,0]
	v_pk_mul_f32 v[44:45], v[90:91], v[150:151] op_sel:[0,1] op_sel_hi:[1,0]
	v_pk_mul_f32 v[46:47], v[94:95], v[166:167] op_sel:[0,1] op_sel_hi:[1,0]
	v_pk_mul_f32 v[48:49], v[98:99], v[132:133] op_sel:[0,1] op_sel_hi:[1,0]
	v_pk_mul_f32 v[50:51], v[102:103], v[162:163] op_sel:[0,1] op_sel_hi:[1,0]
	v_pk_mul_f32 v[52:53], v[106:107], v[176:177] op_sel:[0,1] op_sel_hi:[1,0]
	v_pk_mul_f32 v[54:55], v[110:111], v[172:173] op_sel:[0,1] op_sel_hi:[1,0]
	v_pk_mul_f32 v[56:57], v[114:115], v[138:139] op_sel:[0,1] op_sel_hi:[1,0]
	v_pk_mul_f32 v[58:59], v[118:119], v[182:183] op_sel:[0,1] op_sel_hi:[1,0]
	v_pk_mul_f32 v[60:61], v[122:123], v[152:153] op_sel:[0,1] op_sel_hi:[1,0]
	v_pk_mul_f32 v[62:63], v[124:125], v[144:145] op_sel:[0,1] op_sel_hi:[1,0]
	v_pk_mul_f32 v[64:65], v[126:127], v[128:129] op_sel:[0,1] op_sel_hi:[1,0]
	v_pk_fma_f32 v[38:39], v[68:69], v[170:171], v[38:39] op_sel_hi:[0,1,1]
	v_pk_fma_f32 v[40:41], v[72:73], v[136:137], v[40:41] op_sel_hi:[0,1,1]
	v_pk_fma_f32 v[42:43], v[76:77], v[164:165], v[42:43] op_sel_hi:[0,1,1]
	v_pk_fma_f32 v[44:45], v[80:81], v[150:151], v[44:45] op_sel_hi:[0,1,1]
	v_pk_fma_f32 v[46:47], v[84:85], v[166:167], v[46:47] op_sel_hi:[0,1,1]
	v_pk_fma_f32 v[48:49], v[88:89], v[132:133], v[48:49] op_sel_hi:[0,1,1]
	v_pk_fma_f32 v[50:51], v[92:93], v[162:163], v[50:51] op_sel_hi:[0,1,1]
	v_pk_fma_f32 v[52:53], v[96:97], v[176:177], v[52:53] op_sel_hi:[0,1,1]
	v_pk_fma_f32 v[54:55], v[100:101], v[172:173], v[54:55] op_sel_hi:[0,1,1]
	v_pk_fma_f32 v[56:57], v[104:105], v[138:139], v[56:57] op_sel_hi:[0,1,1]
	v_pk_fma_f32 v[58:59], v[108:109], v[182:183], v[58:59] op_sel_hi:[0,1,1]
	v_pk_fma_f32 v[60:61], v[112:113], v[152:153], v[60:61] op_sel_hi:[0,1,1]
	v_pk_fma_f32 v[62:63], v[116:117], v[144:145], v[62:63] op_sel_hi:[0,1,1]
	v_pk_fma_f32 v[64:65], v[120:121], v[128:129], v[64:65] op_sel_hi:[0,1,1]
	ds_write2_b64 v18, v[130:131], v[34:35] offset1:16
	ds_write2_b64 v18, v[16:17], v[50:51] offset0:33 offset1:49
	ds_write2_b64 v18, v[8:9], v[42:43] offset0:66 offset1:82
	ds_write2_b64 v18, v[26:27], v[58:59] offset0:99 offset1:115
	ds_write2_b64 v18, v[4:5], v[38:39] offset0:132 offset1:148
	ds_write2_b64 v18, v[22:23], v[54:55] offset0:165 offset1:181
	ds_write2_b64 v18, v[12:13], v[46:47] offset0:198 offset1:214
	ds_write2_b64 v18, v[30:31], v[62:63] offset0:231 offset1:247
	ds_write2_b64 v196, v[2:3], v[36:37] offset0:8 offset1:24
	ds_write2_b64 v196, v[20:21], v[52:53] offset0:41 offset1:57
	ds_write2_b64 v196, v[10:11], v[44:45] offset0:74 offset1:90
	ds_write2_b64 v196, v[28:29], v[60:61] offset0:107 offset1:123
	ds_write2_b64 v196, v[6:7], v[40:41] offset0:140 offset1:156
	ds_write2_b64 v196, v[24:25], v[56:57] offset0:173 offset1:189
	ds_write2_b64 v196, v[14:15], v[48:49] offset0:206 offset1:222
	ds_write2_b64 v196, v[32:33], v[64:65] offset0:239 offset1:255
	v_ashrrev_i32_e32 v2, 31, v210
	v_lshrrev_b32_e32 v2, 23, v2
	v_add_u32_e32 v2, v210, v2
	s_lshl_b64 s[74:75], s[76:77], 16
	v_and_b32_e32 v2, 0xfffffe00, v2
	s_add_u32 s0, s54, s74
	v_sub_u32_e32 v2, v210, v2
	s_addc_u32 s1, s55, s75
	v_ashrrev_i32_e32 v3, 31, v2
	v_lshl_add_u64 v[14:15], v[2:3], 3, s[0:1]
	v_add_co_u32_e32 v2, vcc, s92, v14
	s_mov_b32 s0, 0x8000
	s_nop 0
	v_addc_co_u32_e32 v3, vcc, 0, v15, vcc
	v_add_co_u32_e32 v4, vcc, s95, v14
	s_waitcnt lgkmcnt(0)
	s_nop 0
	v_addc_co_u32_e32 v5, vcc, 0, v15, vcc
	v_add_co_u32_e32 v8, vcc, s96, v14
	s_barrier
	s_nop 0
	v_addc_co_u32_e32 v9, vcc, 0, v15, vcc
	global_load_dwordx2 v[24:25], v[4:5], off offset:-4096 nt
	global_load_dwordx2 v[12:13], v[4:5], off nt
	global_load_dwordx2 v[6:7], v[8:9], off offset:-4096 nt
	s_nop 0
	global_load_dwordx2 v[4:5], v[8:9], off nt
	v_add_co_u32_e32 v8, vcc, s0, v14
	s_waitcnt vmcnt(3)
	v_cvt_f32_f16_sdwa v174, v24 dst_sel:DWORD dst_unused:UNUSED_PAD src0_sel:WORD_1
	v_addc_co_u32_e32 v9, vcc, 0, v15, vcc
	v_add_co_u32_e32 v10, vcc, s34, v14
	v_cvt_f32_f16_e32 v175, v25
	s_nop 0
	v_addc_co_u32_e32 v11, vcc, 0, v15, vcc
	global_load_dwordx2 v[16:17], v[8:9], off offset:-4096 nt
	global_load_dwordx2 v[122:123], v[8:9], off nt
	global_load_dwordx2 v[46:47], v[10:11], off offset:-4096 nt
	global_load_dwordx2 v[36:37], v[10:11], off nt
	v_add_co_u32_e32 v8, vcc, s35, v14
	v_cvt_f32_f16_sdwa v177, v25 dst_sel:DWORD dst_unused:UNUSED_PAD src0_sel:WORD_1
	s_nop 0
	v_addc_co_u32_e32 v9, vcc, 0, v15, vcc
	v_add_co_u32_e32 v22, vcc, s30, v14
	v_cvt_f32_f16_e32 v176, v24
	s_nop 0
	v_addc_co_u32_e32 v23, vcc, 0, v15, vcc
	global_load_dwordx2 v[26:27], v[8:9], off offset:-4096 nt
	global_load_dwordx2 v[20:21], v[8:9], off nt
	global_load_dwordx2 v[10:11], v[22:23], off offset:-4096 nt
	s_nop 0
	global_load_dwordx2 v[8:9], v[22:23], off nt
	v_add_co_u32_e32 v22, vcc, s31, v14
	s_waitcnt vmcnt(10)
	v_cvt_f32_f16_sdwa v164, v12 dst_sel:DWORD dst_unused:UNUSED_PAD src0_sel:WORD_1
	v_addc_co_u32_e32 v23, vcc, 0, v15, vcc
	global_load_dwordx2 v[30:31], v[2:3], off offset:-4096 nt
	global_load_dwordx2 v[28:29], v[2:3], off nt
	s_nop 0
	global_load_dwordx2 v[2:3], v[22:23], off nt
	global_load_dwordx2 v[32:33], v[14:15], off nt
	v_mov_b32_e32 v14, v210
	v_cvt_f32_f16_e32 v165, v13
	v_ashrrev_i32_e32 v15, 31, v14
	v_lshrrev_b32_e32 v15, 23, v15
	v_add_u32_e32 v15, v14, v15
	v_ashrrev_i32_e32 v15, 9, v15
	v_mul_i32_i24_e32 v18, 0x200, v15
	v_sub_u32_e32 v18, v14, v18
	v_lshlrev_b32_e32 v14, 14, v15
	v_lshlrev_b32_e32 v15, 1, v18
	v_bfrev_b32_e32 v15, v15
	v_lshrrev_b32_e32 v15, 22, v15
	v_sub_u32_e32 v15, 0x400, v15
	v_bfrev_b32_e32 v15, v15
	v_lshrrev_b32_e32 v15, 18, v15
	v_and_b32_e32 v15, 0x3ff0, v15
	v_cmp_eq_u32_e64 s[0:1], 0, v18
	v_lshl_add_u32 v22, v18, 5, v14
	v_lshl_add_u32 v23, v22, 3, 0
	v_cndmask_b32_e64 v15, v15, 16, s[0:1]
	v_or_b32_e32 v14, v15, v14
	v_ashrrev_i32_e32 v22, 2, v22
	v_ashrrev_i32_e32 v15, 5, v14
	v_add_u32_e32 v211, v23, v22
	v_lshlrev_b32_e32 v14, 3, v14
	v_lshlrev_b32_e32 v15, 3, v15
	v_add3_u32 v212, 0, v14, v15
	ds_read2_b64 v[38:41], v211 offset1:1
	ds_read2_b64 v[42:45], v211 offset0:2 offset1:3
	ds_read2_b64 v[48:51], v212 offset1:1
	ds_read2_b64 v[52:55], v212 offset0:2 offset1:3
	ds_read2_b64 v[56:59], v211 offset0:4 offset1:5
	ds_read2_b64 v[60:63], v211 offset0:6 offset1:7
	ds_read2_b64 v[68:71], v212 offset0:4 offset1:5
	ds_read2_b64 v[72:75], v212 offset0:6 offset1:7
	ds_read2_b64 v[64:67], v211 offset0:8 offset1:9
	ds_read2_b64 v[76:79], v211 offset0:10 offset1:11
	ds_read2_b64 v[80:83], v212 offset0:8 offset1:9
	ds_read2_b64 v[98:101], v212 offset0:10 offset1:11
	ds_read2_b64 v[84:87], v211 offset0:12 offset1:13
	ds_read2_b64 v[88:91], v211 offset0:14 offset1:15
	ds_read2_b64 v[102:105], v212 offset0:12 offset1:13
	ds_read2_b64 v[106:109], v212 offset0:14 offset1:15
	s_waitcnt lgkmcnt(7)
	v_pk_add_f32 v[14:15], v[38:39], v[64:65]
	v_pk_add_f32 v[22:23], v[38:39], v[64:65] neg_lo:[0,1] neg_hi:[0,1]
	v_pk_add_f32 v[38:39], v[40:41], v[66:67] neg_lo:[0,1] neg_hi:[0,1]
	v_pk_add_f32 v[34:35], v[40:41], v[66:67]
	v_pk_mul_f32 v[40:41], v[38:39], s[18:19]
	v_cmp_ne_u32_e32 vcc, 0, v18
	v_pk_fma_f32 v[38:39], v[38:39], s[16:17], v[40:41] op_sel:[0,0,1] op_sel_hi:[1,0,0]
	s_waitcnt lgkmcnt(6)
	v_pk_add_f32 v[40:41], v[42:43], v[76:77]
	v_pk_add_f32 v[42:43], v[42:43], v[76:77] neg_lo:[0,1] neg_hi:[0,1]
	v_bfrev_b32_e32 v18, v18
	v_pk_mul_f32 v[64:65], v[42:43], s[36:37]
	v_lshrrev_b32_e32 v18, 23, v18
	v_pk_fma_f32 v[42:43], v[42:43], s[78:79], v[64:65] op_sel:[0,0,1] op_sel_hi:[1,0,0]
	v_pk_add_f32 v[64:65], v[44:45], v[78:79]
	v_pk_add_f32 v[44:45], v[44:45], v[78:79] neg_lo:[0,1] neg_hi:[0,1]
	s_waitcnt lgkmcnt(3)
	v_pk_add_f32 v[78:79], v[58:59], v[86:87]
	v_pk_mul_f32 v[66:67], v[44:45], s[40:41]
	v_pk_add_f32 v[58:59], v[58:59], v[86:87] neg_lo:[0,1] neg_hi:[0,1]
	v_pk_fma_f32 v[44:45], v[44:45], s[80:81], v[66:67] op_sel:[0,0,1] op_sel_hi:[1,0,0]
	v_pk_add_f32 v[66:67], v[56:57], v[84:85]
	v_pk_add_f32 v[76:77], v[56:57], v[84:85] neg_lo:[0,1] neg_hi:[0,1]
	v_pk_mul_f32 v[84:85], v[58:59], s[40:41]
	v_pk_fma_f32 v[58:59], v[58:59], s[80:81], v[84:85] op_sel:[0,0,1] op_sel_hi:[1,0,0] neg_lo:[1,0,0] neg_hi:[1,0,0]
	s_waitcnt lgkmcnt(2)
	v_pk_add_f32 v[84:85], v[60:61], v[88:89]
	v_pk_add_f32 v[60:61], v[60:61], v[88:89] neg_lo:[0,1] neg_hi:[0,1]
	v_pk_mul_f32 v[86:87], v[60:61], s[36:37]
	v_pk_add_f32 v[56:57], v[22:23], v[76:77] op_sel:[0,1] op_sel_hi:[1,0] neg_hi:[0,1]
	v_pk_fma_f32 v[60:61], v[60:61], s[78:79], v[86:87] op_sel:[0,0,1] op_sel_hi:[1,0,0] neg_lo:[1,0,0] neg_hi:[1,0,0]
	v_pk_add_f32 v[86:87], v[62:63], v[90:91]
	v_pk_add_f32 v[62:63], v[62:63], v[90:91] neg_lo:[0,1] neg_hi:[0,1]
	v_pk_add_f32 v[90:91], v[64:65], v[86:87]
	v_pk_mul_f32 v[88:89], v[62:63], s[18:19]
	v_pk_add_f32 v[64:65], v[64:65], v[86:87] neg_lo:[0,1] neg_hi:[0,1]
	v_pk_fma_f32 v[62:63], v[62:63], s[16:17], v[88:89] op_sel:[0,0,1] op_sel_hi:[1,0,0] neg_lo:[1,0,0] neg_hi:[1,0,0]
	v_pk_add_f32 v[88:89], v[14:15], v[66:67]
	v_pk_add_f32 v[14:15], v[14:15], v[66:67] neg_lo:[0,1] neg_hi:[0,1]
	v_pk_add_f32 v[66:67], v[34:35], v[78:79]
	v_pk_add_f32 v[34:35], v[34:35], v[78:79] neg_lo:[0,1] neg_hi:[0,1]
	v_pk_add_f32 v[22:23], v[22:23], v[76:77] op_sel:[0,1] op_sel_hi:[1,0] neg_lo:[0,1]
	v_pk_mul_f32 v[78:79], v[34:35], s[36:37]
	v_pk_add_f32 v[76:77], v[38:39], v[58:59]
	v_pk_add_f32 v[38:39], v[38:39], v[58:59] neg_lo:[0,1] neg_hi:[0,1]
	v_pk_fma_f32 v[34:35], v[34:35], s[78:79], v[78:79] op_sel:[0,0,1] op_sel_hi:[1,0,0]
	v_pk_add_f32 v[78:79], v[40:41], v[84:85]
	v_pk_add_f32 v[84:85], v[40:41], v[84:85] neg_lo:[0,1] neg_hi:[0,1]
	v_pk_mul_f32 v[86:87], v[64:65], s[36:37]
	v_pk_mul_f32 v[58:59], v[38:39], s[36:37]
	v_pk_fma_f32 v[64:65], v[64:65], s[78:79], v[86:87] op_sel:[0,0,1] op_sel_hi:[1,0,0] neg_lo:[1,0,0] neg_hi:[1,0,0]
	v_pk_fma_f32 v[38:39], v[38:39], s[78:79], v[58:59] op_sel:[0,0,1] op_sel_hi:[1,0,0]
	v_pk_add_f32 v[58:59], v[42:43], v[60:61]
	v_pk_add_f32 v[86:87], v[44:45], v[62:63]
	v_pk_add_f32 v[44:45], v[44:45], v[62:63] neg_lo:[0,1] neg_hi:[0,1]
	v_pk_mul_f32 v[62:63], v[44:45], s[36:37]
	v_pk_add_f32 v[40:41], v[14:15], v[84:85] op_sel:[0,1] op_sel_hi:[1,0] neg_hi:[0,1]
	v_pk_add_f32 v[14:15], v[14:15], v[84:85] op_sel:[0,1] op_sel_hi:[1,0] neg_lo:[0,1]
	v_pk_add_f32 v[84:85], v[34:35], v[64:65]
	v_pk_add_f32 v[64:65], v[34:35], v[64:65] neg_lo:[0,1] neg_hi:[0,1]
	v_pk_add_f32 v[94:95], v[56:57], v[58:59]
	v_pk_add_f32 v[56:57], v[56:57], v[58:59] neg_lo:[0,1] neg_hi:[0,1]
	v_pk_add_f32 v[58:59], v[76:77], v[86:87]
	v_pk_fma_f32 v[44:45], v[44:45], s[78:79], v[62:63] op_sel:[0,0,1] op_sel_hi:[1,0,0] neg_lo:[1,0,0] neg_hi:[1,0,0]
	v_pk_add_f32 v[62:63], v[88:89], v[78:79]
	v_pk_add_f32 v[78:79], v[88:89], v[78:79] neg_lo:[0,1] neg_hi:[0,1]
	v_pk_add_f32 v[88:89], v[66:67], v[90:91]
	v_pk_add_f32 v[110:111], v[76:77], v[86:87] neg_lo:[0,1] neg_hi:[0,1]
	v_pk_add_f32 v[86:87], v[94:95], v[58:59]
	v_pk_add_f32 v[34:35], v[94:95], v[58:59] neg_lo:[0,1] neg_hi:[0,1]
	v_pk_add_f32 v[58:59], v[50:51], v[82:83]
	v_pk_add_f32 v[50:51], v[50:51], v[82:83] neg_lo:[0,1] neg_hi:[0,1]
	v_pk_add_f32 v[60:61], v[42:43], v[60:61] neg_lo:[0,1] neg_hi:[0,1]
	v_pk_add_f32 v[148:149], v[62:63], v[88:89]
	v_pk_add_f32 v[138:139], v[62:63], v[88:89] neg_lo:[0,1] neg_hi:[0,1]
	v_pk_mul_f32 v[62:63], v[50:51], s[18:19]
	v_pk_add_f32 v[90:91], v[66:67], v[90:91] neg_lo:[0,1] neg_hi:[0,1]
	v_pk_fma_f32 v[50:51], v[50:51], s[16:17], v[62:63] op_sel:[0,0,1] op_sel_hi:[1,0,0]
	v_pk_add_f32 v[62:63], v[52:53], v[98:99]
	v_pk_add_f32 v[52:53], v[52:53], v[98:99] neg_lo:[0,1] neg_hi:[0,1]
	v_pk_add_f32 v[112:113], v[22:23], v[60:61] op_sel:[0,1] op_sel_hi:[1,0] neg_hi:[0,1]
	v_pk_add_f32 v[114:115], v[22:23], v[60:61] op_sel:[0,1] op_sel_hi:[1,0] neg_lo:[0,1]
	v_pk_add_f32 v[96:97], v[40:41], v[84:85]
	v_pk_add_f32 v[66:67], v[40:41], v[84:85] neg_lo:[0,1] neg_hi:[0,1]
	v_pk_add_f32 v[60:61], v[14:15], v[64:65] op_sel:[0,1] op_sel_hi:[1,0] neg_hi:[0,1]
	v_pk_add_f32 v[84:85], v[14:15], v[64:65] op_sel:[0,1] op_sel_hi:[1,0] neg_lo:[0,1]
	v_pk_mul_f32 v[64:65], v[52:53], s[36:37]
	v_pk_fma_f32 v[52:53], v[52:53], s[78:79], v[64:65] op_sel:[0,0,1] op_sel_hi:[1,0,0]
	v_pk_add_f32 v[64:65], v[54:55], v[100:101]
	v_pk_add_f32 v[54:55], v[54:55], v[100:101] neg_lo:[0,1] neg_hi:[0,1]
	v_pk_mul_f32 v[76:77], v[54:55], s[40:41]
	v_pk_add_f32 v[92:93], v[78:79], v[90:91] op_sel:[0,1] op_sel_hi:[1,0] neg_hi:[0,1]
	v_pk_fma_f32 v[54:55], v[54:55], s[80:81], v[76:77] op_sel:[0,0,1] op_sel_hi:[1,0,0]
	s_waitcnt lgkmcnt(1)
	v_pk_add_f32 v[76:77], v[68:69], v[102:103]
	v_pk_add_f32 v[68:69], v[68:69], v[102:103] neg_lo:[0,1] neg_hi:[0,1]
	v_pk_add_f32 v[88:89], v[78:79], v[90:91] op_sel:[0,1] op_sel_hi:[1,0] neg_lo:[0,1]
	v_xor_b32_e32 v79, 0x80000000, v68
	v_mov_b32_e32 v78, v69
	v_pk_add_f32 v[68:69], v[70:71], v[104:105]
	v_pk_add_f32 v[70:71], v[70:71], v[104:105] neg_lo:[0,1] neg_hi:[0,1]
	v_pk_add_f32 v[22:23], v[38:39], v[44:45]
	v_pk_add_f32 v[116:117], v[38:39], v[44:45] neg_lo:[0,1] neg_hi:[0,1]
	v_pk_add_f32 v[40:41], v[56:57], v[110:111] op_sel:[0,1] op_sel_hi:[1,0] neg_hi:[0,1]
	v_pk_add_f32 v[44:45], v[56:57], v[110:111] op_sel:[0,1] op_sel_hi:[1,0] neg_lo:[0,1]
	v_pk_add_f32 v[56:57], v[48:49], v[80:81]
	v_pk_add_f32 v[48:49], v[48:49], v[80:81] neg_lo:[0,1] neg_hi:[0,1]
	v_pk_mul_f32 v[80:81], v[70:71], s[40:41]
	v_cvt_f32_u32_e32 v18, v18
	v_pk_fma_f32 v[70:71], v[70:71], s[80:81], v[80:81] op_sel:[0,0,1] op_sel_hi:[1,0,0] neg_lo:[1,0,0] neg_hi:[1,0,0]
	s_waitcnt lgkmcnt(0)
	v_pk_add_f32 v[80:81], v[72:73], v[106:107]
	v_pk_add_f32 v[72:73], v[72:73], v[106:107] neg_lo:[0,1] neg_hi:[0,1]
	v_mul_f32_e32 v18, 0x38000000, v18
	v_pk_mul_f32 v[82:83], v[72:73], s[36:37]
	v_cndmask_b32_e64 v18, v18, v208, s[0:1]
	v_pk_fma_f32 v[72:73], v[72:73], s[78:79], v[82:83] op_sel:[0,0,1] op_sel_hi:[1,0,0] neg_lo:[1,0,0] neg_hi:[1,0,0]
	v_pk_add_f32 v[82:83], v[74:75], v[108:109]
	v_pk_add_f32 v[74:75], v[74:75], v[108:109] neg_lo:[0,1] neg_hi:[0,1]
	s_nop 0
	v_pk_mul_f32 v[90:91], v[74:75], s[18:19]
	v_pk_fma_f32 v[74:75], v[74:75], s[16:17], v[90:91] op_sel:[0,0,1] op_sel_hi:[1,0,0] neg_lo:[1,0,0] neg_hi:[1,0,0]
	v_pk_add_f32 v[90:91], v[56:57], v[76:77]
	v_pk_add_f32 v[56:57], v[56:57], v[76:77] neg_lo:[0,1] neg_hi:[0,1]
	v_pk_add_f32 v[76:77], v[58:59], v[68:69]
	v_pk_add_f32 v[58:59], v[58:59], v[68:69] neg_lo:[0,1] neg_hi:[0,1]
	v_pk_add_f32 v[14:15], v[114:115], v[116:117] op_sel:[0,1] op_sel_hi:[1,0] neg_hi:[0,1]
	v_pk_mul_f32 v[68:69], v[58:59], s[36:37]
	v_pk_add_f32 v[38:39], v[114:115], v[116:117] op_sel:[0,1] op_sel_hi:[1,0] neg_lo:[0,1]
	v_pk_fma_f32 v[58:59], v[58:59], s[78:79], v[68:69] op_sel:[0,0,1] op_sel_hi:[1,0,0]
	v_pk_add_f32 v[68:69], v[62:63], v[80:81]
	v_pk_add_f32 v[80:81], v[62:63], v[80:81] neg_lo:[0,1] neg_hi:[0,1]
	s_waitcnt vmcnt(0)
	v_cvt_f32_f16_e32 v193, v33
	s_nop 0
	s_nop 0
	v_pk_add_f32 v[62:63], v[64:65], v[82:83]
	v_pk_add_f32 v[64:65], v[64:65], v[82:83] neg_lo:[0,1] neg_hi:[0,1]
	v_cvt_f32_f16_sdwa v192, v32 dst_sel:DWORD dst_unused:UNUSED_PAD src0_sel:WORD_1
	v_pk_mul_f32 v[82:83], v[64:65], s[36:37]
	v_cvt_f32_f16_e32 v194, v32
	v_pk_fma_f32 v[64:65], v[64:65], s[78:79], v[82:83] op_sel:[0,0,1] op_sel_hi:[1,0,0] neg_lo:[1,0,0] neg_hi:[1,0,0]
	v_pk_add_f32 v[82:83], v[48:49], v[78:79]
	v_pk_add_f32 v[48:49], v[48:49], v[78:79] neg_lo:[0,1] neg_hi:[0,1]
	v_pk_add_f32 v[78:79], v[50:51], v[70:71]
	v_pk_add_f32 v[50:51], v[50:51], v[70:71] neg_lo:[0,1] neg_hi:[0,1]
	v_cvt_f32_f16_sdwa v195, v33 dst_sel:DWORD dst_unused:UNUSED_PAD src0_sel:WORD_1
	v_pk_mul_f32 v[70:71], v[50:51], s[36:37]
	v_cvt_f32_f16_sdwa v170, v30 dst_sel:DWORD dst_unused:UNUSED_PAD src0_sel:WORD_1
	v_pk_fma_f32 v[50:51], v[50:51], s[78:79], v[70:71] op_sel:[0,0,1] op_sel_hi:[1,0,0]
	v_pk_add_f32 v[70:71], v[52:53], v[72:73]
	v_pk_add_f32 v[72:73], v[52:53], v[72:73] neg_lo:[0,1] neg_hi:[0,1]
	v_cvt_f32_f16_e32 v171, v31
	s_nop 0
	s_nop 0
	v_pk_add_f32 v[52:53], v[54:55], v[74:75]
	v_pk_add_f32 v[54:55], v[54:55], v[74:75] neg_lo:[0,1] neg_hi:[0,1]
	v_cvt_f32_f16_sdwa v185, v31 dst_sel:DWORD dst_unused:UNUSED_PAD src0_sel:WORD_1
	v_pk_mul_f32 v[74:75], v[54:55], s[36:37]
	v_cvt_f32_f16_e32 v184, v30
	v_pk_fma_f32 v[54:55], v[54:55], s[78:79], v[74:75] op_sel:[0,0,1] op_sel_hi:[1,0,0] neg_lo:[1,0,0] neg_hi:[1,0,0]
	v_pk_add_f32 v[74:75], v[90:91], v[68:69]
	v_pk_add_f32 v[68:69], v[90:91], v[68:69] neg_lo:[0,1] neg_hi:[0,1]
	v_pk_add_f32 v[90:91], v[76:77], v[62:63]
	v_pk_add_f32 v[62:63], v[76:77], v[62:63] neg_lo:[0,1] neg_hi:[0,1]
	v_cvt_f32_f16_sdwa v172, v28 dst_sel:DWORD dst_unused:UNUSED_PAD src0_sel:WORD_1
	v_xor_b32_e32 v77, 0x80000000, v62
	v_mov_b32_e32 v76, v63
	v_pk_add_f32 v[62:63], v[56:57], v[80:81] op_sel:[0,1] op_sel_hi:[1,0] neg_hi:[0,1]
	v_pk_add_f32 v[56:57], v[56:57], v[80:81] op_sel:[0,1] op_sel_hi:[1,0] neg_lo:[0,1]
	v_pk_add_f32 v[80:81], v[58:59], v[64:65]
	v_pk_add_f32 v[58:59], v[58:59], v[64:65] neg_lo:[0,1] neg_hi:[0,1]
	v_cvt_f32_f16_e32 v173, v29
	v_xor_b32_e32 v65, 0x80000000, v58
	v_mov_b32_e32 v64, v59
	v_pk_add_f32 v[58:59], v[82:83], v[70:71]
	v_pk_add_f32 v[70:71], v[82:83], v[70:71] neg_lo:[0,1] neg_hi:[0,1]
	v_pk_add_f32 v[82:83], v[78:79], v[52:53]
	v_pk_add_f32 v[52:53], v[78:79], v[52:53] neg_lo:[0,1] neg_hi:[0,1]
	v_pk_add_f32 v[118:119], v[58:59], v[82:83]
	v_pk_add_f32 v[134:135], v[58:59], v[82:83] neg_lo:[0,1] neg_hi:[0,1]
	v_cos_f32_e32 v83, v18
	v_sin_f32_e32 v82, v18
	v_cvt_f32_f16_sdwa v181, v29 dst_sel:DWORD dst_unused:UNUSED_PAD src0_sel:WORD_1
	v_cvt_f32_f16_e32 v180, v28
	v_cvt_f32_f16_sdwa v167, v13 dst_sel:DWORD dst_unused:UNUSED_PAD src0_sel:WORD_1
	v_cvt_f32_f16_e32 v166, v12
	v_cvt_f32_f16_e32 v154, v6
	v_cvt_f32_f16_e32 v155, v7
	v_cvt_f32_f16_sdwa v157, v7 dst_sel:DWORD dst_unused:UNUSED_PAD src0_sel:WORD_1
	v_cvt_f32_f16_sdwa v156, v6 dst_sel:DWORD dst_unused:UNUSED_PAD src0_sel:WORD_1
	v_cvt_f32_f16_sdwa v140, v4 dst_sel:DWORD dst_unused:UNUSED_PAD src0_sel:WORD_1
	v_cvt_f32_f16_e32 v141, v5
	v_cvt_f32_f16_sdwa v143, v5 dst_sel:DWORD dst_unused:UNUSED_PAD src0_sel:WORD_1
	v_cvt_f32_f16_e32 v142, v4
	v_cvt_f32_f16_e32 v124, v16
	v_cvt_f32_f16_e32 v125, v17
	v_cvt_f32_f16_sdwa v127, v17 dst_sel:DWORD dst_unused:UNUSED_PAD src0_sel:WORD_1
	v_cvt_f32_f16_sdwa v126, v16 dst_sel:DWORD dst_unused:UNUSED_PAD src0_sel:WORD_1
	v_cvt_f32_f16_sdwa v114, v122 dst_sel:DWORD dst_unused:UNUSED_PAD src0_sel:WORD_1
	v_cvt_f32_f16_e32 v115, v123
	v_cvt_f32_f16_sdwa v117, v123 dst_sel:DWORD dst_unused:UNUSED_PAD src0_sel:WORD_1
	v_cvt_f32_f16_e32 v116, v122
	v_xor_b32_e32 v79, 0x80000000, v52
	v_mov_b32_e32 v78, v53
	v_pk_add_f32 v[52:53], v[48:49], v[72:73] op_sel:[0,1] op_sel_hi:[1,0] neg_hi:[0,1]
	v_pk_add_f32 v[48:49], v[48:49], v[72:73] op_sel:[0,1] op_sel_hi:[1,0] neg_lo:[0,1]
	v_pk_add_f32 v[72:73], v[50:51], v[54:55]
	v_pk_add_f32 v[50:51], v[50:51], v[54:55] neg_lo:[0,1] neg_hi:[0,1]
	v_pk_fma_f32 v[160:161], v[82:83], 0, v[82:83] op_sel:[0,0,1] op_sel_hi:[1,0,0] neg_lo:[1,0,0] neg_hi:[1,0,0]
	v_xor_b32_e32 v55, 0x80000000, v50
	v_mov_b32_e32 v54, v51
	v_pk_fma_f32 v[198:199], v[82:83], 0, v[82:83] op_sel:[0,0,1] op_sel_hi:[1,0,0]
	v_pk_add_f32 v[42:43], v[112:113], v[22:23]
	v_pk_add_f32 v[22:23], v[112:113], v[22:23] neg_lo:[0,1] neg_hi:[0,1]
	v_pk_add_f32 v[98:99], v[74:75], v[90:91]
	v_pk_add_f32 v[100:101], v[74:75], v[90:91] neg_lo:[0,1] neg_hi:[0,1]
	v_pk_add_f32 v[102:103], v[68:69], v[76:77]
	v_pk_add_f32 v[106:107], v[68:69], v[76:77] neg_lo:[0,1] neg_hi:[0,1]
	v_pk_add_f32 v[104:105], v[62:63], v[80:81]
	v_pk_add_f32 v[108:109], v[62:63], v[80:81] neg_lo:[0,1] neg_hi:[0,1]
	v_pk_add_f32 v[110:111], v[56:57], v[64:65]
	v_pk_add_f32 v[112:113], v[56:57], v[64:65] neg_lo:[0,1] neg_hi:[0,1]
	v_pk_add_f32 v[152:153], v[70:71], v[78:79]
	v_pk_add_f32 v[162:163], v[70:71], v[78:79] neg_lo:[0,1] neg_hi:[0,1]
	v_pk_add_f32 v[178:179], v[52:53], v[72:73]
	v_pk_add_f32 v[182:183], v[52:53], v[72:73] neg_lo:[0,1] neg_hi:[0,1]
	v_pk_add_f32 v[188:189], v[48:49], v[54:55]
	v_pk_add_f32 v[196:197], v[48:49], v[54:55] neg_lo:[0,1] neg_hi:[0,1]
	v_pk_mul_f32 v[186:187], v[82:83], 0 op_sel_hi:[1,0]
	v_mov_b32_e32 v190, v160
	v_mov_b32_e32 v191, v199
	v_mul_f32_e32 v18, 0x3f3504f3, v83
	v_mul_f32_e32 v158, 0xbec3ef15, v83
	v_mul_f32_e32 v132, 0xbf6c835e, v83
	s_and_saveexec_b64 s[0:1], vcc
	s_xor_b64 s[0:1], exec, s[0:1]
	s_cbranch_execz .LBB0_501
	v_pk_add_f32 v[4:5], v[148:149], v[196:197]
	v_pk_add_f32 v[6:7], v[148:149], v[196:197] neg_lo:[0,1] neg_hi:[0,1]
	v_mul_f32_e32 v4, 0.5, v4
	v_mul_f32_e32 v12, 0.5, v7
	v_mov_b32_e32 v7, v5
	v_pk_mul_f32 v[6:7], v[6:7], s[44:45]
	v_pk_mov_b32 v[16:17], v[198:199], v[160:161] op_sel:[1,0]
	v_pk_mul_f32 v[24:25], v[190:191], v[6:7] op_sel:[0,1] op_sel_hi:[1,0]
	v_pk_mul_f32 v[6:7], v[190:191], v[6:7]
	v_pk_add_f32 v[24:25], v[24:25], v[24:25] op_sel:[0,1] op_sel_hi:[0,1]
	v_pk_add_f32 v[28:29], v[4:5], v[24:25] op_sel_hi:[0,1] neg_hi:[0,1]
	v_pk_add_f32 v[4:5], v[6:7], v[6:7] op_sel:[0,1] op_sel_hi:[0,1] neg_lo:[0,1] neg_hi:[0,1]
	v_pk_add_f32 v[6:7], v[12:13], v[4:5] op_sel_hi:[0,1] neg_hi:[0,1]
	v_pk_mul_f32 v[4:5], v[6:7], v[194:195]
	v_pk_mul_f32 v[6:7], v[6:7], v[192:193]
	v_pk_fma_f32 v[4:5], v[28:29], v[192:193], v[4:5]
	v_pk_fma_f32 v[6:7], v[28:29], v[194:195], v[6:7] neg_lo:[0,0,1] neg_hi:[0,0,1]
	s_mov_b32 s78, s19
	v_pk_add_f32 v[12:13], v[6:7], v[4:5] op_sel:[0,1] op_sel_hi:[1,0] neg_lo:[0,1]
	v_pk_add_f32 v[28:29], v[6:7], v[4:5] op_sel:[0,1] op_sel_hi:[1,0]
	v_pk_add_f32 v[4:5], v[4:5], v[6:7] op_sel:[1,0] op_sel_hi:[0,1] neg_lo:[0,1] neg_hi:[0,1]
	s_nop 0
	v_pk_mul_f32 v[12:13], v[12:13], 0.5 op_sel_hi:[1,0]
	v_mov_b32_e32 v29, v5
	v_mul_f32_e32 v24, v190, v12
	v_pk_fma_f32 v[30:31], v[190:191], v[12:13], v[24:25] op_sel_hi:[1,1,0] neg_lo:[1,0,0] neg_hi:[1,0,0]
	v_mul_f32_e32 v24, v160, v13
	v_pk_fma_f32 v[12:13], v[16:17], v[12:13], v[24:25] op_sel_hi:[1,1,0]
	v_mov_b32_e32 v16, v83
	v_mov_b32_e32 v30, v12
	v_pk_fma_f32 v[4:5], v[28:29], 0.5, v[12:13] op_sel_hi:[1,0,1] neg_lo:[0,0,1] neg_hi:[0,0,1]
	v_pk_fma_f32 v[122:123], v[28:29], 0.5, v[30:31] op_sel_hi:[1,0,1]
	v_pk_fma_f32 v[6:7], v[28:29], 0.5, v[30:31] op_sel_hi:[1,0,1] neg_lo:[1,0,0] neg_hi:[1,0,0]
	v_mov_b32_e32 v5, v123
	v_pk_mul_f32 v[24:25], v[4:5], s[6:7] op_sel_hi:[1,0]
	v_pk_add_f32 v[4:5], v[138:139], v[188:189]
	v_pk_add_f32 v[12:13], v[138:139], v[188:189] neg_lo:[0,1] neg_hi:[0,1]
	v_mov_b32_e32 v17, v82
	v_mul_f32_e32 v6, 0.5, v13
	v_pk_add_f32 v[28:29], v[186:187], v[16:17] neg_lo:[0,1] neg_hi:[0,1]
	v_pk_add_f32 v[30:31], v[186:187], v[16:17]
	v_mov_b32_e32 v13, v5
	v_pk_mov_b32 v[32:33], v[28:29], v[30:31] op_sel:[1,0]
	v_pk_mul_f32 v[12:13], v[12:13], s[44:45]
	v_mul_f32_e32 v4, 0.5, v4
	v_pk_mul_f32 v[48:49], v[32:33], v[12:13] op_sel:[0,1] op_sel_hi:[1,0]
	v_pk_mul_f32 v[12:13], v[32:33], v[12:13]
	v_pk_add_f32 v[48:49], v[48:49], v[48:49] op_sel:[0,1] op_sel_hi:[0,1]
	v_pk_add_f32 v[50:51], v[4:5], v[48:49] op_sel_hi:[0,1] neg_hi:[0,1]
	v_pk_add_f32 v[4:5], v[12:13], v[12:13] op_sel:[0,1] op_sel_hi:[0,1] neg_lo:[0,1] neg_hi:[0,1]
	v_pk_add_f32 v[12:13], v[6:7], v[4:5] op_sel_hi:[0,1] neg_hi:[0,1]
	v_pk_mul_f32 v[4:5], v[12:13], v[184:185]
	v_pk_mul_f32 v[12:13], v[12:13], v[170:171]
	v_pk_fma_f32 v[4:5], v[50:51], v[170:171], v[4:5]
	v_pk_fma_f32 v[12:13], v[50:51], v[184:185], v[12:13] neg_lo:[0,0,1] neg_hi:[0,0,1]
	v_mov_b32_e32 v31, v29
	v_pk_add_f32 v[48:49], v[12:13], v[4:5] op_sel:[0,1] op_sel_hi:[1,0] neg_lo:[0,1]
	v_pk_add_f32 v[50:51], v[12:13], v[4:5] op_sel:[0,1] op_sel_hi:[1,0]
	v_pk_add_f32 v[4:5], v[4:5], v[12:13] op_sel:[1,0] op_sel_hi:[0,1] neg_lo:[0,1] neg_hi:[0,1]
	v_pk_mul_f32 v[48:49], v[48:49], 0.5 op_sel_hi:[1,0]
	v_mov_b32_e32 v51, v5
	v_mul_f32_e32 v6, v29, v48
	v_pk_fma_f32 v[32:33], v[32:33], v[48:49], v[6:7] op_sel_hi:[1,1,0] neg_lo:[1,0,0] neg_hi:[1,0,0]
	v_mul_f32_e32 v6, v29, v49
	v_pk_fma_f32 v[28:29], v[30:31], v[48:49], v[6:7] op_sel_hi:[1,1,0]
	v_pk_mul_f32 v[12:13], v[16:17], s[36:37]
	v_mov_b32_e32 v32, v28
	v_pk_fma_f32 v[4:5], v[50:51], 0.5, v[28:29] op_sel_hi:[1,0,1] neg_lo:[0,0,1] neg_hi:[0,0,1]
	v_pk_fma_f32 v[138:139], v[50:51], 0.5, v[32:33] op_sel_hi:[1,0,1]
	v_pk_add_f32 v[16:17], v[92:93], v[182:183]
	v_mov_b32_e32 v5, v139
	v_pk_add_f32 v[28:29], v[92:93], v[182:183] neg_lo:[0,1] neg_hi:[0,1]
	v_pk_mul_f32 v[30:31], v[4:5], s[6:7] op_sel_hi:[1,0]
	v_pk_fma_f32 v[4:5], v[50:51], 0.5, v[32:33] op_sel_hi:[1,0,1] neg_lo:[1,0,0] neg_hi:[1,0,0]
	v_mul_f32_e32 v6, 0.5, v29
	v_pk_add_f32 v[32:33], v[18:19], v[12:13] op_sel:[0,1] op_sel_hi:[0,1] neg_lo:[0,1] neg_hi:[0,1]
	v_pk_add_f32 v[48:49], v[18:19], v[12:13] op_sel:[0,1] op_sel_hi:[0,1]
	v_mov_b32_e32 v29, v17
	v_mul_f32_e32 v4, 0.5, v16
	v_mov_b32_e32 v50, v32
	v_mov_b32_e32 v51, v49
	v_pk_mul_f32 v[16:17], v[28:29], s[44:45]
	v_pk_mov_b32 v[48:49], v[48:49], v[32:33] op_sel:[1,0]
	v_pk_mul_f32 v[28:29], v[50:51], v[16:17] op_sel:[0,1] op_sel_hi:[1,0]
	v_pk_mul_f32 v[16:17], v[50:51], v[16:17]
	v_pk_add_f32 v[28:29], v[28:29], v[28:29] op_sel:[0,1] op_sel_hi:[0,1]
	v_pk_add_f32 v[52:53], v[4:5], v[28:29] op_sel_hi:[0,1] neg_hi:[0,1]
	v_pk_add_f32 v[16:17], v[16:17], v[16:17] op_sel:[0,1] op_sel_hi:[0,1] neg_lo:[0,1] neg_hi:[0,1]
	v_pk_add_f32 v[28:29], v[6:7], v[16:17] op_sel_hi:[0,1] neg_hi:[0,1]
	v_pk_mul_f32 v[16:17], v[28:29], v[180:181]
	v_pk_mul_f32 v[28:29], v[28:29], v[172:173]
	v_pk_fma_f32 v[16:17], v[52:53], v[172:173], v[16:17]
	v_pk_fma_f32 v[28:29], v[52:53], v[180:181], v[28:29] neg_lo:[0,0,1] neg_hi:[0,0,1]
	v_sub_f32_e32 v6, v89, v179
	v_pk_add_f32 v[52:53], v[28:29], v[16:17] op_sel:[0,1] op_sel_hi:[1,0] neg_lo:[0,1]
	v_pk_add_f32 v[54:55], v[28:29], v[16:17] op_sel:[0,1] op_sel_hi:[1,0]
	v_pk_add_f32 v[16:17], v[16:17], v[28:29] op_sel:[1,0] op_sel_hi:[0,1] neg_lo:[0,1] neg_hi:[0,1]
	v_pk_mul_f32 v[52:53], v[52:53], 0.5 op_sel_hi:[1,0]
	v_mov_b32_e32 v55, v17
	v_mul_f32_e32 v4, v32, v52
	v_pk_fma_f32 v[56:57], v[50:51], v[52:53], v[4:5] op_sel_hi:[1,1,0] neg_lo:[1,0,0] neg_hi:[1,0,0]
	v_mul_f32_e32 v4, v32, v53
	v_pk_fma_f32 v[48:49], v[48:49], v[52:53], v[4:5] op_sel_hi:[1,1,0]
	v_pk_add_f32 v[28:29], v[88:89], v[178:179]
	v_mov_b32_e32 v56, v48
	v_pk_fma_f32 v[16:17], v[54:55], 0.5, v[48:49] op_sel_hi:[1,0,1] neg_lo:[0,0,1] neg_hi:[0,0,1]
	v_mov_b32_e32 v48, v12
	v_mov_b32_e32 v49, v88
	v_pk_mov_b32 v[12:13], v[12:13], v[178:179] op_sel:[1,0]
	v_mul_f32_e32 v18, 0.5, v29
	v_pk_add_f32 v[12:13], v[48:49], v[12:13] neg_lo:[0,1] neg_hi:[0,1]
	v_mul_f32_e32 v4, 0.5, v28
	v_pk_mul_f32 v[48:49], v[12:13], v[18:19]
	v_mov_b32_e32 v13, v32
	v_pk_fma_f32 v[50:51], v[50:51], v[48:49], v[48:49] op_sel:[0,1,0] op_sel_hi:[1,0,1]
	v_mov_b32_e32 v48, v49
	v_mov_b32_e32 v49, v18
	v_pk_mul_f32 v[48:49], v[12:13], v[48:49]
	v_pk_add_f32 v[52:53], v[4:5], v[50:51]
	v_mul_f32_e32 v6, 0.5, v6
	v_fma_f32 v53, v28, 0.5, -v50
	v_pk_add_f32 v[28:29], v[48:49], v[48:49] op_sel:[0,1] op_sel_hi:[0,1] neg_lo:[0,1] neg_hi:[0,1]
	v_pk_add_f32 v[48:49], v[6:7], v[28:29] op_sel_hi:[0,1] neg_hi:[0,1]
	v_pk_mul_f32 v[28:29], v[48:49], v[176:177]
	v_pk_mul_f32 v[48:49], v[48:49], v[174:175]
	v_pk_fma_f32 v[28:29], v[52:53], v[174:175], v[28:29]
	v_pk_fma_f32 v[48:49], v[52:53], v[176:177], v[48:49] neg_lo:[0,0,1] neg_hi:[0,0,1]
	v_pk_fma_f32 v[92:93], v[54:55], 0.5, v[56:57] op_sel_hi:[1,0,1]
	v_pk_add_f32 v[50:51], v[48:49], v[28:29] op_sel:[0,1] op_sel_hi:[1,0] neg_lo:[0,1]
	v_pk_add_f32 v[52:53], v[48:49], v[28:29] op_sel:[0,1] op_sel_hi:[1,0]
	v_mov_b32_e32 v17, v93
	v_pk_mul_f32 v[50:51], v[50:51], 0.5 op_sel_hi:[1,0]
	v_pk_mul_f32 v[64:65], v[16:17], s[6:7] op_sel_hi:[1,0]
	v_mul_f32_e32 v4, v12, v50
	v_pk_fma_f32 v[16:17], v[54:55], 0.5, v[56:57] op_sel_hi:[1,0,1] neg_lo:[1,0,0] neg_hi:[1,0,0]
	v_pk_fma_f32 v[54:55], v[12:13], v[50:51], v[4:5] op_sel_hi:[1,1,0] neg_lo:[1,0,0] neg_hi:[1,0,0]
	v_mov_b32_e32 v33, v12
	v_mul_f32_e32 v4, v12, v51
	v_pk_fma_f32 v[12:13], v[32:33], v[50:51], v[4:5] op_sel_hi:[1,1,0]
	v_pk_add_f32 v[28:29], v[28:29], v[48:49] op_sel:[1,0] op_sel_hi:[0,1] neg_lo:[0,1] neg_hi:[0,1]
	v_mov_b32_e32 v53, v29
	v_mov_b32_e32 v54, v12
	v_pk_fma_f32 v[12:13], v[52:53], 0.5, v[12:13] op_sel_hi:[1,0,1] neg_lo:[0,0,1] neg_hi:[0,0,1]
	v_pk_fma_f32 v[88:89], v[52:53], 0.5, v[54:55] op_sel_hi:[1,0,1]
	s_mov_b32 s79, s16
	v_mov_b32_e32 v13, v89
	v_pk_mul_f32 v[68:69], v[12:13], s[6:7] op_sel_hi:[1,0]
	v_pk_fma_f32 v[12:13], v[52:53], 0.5, v[54:55] op_sel_hi:[1,0,1] neg_lo:[1,0,0] neg_hi:[1,0,0]
	v_mov_b32_e32 v4, v83
	s_mov_b32 s17, s19
	v_pk_mul_f32 v[48:49], v[82:83], s[78:79] op_sel_hi:[0,1]
	v_pk_add_f32 v[28:29], v[96:97], v[162:163]
	v_pk_add_f32 v[32:33], v[96:97], v[162:163] neg_lo:[0,1] neg_hi:[0,1]
	v_pk_fma_f32 v[52:53], v[4:5], s[16:17], v[48:49] op_sel_hi:[0,1,1] neg_lo:[0,0,1] neg_hi:[0,0,1]
	v_mul_f32_e32 v12, 0.5, v33
	v_pk_fma_f32 v[50:51], v[4:5], s[16:17], v[48:49] op_sel_hi:[0,1,1]
	v_mov_b32_e32 v33, v29
	v_mul_f32_e32 v6, 0.5, v28
	v_mov_b32_e32 v54, v52
	v_mov_b32_e32 v55, v51
	v_pk_mul_f32 v[28:29], v[32:33], s[44:45]
	v_pk_mov_b32 v[56:57], v[50:51], v[52:53] op_sel:[1,0]
	v_pk_mul_f32 v[32:33], v[54:55], v[28:29] op_sel:[0,1] op_sel_hi:[1,0]
	v_pk_mul_f32 v[28:29], v[54:55], v[28:29]
	v_pk_add_f32 v[32:33], v[32:33], v[32:33] op_sel:[0,1] op_sel_hi:[0,1]
	v_pk_add_f32 v[58:59], v[6:7], v[32:33] op_sel_hi:[0,1] neg_hi:[0,1]
	v_pk_add_f32 v[28:29], v[28:29], v[28:29] op_sel:[0,1] op_sel_hi:[0,1] neg_lo:[0,1] neg_hi:[0,1]
	v_pk_add_f32 v[32:33], v[12:13], v[28:29] op_sel_hi:[0,1] neg_hi:[0,1]
	v_pk_mul_f32 v[28:29], v[32:33], v[166:167]
	v_pk_mul_f32 v[32:33], v[32:33], v[164:165]
	v_pk_fma_f32 v[28:29], v[58:59], v[164:165], v[28:29]
	v_pk_fma_f32 v[32:33], v[58:59], v[166:167], v[32:33] neg_lo:[0,0,1] neg_hi:[0,0,1]
	v_mov_b32_e32 v159, v66
	v_pk_add_f32 v[58:59], v[32:33], v[28:29] op_sel:[0,1] op_sel_hi:[1,0] neg_lo:[0,1]
	v_pk_add_f32 v[70:71], v[32:33], v[28:29] op_sel:[0,1] op_sel_hi:[1,0]
	v_pk_add_f32 v[28:29], v[28:29], v[32:33] op_sel:[1,0] op_sel_hi:[0,1] neg_lo:[0,1] neg_hi:[0,1]
	v_pk_mul_f32 v[58:59], v[58:59], 0.5 op_sel_hi:[1,0]
	v_mov_b32_e32 v71, v29
	v_mul_f32_e32 v6, v52, v58
	v_pk_fma_f32 v[72:73], v[54:55], v[58:59], v[6:7] op_sel_hi:[1,1,0] neg_lo:[1,0,0] neg_hi:[1,0,0]
	v_mul_f32_e32 v6, v52, v59
	v_pk_fma_f32 v[56:57], v[56:57], v[58:59], v[6:7] op_sel_hi:[1,1,0]
	v_sub_f32_e32 v12, v67, v153
	v_mov_b32_e32 v72, v56
	v_pk_fma_f32 v[28:29], v[70:71], 0.5, v[56:57] op_sel_hi:[1,0,1] neg_lo:[0,0,1] neg_hi:[0,0,1]
	v_pk_fma_f32 v[96:97], v[70:71], 0.5, v[72:73] op_sel_hi:[1,0,1]
	v_pk_mov_b32 v[56:57], v[48:49], v[152:153] op_sel:[1,0]
	v_mov_b32_e32 v29, v97
	v_pk_mul_f32 v[62:63], v[28:29], s[6:7] op_sel_hi:[1,0]
	v_pk_add_f32 v[28:29], v[66:67], v[152:153]
	v_pk_add_f32 v[56:57], v[158:159], v[56:57] neg_lo:[0,1] neg_hi:[0,1]
	v_mul_f32_e32 v18, 0.5, v29
	v_pk_mul_f32 v[58:59], v[56:57], v[18:19]
	v_mul_f32_e32 v6, 0.5, v28
	v_pk_fma_f32 v[54:55], v[54:55], v[58:59], v[58:59] op_sel:[0,1,0] op_sel_hi:[1,0,1]
	v_mov_b32_e32 v66, v56
	v_mov_b32_e32 v67, v52
	v_mov_b32_e32 v58, v59
	v_mov_b32_e32 v59, v18
	v_pk_mul_f32 v[58:59], v[66:67], v[58:59]
	v_pk_add_f32 v[66:67], v[6:7], v[54:55]
	v_mul_f32_e32 v12, 0.5, v12
	v_fma_f32 v67, v28, 0.5, -v54
	v_pk_add_f32 v[28:29], v[58:59], v[58:59] op_sel:[0,1] op_sel_hi:[0,1] neg_lo:[0,1] neg_hi:[0,1]
	v_pk_add_f32 v[54:55], v[12:13], v[28:29] op_sel_hi:[0,1] neg_hi:[0,1]
	v_pk_mul_f32 v[28:29], v[54:55], v[156:157]
	v_pk_mul_f32 v[54:55], v[54:55], v[154:155]
	v_pk_fma_f32 v[32:33], v[70:71], 0.5, v[72:73] op_sel_hi:[1,0,1] neg_lo:[1,0,0] neg_hi:[1,0,0]
	v_pk_fma_f32 v[58:59], v[66:67], v[154:155], v[28:29] neg_lo:[0,0,1] neg_hi:[0,0,1]
	v_pk_fma_f32 v[28:29], v[66:67], v[154:155], v[28:29]
	v_pk_fma_f32 v[70:71], v[66:67], v[156:157], v[54:55]
	v_pk_fma_f32 v[54:55], v[66:67], v[156:157], v[54:55] neg_lo:[0,0,1] neg_hi:[0,0,1]
	v_pk_add_f32 v[72:73], v[58:59], v[28:29] op_sel:[0,1] op_sel_hi:[1,0]
	v_pk_add_f32 v[66:67], v[70:71], v[54:55] op_sel_hi:[0,1] neg_lo:[0,1] neg_hi:[0,1]
	v_pk_add_f32 v[28:29], v[58:59], v[28:29] op_sel_hi:[0,1] neg_lo:[0,1] neg_hi:[0,1]
	v_pk_add_f32 v[54:55], v[70:71], v[54:55] op_sel:[0,1] op_sel_hi:[1,0]
	v_mov_b32_e32 v73, v67
	v_mov_b32_e32 v55, v29
	v_pk_mul_f32 v[28:29], v[54:55], 0.5 op_sel_hi:[1,0]
	v_mov_b32_e32 v133, v84
	v_pk_mul_f32 v[54:55], v[52:53], v[28:29] op_sel:[0,1] op_sel_hi:[0,0]
	v_pk_fma_f32 v[58:59], v[56:57], v[28:29], v[54:55] op_sel_hi:[0,1,1]
	v_pk_fma_f32 v[28:29], v[56:57], v[28:29], v[54:55] op_sel_hi:[0,1,1] neg_hi:[0,0,1]
	v_pk_fma_f32 v[54:55], v[72:73], 0.5, v[58:59] op_sel_hi:[1,0,1] neg_lo:[0,0,1] neg_hi:[0,0,1]
	v_pk_fma_f32 v[66:67], v[72:73], 0.5, v[28:29] op_sel_hi:[1,0,1]
	v_pk_add_f32 v[56:57], v[60:61], v[134:135] neg_lo:[0,1] neg_hi:[0,1]
	v_mov_b32_e32 v55, v67
	v_pk_mul_f32 v[90:91], v[54:55], s[6:7] op_sel_hi:[1,0]
	v_pk_add_f32 v[54:55], v[134:135], v[60:61]
	v_mul_f32_e32 v12, 0.5, v57
	v_mov_b32_e32 v57, v55
	v_mul_f32_e32 v6, 0.5, v54
	v_pk_mov_b32 v[58:59], v[52:53], v[50:51] op_sel:[1,0]
	v_pk_mul_f32 v[54:55], v[56:57], s[44:45]
	v_pk_fma_f32 v[28:29], v[72:73], 0.5, v[28:29] op_sel_hi:[1,0,1] neg_lo:[1,0,0] neg_hi:[1,0,0]
	v_pk_mul_f32 v[56:57], v[58:59], v[54:55] op_sel:[0,1] op_sel_hi:[1,0]
	v_pk_mul_f32 v[54:55], v[58:59], v[54:55]
	v_pk_add_f32 v[56:57], v[56:57], v[56:57] op_sel:[0,1] op_sel_hi:[0,1]
	v_pk_add_f32 v[60:61], v[6:7], v[56:57] op_sel_hi:[0,1] neg_hi:[0,1]
	v_pk_add_f32 v[54:55], v[54:55], v[54:55] op_sel:[0,1] op_sel_hi:[0,1] neg_lo:[0,1] neg_hi:[0,1]
	v_pk_add_f32 v[56:57], v[12:13], v[54:55] op_sel_hi:[0,1] neg_hi:[0,1]
	v_pk_mul_f32 v[54:55], v[56:57], v[142:143]
	v_pk_mul_f32 v[56:57], v[56:57], v[140:141]
	v_pk_fma_f32 v[54:55], v[60:61], v[140:141], v[54:55]
	v_pk_fma_f32 v[56:57], v[60:61], v[142:143], v[56:57] neg_lo:[0,0,1] neg_hi:[0,0,1]
	v_mov_b32_e32 v51, v53
	v_pk_add_f32 v[60:61], v[56:57], v[54:55] op_sel:[0,1] op_sel_hi:[1,0] neg_lo:[0,1]
	v_pk_add_f32 v[70:71], v[56:57], v[54:55] op_sel:[0,1] op_sel_hi:[1,0]
	v_pk_add_f32 v[54:55], v[54:55], v[56:57] op_sel:[1,0] op_sel_hi:[0,1] neg_lo:[0,1] neg_hi:[0,1]
	v_pk_mul_f32 v[60:61], v[60:61], 0.5 op_sel_hi:[1,0]
	v_mov_b32_e32 v71, v55
	v_mul_f32_e32 v6, v53, v60
	v_pk_fma_f32 v[72:73], v[58:59], v[60:61], v[6:7] op_sel_hi:[1,1,0] neg_lo:[1,0,0] neg_hi:[1,0,0]
	v_mul_f32_e32 v6, v53, v61
	v_pk_fma_f32 v[50:51], v[50:51], v[60:61], v[6:7] op_sel_hi:[1,1,0]
	v_pk_add_f32 v[54:55], v[118:119], v[84:85]
	v_mov_b32_e32 v72, v50
	v_mov_b32_e32 v49, v118
	v_pk_fma_f32 v[50:51], v[70:71], 0.5, v[50:51] op_sel_hi:[1,0,1] neg_lo:[0,0,1] neg_hi:[0,0,1]
	v_pk_fma_f32 v[60:61], v[70:71], 0.5, v[72:73] op_sel_hi:[1,0,1]
	v_mul_f32_e32 v18, 0.5, v55
	v_pk_add_f32 v[48:49], v[132:133], v[48:49] neg_lo:[0,1] neg_hi:[0,1]
	v_mov_b32_e32 v51, v61
	v_pk_mul_f32 v[56:57], v[48:49], v[18:19]
	v_pk_mul_f32 v[94:95], v[50:51], s[6:7] op_sel_hi:[1,0]
	v_pk_fma_f32 v[50:51], v[70:71], 0.5, v[72:73] op_sel_hi:[1,0,1] neg_lo:[1,0,0] neg_hi:[1,0,0]
	v_mul_f32_e32 v6, 0.5, v54
	v_pk_fma_f32 v[58:59], v[58:59], v[56:57], v[56:57] op_sel:[0,1,0] op_sel_hi:[1,0,1]
	v_mov_b32_e32 v70, v48
	v_mov_b32_e32 v71, v53
	v_mov_b32_e32 v56, v57
	v_mov_b32_e32 v57, v18
	v_sub_f32_e32 v12, v85, v119
	v_pk_mul_f32 v[56:57], v[70:71], v[56:57]
	v_pk_add_f32 v[70:71], v[6:7], v[58:59]
	v_mul_f32_e32 v12, 0.5, v12
	v_fma_f32 v71, v54, 0.5, -v58
	v_pk_add_f32 v[54:55], v[56:57], v[56:57] op_sel:[0,1] op_sel_hi:[0,1] neg_lo:[0,1] neg_hi:[0,1]
	v_pk_add_f32 v[56:57], v[12:13], v[54:55] op_sel_hi:[0,1] neg_hi:[0,1]
	v_pk_mul_f32 v[54:55], v[56:57], v[126:127]
	v_pk_mul_f32 v[56:57], v[56:57], v[124:125]
	v_pk_fma_f32 v[58:59], v[70:71], v[124:125], v[54:55] neg_lo:[0,0,1] neg_hi:[0,0,1]
	v_pk_fma_f32 v[54:55], v[70:71], v[124:125], v[54:55]
	v_pk_fma_f32 v[72:73], v[70:71], v[126:127], v[56:57]
	v_pk_fma_f32 v[56:57], v[70:71], v[126:127], v[56:57] neg_lo:[0,0,1] neg_hi:[0,0,1]
	v_pk_add_f32 v[70:71], v[58:59], v[54:55] op_sel:[0,1] op_sel_hi:[1,0]
	v_pk_add_f32 v[74:75], v[72:73], v[56:57] op_sel_hi:[0,1] neg_lo:[0,1] neg_hi:[0,1]
	v_pk_add_f32 v[54:55], v[58:59], v[54:55] op_sel_hi:[0,1] neg_lo:[0,1] neg_hi:[0,1]
	v_pk_add_f32 v[56:57], v[72:73], v[56:57] op_sel:[0,1] op_sel_hi:[1,0]
	v_mov_b32_e32 v71, v75
	v_mov_b32_e32 v57, v55
	v_pk_mul_f32 v[54:55], v[56:57], 0.5 op_sel_hi:[1,0]
	s_mov_b32 s78, s11
	v_pk_mul_f32 v[52:53], v[52:53], v[54:55] op_sel:[1,1] op_sel_hi:[1,0]
	s_mov_b32 s79, s8
	v_pk_fma_f32 v[56:57], v[48:49], v[54:55], v[52:53] op_sel_hi:[0,1,1]
	v_pk_fma_f32 v[48:49], v[48:49], v[54:55], v[52:53] op_sel_hi:[0,1,1] neg_hi:[0,0,1]
	s_nop 0
	v_pk_fma_f32 v[52:53], v[70:71], 0.5, v[56:57] op_sel_hi:[1,0,1] neg_lo:[0,0,1] neg_hi:[0,0,1]
	v_pk_fma_f32 v[84:85], v[70:71], 0.5, v[48:49] op_sel_hi:[1,0,1]
	s_mov_b32 s9, s11
	v_mov_b32_e32 v53, v85
	v_pk_mul_f32 v[80:81], v[52:53], s[6:7] op_sel_hi:[1,0]
	v_pk_mul_f32 v[118:119], v[82:83], s[78:79] op_sel_hi:[0,1]
	v_pk_add_f32 v[52:53], v[86:87], v[112:113]
	v_pk_add_f32 v[54:55], v[86:87], v[112:113] neg_lo:[0,1] neg_hi:[0,1]
	v_pk_fma_f32 v[58:59], v[4:5], s[8:9], v[118:119] op_sel_hi:[0,1,1] neg_lo:[0,0,1] neg_hi:[0,0,1]
	v_mul_f32_e32 v12, 0.5, v55
	v_pk_fma_f32 v[72:73], v[4:5], s[8:9], v[118:119] op_sel_hi:[0,1,1]
	v_mov_b32_e32 v55, v53
	v_mul_f32_e32 v6, 0.5, v52
	v_mov_b32_e32 v56, v58
	v_mov_b32_e32 v57, v73
	v_pk_mul_f32 v[52:53], v[54:55], s[44:45]
	v_pk_fma_f32 v[48:49], v[70:71], 0.5, v[48:49] op_sel_hi:[1,0,1] neg_lo:[1,0,0] neg_hi:[1,0,0]
	v_pk_mul_f32 v[54:55], v[56:57], v[52:53] op_sel:[0,1] op_sel_hi:[1,0]
	v_pk_mul_f32 v[52:53], v[56:57], v[52:53]
	v_pk_add_f32 v[54:55], v[54:55], v[54:55] op_sel:[0,1] op_sel_hi:[0,1]
	v_pk_add_f32 v[74:75], v[6:7], v[54:55] op_sel_hi:[0,1] neg_hi:[0,1]
	v_pk_add_f32 v[52:53], v[52:53], v[52:53] op_sel:[0,1] op_sel_hi:[0,1] neg_lo:[0,1] neg_hi:[0,1]
	v_pk_add_f32 v[54:55], v[12:13], v[52:53] op_sel_hi:[0,1] neg_hi:[0,1]
	v_pk_mul_f32 v[52:53], v[54:55], v[116:117]
	v_pk_mul_f32 v[54:55], v[54:55], v[114:115]
	v_pk_fma_f32 v[52:53], v[74:75], v[114:115], v[52:53]
	v_pk_fma_f32 v[54:55], v[74:75], v[116:117], v[54:55] neg_lo:[0,0,1] neg_hi:[0,0,1]
	v_pk_mov_b32 v[70:71], v[72:73], v[58:59] op_sel:[1,0]
	v_pk_add_f32 v[74:75], v[54:55], v[52:53] op_sel:[0,1] op_sel_hi:[1,0] neg_lo:[0,1]
	v_pk_add_f32 v[76:77], v[54:55], v[52:53] op_sel:[0,1] op_sel_hi:[1,0]
	v_pk_add_f32 v[52:53], v[52:53], v[54:55] op_sel:[1,0] op_sel_hi:[0,1] neg_lo:[0,1] neg_hi:[0,1]
	v_pk_mul_f32 v[74:75], v[74:75], 0.5 op_sel_hi:[1,0]
	v_mov_b32_e32 v77, v53
	v_mul_f32_e32 v6, v58, v74
	v_pk_fma_f32 v[112:113], v[56:57], v[74:75], v[6:7] op_sel_hi:[1,1,0] neg_lo:[1,0,0] neg_hi:[1,0,0]
	v_mul_f32_e32 v6, v58, v75
	v_pk_fma_f32 v[70:71], v[70:71], v[74:75], v[6:7] op_sel_hi:[1,1,0]
	v_pk_add_f32 v[54:55], v[34:35], v[110:111]
	v_mov_b32_e32 v112, v70
	v_pk_fma_f32 v[52:53], v[76:77], 0.5, v[70:71] op_sel_hi:[1,0,1] neg_lo:[0,0,1] neg_hi:[0,0,1]
	v_pk_fma_f32 v[86:87], v[76:77], 0.5, v[112:113] op_sel_hi:[1,0,1]
	v_sub_f32_e32 v12, v35, v111
	v_mov_b32_e32 v53, v87
	v_pk_mul_f32 v[78:79], v[52:53], s[6:7] op_sel_hi:[1,0]
	v_mul_f32_e32 v52, 0xbe47c5c2, v83
	v_mov_b32_e32 v53, v34
	v_pk_mov_b32 v[34:35], v[118:119], v[110:111] op_sel:[1,0]
	v_mul_f32_e32 v18, 0.5, v55
	v_pk_add_f32 v[34:35], v[52:53], v[34:35] neg_lo:[0,1] neg_hi:[0,1]
	v_mov_b32_e32 v71, v58
	v_pk_mul_f32 v[52:53], v[34:35], v[18:19]
	v_mov_b32_e32 v70, v34
	v_pk_fma_f32 v[56:57], v[56:57], v[52:53], v[52:53] op_sel:[0,1,0] op_sel_hi:[1,0,1]
	v_mov_b32_e32 v52, v53
	v_mov_b32_e32 v53, v18
	v_mul_f32_e32 v6, 0.5, v54
	v_pk_mul_f32 v[52:53], v[70:71], v[52:53]
	v_cvt_f32_f16_e32 v70, v46
	v_cvt_f32_f16_e32 v71, v47
	v_cvt_f32_f16_sdwa v47, v47 dst_sel:DWORD dst_unused:UNUSED_PAD src0_sel:WORD_1
	v_cvt_f32_f16_sdwa v46, v46 dst_sel:DWORD dst_unused:UNUSED_PAD src0_sel:WORD_1
	v_pk_fma_f32 v[74:75], v[76:77], 0.5, v[112:113] op_sel_hi:[1,0,1] neg_lo:[1,0,0] neg_hi:[1,0,0]
	v_mul_f32_e32 v12, 0.5, v12
	v_pk_add_f32 v[76:77], v[6:7], v[56:57]
	v_pk_add_f32 v[52:53], v[52:53], v[52:53] op_sel:[0,1] op_sel_hi:[0,1] neg_lo:[0,1] neg_hi:[0,1]
	v_fma_f32 v77, v54, 0.5, -v56
	v_pk_add_f32 v[54:55], v[12:13], v[52:53] op_sel_hi:[0,1] neg_hi:[0,1]
	v_pk_mul_f32 v[52:53], v[54:55], v[46:47]
	v_pk_mul_f32 v[54:55], v[54:55], v[70:71]
	v_pk_fma_f32 v[56:57], v[76:77], v[70:71], v[52:53] neg_lo:[0,0,1] neg_hi:[0,0,1]
	v_pk_fma_f32 v[52:53], v[76:77], v[70:71], v[52:53]
	v_pk_fma_f32 v[70:71], v[76:77], v[46:47], v[54:55]
	v_pk_fma_f32 v[46:47], v[76:77], v[46:47], v[54:55] neg_lo:[0,0,1] neg_hi:[0,0,1]
	v_pk_add_f32 v[54:55], v[56:57], v[52:53] op_sel:[0,1] op_sel_hi:[1,0]
	v_pk_add_f32 v[76:77], v[70:71], v[46:47] op_sel_hi:[0,1] neg_lo:[0,1] neg_hi:[0,1]
	v_pk_add_f32 v[52:53], v[56:57], v[52:53] op_sel_hi:[0,1] neg_lo:[0,1] neg_hi:[0,1]
	v_pk_add_f32 v[46:47], v[70:71], v[46:47] op_sel:[0,1] op_sel_hi:[1,0]
	v_mov_b32_e32 v55, v77
	v_mov_b32_e32 v47, v53
	v_pk_mul_f32 v[46:47], v[46:47], 0.5 op_sel_hi:[1,0]
	s_mov_b32 s25, s27
	v_pk_mul_f32 v[52:53], v[58:59], v[46:47] op_sel:[0,1] op_sel_hi:[0,0]
	v_pk_fma_f32 v[56:57], v[34:35], v[46:47], v[52:53] op_sel_hi:[0,1,1]
	v_pk_fma_f32 v[46:47], v[34:35], v[46:47], v[52:53] op_sel_hi:[0,1,1] neg_hi:[0,0,1]
	s_nop 0
	v_pk_fma_f32 v[52:53], v[54:55], 0.5, v[56:57] op_sel_hi:[1,0,1] neg_lo:[0,0,1] neg_hi:[0,0,1]
	v_pk_fma_f32 v[34:35], v[54:55], 0.5, v[46:47] op_sel_hi:[1,0,1]
	s_mov_b32 s78, s27
	v_mov_b32_e32 v53, v35
	v_pk_mul_f32 v[136:137], v[52:53], s[6:7] op_sel_hi:[1,0]
	v_pk_fma_f32 v[52:53], v[54:55], 0.5, v[46:47] op_sel_hi:[1,0,1] neg_lo:[1,0,0] neg_hi:[1,0,0]
	s_mov_b32 s79, s24
	v_pk_mul_f32 v[46:47], v[82:83], s[24:25] op_sel_hi:[0,1]
	v_pk_add_f32 v[54:55], v[108:109], v[40:41]
	v_pk_add_f32 v[40:41], v[40:41], v[108:109] neg_lo:[0,1] neg_hi:[0,1]
	v_pk_fma_f32 v[108:109], v[4:5], s[78:79], v[46:47] op_sel_hi:[0,1,1] neg_lo:[0,0,1] neg_hi:[0,0,1]
	v_mul_f32_e32 v12, 0.5, v41
	v_pk_fma_f32 v[70:71], v[4:5], s[78:79], v[46:47] op_sel_hi:[0,1,1]
	v_mov_b32_e32 v41, v55
	v_mov_b32_e32 v56, v108
	v_mov_b32_e32 v57, v71
	v_pk_mul_f32 v[40:41], v[40:41], s[44:45]
	v_mul_f32_e32 v6, 0.5, v54
	v_pk_mul_f32 v[54:55], v[56:57], v[40:41] op_sel:[0,1] op_sel_hi:[1,0]
	v_cvt_f32_f16_sdwa v76, v36 dst_sel:DWORD dst_unused:UNUSED_PAD src0_sel:WORD_1
	v_cvt_f32_f16_e32 v77, v37
	v_cvt_f32_f16_sdwa v37, v37 dst_sel:DWORD dst_unused:UNUSED_PAD src0_sel:WORD_1
	v_cvt_f32_f16_e32 v36, v36
	v_pk_mul_f32 v[40:41], v[56:57], v[40:41]
	v_pk_add_f32 v[54:55], v[54:55], v[54:55] op_sel:[0,1] op_sel_hi:[0,1]
	v_pk_add_f32 v[112:113], v[6:7], v[54:55] op_sel_hi:[0,1] neg_hi:[0,1]
	s_nop 0
	v_pk_add_f32 v[40:41], v[40:41], v[40:41] op_sel:[0,1] op_sel_hi:[0,1] neg_lo:[0,1] neg_hi:[0,1]
	v_pk_add_f32 v[54:55], v[12:13], v[40:41] op_sel_hi:[0,1] neg_hi:[0,1]
	v_pk_mul_f32 v[40:41], v[54:55], v[36:37]
	v_pk_mul_f32 v[54:55], v[54:55], v[76:77]
	v_pk_fma_f32 v[40:41], v[112:113], v[76:77], v[40:41]
	v_pk_fma_f32 v[36:37], v[112:113], v[36:37], v[54:55] neg_lo:[0,0,1] neg_hi:[0,0,1]
	v_pk_mov_b32 v[110:111], v[70:71], v[108:109] op_sel:[1,0]
	v_pk_add_f32 v[54:55], v[36:37], v[40:41] op_sel:[0,1] op_sel_hi:[1,0] neg_lo:[0,1]
	v_pk_add_f32 v[76:77], v[36:37], v[40:41] op_sel:[0,1] op_sel_hi:[1,0]
	v_pk_add_f32 v[36:37], v[40:41], v[36:37] op_sel:[1,0] op_sel_hi:[0,1] neg_lo:[0,1] neg_hi:[0,1]
	v_pk_mul_f32 v[54:55], v[54:55], 0.5 op_sel_hi:[1,0]
	v_mov_b32_e32 v77, v37
	v_mul_f32_e32 v4, v108, v54
	v_pk_fma_f32 v[112:113], v[56:57], v[54:55], v[4:5] op_sel_hi:[1,1,0] neg_lo:[1,0,0] neg_hi:[1,0,0]
	v_mul_f32_e32 v4, v108, v55
	v_pk_fma_f32 v[54:55], v[110:111], v[54:55], v[4:5] op_sel_hi:[1,1,0]
	v_sub_f32_e32 v6, v45, v105
	v_mov_b32_e32 v112, v54
	v_pk_fma_f32 v[40:41], v[76:77], 0.5, v[54:55] op_sel_hi:[1,0,1] neg_lo:[0,0,1] neg_hi:[0,0,1]
	v_pk_fma_f32 v[36:37], v[76:77], 0.5, v[112:113] op_sel_hi:[1,0,1]
	v_pk_add_f32 v[54:55], v[104:105], v[44:45]
	v_mov_b32_e32 v41, v37
	v_pk_mul_f32 v[130:131], v[40:41], s[6:7] op_sel_hi:[1,0]
	v_mul_f32_e32 v40, 0xbf54db31, v83
	v_mov_b32_e32 v41, v44
	v_pk_mov_b32 v[44:45], v[46:47], v[104:105] op_sel:[1,0]
	v_mul_f32_e32 v18, 0.5, v55
	v_pk_add_f32 v[40:41], v[40:41], v[44:45] neg_lo:[0,1] neg_hi:[0,1]
	v_mov_b32_e32 v105, v108
	v_pk_mul_f32 v[44:45], v[40:41], v[18:19]
	v_mov_b32_e32 v104, v40
	v_pk_fma_f32 v[56:57], v[56:57], v[44:45], v[44:45] op_sel:[0,1,0] op_sel_hi:[1,0,1]
	v_mov_b32_e32 v44, v45
	v_mov_b32_e32 v45, v18
	v_mul_f32_e32 v4, 0.5, v54
	v_pk_mul_f32 v[44:45], v[104:105], v[44:45]
	v_cvt_f32_f16_e32 v104, v26
	v_cvt_f32_f16_e32 v105, v27
	v_cvt_f32_f16_sdwa v27, v27 dst_sel:DWORD dst_unused:UNUSED_PAD src0_sel:WORD_1
	v_cvt_f32_f16_sdwa v26, v26 dst_sel:DWORD dst_unused:UNUSED_PAD src0_sel:WORD_1
	v_mul_f32_e32 v6, 0.5, v6
	v_pk_add_f32 v[110:111], v[4:5], v[56:57]
	v_pk_add_f32 v[44:45], v[44:45], v[44:45] op_sel:[0,1] op_sel_hi:[0,1] neg_lo:[0,1] neg_hi:[0,1]
	v_fma_f32 v111, v54, 0.5, -v56
	v_pk_add_f32 v[54:55], v[6:7], v[44:45] op_sel_hi:[0,1] neg_hi:[0,1]
	v_pk_mul_f32 v[44:45], v[54:55], v[26:27]
	v_pk_mul_f32 v[54:55], v[54:55], v[104:105]
	v_pk_fma_f32 v[56:57], v[110:111], v[104:105], v[44:45] neg_lo:[0,0,1] neg_hi:[0,0,1]
	v_pk_fma_f32 v[44:45], v[110:111], v[104:105], v[44:45]
	v_pk_fma_f32 v[104:105], v[110:111], v[26:27], v[54:55]
	v_pk_fma_f32 v[26:27], v[110:111], v[26:27], v[54:55] neg_lo:[0,0,1] neg_hi:[0,0,1]
	v_pk_add_f32 v[54:55], v[56:57], v[44:45] op_sel:[0,1] op_sel_hi:[1,0]
	v_pk_add_f32 v[110:111], v[104:105], v[26:27] op_sel_hi:[0,1] neg_lo:[0,1] neg_hi:[0,1]
	v_pk_add_f32 v[44:45], v[56:57], v[44:45] op_sel_hi:[0,1] neg_lo:[0,1] neg_hi:[0,1]
	v_pk_add_f32 v[26:27], v[104:105], v[26:27] op_sel:[0,1] op_sel_hi:[1,0]
	v_mov_b32_e32 v55, v111
	v_mov_b32_e32 v27, v45
	v_pk_mul_f32 v[26:27], v[26:27], 0.5 op_sel_hi:[1,0]
	v_mov_b32_e32 v47, v102
	v_pk_mul_f32 v[44:45], v[108:109], v[26:27] op_sel:[0,1] op_sel_hi:[0,0]
	v_pk_fma_f32 v[56:57], v[40:41], v[26:27], v[44:45] op_sel_hi:[0,1,1]
	v_pk_fma_f32 v[40:41], v[40:41], v[26:27], v[44:45] op_sel_hi:[0,1,1] neg_hi:[0,0,1]
	v_pk_fma_f32 v[44:45], v[54:55], 0.5, v[56:57] op_sel_hi:[1,0,1] neg_lo:[0,0,1] neg_hi:[0,0,1]
	v_pk_fma_f32 v[26:27], v[54:55], 0.5, v[40:41] op_sel_hi:[1,0,1]
	v_pk_fma_f32 v[56:57], v[54:55], 0.5, v[40:41] op_sel_hi:[1,0,1] neg_lo:[1,0,0] neg_hi:[1,0,0]
	v_pk_add_f32 v[40:41], v[106:107], v[42:43]
	v_pk_add_f32 v[42:43], v[42:43], v[106:107] neg_lo:[0,1] neg_hi:[0,1]
	v_mov_b32_e32 v45, v27
	v_mul_f32_e32 v6, 0.5, v43
	v_mov_b32_e32 v43, v41
	v_pk_mul_f32 v[120:121], v[44:45], s[6:7] op_sel_hi:[1,0]
	v_mul_f32_e32 v4, 0.5, v40
	v_pk_mov_b32 v[44:45], v[108:109], v[70:71] op_sel:[1,0]
	v_pk_mul_f32 v[40:41], v[42:43], s[44:45]
	v_cvt_f32_f16_sdwa v54, v20 dst_sel:DWORD dst_unused:UNUSED_PAD src0_sel:WORD_1
	v_pk_mul_f32 v[42:43], v[44:45], v[40:41] op_sel:[0,1] op_sel_hi:[1,0]
	v_cvt_f32_f16_e32 v55, v21
	v_cvt_f32_f16_sdwa v21, v21 dst_sel:DWORD dst_unused:UNUSED_PAD src0_sel:WORD_1
	v_cvt_f32_f16_e32 v20, v20
	v_pk_mul_f32 v[40:41], v[44:45], v[40:41]
	v_pk_add_f32 v[42:43], v[42:43], v[42:43] op_sel:[0,1] op_sel_hi:[0,1]
	v_pk_add_f32 v[104:105], v[4:5], v[42:43] op_sel_hi:[0,1] neg_hi:[0,1]
	s_nop 0
	v_pk_add_f32 v[40:41], v[40:41], v[40:41] op_sel:[0,1] op_sel_hi:[0,1] neg_lo:[0,1] neg_hi:[0,1]
	v_pk_add_f32 v[42:43], v[6:7], v[40:41] op_sel_hi:[0,1] neg_hi:[0,1]
	v_pk_mul_f32 v[40:41], v[42:43], v[20:21]
	v_pk_mul_f32 v[42:43], v[42:43], v[54:55]
	v_pk_fma_f32 v[40:41], v[104:105], v[54:55], v[40:41]
	v_pk_fma_f32 v[20:21], v[104:105], v[20:21], v[42:43] neg_lo:[0,0,1] neg_hi:[0,0,1]
	v_mov_b32_e32 v71, v109
	v_pk_add_f32 v[42:43], v[20:21], v[40:41] op_sel:[0,1] op_sel_hi:[1,0] neg_lo:[0,1]
	v_pk_add_f32 v[54:55], v[20:21], v[40:41] op_sel:[0,1] op_sel_hi:[1,0]
	v_pk_add_f32 v[20:21], v[40:41], v[20:21] op_sel:[1,0] op_sel_hi:[0,1] neg_lo:[0,1] neg_hi:[0,1]
	v_pk_mul_f32 v[42:43], v[42:43], 0.5 op_sel_hi:[1,0]
	v_mov_b32_e32 v55, v21
	v_mul_f32_e32 v4, v109, v42
	v_pk_fma_f32 v[104:105], v[44:45], v[42:43], v[4:5] op_sel_hi:[1,1,0] neg_lo:[1,0,0] neg_hi:[1,0,0]
	v_mul_f32_e32 v4, v109, v43
	v_pk_fma_f32 v[42:43], v[70:71], v[42:43], v[4:5] op_sel_hi:[1,1,0]
	v_sub_f32_e32 v6, v23, v103
	v_mov_b32_e32 v104, v42
	v_pk_fma_f32 v[40:41], v[54:55], 0.5, v[42:43] op_sel_hi:[1,0,1] neg_lo:[0,0,1] neg_hi:[0,0,1]
	v_pk_fma_f32 v[20:21], v[54:55], 0.5, v[104:105] op_sel_hi:[1,0,1]
	v_pk_add_f32 v[42:43], v[102:103], v[22:23]
	v_mov_b32_e32 v41, v21
	v_pk_mul_f32 v[128:129], v[40:41], s[6:7] op_sel_hi:[1,0]
	v_mul_f32_e32 v40, 0xbf0e39da, v83
	v_mov_b32_e32 v41, v22
	v_mul_f32_e32 v18, 0.5, v43
	v_pk_add_f32 v[22:23], v[40:41], v[46:47] neg_lo:[0,1] neg_hi:[0,1]
	v_mov_b32_e32 v47, v109
	v_pk_mul_f32 v[40:41], v[22:23], v[18:19]
	v_mov_b32_e32 v46, v22
	v_pk_fma_f32 v[44:45], v[44:45], v[40:41], v[40:41] op_sel:[0,1,0] op_sel_hi:[1,0,1]
	v_mov_b32_e32 v40, v41
	v_mov_b32_e32 v41, v18
	v_mul_f32_e32 v4, 0.5, v42
	v_pk_mul_f32 v[40:41], v[46:47], v[40:41]
	v_cvt_f32_f16_e32 v46, v10
	v_cvt_f32_f16_e32 v47, v11
	v_cvt_f32_f16_sdwa v11, v11 dst_sel:DWORD dst_unused:UNUSED_PAD src0_sel:WORD_1
	v_cvt_f32_f16_sdwa v10, v10 dst_sel:DWORD dst_unused:UNUSED_PAD src0_sel:WORD_1
	v_pk_fma_f32 v[70:71], v[54:55], 0.5, v[104:105] op_sel_hi:[1,0,1] neg_lo:[1,0,0] neg_hi:[1,0,0]
	v_mul_f32_e32 v6, 0.5, v6
	v_pk_add_f32 v[54:55], v[4:5], v[44:45]
	v_pk_add_f32 v[40:41], v[40:41], v[40:41] op_sel:[0,1] op_sel_hi:[0,1] neg_lo:[0,1] neg_hi:[0,1]
	v_fma_f32 v55, v42, 0.5, -v44
	v_pk_add_f32 v[42:43], v[6:7], v[40:41] op_sel_hi:[0,1] neg_hi:[0,1]
	v_pk_mul_f32 v[40:41], v[42:43], v[10:11]
	v_pk_mul_f32 v[42:43], v[42:43], v[46:47]
	v_pk_fma_f32 v[44:45], v[54:55], v[46:47], v[40:41] neg_lo:[0,0,1] neg_hi:[0,0,1]
	v_pk_fma_f32 v[40:41], v[54:55], v[46:47], v[40:41]
	v_pk_fma_f32 v[46:47], v[54:55], v[10:11], v[42:43]
	v_pk_fma_f32 v[10:11], v[54:55], v[10:11], v[42:43] neg_lo:[0,0,1] neg_hi:[0,0,1]
	v_pk_add_f32 v[42:43], v[44:45], v[40:41] op_sel:[0,1] op_sel_hi:[1,0]
	v_pk_add_f32 v[54:55], v[46:47], v[10:11] op_sel_hi:[0,1] neg_lo:[0,1] neg_hi:[0,1]
	v_pk_add_f32 v[40:41], v[44:45], v[40:41] op_sel_hi:[0,1] neg_lo:[0,1] neg_hi:[0,1]
	v_pk_add_f32 v[10:11], v[46:47], v[10:11] op_sel:[0,1] op_sel_hi:[1,0]
	v_mov_b32_e32 v43, v55
	v_mov_b32_e32 v11, v41
	v_pk_mul_f32 v[10:11], v[10:11], 0.5 op_sel_hi:[1,0]
	v_mov_b32_e32 v119, v98
	v_pk_mul_f32 v[40:41], v[108:109], v[10:11] op_sel:[1,1] op_sel_hi:[1,0]
	v_pk_fma_f32 v[76:77], v[76:77], 0.5, v[112:113] op_sel_hi:[1,0,1] neg_lo:[1,0,0] neg_hi:[1,0,0]
	v_pk_fma_f32 v[44:45], v[22:23], v[10:11], v[40:41] op_sel_hi:[0,1,1]
	v_pk_fma_f32 v[10:11], v[22:23], v[10:11], v[40:41] op_sel_hi:[0,1,1] neg_hi:[0,0,1]
	v_pk_fma_f32 v[22:23], v[42:43], 0.5, v[44:45] op_sel_hi:[1,0,1] neg_lo:[0,0,1] neg_hi:[0,0,1]
	v_pk_fma_f32 v[40:41], v[42:43], 0.5, v[10:11] op_sel_hi:[1,0,1]
	v_pk_fma_f32 v[54:55], v[42:43], 0.5, v[10:11] op_sel_hi:[1,0,1] neg_lo:[1,0,0] neg_hi:[1,0,0]
	v_pk_add_f32 v[10:11], v[100:101], v[14:15]
	v_pk_add_f32 v[14:15], v[14:15], v[100:101] neg_lo:[0,1] neg_hi:[0,1]
	v_mov_b32_e32 v23, v41
	v_mul_f32_e32 v6, 0.5, v15
	v_mov_b32_e32 v15, v11
	v_pk_mul_f32 v[150:151], v[22:23], s[6:7] op_sel_hi:[1,0]
	v_mul_f32_e32 v4, 0.5, v10
	v_pk_mov_b32 v[22:23], v[58:59], v[72:73] op_sel:[1,0]
	v_pk_mul_f32 v[10:11], v[14:15], s[44:45]
	v_cvt_f32_f16_sdwa v42, v8 dst_sel:DWORD dst_unused:UNUSED_PAD src0_sel:WORD_1
	v_pk_mul_f32 v[14:15], v[22:23], v[10:11] op_sel:[0,1] op_sel_hi:[1,0]
	v_cvt_f32_f16_e32 v43, v9
	v_cvt_f32_f16_sdwa v9, v9 dst_sel:DWORD dst_unused:UNUSED_PAD src0_sel:WORD_1
	v_cvt_f32_f16_e32 v8, v8
	v_pk_mul_f32 v[10:11], v[22:23], v[10:11]
	v_pk_add_f32 v[14:15], v[14:15], v[14:15] op_sel:[0,1] op_sel_hi:[0,1]
	v_pk_add_f32 v[44:45], v[4:5], v[14:15] op_sel_hi:[0,1] neg_hi:[0,1]
	s_nop 0
	v_pk_add_f32 v[10:11], v[10:11], v[10:11] op_sel:[0,1] op_sel_hi:[0,1] neg_lo:[0,1] neg_hi:[0,1]
	v_pk_add_f32 v[14:15], v[6:7], v[10:11] op_sel_hi:[0,1] neg_hi:[0,1]
	v_pk_mul_f32 v[10:11], v[14:15], v[8:9]
	v_pk_mul_f32 v[14:15], v[14:15], v[42:43]
	v_pk_fma_f32 v[10:11], v[44:45], v[42:43], v[10:11]
	v_pk_fma_f32 v[8:9], v[44:45], v[8:9], v[14:15] neg_lo:[0,0,1] neg_hi:[0,0,1]
	v_mov_b32_e32 v73, v59
	v_pk_add_f32 v[14:15], v[8:9], v[10:11] op_sel:[0,1] op_sel_hi:[1,0] neg_lo:[0,1]
	v_pk_add_f32 v[42:43], v[8:9], v[10:11] op_sel:[0,1] op_sel_hi:[1,0]
	v_pk_add_f32 v[8:9], v[10:11], v[8:9] op_sel:[1,0] op_sel_hi:[0,1] neg_lo:[0,1] neg_hi:[0,1]
	v_pk_mul_f32 v[14:15], v[14:15], 0.5 op_sel_hi:[1,0]
	v_mov_b32_e32 v43, v9
	v_mul_f32_e32 v4, v59, v14
	v_pk_fma_f32 v[44:45], v[22:23], v[14:15], v[4:5] op_sel_hi:[1,1,0] neg_lo:[1,0,0] neg_hi:[1,0,0]
	v_mul_f32_e32 v4, v59, v15
	v_pk_fma_f32 v[14:15], v[72:73], v[14:15], v[4:5] op_sel_hi:[1,1,0]
	v_sub_f32_e32 v6, v39, v99
	v_mov_b32_e32 v44, v14
	v_pk_fma_f32 v[8:9], v[42:43], 0.5, v[14:15] op_sel_hi:[1,0,1] neg_lo:[0,0,1] neg_hi:[0,0,1]
	v_pk_fma_f32 v[10:11], v[42:43], 0.5, v[44:45] op_sel_hi:[1,0,1]
	v_pk_add_f32 v[14:15], v[98:99], v[38:39]
	v_mov_b32_e32 v9, v11
	v_pk_mul_f32 v[168:169], v[8:9], s[6:7] op_sel_hi:[1,0]
	v_mul_f32_e32 v8, 0xbf7b14be, v83
	v_mov_b32_e32 v9, v38
	v_mul_f32_e32 v18, 0.5, v15
	v_pk_add_f32 v[8:9], v[8:9], v[118:119] neg_lo:[0,1] neg_hi:[0,1]
	v_pk_fma_f32 v[72:73], v[42:43], 0.5, v[44:45] op_sel_hi:[1,0,1] neg_lo:[1,0,0] neg_hi:[1,0,0]
	v_pk_mul_f32 v[38:39], v[8:9], v[18:19]
	v_mov_b32_e32 v42, v8
	v_pk_fma_f32 v[22:23], v[22:23], v[38:39], v[38:39] op_sel:[0,1,0] op_sel_hi:[1,0,1]
	v_mov_b32_e32 v43, v59
	v_mov_b32_e32 v38, v39
	v_mov_b32_e32 v39, v18
	v_mul_f32_e32 v4, 0.5, v14
	v_pk_mul_f32 v[38:39], v[42:43], v[38:39]
	v_cvt_f32_f16_e32 v44, v2
	v_cvt_f32_f16_e32 v45, v3
	v_cvt_f32_f16_sdwa v3, v3 dst_sel:DWORD dst_unused:UNUSED_PAD src0_sel:WORD_1
	v_cvt_f32_f16_sdwa v2, v2 dst_sel:DWORD dst_unused:UNUSED_PAD src0_sel:WORD_1
	v_mul_f32_e32 v6, 0.5, v6
	v_pk_add_f32 v[46:47], v[4:5], v[22:23]
	v_fma_f32 v4, v14, 0.5, -v22
	v_pk_add_f32 v[22:23], v[38:39], v[38:39] op_sel:[0,1] op_sel_hi:[0,1] neg_lo:[0,1] neg_hi:[0,1]
	v_pk_add_f32 v[38:39], v[6:7], v[22:23] op_sel_hi:[0,1] neg_hi:[0,1]
	v_mov_b32_e32 v14, v46
	v_mov_b32_e32 v15, v4
	v_pk_mul_f32 v[22:23], v[4:5], v[44:45] op_sel_hi:[0,1]
	v_pk_mul_f32 v[82:83], v[38:39], v[2:3]
	v_pk_mul_f32 v[46:47], v[46:47], v[2:3]
	v_pk_mul_f32 v[38:39], v[38:39], v[44:45]
	v_pk_fma_f32 v[98:99], v[14:15], v[44:45], v[82:83] neg_lo:[0,0,1] neg_hi:[0,0,1]
	v_pk_fma_f32 v[2:3], v[14:15], v[2:3], v[38:39] neg_lo:[0,0,1] neg_hi:[0,0,1]
	v_add_f32_e32 v4, v23, v83
	v_add_f32_e32 v6, v46, v38
	v_pk_add_f32 v[22:23], v[6:7], v[2:3] op_sel_hi:[0,1] neg_lo:[0,1] neg_hi:[0,1]
	v_pk_add_f32 v[38:39], v[98:99], v[4:5] op_sel_hi:[1,0] neg_lo:[0,1] neg_hi:[0,1]
	v_pk_add_f32 v[2:3], v[6:7], v[2:3] op_sel_hi:[0,1]
	v_mov_b32_e32 v39, v3
	v_pk_mul_f32 v[2:3], v[38:39], 0.5 op_sel_hi:[1,0]
	v_pk_add_f32 v[14:15], v[98:99], v[4:5] op_sel_hi:[1,0]
	v_mul_f32_e32 v4, v59, v3
	v_pk_fma_f32 v[38:39], v[42:43], v[2:3], v[4:5] op_sel_hi:[1,1,0] neg_lo:[0,0,1] neg_hi:[0,0,1]
	v_pk_mov_b32 v[42:43], v[58:59], v[8:9] op_sel:[1,0]
	v_mul_f32_e32 v4, v8, v3
	v_pk_fma_f32 v[2:3], v[42:43], v[2:3], v[4:5] op_sel_hi:[1,1,0]
	v_mov_b32_e32 v15, v23
	v_pk_fma_f32 v[8:9], v[14:15], 0.5, v[2:3] op_sel_hi:[1,0,1] neg_lo:[0,0,1] neg_hi:[0,0,1]
	v_pk_fma_f32 v[42:43], v[14:15], 0.5, v[38:39] op_sel_hi:[1,0,0]
	v_pk_fma_f32 v[2:3], v[14:15], 0.5, v[2:3] op_sel_hi:[1,0,1]
	v_mov_b32_e32 v9, v43
	v_pk_fma_f32 v[58:59], v[22:23], 0.5, v[38:39] op_sel_hi:[1,0,0] neg_lo:[1,0,0] neg_hi:[1,0,0]
	v_pk_mul_f32 v[144:145], v[8:9], s[6:7] op_sel_hi:[1,0]
	v_mov_b32_e32 v58, v2
	v_mov_b32_e32 v72, v10
	v_mov_b32_e32 v54, v40
	v_mov_b32_e32 v70, v20
	v_mov_b32_e32 v56, v26
	v_mov_b32_e32 v76, v36
	v_mov_b32_e32 v52, v34
	v_mov_b32_e32 v74, v86
	v_mov_b32_e32 v48, v84
	v_mov_b32_e32 v50, v60
	v_mov_b32_e32 v28, v66
	v_mov_b32_e32 v32, v96
	v_mov_b32_e32 v12, v88
	v_mov_b32_e32 v16, v92
	v_mov_b32_e32 v4, v138
	v_mov_b32_e32 v6, v122
.LBB0_501:
	s_andn2_saveexec_b64 s[0:1], s[0:1]
	s_cbranch_execz .LBB0_503
	v_pk_add_f32 v[4:5], v[98:99], v[196:197]
	v_pk_add_f32 v[6:7], v[98:99], v[196:197] neg_lo:[0,1] neg_hi:[0,1]
	v_mul_f32_e32 v4, 0.5, v4
	v_mul_f32_e32 v12, 0.5, v7
	v_mov_b32_e32 v7, v5
	v_pk_mul_f32 v[6:7], v[6:7], s[44:45]
	v_pk_mov_b32 v[16:17], v[198:199], v[160:161] op_sel:[1,0]
	v_pk_mul_f32 v[24:25], v[190:191], v[6:7] op_sel:[0,1] op_sel_hi:[1,0]
	v_pk_mul_f32 v[6:7], v[190:191], v[6:7]
	v_pk_add_f32 v[24:25], v[24:25], v[24:25] op_sel:[0,1] op_sel_hi:[0,1]
	v_pk_add_f32 v[28:29], v[4:5], v[24:25] op_sel_hi:[0,1] neg_hi:[0,1]
	v_pk_add_f32 v[4:5], v[6:7], v[6:7] op_sel:[0,1] op_sel_hi:[0,1] neg_lo:[0,1] neg_hi:[0,1]
	v_pk_add_f32 v[6:7], v[12:13], v[4:5] op_sel_hi:[0,1] neg_hi:[0,1]
	v_pk_mul_f32 v[4:5], v[6:7], v[194:195]
	v_pk_mul_f32 v[6:7], v[6:7], v[192:193]
	v_pk_fma_f32 v[4:5], v[28:29], v[192:193], v[4:5]
	v_pk_fma_f32 v[6:7], v[28:29], v[194:195], v[6:7] neg_lo:[0,0,1] neg_hi:[0,0,1]
	s_mov_b32 s78, s19
	v_pk_add_f32 v[12:13], v[6:7], v[4:5] op_sel:[0,1] op_sel_hi:[1,0] neg_lo:[0,1]
	v_pk_add_f32 v[24:25], v[6:7], v[4:5] op_sel:[0,1] op_sel_hi:[1,0]
	v_pk_add_f32 v[4:5], v[4:5], v[6:7] op_sel:[1,0] op_sel_hi:[0,1] neg_lo:[0,1] neg_hi:[0,1]
	s_nop 0
	v_pk_mul_f32 v[12:13], v[12:13], 0.5 op_sel_hi:[1,0]
	v_mov_b32_e32 v25, v5
	v_mul_f32_e32 v28, v191, v13
	v_mul_f32_e32 v30, v160, v13
	v_pk_fma_f32 v[28:29], v[190:191], v[12:13], v[28:29] op_sel_hi:[1,1,0] neg_lo:[0,0,1] neg_hi:[0,0,1]
	v_pk_fma_f32 v[12:13], v[16:17], v[12:13], v[30:31] op_sel_hi:[1,1,0]
	v_mov_b32_e32 v7, v28
	v_mov_b32_e32 v6, v12
	v_pk_fma_f32 v[58:59], v[24:25], 0.5, v[12:13] op_sel_hi:[1,0,1] neg_lo:[0,0,1] neg_hi:[0,0,1]
	v_pk_fma_f32 v[98:99], v[24:25], 0.5, v[6:7] op_sel_hi:[1,0,1]
	v_pk_fma_f32 v[6:7], v[24:25], 0.5, v[12:13] op_sel_hi:[1,0,1]
	v_pk_fma_f32 v[160:161], v[4:5], 0.5, v[28:29] op_sel_hi:[1,0,0] neg_lo:[1,0,0] neg_hi:[1,0,0]
	v_pk_add_f32 v[4:5], v[100:101], v[188:189]
	v_pk_add_f32 v[12:13], v[100:101], v[188:189] neg_lo:[0,1] neg_hi:[0,1]
	v_mov_b32_e32 v24, v83
	v_mov_b32_e32 v25, v82
	v_mul_f32_e32 v16, 0.5, v13
	v_pk_add_f32 v[28:29], v[186:187], v[24:25] neg_lo:[0,1] neg_hi:[0,1]
	v_pk_add_f32 v[30:31], v[186:187], v[24:25]
	v_mov_b32_e32 v13, v5
	v_pk_mov_b32 v[32:33], v[28:29], v[30:31] op_sel:[1,0]
	v_pk_mul_f32 v[12:13], v[12:13], s[44:45]
	v_mul_f32_e32 v4, 0.5, v4
	v_pk_mul_f32 v[48:49], v[32:33], v[12:13] op_sel:[0,1] op_sel_hi:[1,0]
	v_pk_mul_f32 v[12:13], v[32:33], v[12:13]
	v_pk_add_f32 v[48:49], v[48:49], v[48:49] op_sel:[0,1] op_sel_hi:[0,1]
	v_pk_add_f32 v[50:51], v[4:5], v[48:49] op_sel_hi:[0,1] neg_hi:[0,1]
	v_pk_add_f32 v[4:5], v[12:13], v[12:13] op_sel:[0,1] op_sel_hi:[0,1] neg_lo:[0,1] neg_hi:[0,1]
	v_pk_add_f32 v[12:13], v[16:17], v[4:5] op_sel_hi:[0,1] neg_hi:[0,1]
	v_pk_mul_f32 v[4:5], v[12:13], v[184:185]
	v_pk_mul_f32 v[12:13], v[12:13], v[170:171]
	v_pk_fma_f32 v[4:5], v[50:51], v[170:171], v[4:5]
	v_pk_fma_f32 v[12:13], v[50:51], v[184:185], v[12:13] neg_lo:[0,0,1] neg_hi:[0,0,1]
	v_mov_b32_e32 v31, v29
	v_pk_add_f32 v[16:17], v[12:13], v[4:5] op_sel:[0,1] op_sel_hi:[1,0] neg_lo:[0,1]
	v_pk_add_f32 v[48:49], v[12:13], v[4:5] op_sel:[0,1] op_sel_hi:[1,0]
	v_pk_add_f32 v[12:13], v[4:5], v[12:13] op_sel:[1,0] op_sel_hi:[0,1] neg_lo:[0,1] neg_hi:[0,1]
	v_pk_mul_f32 v[16:17], v[16:17], 0.5 op_sel_hi:[1,0]
	v_mov_b32_e32 v49, v13
	v_mul_f32_e32 v28, v30, v17
	v_pk_fma_f32 v[32:33], v[32:33], v[16:17], v[28:29] op_sel_hi:[1,1,0] neg_lo:[0,0,1] neg_hi:[0,0,1]
	v_mul_f32_e32 v28, v29, v17
	v_pk_fma_f32 v[16:17], v[30:31], v[16:17], v[28:29] op_sel_hi:[1,1,0]
	v_mov_b32_e32 v5, v32
	v_mov_b32_e32 v4, v16
	v_pk_fma_f32 v[72:73], v[48:49], 0.5, v[16:17] op_sel_hi:[1,0,1] neg_lo:[0,0,1] neg_hi:[0,0,1]
	v_pk_fma_f32 v[100:101], v[48:49], 0.5, v[4:5] op_sel_hi:[1,0,1]
	v_pk_fma_f32 v[4:5], v[48:49], 0.5, v[16:17] op_sel_hi:[1,0,1]
	v_pk_fma_f32 v[170:171], v[12:13], 0.5, v[32:33] op_sel_hi:[1,0,0] neg_lo:[1,0,0] neg_hi:[1,0,0]
	v_pk_mul_f32 v[12:13], v[24:25], s[36:37]
	v_pk_add_f32 v[16:17], v[102:103], v[182:183]
	v_pk_add_f32 v[24:25], v[102:103], v[182:183] neg_lo:[0,1] neg_hi:[0,1]
	v_pk_add_f32 v[30:31], v[18:19], v[12:13] op_sel:[0,1] op_sel_hi:[0,1] neg_lo:[0,1] neg_hi:[0,1]
	v_mul_f32_e32 v28, 0.5, v25
	v_pk_add_f32 v[32:33], v[18:19], v[12:13] op_sel:[0,1] op_sel_hi:[0,1]
	v_mov_b32_e32 v25, v17
	v_mov_b32_e32 v48, v30
	v_mov_b32_e32 v49, v33
	v_pk_mul_f32 v[24:25], v[24:25], s[44:45]
	v_mul_f32_e32 v16, 0.5, v16
	v_pk_mul_f32 v[52:53], v[48:49], v[24:25] op_sel:[0,1] op_sel_hi:[1,0]
	v_pk_mul_f32 v[24:25], v[48:49], v[24:25]
	v_pk_add_f32 v[52:53], v[52:53], v[52:53] op_sel:[0,1] op_sel_hi:[0,1]
	v_pk_add_f32 v[54:55], v[16:17], v[52:53] op_sel_hi:[0,1] neg_hi:[0,1]
	v_pk_add_f32 v[16:17], v[24:25], v[24:25] op_sel:[0,1] op_sel_hi:[0,1] neg_lo:[0,1] neg_hi:[0,1]
	v_pk_add_f32 v[24:25], v[28:29], v[16:17] op_sel_hi:[0,1] neg_hi:[0,1]
	v_pk_mul_f32 v[16:17], v[24:25], v[180:181]
	v_pk_mul_f32 v[24:25], v[24:25], v[172:173]
	v_pk_fma_f32 v[16:17], v[54:55], v[172:173], v[16:17]
	v_pk_fma_f32 v[24:25], v[54:55], v[180:181], v[24:25] neg_lo:[0,0,1] neg_hi:[0,0,1]
	v_pk_mov_b32 v[50:51], v[32:33], v[30:31] op_sel:[1,0]
	v_pk_add_f32 v[28:29], v[24:25], v[16:17] op_sel:[0,1] op_sel_hi:[1,0] neg_lo:[0,1]
	v_pk_add_f32 v[52:53], v[24:25], v[16:17] op_sel:[0,1] op_sel_hi:[1,0]
	v_pk_add_f32 v[24:25], v[16:17], v[24:25] op_sel:[1,0] op_sel_hi:[0,1] neg_lo:[0,1] neg_hi:[0,1]
	v_pk_mul_f32 v[28:29], v[28:29], 0.5 op_sel_hi:[1,0]
	v_mov_b32_e32 v53, v25
	v_mul_f32_e32 v18, v33, v29
	v_pk_fma_f32 v[32:33], v[48:49], v[28:29], v[18:19] op_sel_hi:[1,1,0] neg_lo:[0,0,1] neg_hi:[0,0,1]
	v_mul_f32_e32 v18, v30, v29
	v_pk_fma_f32 v[28:29], v[50:51], v[28:29], v[18:19] op_sel_hi:[1,1,0]
	v_pk_fma_f32 v[172:173], v[24:25], 0.5, v[32:33] op_sel_hi:[1,0,0] neg_lo:[1,0,0] neg_hi:[1,0,0]
	v_pk_add_f32 v[24:25], v[106:107], v[178:179]
	v_mov_b32_e32 v50, v12
	v_mov_b32_e32 v51, v106
	v_pk_mov_b32 v[12:13], v[12:13], v[178:179] op_sel:[1,0]
	v_mul_f32_e32 v18, 0.5, v25
	v_pk_add_f32 v[12:13], v[50:51], v[12:13] neg_lo:[0,1] neg_hi:[0,1]
	v_mov_b32_e32 v16, v28
	v_mov_b32_e32 v17, v32
	v_pk_mul_f32 v[50:51], v[12:13], v[18:19]
	v_pk_fma_f32 v[54:55], v[52:53], 0.5, v[28:29] op_sel_hi:[1,0,1] neg_lo:[0,0,1] neg_hi:[0,0,1]
	v_pk_fma_f32 v[102:103], v[52:53], 0.5, v[16:17] op_sel_hi:[1,0,1]
	v_pk_fma_f32 v[16:17], v[52:53], 0.5, v[28:29] op_sel_hi:[1,0,1]
	v_mul_f32_e32 v28, 0.5, v24
	v_pk_fma_f32 v[48:49], v[48:49], v[50:51], v[50:51] op_sel:[0,1,0] op_sel_hi:[1,0,1]
	v_mov_b32_e32 v13, v30
	v_mov_b32_e32 v50, v51
	v_mov_b32_e32 v51, v18
	v_sub_f32_e32 v5, v107, v179
	v_pk_mul_f32 v[50:51], v[12:13], v[50:51]
	v_pk_add_f32 v[28:29], v[28:29], v[48:49]
	v_mul_f32_e32 v32, 0.5, v5
	v_fma_f32 v29, v24, 0.5, -v48
	v_pk_add_f32 v[24:25], v[50:51], v[50:51] op_sel:[0,1] op_sel_hi:[0,1] neg_lo:[0,1] neg_hi:[0,1]
	v_pk_add_f32 v[48:49], v[32:33], v[24:25] op_sel_hi:[0,1] neg_hi:[0,1]
	v_pk_mul_f32 v[24:25], v[48:49], v[176:177]
	v_pk_mul_f32 v[32:33], v[48:49], v[174:175]
	v_pk_fma_f32 v[24:25], v[28:29], v[174:175], v[24:25]
	v_pk_fma_f32 v[28:29], v[28:29], v[176:177], v[32:33] neg_lo:[0,0,1] neg_hi:[0,0,1]
	v_mov_b32_e32 v31, v12
	v_pk_add_f32 v[32:33], v[28:29], v[24:25] op_sel:[0,1] op_sel_hi:[1,0] neg_lo:[0,1]
	v_pk_add_f32 v[48:49], v[28:29], v[24:25] op_sel:[0,1] op_sel_hi:[1,0]
	v_pk_add_f32 v[24:25], v[24:25], v[28:29] op_sel:[1,0] op_sel_hi:[0,1] neg_lo:[0,1] neg_hi:[0,1]
	v_pk_mul_f32 v[32:33], v[32:33], 0.5 op_sel_hi:[1,0]
	v_mov_b32_e32 v49, v25
	v_mul_f32_e32 v18, v30, v33
	v_pk_fma_f32 v[50:51], v[12:13], v[32:33], v[18:19] op_sel_hi:[1,1,0] neg_lo:[0,0,1] neg_hi:[0,0,1]
	v_mul_f32_e32 v12, v12, v33
	v_pk_fma_f32 v[12:13], v[30:31], v[32:33], v[12:13] op_sel_hi:[1,1,0]
	v_mov_b32_e32 v29, v50
	v_mov_b32_e32 v28, v12
	s_mov_b32 s79, s16
	v_pk_fma_f32 v[106:107], v[48:49], 0.5, v[28:29] op_sel_hi:[1,0,1]
	v_pk_fma_f32 v[174:175], v[24:25], 0.5, v[50:51] op_sel_hi:[1,0,0] neg_lo:[1,0,0] neg_hi:[1,0,0]
	v_mov_b32_e32 v18, v83
	s_mov_b32 s17, s19
	v_pk_mul_f32 v[24:25], v[82:83], s[78:79] op_sel_hi:[0,1]
	v_pk_add_f32 v[28:29], v[104:105], v[162:163]
	v_pk_add_f32 v[30:31], v[104:105], v[162:163] neg_lo:[0,1] neg_hi:[0,1]
	v_pk_fma_f32 v[70:71], v[48:49], 0.5, v[12:13] op_sel_hi:[1,0,1] neg_lo:[0,0,1] neg_hi:[0,0,1]
	v_pk_fma_f32 v[12:13], v[48:49], 0.5, v[12:13] op_sel_hi:[1,0,1]
	v_mul_f32_e32 v32, 0.5, v31
	v_pk_fma_f32 v[48:49], v[18:19], s[16:17], v[24:25] op_sel_hi:[0,1,1] neg_lo:[0,0,1] neg_hi:[0,0,1]
	v_pk_fma_f32 v[50:51], v[18:19], s[16:17], v[24:25] op_sel_hi:[0,1,1]
	v_mov_b32_e32 v31, v29
	v_mov_b32_e32 v52, v48
	v_mov_b32_e32 v53, v51
	v_pk_mul_f32 v[30:31], v[30:31], s[44:45]
	v_mul_f32_e32 v28, 0.5, v28
	v_pk_mul_f32 v[62:63], v[52:53], v[30:31] op_sel:[0,1] op_sel_hi:[1,0]
	v_pk_mul_f32 v[30:31], v[52:53], v[30:31]
	v_pk_add_f32 v[62:63], v[62:63], v[62:63] op_sel:[0,1] op_sel_hi:[0,1]
	v_pk_add_f32 v[64:65], v[28:29], v[62:63] op_sel_hi:[0,1] neg_hi:[0,1]
	v_pk_add_f32 v[28:29], v[30:31], v[30:31] op_sel:[0,1] op_sel_hi:[0,1] neg_lo:[0,1] neg_hi:[0,1]
	v_pk_add_f32 v[30:31], v[32:33], v[28:29] op_sel_hi:[0,1] neg_hi:[0,1]
	v_pk_mul_f32 v[28:29], v[30:31], v[166:167]
	v_pk_mul_f32 v[30:31], v[30:31], v[164:165]
	v_pk_fma_f32 v[28:29], v[64:65], v[164:165], v[28:29]
	v_pk_fma_f32 v[30:31], v[64:65], v[166:167], v[30:31] neg_lo:[0,0,1] neg_hi:[0,0,1]
	v_pk_mov_b32 v[56:57], v[50:51], v[48:49] op_sel:[1,0]
	v_pk_add_f32 v[32:33], v[30:31], v[28:29] op_sel:[0,1] op_sel_hi:[1,0] neg_lo:[0,1]
	v_pk_add_f32 v[62:63], v[30:31], v[28:29] op_sel:[0,1] op_sel_hi:[1,0]
	v_pk_add_f32 v[28:29], v[28:29], v[30:31] op_sel:[1,0] op_sel_hi:[0,1] neg_lo:[0,1] neg_hi:[0,1]
	v_pk_mul_f32 v[32:33], v[32:33], 0.5 op_sel_hi:[1,0]
	v_mov_b32_e32 v63, v29
	v_mul_f32_e32 v18, v51, v33
	v_pk_fma_f32 v[52:53], v[52:53], v[32:33], v[18:19] op_sel_hi:[1,1,0] neg_lo:[0,0,1] neg_hi:[0,0,1]
	v_mul_f32_e32 v18, v48, v33
	v_pk_fma_f32 v[32:33], v[56:57], v[32:33], v[18:19] op_sel_hi:[1,1,0]
	v_mov_b32_e32 v31, v52
	v_mov_b32_e32 v30, v32
	v_pk_fma_f32 v[56:57], v[62:63], 0.5, v[32:33] op_sel_hi:[1,0,1] neg_lo:[0,0,1] neg_hi:[0,0,1]
	v_pk_fma_f32 v[82:83], v[62:63], 0.5, v[30:31] op_sel_hi:[1,0,1]
	v_pk_fma_f32 v[32:33], v[62:63], 0.5, v[32:33] op_sel_hi:[1,0,1]
	v_pk_fma_f32 v[104:105], v[28:29], 0.5, v[52:53] op_sel_hi:[1,0,0] neg_lo:[1,0,0] neg_hi:[1,0,0]
	v_pk_add_f32 v[28:29], v[108:109], v[152:153]
	v_mov_b32_e32 v159, v108
	v_pk_mov_b32 v[62:63], v[24:25], v[152:153] op_sel:[1,0]
	v_mul_f32_e32 v18, 0.5, v29
	v_pk_add_f32 v[62:63], v[158:159], v[62:63] neg_lo:[0,1] neg_hi:[0,1]
	v_sub_f32_e32 v5, v109, v153
	v_pk_mul_f32 v[64:65], v[62:63], v[18:19]
	v_mov_b32_e32 v63, v48
	v_pk_fma_f32 v[68:69], v[48:49], v[64:65], v[64:65] op_sel:[0,1,0] op_sel_hi:[1,0,1]
	v_mov_b32_e32 v64, v65
	v_mov_b32_e32 v65, v18
	v_pk_mul_f32 v[64:65], v[62:63], v[64:65]
	v_mul_f32_e32 v30, 0.5, v28
	v_mul_f32_e32 v52, 0.5, v5
	v_pk_add_f32 v[64:65], v[64:65], v[64:65] op_sel:[0,1] op_sel_hi:[0,1] neg_lo:[0,1] neg_hi:[0,1]
	v_pk_add_f32 v[30:31], v[30:31], v[68:69]
	v_fma_f32 v18, v28, 0.5, -v68
	v_pk_add_f32 v[68:69], v[52:53], v[64:65] op_sel_hi:[0,1] neg_hi:[0,1]
	v_mov_b32_e32 v28, v30
	v_mov_b32_e32 v29, v18
	v_pk_mul_f32 v[52:53], v[18:19], v[154:155] op_sel_hi:[0,1]
	v_pk_mul_f32 v[64:65], v[68:69], v[156:157]
	v_pk_mul_f32 v[30:31], v[30:31], v[156:157]
	v_pk_mul_f32 v[68:69], v[68:69], v[154:155]
	v_pk_fma_f32 v[74:75], v[28:29], v[154:155], v[64:65] neg_lo:[0,0,1] neg_hi:[0,0,1]
	v_pk_fma_f32 v[28:29], v[28:29], v[156:157], v[68:69] neg_lo:[0,0,1] neg_hi:[0,0,1]
	v_add_f32_e32 v18, v53, v65
	v_add_f32_e32 v30, v30, v68
	v_pk_add_f32 v[64:65], v[30:31], v[28:29] op_sel_hi:[0,1] neg_lo:[0,1] neg_hi:[0,1]
	v_pk_add_f32 v[68:69], v[74:75], v[18:19] op_sel_hi:[1,0] neg_lo:[0,1] neg_hi:[0,1]
	v_pk_add_f32 v[28:29], v[30:31], v[28:29] op_sel_hi:[0,1]
	v_mov_b32_e32 v69, v29
	v_pk_mul_f32 v[28:29], v[68:69], 0.5 op_sel_hi:[1,0]
	v_pk_add_f32 v[52:53], v[74:75], v[18:19] op_sel_hi:[1,0]
	v_mul_f32_e32 v18, v48, v29
	v_pk_fma_f32 v[30:31], v[62:63], v[28:29], v[18:19] op_sel_hi:[1,1,0] neg_lo:[0,0,1] neg_hi:[0,0,1]
	v_mov_b32_e32 v68, v48
	v_mov_b32_e32 v69, v62
	v_mul_f32_e32 v18, v62, v29
	v_pk_fma_f32 v[28:29], v[68:69], v[28:29], v[18:19] op_sel_hi:[1,1,0]
	v_mov_b32_e32 v53, v65
	v_mov_b32_e32 v62, v28
	v_mov_b32_e32 v63, v30
	v_pk_fma_f32 v[76:77], v[52:53], 0.5, v[28:29] op_sel_hi:[1,0,1] neg_lo:[0,0,1] neg_hi:[0,0,1]
	v_pk_fma_f32 v[108:109], v[52:53], 0.5, v[62:63] op_sel_hi:[1,0,1]
	v_pk_fma_f32 v[28:29], v[52:53], 0.5, v[28:29] op_sel_hi:[1,0,1]
	v_pk_fma_f32 v[152:153], v[64:65], 0.5, v[30:31] op_sel_hi:[1,0,0] neg_lo:[1,0,0] neg_hi:[1,0,0]
	v_pk_add_f32 v[30:31], v[134:135], v[110:111]
	v_pk_add_f32 v[52:53], v[110:111], v[134:135] neg_lo:[0,1] neg_hi:[0,1]
	v_mul_f32_e32 v18, 0.5, v30
	v_mul_f32_e32 v30, 0.5, v53
	v_mov_b32_e32 v53, v31
	v_pk_mov_b32 v[62:63], v[48:49], v[50:51] op_sel:[1,0]
	v_pk_mul_f32 v[52:53], v[52:53], s[44:45]
	v_mov_b32_e32 v51, v49
	v_pk_mul_f32 v[64:65], v[62:63], v[52:53] op_sel:[0,1] op_sel_hi:[1,0]
	v_pk_mul_f32 v[52:53], v[62:63], v[52:53]
	v_pk_add_f32 v[64:65], v[64:65], v[64:65] op_sel:[0,1] op_sel_hi:[0,1]
	v_pk_add_f32 v[68:69], v[18:19], v[64:65] op_sel_hi:[0,1] neg_hi:[0,1]
	v_pk_add_f32 v[52:53], v[52:53], v[52:53] op_sel:[0,1] op_sel_hi:[0,1] neg_lo:[0,1] neg_hi:[0,1]
	v_pk_add_f32 v[64:65], v[30:31], v[52:53] op_sel_hi:[0,1] neg_hi:[0,1]
	v_pk_mul_f32 v[30:31], v[64:65], v[142:143]
	v_pk_mul_f32 v[52:53], v[64:65], v[140:141]
	v_pk_fma_f32 v[30:31], v[68:69], v[140:141], v[30:31]
	v_pk_fma_f32 v[52:53], v[68:69], v[142:143], v[52:53] neg_lo:[0,0,1] neg_hi:[0,0,1]
	v_mov_b32_e32 v133, v112
	v_pk_add_f32 v[64:65], v[52:53], v[30:31] op_sel:[0,1] op_sel_hi:[1,0] neg_lo:[0,1]
	v_pk_add_f32 v[68:69], v[52:53], v[30:31] op_sel:[0,1] op_sel_hi:[1,0]
	v_pk_add_f32 v[30:31], v[30:31], v[52:53] op_sel:[1,0] op_sel_hi:[0,1] neg_lo:[0,1] neg_hi:[0,1]
	v_pk_mul_f32 v[64:65], v[64:65], 0.5 op_sel_hi:[1,0]
	v_mov_b32_e32 v69, v31
	v_mul_f32_e32 v18, v50, v65
	v_pk_fma_f32 v[74:75], v[62:63], v[64:65], v[18:19] op_sel_hi:[1,1,0] neg_lo:[0,0,1] neg_hi:[0,0,1]
	v_mul_f32_e32 v18, v49, v65
	v_pk_fma_f32 v[134:135], v[30:31], 0.5, v[74:75] op_sel_hi:[1,0,0] neg_lo:[1,0,0] neg_hi:[1,0,0]
	v_pk_add_f32 v[30:31], v[118:119], v[112:113]
	v_mov_b32_e32 v25, v118
	v_pk_fma_f32 v[50:51], v[50:51], v[64:65], v[18:19] op_sel_hi:[1,1,0]
	v_mul_f32_e32 v18, 0.5, v31
	v_pk_add_f32 v[24:25], v[132:133], v[24:25] neg_lo:[0,1] neg_hi:[0,1]
	v_mov_b32_e32 v65, v74
	v_pk_mul_f32 v[74:75], v[24:25], v[18:19]
	v_mov_b32_e32 v64, v50
	v_pk_fma_f32 v[62:63], v[62:63], v[74:75], v[74:75] op_sel:[0,1,0] op_sel_hi:[1,0,1]
	v_mov_b32_e32 v78, v24
	v_mov_b32_e32 v79, v49
	v_mov_b32_e32 v74, v75
	v_mov_b32_e32 v75, v18
	v_pk_fma_f32 v[110:111], v[68:69], 0.5, v[64:65] op_sel_hi:[1,0,1]
	v_mul_f32_e32 v64, 0.5, v30
	v_sub_f32_e32 v5, v113, v119
	v_pk_mul_f32 v[74:75], v[78:79], v[74:75]
	v_pk_fma_f32 v[52:53], v[68:69], 0.5, v[50:51] op_sel_hi:[1,0,1] neg_lo:[0,0,1] neg_hi:[0,0,1]
	v_pk_fma_f32 v[50:51], v[68:69], 0.5, v[50:51] op_sel_hi:[1,0,1]
	v_mul_f32_e32 v68, 0.5, v5
	v_pk_add_f32 v[64:65], v[64:65], v[62:63]
	v_fma_f32 v18, v30, 0.5, -v62
	v_pk_add_f32 v[62:63], v[74:75], v[74:75] op_sel:[0,1] op_sel_hi:[0,1] neg_lo:[0,1] neg_hi:[0,1]
	v_pk_add_f32 v[74:75], v[68:69], v[62:63] op_sel_hi:[0,1] neg_hi:[0,1]
	v_mov_b32_e32 v30, v64
	v_mov_b32_e32 v31, v18
	v_pk_mul_f32 v[62:63], v[18:19], v[124:125] op_sel_hi:[0,1]
	v_pk_mul_f32 v[68:69], v[74:75], v[126:127]
	v_pk_mul_f32 v[64:65], v[64:65], v[126:127]
	v_pk_mul_f32 v[74:75], v[74:75], v[124:125]
	v_pk_fma_f32 v[80:81], v[30:31], v[124:125], v[68:69] neg_lo:[0,0,1] neg_hi:[0,0,1]
	v_pk_fma_f32 v[30:31], v[30:31], v[126:127], v[74:75] neg_lo:[0,0,1] neg_hi:[0,0,1]
	v_add_f32_e32 v18, v63, v69
	v_add_f32_e32 v64, v64, v74
	v_pk_add_f32 v[68:69], v[64:65], v[30:31] op_sel_hi:[0,1] neg_lo:[0,1] neg_hi:[0,1]
	v_pk_add_f32 v[74:75], v[80:81], v[18:19] op_sel_hi:[1,0] neg_lo:[0,1] neg_hi:[0,1]
	v_pk_add_f32 v[30:31], v[64:65], v[30:31] op_sel_hi:[0,1]
	v_mov_b32_e32 v75, v31
	v_pk_mul_f32 v[30:31], v[74:75], 0.5 op_sel_hi:[1,0]
	v_pk_add_f32 v[62:63], v[80:81], v[18:19] op_sel_hi:[1,0]
	v_mul_f32_e32 v18, v49, v31
	v_pk_fma_f32 v[64:65], v[78:79], v[30:31], v[18:19] op_sel_hi:[1,1,0] neg_lo:[0,0,1] neg_hi:[0,0,1]
	v_pk_mov_b32 v[48:49], v[48:49], v[24:25] op_sel:[1,0]
	v_mul_f32_e32 v18, v24, v31
	v_pk_fma_f32 v[24:25], v[48:49], v[30:31], v[18:19] op_sel_hi:[1,1,0]
	v_mov_b32_e32 v63, v69
	v_mov_b32_e32 v30, v24
	v_mov_b32_e32 v31, v64
	v_pk_fma_f32 v[74:75], v[62:63], 0.5, v[24:25] op_sel_hi:[1,0,1] neg_lo:[0,0,1] neg_hi:[0,0,1]
	v_pk_fma_f32 v[112:113], v[62:63], 0.5, v[30:31] op_sel_hi:[1,0,1]
	v_pk_fma_f32 v[48:49], v[62:63], 0.5, v[24:25] op_sel_hi:[1,0,1]
	v_mov_b32_e32 v62, v115
	v_mov_b32_e32 v18, v117
	v_mov_b32_e32 v30, v117
	v_pk_mul_f32 v[62:63], v[138:139], v[62:63] op_sel_hi:[1,0]
	v_pk_fma_f32 v[118:119], v[68:69], 0.5, v[64:65] op_sel_hi:[1,0,0] neg_lo:[1,0,0] neg_hi:[1,0,0]
	v_pk_fma_f32 v[64:65], v[138:139], v[18:19], v[62:63] op_sel:[1,0,0] op_sel_hi:[0,1,1]
	v_pk_fma_f32 v[30:31], v[138:139], v[30:31], v[62:63] op_sel:[1,0,0] op_sel_hi:[0,0,1] neg_lo:[0,0,1] neg_hi:[0,0,1]
	v_pk_add_f32 v[62:63], v[86:87], v[38:39]
	v_pk_add_f32 v[38:39], v[86:87], v[38:39] neg_lo:[0,1] neg_hi:[0,1]
	v_mul_f32_e32 v18, 0.5, v62
	v_mul_f32_e32 v62, 0.5, v39
	v_mov_b32_e32 v39, v63
	v_mov_b32_e32 v65, v31
	v_pk_mul_f32 v[38:39], v[38:39], s[44:45]
	s_mov_b32 s80, s11
	s_mov_b32 s81, s8
	s_mov_b32 s9, s11
	v_cvt_f32_f16_sdwa v69, v47 dst_sel:DWORD dst_unused:UNUSED_PAD src0_sel:WORD_1
	v_cvt_f32_f16_sdwa v78, v46 dst_sel:DWORD dst_unused:UNUSED_PAD src0_sel:WORD_1
	v_pk_mul_f32 v[30:31], v[64:65], s[6:7]
	v_pk_mul_f32 v[64:65], v[38:39], s[80:81]
	v_pk_mul_f32 v[38:39], v[38:39], s[8:9]
	v_cvt_f32_f16_e32 v68, v46
	v_cvt_f32_f16_e32 v79, v47
	v_pk_add_f32 v[64:65], v[64:65], v[64:65] op_sel:[1,0] op_sel_hi:[1,0]
	v_pk_add_f32 v[38:39], v[38:39], v[38:39] op_sel:[0,1] op_sel_hi:[0,1] neg_lo:[0,1] neg_hi:[0,1]
	v_pk_add_f32 v[80:81], v[18:19], v[64:65] op_sel_hi:[0,1]
	v_pk_add_f32 v[90:91], v[62:63], v[38:39] op_sel_hi:[0,1]
	v_pk_add_f32 v[38:39], v[62:63], v[38:39] op_sel_hi:[0,1] neg_lo:[0,1] neg_hi:[0,1]
	v_mov_b32_e32 v46, v69
	v_mov_b32_e32 v47, v78
	v_pk_add_f32 v[64:65], v[18:19], v[64:65] op_sel_hi:[0,1] neg_lo:[0,1] neg_hi:[0,1]
	v_mov_b32_e32 v62, v90
	v_mov_b32_e32 v63, v39
	v_pk_mov_b32 v[38:39], v[38:39], v[80:81] op_sel:[1,0]
	v_mov_b32_e32 v86, v80
	v_mov_b32_e32 v87, v65
	v_pk_mov_b32 v[64:65], v[64:65], v[90:91] op_sel:[1,0]
	v_mov_b32_e32 v90, v79
	v_mov_b32_e32 v91, v68
	v_pk_mul_f32 v[38:39], v[38:39], v[46:47]
	v_pk_mul_f32 v[46:47], v[62:63], v[78:79]
	v_pk_fma_f32 v[38:39], v[64:65], v[90:91], v[38:39]
	v_pk_fma_f32 v[46:47], v[86:87], v[68:69], v[46:47] neg_lo:[0,0,1] neg_hi:[0,0,1]
	s_mov_b32 s82, s45
	v_pk_add_f32 v[62:63], v[46:47], v[38:39] neg_lo:[0,1]
	v_pk_add_f32 v[64:65], v[46:47], v[38:39]
	v_pk_add_f32 v[38:39], v[38:39], v[46:47] neg_lo:[0,1] neg_hi:[0,1]
	s_nop 0
	v_pk_mul_f32 v[62:63], v[62:63], 0.5 op_sel_hi:[1,0]
	v_mov_b32_e32 v65, v39
	v_mul_f32_e32 v18, 0x3f7b14be, v62
	v_pk_fma_f32 v[68:69], v[62:63], s[8:9], v[18:19] op_sel_hi:[1,1,0] neg_lo:[1,0,0] neg_hi:[1,0,0]
	v_mul_f32_e32 v18, 0x3f7b14be, v63
	v_pk_fma_f32 v[62:63], v[62:63], s[80:81], v[18:19] op_sel_hi:[1,1,0]
	v_mov_b32_e32 v39, v69
	v_mov_b32_e32 v38, v62
	v_pk_fma_f32 v[46:47], v[64:65], 0.5, v[62:63] op_sel_hi:[1,0,1] neg_lo:[0,0,1] neg_hi:[0,0,1]
	v_pk_fma_f32 v[38:39], v[64:65], 0.5, v[38:39] op_sel_hi:[1,0,1]
	s_mov_b32 s83, s44
	v_mov_b32_e32 v47, v39
	v_pk_mul_f32 v[78:79], v[46:47], s[6:7] op_sel_hi:[1,0]
	v_pk_fma_f32 v[46:47], v[64:65], 0.5, v[68:69] op_sel_hi:[1,0,1] neg_lo:[1,0,0] neg_hi:[1,0,0]
	s_mov_b32 s84, s19
	v_mov_b32_e32 v39, v47
	v_pk_mul_f32 v[144:145], v[38:39], s[6:7] op_sel_hi:[1,0]
	v_pk_add_f32 v[38:39], v[96:97], v[84:85]
	v_pk_add_f32 v[46:47], v[96:97], v[84:85] neg_lo:[0,1] neg_hi:[0,1]
	v_mov_b32_e32 v80, v38
	v_pk_mov_b32 v[38:39], v[38:39], v[46:47] op_sel:[1,0]
	v_cvt_f32_f16_sdwa v62, v36 dst_sel:DWORD dst_unused:UNUSED_PAD src0_sel:WORD_1
	v_pk_mul_f32 v[38:39], v[38:39], s[82:83]
	v_mov_b32_e32 v81, v47
	v_pk_mul_f32 v[46:47], v[38:39], s[84:85] op_sel_hi:[1,0]
	v_cvt_f32_f16_e32 v63, v37
	v_cvt_f32_f16_e32 v65, v36
	v_cvt_f32_f16_sdwa v36, v37 dst_sel:DWORD dst_unused:UNUSED_PAD src0_sel:WORD_1
	v_pk_fma_f32 v[84:85], v[38:39], s[16:17], v[46:47] op_sel:[0,0,1] op_sel_hi:[1,0,0] neg_hi:[0,0,1]
	s_nop 0
	v_mov_b32_e32 v37, v62
	s_nop 0
	v_pk_fma_f32 v[38:39], v[80:81], 0.5, v[84:85] op_sel_hi:[1,0,1] neg_lo:[0,0,1] neg_hi:[0,0,1]
	v_pk_fma_f32 v[46:47], v[80:81], 0.5, v[84:85] op_sel_hi:[1,0,1]
	v_mov_b32_e32 v64, v63
	v_pk_mov_b32 v[84:85], v[38:39], v[46:47] op_sel:[1,0]
	v_mov_b32_e32 v69, v36
	v_mov_b32_e32 v80, v38
	v_mov_b32_e32 v81, v47
	v_pk_mul_f32 v[36:37], v[84:85], v[36:37]
	v_mov_b32_e32 v68, v65
	v_pk_fma_f32 v[36:37], v[80:81], v[64:65], v[36:37]
	v_mov_b32_e32 v65, v38
	v_mov_b32_e32 v38, v47
	v_mov_b32_e32 v64, v46
	v_pk_mul_f32 v[38:39], v[38:39], v[62:63]
	v_sub_f32_e32 v13, v148, v149
	v_pk_fma_f32 v[38:39], v[64:65], v[68:69], v[38:39] neg_lo:[0,0,1] neg_hi:[0,0,1]
	v_add_f32_e32 v5, v148, v149
	v_mul_f32_e32 v13, v13, v114
	v_pk_add_f32 v[46:47], v[36:37], v[38:39]
	v_mul_f32_e32 v7, v5, v116
	v_fma_mix_f32 v25, v5, v122, -v13 op_sel_hi:[0,1,0]
	v_pk_add_f32 v[64:65], v[36:37], v[38:39] neg_hi:[0,1]
	v_sub_f32_e32 v5, v38, v36
	v_mul_f32_e32 v36, 0.5, v47
	v_mul_f32_e32 v18, 0.5, v5
	v_pk_mul_f32 v[36:37], v[36:37], s[16:17] op_sel_hi:[0,1]
	v_pk_fma_f32 v[38:39], v[18:19], s[78:79], v[36:37] op_sel_hi:[0,1,1]
	v_pk_fma_f32 v[36:37], v[18:19], s[78:79], v[36:37] op_sel_hi:[0,1,1] neg_lo:[0,0,1] neg_hi:[0,0,1]
	v_mov_b32_e32 v46, v38
	v_mov_b32_e32 v47, v37
	v_pk_fma_f32 v[38:39], v[64:65], 0.5, v[38:39] op_sel_hi:[1,0,1] neg_lo:[0,0,1] neg_hi:[0,0,1]
	v_pk_fma_f32 v[46:47], v[64:65], 0.5, v[46:47] op_sel_hi:[1,0,1]
	v_pk_fma_f32 v[36:37], v[64:65], 0.5, v[36:37] op_sel_hi:[1,0,1] neg_lo:[1,0,0] neg_hi:[1,0,0]
	v_mov_b32_e32 v39, v47
	v_pk_mul_f32 v[62:63], v[38:39], s[6:7] op_sel_hi:[1,0]
	v_mov_b32_e32 v47, v37
	v_pk_add_f32 v[36:37], v[42:43], v[44:45]
	v_pk_add_f32 v[38:39], v[42:43], v[44:45] neg_lo:[0,1] neg_hi:[0,1]
	v_mov_b32_e32 v64, v36
	v_pk_mov_b32 v[36:37], v[36:37], v[38:39] op_sel:[1,0]
	s_mov_b32 s86, s27
	v_pk_mul_f32 v[36:37], v[36:37], s[82:83]
	v_cvt_f32_f16_sdwa v42, v26 dst_sel:DWORD dst_unused:UNUSED_PAD src0_sel:WORD_1
	v_mov_b32_e32 v65, v39
	v_pk_mul_f32 v[38:39], v[36:37], s[86:87] op_sel_hi:[1,0]
	v_cvt_f32_f16_e32 v43, v27
	v_cvt_f32_f16_e32 v45, v26
	v_cvt_f32_f16_sdwa v26, v27 dst_sel:DWORD dst_unused:UNUSED_PAD src0_sel:WORD_1
	v_pk_fma_f32 v[68:69], v[36:37], s[24:25], v[38:39] op_sel:[0,0,1] op_sel_hi:[1,0,0] neg_hi:[0,0,1]
	s_nop 0
	v_mov_b32_e32 v27, v42
	s_nop 0
	v_pk_fma_f32 v[36:37], v[64:65], 0.5, v[68:69] op_sel_hi:[1,0,1] neg_lo:[0,0,1] neg_hi:[0,0,1]
	v_pk_fma_f32 v[38:39], v[64:65], 0.5, v[68:69] op_sel_hi:[1,0,1]
	v_pk_mul_f32 v[80:81], v[46:47], s[6:7] op_sel_hi:[1,0]
	v_pk_mov_b32 v[68:69], v[36:37], v[38:39] op_sel:[1,0]
	v_mov_b32_e32 v44, v43
	v_mov_b32_e32 v47, v26
	v_mov_b32_e32 v64, v36
	v_mov_b32_e32 v65, v39
	v_pk_mul_f32 v[26:27], v[68:69], v[26:27]
	v_mov_b32_e32 v46, v45
	v_pk_fma_f32 v[26:27], v[64:65], v[44:45], v[26:27]
	v_mov_b32_e32 v45, v36
	v_mov_b32_e32 v36, v39
	v_mov_b32_e32 v44, v38
	v_pk_mul_f32 v[36:37], v[36:37], v[42:43]
	s_mov_b32 s25, s27
	v_pk_fma_f32 v[36:37], v[44:45], v[46:47], v[36:37] neg_lo:[0,0,1] neg_hi:[0,0,1]
	s_mov_b32 s88, s27
	v_pk_add_f32 v[38:39], v[26:27], v[36:37]
	v_pk_add_f32 v[42:43], v[26:27], v[36:37] neg_hi:[0,1]
	v_sub_f32_e32 v5, v36, v26
	v_mul_f32_e32 v26, 0.5, v39
	v_mul_f32_e32 v18, 0.5, v5
	s_mov_b32 s89, s24
	v_pk_mul_f32 v[26:27], v[26:27], s[24:25] op_sel_hi:[0,1]
	v_pk_fma_f32 v[36:37], v[18:19], s[88:89], v[26:27] op_sel_hi:[0,1,1]
	v_pk_fma_f32 v[26:27], v[18:19], s[88:89], v[26:27] op_sel_hi:[0,1,1] neg_lo:[0,0,1] neg_hi:[0,0,1]
	s_nop 0
	v_mov_b32_e32 v38, v36
	v_mov_b32_e32 v39, v27
	v_pk_fma_f32 v[36:37], v[42:43], 0.5, v[36:37] op_sel_hi:[1,0,1] neg_lo:[0,0,1] neg_hi:[0,0,1]
	v_pk_fma_f32 v[38:39], v[42:43], 0.5, v[38:39] op_sel_hi:[1,0,1]
	v_pk_fma_f32 v[26:27], v[42:43], 0.5, v[26:27] op_sel_hi:[1,0,1] neg_lo:[1,0,0] neg_hi:[1,0,0]
	v_mov_b32_e32 v37, v39
	v_pk_mul_f32 v[128:129], v[36:37], s[6:7] op_sel_hi:[1,0]
	v_mov_b32_e32 v39, v27
	v_pk_add_f32 v[26:27], v[92:93], v[88:89]
	v_pk_add_f32 v[36:37], v[92:93], v[88:89] neg_lo:[0,1] neg_hi:[0,1]
	v_add_f32_e32 v24, v7, v13
	v_pk_mul_f32 v[120:121], v[38:39], s[6:7] op_sel_hi:[1,0]
	v_mul_f32_e32 v5, 0.5, v27
	v_mul_f32_e32 v7, -0.5, v36
	v_cvt_f32_f16_sdwa v38, v20 dst_sel:DWORD dst_unused:UNUSED_PAD src0_sel:WORD_1
	v_mul_f32_e32 v5, 0x3f3504f3, v5
	v_mul_f32_e32 v13, 0x3f3504f3, v7
	v_cvt_f32_f16_e32 v39, v21
	v_cvt_f32_f16_e32 v43, v20
	v_cvt_f32_f16_sdwa v20, v21 dst_sel:DWORD dst_unused:UNUSED_PAD src0_sel:WORD_1
	v_mov_b32_e32 v27, v37
	v_add_f32_e32 v36, v13, v5
	v_fma_f32 v37, v7, s37, -v5
	v_pk_fma_f32 v[46:47], v[26:27], 0.5, v[36:37] op_sel_hi:[1,0,1] neg_lo:[0,0,1] neg_hi:[0,0,1]
	v_pk_fma_f32 v[26:27], v[26:27], 0.5, v[36:37] op_sel_hi:[1,0,1]
	v_mov_b32_e32 v21, v38
	v_pk_mov_b32 v[64:65], v[46:47], v[26:27] op_sel:[1,0]
	v_mov_b32_e32 v42, v39
	v_mov_b32_e32 v45, v20
	v_mov_b32_e32 v36, v46
	v_mov_b32_e32 v37, v27
	v_pk_mul_f32 v[20:21], v[64:65], v[20:21]
	v_mov_b32_e32 v44, v43
	v_pk_fma_f32 v[20:21], v[36:37], v[42:43], v[20:21]
	v_mov_b32_e32 v37, v46
	v_mov_b32_e32 v46, v27
	v_mov_b32_e32 v36, v26
	v_pk_mul_f32 v[26:27], v[46:47], v[38:39]
	v_pk_mul_f32 v[24:25], v[24:25], 0.5 op_sel_hi:[1,0]
	v_pk_fma_f32 v[26:27], v[36:37], v[44:45], v[26:27] neg_lo:[0,0,1] neg_hi:[0,0,1]
	v_pk_mul_f32 v[24:25], v[24:25], s[6:7] op_sel_hi:[1,0]
	v_pk_add_f32 v[36:37], v[20:21], v[26:27]
	v_sub_f32_e32 v5, v26, v20
	v_mul_f32_e32 v7, 0.5, v37
	v_mul_f32_e32 v5, 0.5, v5
	v_mul_f32_e32 v7, 0x3f3504f3, v7
	v_pk_add_f32 v[38:39], v[20:21], v[26:27] neg_hi:[0,1]
	v_mul_f32_e32 v13, 0x3f3504f3, v5
	v_fma_f32 v18, v5, s37, -v7
	v_add_f32_e32 v20, v13, v7
	v_mov_b32_e32 v21, v18
	v_pk_fma_f32 v[26:27], v[38:39], 0.5, v[20:21] op_sel_hi:[1,0,1] neg_lo:[0,0,1]
	v_pk_fma_f32 v[20:21], v[38:39], 0.5, v[20:21] op_sel_hi:[1,0,1]
	v_cvt_f32_f16_e32 v37, v10
	v_pk_mul_f32 v[64:65], v[26:27], s[6:7] op_sel_hi:[1,0]
	v_pk_fma_f32 v[26:27], v[38:39], 0.5, v[18:19] op_sel_hi:[1,0,0] neg_lo:[1,0,0] neg_hi:[1,0,0]
	v_mov_b32_e32 v38, v37
	v_mov_b32_e32 v21, v27
	v_pk_mul_f32 v[68:69], v[20:21], s[6:7] op_sel_hi:[1,0]
	v_pk_add_f32 v[20:21], v[40:41], v[22:23]
	v_pk_add_f32 v[22:23], v[40:41], v[22:23] neg_lo:[0,1] neg_hi:[0,1]
	v_mov_b32_e32 v40, v20
	v_pk_mov_b32 v[20:21], v[20:21], v[22:23] op_sel:[1,0]
	v_cvt_f32_f16_sdwa v26, v10 dst_sel:DWORD dst_unused:UNUSED_PAD src0_sel:WORD_1
	v_pk_mul_f32 v[20:21], v[20:21], s[82:83]
	v_mov_b32_e32 v41, v23
	v_pk_mul_f32 v[22:23], v[20:21], s[24:25] op_sel_hi:[1,0]
	v_cvt_f32_f16_e32 v27, v11
	v_cvt_f32_f16_sdwa v10, v11 dst_sel:DWORD dst_unused:UNUSED_PAD src0_sel:WORD_1
	v_pk_fma_f32 v[42:43], v[20:21], s[86:87], v[22:23] op_sel:[0,0,1] op_sel_hi:[1,0,0] neg_hi:[0,0,1]
	s_nop 0
	v_mov_b32_e32 v11, v26
	s_nop 0
	v_pk_fma_f32 v[20:21], v[40:41], 0.5, v[42:43] op_sel_hi:[1,0,1] neg_lo:[0,0,1] neg_hi:[0,0,1]
	v_pk_fma_f32 v[22:23], v[40:41], 0.5, v[42:43] op_sel_hi:[1,0,1]
	v_mov_b32_e32 v36, v27
	v_pk_mov_b32 v[42:43], v[20:21], v[22:23] op_sel:[1,0]
	v_mov_b32_e32 v39, v10
	v_mov_b32_e32 v40, v20
	v_mov_b32_e32 v41, v23
	v_pk_mul_f32 v[10:11], v[42:43], v[10:11]
	v_mov_b32_e32 v7, v161
	v_pk_fma_f32 v[10:11], v[40:41], v[36:37], v[10:11]
	v_mov_b32_e32 v37, v20
	v_mov_b32_e32 v20, v23
	v_mov_b32_e32 v36, v22
	v_pk_mul_f32 v[20:21], v[20:21], v[26:27]
	v_mov_b32_e32 v17, v173
	v_pk_fma_f32 v[20:21], v[36:37], v[38:39], v[20:21] neg_lo:[0,0,1] neg_hi:[0,0,1]
	v_mov_b32_e32 v13, v175
	v_pk_add_f32 v[22:23], v[10:11], v[20:21]
	v_sub_f32_e32 v5, v20, v10
	v_mul_f32_e32 v18, 0.5, v23
	v_pk_add_f32 v[26:27], v[10:11], v[20:21] neg_hi:[0,1]
	v_mul_f32_e32 v10, 0.5, v5
	v_pk_mul_f32 v[20:21], v[18:19], s[88:89] op_sel_hi:[0,1]
	v_pk_fma_f32 v[22:23], v[10:11], s[24:25], v[20:21] op_sel_hi:[0,1,1]
	v_pk_fma_f32 v[10:11], v[10:11], s[24:25], v[20:21] op_sel_hi:[0,1,1] neg_lo:[0,0,1] neg_hi:[0,0,1]
	v_mov_b32_e32 v20, v22
	v_mov_b32_e32 v21, v11
	v_pk_fma_f32 v[22:23], v[26:27], 0.5, v[22:23] op_sel_hi:[1,0,1] neg_lo:[0,0,1] neg_hi:[0,0,1]
	v_pk_fma_f32 v[20:21], v[26:27], 0.5, v[20:21] op_sel_hi:[1,0,1]
	v_pk_fma_f32 v[10:11], v[26:27], 0.5, v[10:11] op_sel_hi:[1,0,1] neg_lo:[1,0,0] neg_hi:[1,0,0]
	v_mov_b32_e32 v23, v21
	v_mov_b32_e32 v21, v11
	v_pk_mul_f32 v[150:151], v[20:21], s[6:7] op_sel_hi:[1,0]
	v_pk_add_f32 v[10:11], v[66:67], v[60:61]
	v_pk_add_f32 v[20:21], v[60:61], v[66:67] neg_lo:[0,1] neg_hi:[0,1]
	v_mov_b32_e32 v38, v10
	v_pk_mov_b32 v[10:11], v[10:11], v[20:21] op_sel:[1,0]
	v_pk_mul_f32 v[130:131], v[22:23], s[6:7] op_sel_hi:[1,0]
	v_pk_mul_f32 v[10:11], v[10:11], s[82:83]
	v_cvt_f32_f16_sdwa v22, v8 dst_sel:DWORD dst_unused:UNUSED_PAD src0_sel:WORD_1
	v_mov_b32_e32 v39, v21
	v_pk_mul_f32 v[20:21], v[10:11], s[16:17] op_sel_hi:[1,0]
	v_cvt_f32_f16_e32 v23, v9
	v_cvt_f32_f16_e32 v27, v8
	v_cvt_f32_f16_sdwa v8, v9 dst_sel:DWORD dst_unused:UNUSED_PAD src0_sel:WORD_1
	v_pk_fma_f32 v[40:41], v[10:11], s[84:85], v[20:21] op_sel:[0,0,1] op_sel_hi:[1,0,0] neg_hi:[0,0,1]
	s_nop 0
	v_mov_b32_e32 v9, v22
	s_nop 0
	v_pk_fma_f32 v[10:11], v[38:39], 0.5, v[40:41] op_sel_hi:[1,0,1] neg_lo:[0,0,1] neg_hi:[0,0,1]
	v_pk_fma_f32 v[20:21], v[38:39], 0.5, v[40:41] op_sel_hi:[1,0,1]
	v_mov_b32_e32 v26, v23
	v_pk_mov_b32 v[40:41], v[10:11], v[20:21] op_sel:[1,0]
	v_mov_b32_e32 v37, v8
	v_mov_b32_e32 v38, v10
	v_mov_b32_e32 v39, v21
	v_pk_mul_f32 v[8:9], v[40:41], v[8:9]
	v_mov_b32_e32 v36, v27
	v_pk_fma_f32 v[8:9], v[38:39], v[26:27], v[8:9]
	v_mov_b32_e32 v27, v10
	v_mov_b32_e32 v10, v21
	v_mov_b32_e32 v26, v20
	v_pk_mul_f32 v[10:11], v[10:11], v[22:23]
	v_mov_b32_e32 v33, v105
	v_pk_fma_f32 v[10:11], v[26:27], v[36:37], v[10:11] neg_lo:[0,0,1] neg_hi:[0,0,1]
	v_mov_b32_e32 v29, v153
	v_pk_add_f32 v[20:21], v[8:9], v[10:11]
	v_pk_add_f32 v[22:23], v[8:9], v[10:11] neg_hi:[0,1]
	v_sub_f32_e32 v5, v10, v8
	v_mul_f32_e32 v10, 0.5, v21
	v_mul_f32_e32 v8, 0.5, v5
	v_pk_mul_f32 v[10:11], v[10:11], s[78:79] op_sel_hi:[0,1]
	v_pk_fma_f32 v[20:21], v[8:9], s[16:17], v[10:11] op_sel_hi:[0,1,1]
	v_pk_fma_f32 v[8:9], v[8:9], s[16:17], v[10:11] op_sel_hi:[0,1,1] neg_lo:[0,0,1] neg_hi:[0,0,1]
	v_mov_b32_e32 v10, v20
	v_mov_b32_e32 v11, v9
	v_pk_fma_f32 v[20:21], v[22:23], 0.5, v[20:21] op_sel_hi:[1,0,1] neg_lo:[0,0,1] neg_hi:[0,0,1]
	v_pk_fma_f32 v[10:11], v[22:23], 0.5, v[10:11] op_sel_hi:[1,0,1]
	v_pk_fma_f32 v[8:9], v[22:23], 0.5, v[8:9] op_sel_hi:[1,0,1] neg_lo:[1,0,0] neg_hi:[1,0,0]
	v_mov_b32_e32 v21, v11
	v_mov_b32_e32 v11, v9
	v_pk_mul_f32 v[90:91], v[10:11], s[6:7] op_sel_hi:[1,0]
	v_pk_add_f32 v[8:9], v[34:35], v[14:15]
	v_pk_add_f32 v[10:11], v[14:15], v[34:35] neg_lo:[0,1] neg_hi:[0,1]
	v_mov_b32_e32 v26, v8
	v_pk_mov_b32 v[8:9], v[8:9], v[10:11] op_sel:[1,0]
	v_cvt_f32_f16_sdwa v14, v2 dst_sel:DWORD dst_unused:UNUSED_PAD src0_sel:WORD_1
	v_pk_mul_f32 v[8:9], v[8:9], s[82:83]
	v_mov_b32_e32 v27, v11
	s_mov_b32 s78, s11
	v_pk_mul_f32 v[10:11], v[8:9], s[8:9] op_sel_hi:[1,0]
	v_pk_mul_f32 v[94:95], v[20:21], s[6:7] op_sel_hi:[1,0]
	v_cvt_f32_f16_e32 v15, v3
	v_cvt_f32_f16_e32 v21, v2
	v_cvt_f32_f16_sdwa v2, v3 dst_sel:DWORD dst_unused:UNUSED_PAD src0_sel:WORD_1
	v_pk_fma_f32 v[34:35], v[8:9], s[78:79], v[10:11] op_sel:[0,0,1] op_sel_hi:[1,0,0] neg_hi:[0,0,1]
	s_nop 0
	v_mov_b32_e32 v3, v14
	s_nop 0
	v_pk_fma_f32 v[8:9], v[26:27], 0.5, v[34:35] op_sel_hi:[1,0,1] neg_lo:[0,0,1] neg_hi:[0,0,1]
	v_pk_fma_f32 v[10:11], v[26:27], 0.5, v[34:35] op_sel_hi:[1,0,1]
	v_mov_b32_e32 v20, v15
	v_pk_mov_b32 v[34:35], v[8:9], v[10:11] op_sel:[1,0]
	v_mov_b32_e32 v23, v2
	v_mov_b32_e32 v26, v8
	v_mov_b32_e32 v27, v11
	v_pk_mul_f32 v[2:3], v[34:35], v[2:3]
	v_mov_b32_e32 v22, v21
	v_pk_fma_f32 v[2:3], v[26:27], v[20:21], v[2:3]
	v_mov_b32_e32 v21, v8
	v_mov_b32_e32 v8, v11
	v_mov_b32_e32 v20, v10
	v_pk_mul_f32 v[8:9], v[8:9], v[14:15]
	v_mov_b32_e32 v5, v171
	v_pk_fma_f32 v[8:9], v[20:21], v[22:23], v[8:9] neg_lo:[0,0,1] neg_hi:[0,0,1]
	v_mov_b32_e32 v51, v135
	v_pk_add_f32 v[10:11], v[2:3], v[8:9]
	v_pk_add_f32 v[14:15], v[2:3], v[8:9] neg_hi:[0,1]
	v_sub_f32_e32 v2, v8, v2
	v_mul_f32_e32 v8, 0.5, v11
	v_mul_f32_e32 v2, 0.5, v2
	v_pk_mul_f32 v[8:9], v[8:9], s[80:81] op_sel_hi:[0,1]
	v_pk_fma_f32 v[10:11], v[2:3], s[8:9], v[8:9] op_sel_hi:[0,1,1]
	v_pk_fma_f32 v[2:3], v[2:3], s[8:9], v[8:9] op_sel_hi:[0,1,1] neg_lo:[0,0,1] neg_hi:[0,0,1]
	v_mov_b32_e32 v8, v10
	v_mov_b32_e32 v9, v3
	v_pk_fma_f32 v[10:11], v[14:15], 0.5, v[10:11] op_sel_hi:[1,0,1] neg_lo:[0,0,1] neg_hi:[0,0,1]
	v_pk_fma_f32 v[8:9], v[14:15], 0.5, v[8:9] op_sel_hi:[1,0,1]
	v_pk_fma_f32 v[2:3], v[14:15], 0.5, v[2:3] op_sel_hi:[1,0,1] neg_lo:[1,0,0] neg_hi:[1,0,0]
	v_mov_b32_e32 v11, v9
	v_mov_b32_e32 v9, v3
	v_pk_mul_f32 v[168:169], v[10:11], s[6:7] op_sel_hi:[1,0]
	v_pk_mul_f32 v[136:137], v[8:9], s[6:7] op_sel_hi:[1,0]
	v_mov_b32_e32 v49, v119
	v_mov_b32_e32 v75, v113
	v_mov_b32_e32 v53, v111
	v_mov_b32_e32 v77, v109
	v_mov_b32_e32 v57, v83
	v_mov_b32_e32 v71, v107
	v_mov_b32_e32 v55, v103
	v_mov_b32_e32 v73, v101
	v_mov_b32_e32 v59, v99

.LBB0_534:
	v_mov_b32_e32 v2, v210
	s_mov_b32 s43, s8
	v_and_b32_e32 v3, 0xff, v2
	v_lshlrev_b32_e32 v4, 5, v2
	v_and_or_b32 v3, v4, s33, v3
	v_ashrrev_i32_e32 v4, 5, v3
	v_lshlrev_b32_e32 v3, 3, v3
	v_lshlrev_b32_e32 v4, 3, v4
	v_add3_u32 v18, 0, v3, v4
	ds_read_b64 v[128:129], v18
	ds_read_b64 v[132:133], v18 offset:2112
	ds_read_b64 v[134:135], v18 offset:4224
	ds_read_b64 v[136:137], v18 offset:6336
	ds_read_b64 v[138:139], v18 offset:8448
	ds_read_b64 v[140:141], v18 offset:10560
	ds_read_b64 v[142:143], v18 offset:12672
	ds_read_b64 v[130:131], v18 offset:14784
	ds_read_b64 v[144:145], v18 offset:16896
	ds_read_b64 v[148:149], v18 offset:19008
	ds_read_b64 v[150:151], v18 offset:21120
	ds_read_b64 v[152:153], v18 offset:23232
	s_waitcnt lgkmcnt(10)
	v_pk_mul_f32 v[162:163], v[132:133], s[10:11]
	s_mov_b32 s64, s11
	v_pk_fma_f32 v[162:163], v[132:133], s[8:9], v[162:163] op_sel:[0,0,1] op_sel_hi:[1,0,0]
	s_waitcnt lgkmcnt(2)
	v_pk_mul_f32 v[178:179], v[148:149], s[42:43]
	v_pk_add_f32 v[194:195], v[132:133], v[148:149]
	v_pk_add_f32 v[132:133], v[132:133], v[148:149] neg_lo:[0,1] neg_hi:[0,1]
	v_pk_mul_f32 v[164:165], v[134:135], s[18:19]
	s_mov_b32 s41, s16
	v_pk_fma_f32 v[178:179], v[148:149], s[64:65], v[178:179] op_sel:[0,0,1] op_sel_hi:[1,0,0] neg_lo:[1,0,0] neg_hi:[1,0,0]
	v_pk_mul_f32 v[148:149], v[132:133], s[18:19]
	v_pk_fma_f32 v[164:165], v[134:135], s[16:17], v[164:165] op_sel:[0,0,1] op_sel_hi:[1,0,0]
	s_mov_b32 s68, s19
	s_waitcnt lgkmcnt(1)
	v_pk_mul_f32 v[180:181], v[150:151], s[40:41]
	v_pk_fma_f32 v[132:133], v[132:133], s[16:17], v[148:149] op_sel:[0,0,1] op_sel_hi:[1,0,0]
	v_pk_add_f32 v[148:149], v[134:135], v[150:151]
	v_pk_add_f32 v[134:135], v[134:135], v[150:151] neg_lo:[0,1] neg_hi:[0,1]
	v_pk_mul_f32 v[166:167], v[136:137], s[26:27]
	s_mov_b32 s66, s37
	s_mov_b32 s39, s24
	v_pk_fma_f32 v[180:181], v[150:151], s[68:69], v[180:181] op_sel:[0,0,1] op_sel_hi:[1,0,0] neg_lo:[1,0,0] neg_hi:[1,0,0]
	v_pk_mul_f32 v[150:151], v[134:135], s[36:37]
	ds_read_b64 v[154:155], v18 offset:25344
	ds_read_b64 v[156:157], v18 offset:27456
	ds_read_b64 v[158:159], v18 offset:29568
	ds_read_b64 v[160:161], v18 offset:31680
	v_pk_fma_f32 v[166:167], v[136:137], s[24:25], v[166:167] op_sel:[0,0,1] op_sel_hi:[1,0,0]
	s_mov_b32 s0, s27
	s_waitcnt lgkmcnt(4)
	v_pk_mul_f32 v[182:183], v[152:153], s[38:39]
	v_pk_fma_f32 v[134:135], v[134:135], s[66:67], v[150:151] op_sel:[0,0,1] op_sel_hi:[1,0,0]
	v_pk_add_f32 v[150:151], v[136:137], v[152:153]
	v_pk_add_f32 v[136:137], v[136:137], v[152:153] neg_lo:[0,1] neg_hi:[0,1]
	v_pk_mul_f32 v[168:169], v[138:139], s[36:37]
	v_pk_fma_f32 v[182:183], v[152:153], s[0:1], v[182:183] op_sel:[0,0,1] op_sel_hi:[1,0,0] neg_lo:[1,0,0] neg_hi:[1,0,0]
	v_pk_mul_f32 v[152:153], v[136:137], s[40:41]
	v_pk_fma_f32 v[168:169], v[138:139], s[66:67], v[168:169] op_sel:[0,0,1] op_sel_hi:[1,0,0]
	v_pk_mul_f32 v[170:171], v[140:141], s[38:39]
	s_waitcnt lgkmcnt(3)
	v_pk_mul_f32 v[184:185], v[154:155], s[36:37]
	v_pk_fma_f32 v[136:137], v[136:137], s[68:69], v[152:153] op_sel:[0,0,1] op_sel_hi:[1,0,0]
	v_pk_add_f32 v[152:153], v[138:139], v[154:155]
	v_pk_add_f32 v[138:139], v[138:139], v[154:155] neg_lo:[0,1] neg_hi:[0,1]
	v_pk_fma_f32 v[170:171], v[140:141], s[0:1], v[170:171] op_sel:[0,0,1] op_sel_hi:[1,0,0]
	v_pk_fma_f32 v[184:185], v[154:155], s[66:67], v[184:185] op_sel:[0,0,1] op_sel_hi:[1,0,0] neg_lo:[1,0,0] neg_hi:[1,0,0]
	s_waitcnt lgkmcnt(2)
	v_pk_mul_f32 v[186:187], v[156:157], s[26:27]
	v_xor_b32_e32 v155, 0x80000000, v138
	v_mov_b32_e32 v154, v139
	v_pk_add_f32 v[138:139], v[140:141], v[156:157]
	v_pk_add_f32 v[140:141], v[140:141], v[156:157] neg_lo:[0,1] neg_hi:[0,1]
	v_pk_mul_f32 v[172:173], v[142:143], s[40:41]
	v_pk_fma_f32 v[186:187], v[156:157], s[24:25], v[186:187] op_sel:[0,0,1] op_sel_hi:[1,0,0] neg_lo:[1,0,0] neg_hi:[1,0,0]
	v_pk_mul_f32 v[156:157], v[140:141], s[40:41]
	v_pk_fma_f32 v[172:173], v[142:143], s[68:69], v[172:173] op_sel:[0,0,1] op_sel_hi:[1,0,0]
	s_waitcnt lgkmcnt(1)
	v_pk_mul_f32 v[188:189], v[158:159], s[18:19]
	v_pk_fma_f32 v[140:141], v[140:141], s[68:69], v[156:157] op_sel:[0,0,1] op_sel_hi:[1,0,0] neg_lo:[1,0,0] neg_hi:[1,0,0]
	v_pk_add_f32 v[156:157], v[142:143], v[158:159]
	v_pk_add_f32 v[142:143], v[142:143], v[158:159] neg_lo:[0,1] neg_hi:[0,1]
	v_pk_mul_f32 v[174:175], v[130:131], s[42:43]
	v_pk_fma_f32 v[188:189], v[158:159], s[16:17], v[188:189] op_sel:[0,0,1] op_sel_hi:[1,0,0] neg_lo:[1,0,0] neg_hi:[1,0,0]
	v_pk_mul_f32 v[158:159], v[142:143], s[36:37]
	v_pk_fma_f32 v[174:175], v[130:131], s[64:65], v[174:175] op_sel:[0,0,1] op_sel_hi:[1,0,0]
	s_waitcnt lgkmcnt(0)
	v_pk_mul_f32 v[190:191], v[160:161], s[10:11]
	v_pk_fma_f32 v[142:143], v[142:143], s[66:67], v[158:159] op_sel:[0,0,1] op_sel_hi:[1,0,0] neg_lo:[1,0,0] neg_hi:[1,0,0]
	v_pk_add_f32 v[158:159], v[130:131], v[160:161]
	v_pk_add_f32 v[130:131], v[130:131], v[160:161] neg_lo:[0,1] neg_hi:[0,1]
	v_xor_b32_e32 v177, 0x80000000, v144
	v_mov_b32_e32 v176, v145
	v_pk_fma_f32 v[190:191], v[160:161], s[8:9], v[190:191] op_sel:[0,0,1] op_sel_hi:[1,0,0] neg_lo:[1,0,0] neg_hi:[1,0,0]
	v_pk_mul_f32 v[160:161], v[130:131], s[18:19]
	v_pk_add_f32 v[192:193], v[128:129], v[144:145]
	v_pk_add_f32 v[144:145], v[128:129], v[144:145] neg_lo:[0,1] neg_hi:[0,1]
	v_pk_fma_f32 v[130:131], v[130:131], s[16:17], v[160:161] op_sel:[0,0,1] op_sel_hi:[1,0,0] neg_lo:[1,0,0] neg_hi:[1,0,0]
	v_pk_add_f32 v[160:161], v[128:129], v[176:177]
	v_pk_add_f32 v[128:129], v[128:129], v[176:177] neg_lo:[0,1] neg_hi:[0,1]
	v_pk_add_f32 v[176:177], v[162:163], v[178:179]
	v_pk_add_f32 v[162:163], v[162:163], v[178:179] neg_lo:[0,1] neg_hi:[0,1]
	v_cvt_f32_ubyte0_e32 v2, v2
	v_pk_mul_f32 v[178:179], v[162:163], s[18:19]
	v_mul_f32_e32 v2, 0x39000000, v2
	v_pk_fma_f32 v[162:163], v[162:163], s[16:17], v[178:179] op_sel:[0,0,1] op_sel_hi:[1,0,0]
	v_pk_add_f32 v[178:179], v[164:165], v[180:181]
	v_pk_add_f32 v[164:165], v[164:165], v[180:181] neg_lo:[0,1] neg_hi:[0,1]
	v_sin_f32_e32 v34, v2
	v_pk_mul_f32 v[180:181], v[164:165], s[36:37]
	v_cos_f32_e32 v30, v2
	v_pk_fma_f32 v[164:165], v[164:165], s[66:67], v[180:181] op_sel:[0,0,1] op_sel_hi:[1,0,0]
	v_pk_add_f32 v[180:181], v[166:167], v[182:183]
	v_pk_add_f32 v[166:167], v[166:167], v[182:183] neg_lo:[0,1] neg_hi:[0,1]
	v_xor_b32_e32 v31, 0x80000000, v34
	v_pk_mul_f32 v[182:183], v[166:167], s[40:41]
	v_mov_b32_e32 v35, v31
	v_pk_fma_f32 v[166:167], v[166:167], s[68:69], v[182:183] op_sel:[0,0,1] op_sel_hi:[1,0,0]
	v_pk_add_f32 v[182:183], v[168:169], v[184:185]
	v_pk_add_f32 v[184:185], v[168:169], v[184:185] neg_lo:[0,1] neg_hi:[0,1]
	v_pk_mul_f32 v[2:3], v[30:31], v[34:35] op_sel:[1,0] op_sel_hi:[0,1]
	v_pk_add_f32 v[168:169], v[170:171], v[186:187]
	v_pk_add_f32 v[170:171], v[170:171], v[186:187] neg_lo:[0,1] neg_hi:[0,1]
	v_pk_fma_f32 v[44:45], v[30:31], v[30:31], v[2:3] op_sel_hi:[1,0,1]
	v_pk_mul_f32 v[186:187], v[170:171], s[40:41]
	v_pk_mul_f32 v[2:3], v[34:35], v[44:45] op_sel:[0,1] op_sel_hi:[1,0]
	v_pk_fma_f32 v[170:171], v[170:171], s[68:69], v[186:187] op_sel:[0,0,1] op_sel_hi:[1,0,0] neg_lo:[1,0,0] neg_hi:[1,0,0]
	v_pk_add_f32 v[186:187], v[172:173], v[188:189]
	v_pk_add_f32 v[172:173], v[172:173], v[188:189] neg_lo:[0,1] neg_hi:[0,1]
	v_xor_b32_e32 v54, 0x80000000, v45
	v_pk_mul_f32 v[188:189], v[172:173], s[36:37]
	v_mov_b32_e32 v55, v45
	v_pk_fma_f32 v[172:173], v[172:173], s[66:67], v[188:189] op_sel:[0,0,1] op_sel_hi:[1,0,0] neg_lo:[1,0,0] neg_hi:[1,0,0]
	v_pk_add_f32 v[188:189], v[174:175], v[190:191]
	v_pk_add_f32 v[174:175], v[174:175], v[190:191] neg_lo:[0,1] neg_hi:[0,1]
	v_pk_fma_f32 v[46:47], v[30:31], v[44:45], v[2:3] op_sel_hi:[0,1,1]
	v_pk_mul_f32 v[190:191], v[174:175], s[18:19]
	v_pk_mul_f32 v[2:3], v[44:45], v[54:55] op_sel:[1,0] op_sel_hi:[0,1]
	v_pk_fma_f32 v[174:175], v[174:175], s[16:17], v[190:191] op_sel:[0,0,1] op_sel_hi:[1,0,0] neg_lo:[1,0,0] neg_hi:[1,0,0]
	v_pk_add_f32 v[190:191], v[192:193], v[152:153]
	v_pk_add_f32 v[152:153], v[192:193], v[152:153] neg_lo:[0,1] neg_hi:[0,1]
	v_pk_add_f32 v[192:193], v[194:195], v[138:139]
	v_pk_add_f32 v[138:139], v[194:195], v[138:139] neg_lo:[0,1] neg_hi:[0,1]
	v_pk_fma_f32 v[52:53], v[44:45], v[44:45], v[2:3] op_sel_hi:[1,0,1]
	v_pk_mul_f32 v[194:195], v[138:139], s[36:37]
	v_xor_b32_e32 v58, 0x80000000, v53
	v_pk_fma_f32 v[138:139], v[138:139], s[66:67], v[194:195] op_sel:[0,0,1] op_sel_hi:[1,0,0]
	v_pk_add_f32 v[194:195], v[148:149], v[156:157]
	v_pk_add_f32 v[156:157], v[148:149], v[156:157] neg_lo:[0,1] neg_hi:[0,1]
	v_mov_b32_e32 v59, v53
	v_pk_add_f32 v[148:149], v[150:151], v[158:159]
	v_pk_add_f32 v[150:151], v[150:151], v[158:159] neg_lo:[0,1] neg_hi:[0,1]
	v_pk_mul_f32 v[2:3], v[52:53], v[58:59] op_sel:[1,0] op_sel_hi:[0,1]
	v_pk_mul_f32 v[158:159], v[150:151], s[36:37]
	v_pk_fma_f32 v[48:49], v[52:53], v[52:53], v[2:3] op_sel_hi:[1,0,1]
	v_pk_fma_f32 v[150:151], v[150:151], s[66:67], v[158:159] op_sel:[0,0,1] op_sel_hi:[1,0,0] neg_lo:[1,0,0] neg_hi:[1,0,0]
	v_pk_add_f32 v[158:159], v[144:145], v[154:155]
	v_pk_add_f32 v[144:145], v[144:145], v[154:155] neg_lo:[0,1] neg_hi:[0,1]
	v_pk_add_f32 v[154:155], v[132:133], v[140:141]
	v_pk_add_f32 v[132:133], v[132:133], v[140:141] neg_lo:[0,1] neg_hi:[0,1]
	v_pk_mul_f32 v[2:3], v[58:59], v[48:49] op_sel:[0,1] op_sel_hi:[1,0]
	v_pk_mul_f32 v[140:141], v[132:133], s[36:37]
	v_pk_fma_f32 v[36:37], v[52:53], v[48:49], v[2:3] op_sel_hi:[0,1,1]
	v_pk_fma_f32 v[132:133], v[132:133], s[66:67], v[140:141] op_sel:[0,0,1] op_sel_hi:[1,0,0]
	v_pk_add_f32 v[140:141], v[134:135], v[142:143]
	v_pk_add_f32 v[142:143], v[134:135], v[142:143] neg_lo:[0,1] neg_hi:[0,1]
	v_pk_mul_f32 v[2:3], v[58:59], v[36:37] op_sel:[0,1] op_sel_hi:[1,0]
	v_pk_add_f32 v[134:135], v[136:137], v[130:131]
	v_pk_add_f32 v[130:131], v[136:137], v[130:131] neg_lo:[0,1] neg_hi:[0,1]
	v_pk_fma_f32 v[26:27], v[52:53], v[36:37], v[2:3] op_sel_hi:[0,1,1]
	v_pk_mul_f32 v[136:137], v[130:131], s[36:37]
	v_pk_mul_f32 v[2:3], v[58:59], v[26:27] op_sel:[0,1] op_sel_hi:[1,0]
	v_pk_fma_f32 v[130:131], v[130:131], s[66:67], v[136:137] op_sel:[0,0,1] op_sel_hi:[1,0,0] neg_lo:[1,0,0] neg_hi:[1,0,0]
	v_pk_add_f32 v[136:137], v[160:161], v[182:183]
	v_pk_add_f32 v[160:161], v[160:161], v[182:183] neg_lo:[0,1] neg_hi:[0,1]
	v_pk_add_f32 v[182:183], v[176:177], v[168:169]
	v_pk_add_f32 v[168:169], v[176:177], v[168:169] neg_lo:[0,1] neg_hi:[0,1]
	v_pk_fma_f32 v[20:21], v[52:53], v[26:27], v[2:3] op_sel_hi:[0,1,1]
	v_pk_mul_f32 v[176:177], v[168:169], s[36:37]
	v_pk_mul_f32 v[2:3], v[58:59], v[20:21] op_sel:[0,1] op_sel_hi:[1,0]
	v_pk_fma_f32 v[168:169], v[168:169], s[66:67], v[176:177] op_sel:[0,0,1] op_sel_hi:[1,0,0]
	v_pk_add_f32 v[176:177], v[178:179], v[186:187]
	v_pk_add_f32 v[186:187], v[178:179], v[186:187] neg_lo:[0,1] neg_hi:[0,1]
	v_pk_fma_f32 v[10:11], v[52:53], v[20:21], v[2:3] op_sel_hi:[0,1,1]
	v_pk_add_f32 v[178:179], v[180:181], v[188:189]
	v_pk_add_f32 v[180:181], v[180:181], v[188:189] neg_lo:[0,1] neg_hi:[0,1]
	v_pk_mul_f32 v[2:3], v[58:59], v[10:11] op_sel:[0,1] op_sel_hi:[1,0]
	v_pk_mul_f32 v[188:189], v[180:181], s[36:37]
	v_pk_fma_f32 v[4:5], v[52:53], v[10:11], v[2:3] op_sel_hi:[0,1,1]
	v_pk_fma_f32 v[180:181], v[180:181], s[66:67], v[188:189] op_sel:[0,0,1] op_sel_hi:[1,0,0] neg_lo:[1,0,0] neg_hi:[1,0,0]
	v_pk_add_f32 v[188:189], v[128:129], v[184:185] op_sel:[0,1] op_sel_hi:[1,0] neg_hi:[0,1]
	v_pk_add_f32 v[128:129], v[128:129], v[184:185] op_sel:[0,1] op_sel_hi:[1,0] neg_lo:[0,1]
	v_pk_add_f32 v[184:185], v[162:163], v[170:171]
	v_pk_add_f32 v[162:163], v[162:163], v[170:171] neg_lo:[0,1] neg_hi:[0,1]
	v_xor_b32_e32 v72, 0x80000000, v47
	v_pk_mul_f32 v[170:171], v[162:163], s[36:37]
	v_mov_b32_e32 v73, v47
	v_pk_fma_f32 v[162:163], v[162:163], s[66:67], v[170:171] op_sel:[0,0,1] op_sel_hi:[1,0,0]
	v_pk_add_f32 v[170:171], v[164:165], v[172:173]
	v_pk_add_f32 v[172:173], v[164:165], v[172:173] neg_lo:[0,1] neg_hi:[0,1]
	v_pk_mul_f32 v[2:3], v[72:73], v[4:5] op_sel:[0,1] op_sel_hi:[1,0]
	v_pk_add_f32 v[164:165], v[166:167], v[174:175]
	v_pk_add_f32 v[166:167], v[166:167], v[174:175] neg_lo:[0,1] neg_hi:[0,1]
	v_pk_mul_f32 v[14:15], v[34:35], v[4:5] op_sel:[0,1] op_sel_hi:[1,0]
	v_pk_mul_f32 v[174:175], v[166:167], s[36:37]
	v_pk_mul_f32 v[40:41], v[34:35], v[10:11] op_sel:[0,1] op_sel_hi:[1,0]
	v_pk_fma_f32 v[166:167], v[166:167], s[66:67], v[174:175] op_sel:[0,0,1] op_sel_hi:[1,0,0] neg_lo:[1,0,0] neg_hi:[1,0,0]
	v_pk_add_f32 v[174:175], v[190:191], v[194:195]
	v_pk_add_f32 v[190:191], v[190:191], v[194:195] neg_lo:[0,1] neg_hi:[0,1]
	v_pk_add_f32 v[194:195], v[192:193], v[148:149]
	v_pk_add_f32 v[192:193], v[192:193], v[148:149] neg_lo:[0,1] neg_hi:[0,1]
	v_pk_mul_f32 v[66:67], v[34:35], v[20:21] op_sel:[0,1] op_sel_hi:[1,0]
	v_pk_add_f32 v[148:149], v[152:153], v[156:157] op_sel:[0,1] op_sel_hi:[1,0] neg_hi:[0,1]
	v_pk_add_f32 v[152:153], v[152:153], v[156:157] op_sel:[0,1] op_sel_hi:[1,0] neg_lo:[0,1]
	v_pk_add_f32 v[156:157], v[138:139], v[150:151]
	v_pk_add_f32 v[150:151], v[138:139], v[150:151] neg_lo:[0,1] neg_hi:[0,1]
	v_pk_mul_f32 v[82:83], v[34:35], v[26:27] op_sel:[0,1] op_sel_hi:[1,0]
	v_pk_add_f32 v[138:139], v[158:159], v[140:141]
	v_pk_add_f32 v[140:141], v[158:159], v[140:141] neg_lo:[0,1] neg_hi:[0,1]
	v_pk_add_f32 v[158:159], v[154:155], v[134:135]
	v_pk_add_f32 v[154:155], v[154:155], v[134:135] neg_lo:[0,1] neg_hi:[0,1]
	v_pk_mul_f32 v[96:97], v[34:35], v[36:37] op_sel:[0,1] op_sel_hi:[1,0]
	v_pk_add_f32 v[134:135], v[144:145], v[142:143] op_sel:[0,1] op_sel_hi:[1,0] neg_hi:[0,1]
	v_pk_add_f32 v[142:143], v[144:145], v[142:143] op_sel:[0,1] op_sel_hi:[1,0] neg_lo:[0,1]
	v_pk_add_f32 v[144:145], v[132:133], v[130:131]
	v_pk_add_f32 v[132:133], v[132:133], v[130:131] neg_lo:[0,1] neg_hi:[0,1]
	v_pk_mul_f32 v[110:111], v[34:35], v[48:49] op_sel:[0,1] op_sel_hi:[1,0]
	v_pk_add_f32 v[130:131], v[136:137], v[176:177]
	v_pk_add_f32 v[136:137], v[136:137], v[176:177] neg_lo:[0,1] neg_hi:[0,1]
	v_pk_add_f32 v[176:177], v[182:183], v[178:179]
	v_pk_add_f32 v[182:183], v[182:183], v[178:179] neg_lo:[0,1] neg_hi:[0,1]
	v_pk_mul_f32 v[124:125], v[34:35], v[52:53] op_sel:[0,1] op_sel_hi:[1,0]
	v_pk_add_f32 v[178:179], v[160:161], v[186:187] op_sel:[0,1] op_sel_hi:[1,0] neg_hi:[0,1]
	v_pk_add_f32 v[160:161], v[160:161], v[186:187] op_sel:[0,1] op_sel_hi:[1,0] neg_lo:[0,1]
	v_pk_add_f32 v[186:187], v[168:169], v[180:181]
	v_pk_add_f32 v[180:181], v[168:169], v[180:181] neg_lo:[0,1] neg_hi:[0,1]
	v_pk_fma_f32 v[2:3], v[46:47], v[4:5], v[2:3] op_sel_hi:[0,1,1]
	v_pk_add_f32 v[168:169], v[188:189], v[170:171]
	v_pk_add_f32 v[170:171], v[188:189], v[170:171] neg_lo:[0,1] neg_hi:[0,1]
	v_pk_add_f32 v[188:189], v[184:185], v[164:165]
	v_pk_add_f32 v[184:185], v[184:185], v[164:165] neg_lo:[0,1] neg_hi:[0,1]
	v_pk_mul_f32 v[8:9], v[54:55], v[4:5] op_sel:[0,1] op_sel_hi:[1,0]
	v_pk_add_f32 v[164:165], v[128:129], v[172:173] op_sel:[0,1] op_sel_hi:[1,0] neg_hi:[0,1]
	v_pk_add_f32 v[128:129], v[128:129], v[172:173] op_sel:[0,1] op_sel_hi:[1,0] neg_lo:[0,1]
	v_pk_add_f32 v[172:173], v[162:163], v[166:167]
	v_pk_add_f32 v[166:167], v[162:163], v[166:167] neg_lo:[0,1] neg_hi:[0,1]
	v_pk_fma_f32 v[14:15], v[30:31], v[4:5], v[14:15] op_sel_hi:[0,1,1]
	v_pk_add_f32 v[162:163], v[174:175], v[194:195]
	v_pk_add_f32 v[174:175], v[174:175], v[194:195] neg_lo:[0,1] neg_hi:[0,1]
	v_pk_add_f32 v[194:195], v[190:191], v[192:193] op_sel:[0,1] op_sel_hi:[1,0] neg_hi:[0,1]
	v_pk_add_f32 v[190:191], v[190:191], v[192:193] op_sel:[0,1] op_sel_hi:[1,0] neg_lo:[0,1]
	v_pk_add_f32 v[192:193], v[148:149], v[156:157]
	v_pk_add_f32 v[148:149], v[148:149], v[156:157] neg_lo:[0,1] neg_hi:[0,1]
	v_pk_add_f32 v[156:157], v[152:153], v[150:151] op_sel:[0,1] op_sel_hi:[1,0] neg_hi:[0,1]
	v_pk_add_f32 v[150:151], v[152:153], v[150:151] op_sel:[0,1] op_sel_hi:[1,0] neg_lo:[0,1]
	v_pk_add_f32 v[152:153], v[138:139], v[158:159]
	v_pk_add_f32 v[138:139], v[138:139], v[158:159] neg_lo:[0,1] neg_hi:[0,1]
	v_pk_add_f32 v[158:159], v[140:141], v[154:155] op_sel:[0,1] op_sel_hi:[1,0] neg_hi:[0,1]
	v_pk_add_f32 v[140:141], v[140:141], v[154:155] op_sel:[0,1] op_sel_hi:[1,0] neg_lo:[0,1]
	v_pk_add_f32 v[154:155], v[134:135], v[144:145]
	v_pk_add_f32 v[134:135], v[134:135], v[144:145] neg_lo:[0,1] neg_hi:[0,1]
	v_pk_add_f32 v[144:145], v[142:143], v[132:133] op_sel:[0,1] op_sel_hi:[1,0] neg_hi:[0,1]
	v_pk_add_f32 v[132:133], v[142:143], v[132:133] op_sel:[0,1] op_sel_hi:[1,0] neg_lo:[0,1]
	v_pk_add_f32 v[142:143], v[130:131], v[176:177]
	v_pk_mul_f32 v[24:25], v[72:73], v[10:11] op_sel:[0,1] op_sel_hi:[1,0]
	v_pk_mul_f32 v[34:35], v[34:35], v[142:143] op_sel:[0,1] op_sel_hi:[1,0]
	v_pk_mul_f32 v[32:33], v[54:55], v[10:11] op_sel:[0,1] op_sel_hi:[1,0]
	v_pk_fma_f32 v[40:41], v[30:31], v[10:11], v[40:41] op_sel_hi:[0,1,1]
	v_pk_mul_f32 v[56:57], v[72:73], v[20:21] op_sel:[0,1] op_sel_hi:[1,0]
	v_pk_mul_f32 v[62:63], v[54:55], v[20:21] op_sel:[0,1] op_sel_hi:[1,0]
	v_pk_fma_f32 v[66:67], v[30:31], v[20:21], v[66:67] op_sel_hi:[0,1,1]
	v_pk_mul_f32 v[74:75], v[72:73], v[26:27] op_sel:[0,1] op_sel_hi:[1,0]
	v_pk_mul_f32 v[78:79], v[54:55], v[26:27] op_sel:[0,1] op_sel_hi:[1,0]
	v_pk_fma_f32 v[82:83], v[30:31], v[26:27], v[82:83] op_sel_hi:[0,1,1]
	v_pk_mul_f32 v[88:89], v[72:73], v[36:37] op_sel:[0,1] op_sel_hi:[1,0]
	v_pk_mul_f32 v[92:93], v[54:55], v[36:37] op_sel:[0,1] op_sel_hi:[1,0]
	v_pk_fma_f32 v[96:97], v[30:31], v[36:37], v[96:97] op_sel_hi:[0,1,1]
	v_pk_mul_f32 v[102:103], v[72:73], v[48:49] op_sel:[0,1] op_sel_hi:[1,0]
	v_pk_mul_f32 v[106:107], v[54:55], v[48:49] op_sel:[0,1] op_sel_hi:[1,0]
	v_pk_fma_f32 v[110:111], v[30:31], v[48:49], v[110:111] op_sel_hi:[0,1,1]
	v_pk_mul_f32 v[116:117], v[52:53], v[72:73] op_sel:[1,0] op_sel_hi:[0,1]
	v_pk_mul_f32 v[120:121], v[54:55], v[52:53] op_sel:[0,1] op_sel_hi:[1,0]
	v_pk_fma_f32 v[124:125], v[30:31], v[52:53], v[124:125] op_sel_hi:[0,1,1]
	v_pk_add_f32 v[130:131], v[130:131], v[176:177] neg_lo:[0,1] neg_hi:[0,1]
	v_pk_add_f32 v[176:177], v[136:137], v[182:183] op_sel:[0,1] op_sel_hi:[1,0] neg_hi:[0,1]
	v_pk_add_f32 v[136:137], v[136:137], v[182:183] op_sel:[0,1] op_sel_hi:[1,0] neg_lo:[0,1]
	v_pk_add_f32 v[182:183], v[178:179], v[186:187]
	v_pk_add_f32 v[178:179], v[178:179], v[186:187] neg_lo:[0,1] neg_hi:[0,1]
	v_pk_add_f32 v[186:187], v[160:161], v[180:181] op_sel:[0,1] op_sel_hi:[1,0] neg_hi:[0,1]
	v_pk_add_f32 v[160:161], v[160:161], v[180:181] op_sel:[0,1] op_sel_hi:[1,0] neg_lo:[0,1]
	v_pk_add_f32 v[180:181], v[168:169], v[188:189]
	v_pk_fma_f32 v[30:31], v[30:31], v[142:143], v[34:35] op_sel_hi:[0,1,1]
	v_pk_mul_f32 v[34:35], v[54:55], v[152:153] op_sel:[0,1] op_sel_hi:[1,0]
	v_xor_b32_e32 v6, 0x80000000, v3
	v_pk_fma_f32 v[8:9], v[44:45], v[4:5], v[8:9] op_sel_hi:[0,1,1]
	v_pk_fma_f32 v[24:25], v[46:47], v[10:11], v[24:25] op_sel_hi:[0,1,1]
	v_pk_fma_f32 v[32:33], v[44:45], v[10:11], v[32:33] op_sel_hi:[0,1,1]
	v_pk_fma_f32 v[56:57], v[46:47], v[20:21], v[56:57] op_sel_hi:[0,1,1]
	v_pk_fma_f32 v[62:63], v[44:45], v[20:21], v[62:63] op_sel_hi:[0,1,1]
	v_pk_fma_f32 v[74:75], v[46:47], v[26:27], v[74:75] op_sel_hi:[0,1,1]
	v_pk_fma_f32 v[78:79], v[44:45], v[26:27], v[78:79] op_sel_hi:[0,1,1]
	v_pk_fma_f32 v[88:89], v[46:47], v[36:37], v[88:89] op_sel_hi:[0,1,1]
	v_pk_fma_f32 v[92:93], v[44:45], v[36:37], v[92:93] op_sel_hi:[0,1,1]
	v_pk_fma_f32 v[102:103], v[46:47], v[48:49], v[102:103] op_sel_hi:[0,1,1]
	v_pk_fma_f32 v[106:107], v[44:45], v[48:49], v[106:107] op_sel_hi:[0,1,1]
	v_xor_b32_e32 v114, 0x80000000, v49
	v_pk_fma_f32 v[116:117], v[52:53], v[46:47], v[116:117] op_sel_hi:[1,0,1]
	v_pk_fma_f32 v[120:121], v[44:45], v[52:53], v[120:121] op_sel_hi:[0,1,1]
	v_mov_b32_e32 v115, v49
	v_mov_b32_e32 v7, v3
	v_pk_add_f32 v[168:169], v[168:169], v[188:189] neg_lo:[0,1] neg_hi:[0,1]
	v_pk_add_f32 v[188:189], v[170:171], v[184:185] op_sel:[0,1] op_sel_hi:[1,0] neg_hi:[0,1]
	v_pk_add_f32 v[170:171], v[170:171], v[184:185] op_sel:[0,1] op_sel_hi:[1,0] neg_lo:[0,1]
	v_pk_add_f32 v[184:185], v[164:165], v[172:173]
	v_pk_add_f32 v[164:165], v[164:165], v[172:173] neg_lo:[0,1] neg_hi:[0,1]
	v_pk_add_f32 v[172:173], v[128:129], v[166:167] op_sel:[0,1] op_sel_hi:[1,0] neg_hi:[0,1]
	v_pk_add_f32 v[128:129], v[128:129], v[166:167] op_sel:[0,1] op_sel_hi:[1,0] neg_lo:[0,1]
	v_pk_fma_f32 v[34:35], v[44:45], v[152:153], v[34:35] op_sel_hi:[0,1,1]
	v_pk_mul_f32 v[44:45], v[72:73], v[180:181] op_sel:[0,1] op_sel_hi:[1,0]
	v_xor_b32_e32 v12, 0x80000000, v9
	v_xor_b32_e32 v16, 0x80000000, v15
	v_xor_b32_e32 v22, 0x80000000, v5
	v_xor_b32_e32 v28, 0x80000000, v25
	v_xor_b32_e32 v38, 0x80000000, v33
	v_xor_b32_e32 v42, 0x80000000, v41
	v_xor_b32_e32 v50, 0x80000000, v11
	v_xor_b32_e32 v60, 0x80000000, v57
	v_xor_b32_e32 v64, 0x80000000, v63
	v_xor_b32_e32 v68, 0x80000000, v67
	v_xor_b32_e32 v70, 0x80000000, v21
	v_xor_b32_e32 v76, 0x80000000, v75
	v_xor_b32_e32 v80, 0x80000000, v79
	v_xor_b32_e32 v84, 0x80000000, v83
	v_xor_b32_e32 v86, 0x80000000, v27
	v_xor_b32_e32 v90, 0x80000000, v89
	v_xor_b32_e32 v94, 0x80000000, v93
	v_xor_b32_e32 v98, 0x80000000, v97
	v_xor_b32_e32 v100, 0x80000000, v37
	v_xor_b32_e32 v104, 0x80000000, v103
	v_xor_b32_e32 v108, 0x80000000, v107
	v_xor_b32_e32 v112, 0x80000000, v111
	v_xor_b32_e32 v118, 0x80000000, v117
	v_xor_b32_e32 v122, 0x80000000, v121
	v_xor_b32_e32 v126, 0x80000000, v125
	v_mov_b32_e32 v127, v125
	v_mov_b32_e32 v123, v121
	v_mov_b32_e32 v119, v117
	v_mov_b32_e32 v113, v111
	v_mov_b32_e32 v109, v107
	v_mov_b32_e32 v105, v103
	v_mov_b32_e32 v101, v37
	v_mov_b32_e32 v99, v97
	v_mov_b32_e32 v95, v93
	v_mov_b32_e32 v91, v89
	v_mov_b32_e32 v87, v27
	v_mov_b32_e32 v85, v83
	v_mov_b32_e32 v81, v79
	v_mov_b32_e32 v77, v75
	v_mov_b32_e32 v71, v21
	v_mov_b32_e32 v69, v67
	v_mov_b32_e32 v65, v63
	v_mov_b32_e32 v61, v57
	v_mov_b32_e32 v51, v11
	v_mov_b32_e32 v43, v41
	v_mov_b32_e32 v39, v33
	v_mov_b32_e32 v29, v25
	v_mov_b32_e32 v23, v5
	v_mov_b32_e32 v17, v15
	v_mov_b32_e32 v13, v9
	v_pk_fma_f32 v[44:45], v[46:47], v[180:181], v[44:45] op_sel_hi:[0,1,1]
	v_pk_mul_f32 v[46:47], v[58:59], v[192:193] op_sel:[0,1] op_sel_hi:[1,0]
	v_pk_mul_f32 v[72:73], v[114:115], v[194:195] op_sel:[0,1] op_sel_hi:[1,0]
	v_pk_mul_f32 v[6:7], v[128:129], v[6:7] op_sel:[1,0] op_sel_hi:[0,1]
	v_pk_fma_f32 v[46:47], v[52:53], v[192:193], v[46:47] op_sel_hi:[0,1,1]
	v_pk_mul_f32 v[52:53], v[126:127], v[182:183] op_sel:[0,1] op_sel_hi:[1,0]
	v_pk_mul_f32 v[54:55], v[122:123], v[154:155] op_sel:[0,1] op_sel_hi:[1,0]
	v_pk_mul_f32 v[58:59], v[118:119], v[184:185] op_sel:[0,1] op_sel_hi:[1,0]
	v_pk_fma_f32 v[48:49], v[48:49], v[194:195], v[72:73] op_sel_hi:[0,1,1]
	v_pk_mul_f32 v[72:73], v[112:113], v[176:177] op_sel:[0,1] op_sel_hi:[1,0]
	v_pk_mul_f32 v[108:109], v[108:109], v[158:159] op_sel:[0,1] op_sel_hi:[1,0]
	v_pk_mul_f32 v[104:105], v[104:105], v[188:189] op_sel:[0,1] op_sel_hi:[1,0]
	v_pk_mul_f32 v[100:101], v[100:101], v[156:157] op_sel:[0,1] op_sel_hi:[1,0]
	v_pk_mul_f32 v[98:99], v[98:99], v[186:187] op_sel:[0,1] op_sel_hi:[1,0]
	v_pk_mul_f32 v[94:95], v[94:95], v[144:145] op_sel:[0,1] op_sel_hi:[1,0]
	v_pk_mul_f32 v[90:91], v[90:91], v[172:173] op_sel:[0,1] op_sel_hi:[1,0]
	v_pk_mul_f32 v[86:87], v[174:175], v[86:87] op_sel:[1,0] op_sel_hi:[0,1]
	v_pk_mul_f32 v[84:85], v[130:131], v[84:85] op_sel:[1,0] op_sel_hi:[0,1]
	v_pk_mul_f32 v[80:81], v[138:139], v[80:81] op_sel:[1,0] op_sel_hi:[0,1]
	v_pk_mul_f32 v[76:77], v[168:169], v[76:77] op_sel:[1,0] op_sel_hi:[0,1]
	v_pk_mul_f32 v[70:71], v[148:149], v[70:71] op_sel:[1,0] op_sel_hi:[0,1]
	v_pk_mul_f32 v[68:69], v[178:179], v[68:69] op_sel:[1,0] op_sel_hi:[0,1]
	v_pk_mul_f32 v[64:65], v[134:135], v[64:65] op_sel:[1,0] op_sel_hi:[0,1]
	v_pk_mul_f32 v[60:61], v[164:165], v[60:61] op_sel:[1,0] op_sel_hi:[0,1]
	v_pk_mul_f32 v[50:51], v[190:191], v[50:51] op_sel:[1,0] op_sel_hi:[0,1]
	v_pk_mul_f32 v[42:43], v[136:137], v[42:43] op_sel:[1,0] op_sel_hi:[0,1]
	v_pk_mul_f32 v[38:39], v[140:141], v[38:39] op_sel:[1,0] op_sel_hi:[0,1]
	v_pk_mul_f32 v[28:29], v[170:171], v[28:29] op_sel:[1,0] op_sel_hi:[0,1]
	v_pk_mul_f32 v[22:23], v[150:151], v[22:23] op_sel:[1,0] op_sel_hi:[0,1]
	v_pk_mul_f32 v[16:17], v[160:161], v[16:17] op_sel:[1,0] op_sel_hi:[0,1]
	v_pk_mul_f32 v[12:13], v[132:133], v[12:13] op_sel:[1,0] op_sel_hi:[0,1]
	v_pk_fma_f32 v[2:3], v[128:129], v[2:3], v[6:7] op_sel_hi:[1,0,1]
	v_pk_fma_f32 v[52:53], v[124:125], v[182:183], v[52:53] op_sel_hi:[0,1,1]
	v_pk_fma_f32 v[54:55], v[120:121], v[154:155], v[54:55] op_sel_hi:[0,1,1]
	v_pk_fma_f32 v[58:59], v[116:117], v[184:185], v[58:59] op_sel_hi:[0,1,1]
	v_pk_fma_f32 v[72:73], v[110:111], v[176:177], v[72:73] op_sel_hi:[0,1,1]
	v_pk_fma_f32 v[106:107], v[106:107], v[158:159], v[108:109] op_sel_hi:[0,1,1]
	v_pk_fma_f32 v[102:103], v[102:103], v[188:189], v[104:105] op_sel_hi:[0,1,1]
	v_pk_fma_f32 v[36:37], v[36:37], v[156:157], v[100:101] op_sel_hi:[0,1,1]
	v_pk_fma_f32 v[96:97], v[96:97], v[186:187], v[98:99] op_sel_hi:[0,1,1]
	v_pk_fma_f32 v[92:93], v[92:93], v[144:145], v[94:95] op_sel_hi:[0,1,1]
	v_pk_fma_f32 v[88:89], v[88:89], v[172:173], v[90:91] op_sel_hi:[0,1,1]
	v_pk_fma_f32 v[26:27], v[174:175], v[26:27], v[86:87] op_sel_hi:[1,0,1]
	v_pk_fma_f32 v[82:83], v[130:131], v[82:83], v[84:85] op_sel_hi:[1,0,1]
	v_pk_fma_f32 v[78:79], v[138:139], v[78:79], v[80:81] op_sel_hi:[1,0,1]
	v_pk_fma_f32 v[74:75], v[168:169], v[74:75], v[76:77] op_sel_hi:[1,0,1]
	v_pk_fma_f32 v[20:21], v[148:149], v[20:21], v[70:71] op_sel_hi:[1,0,1]
	v_pk_fma_f32 v[66:67], v[178:179], v[66:67], v[68:69] op_sel_hi:[1,0,1]
	v_pk_fma_f32 v[62:63], v[134:135], v[62:63], v[64:65] op_sel_hi:[1,0,1]
	v_pk_fma_f32 v[56:57], v[164:165], v[56:57], v[60:61] op_sel_hi:[1,0,1]
	v_pk_fma_f32 v[10:11], v[190:191], v[10:11], v[50:51] op_sel_hi:[1,0,1]
	v_pk_fma_f32 v[40:41], v[136:137], v[40:41], v[42:43] op_sel_hi:[1,0,1]
	v_pk_fma_f32 v[32:33], v[140:141], v[32:33], v[38:39] op_sel_hi:[1,0,1]
	v_pk_fma_f32 v[24:25], v[170:171], v[24:25], v[28:29] op_sel_hi:[1,0,1]
	v_pk_fma_f32 v[4:5], v[150:151], v[4:5], v[22:23] op_sel_hi:[1,0,1]
	v_pk_fma_f32 v[14:15], v[160:161], v[14:15], v[16:17] op_sel_hi:[1,0,1]
	v_pk_fma_f32 v[8:9], v[132:133], v[8:9], v[12:13] op_sel_hi:[1,0,1]
	ds_write_b64 v18, v[162:163]
	ds_write_b64 v18, v[26:27] offset:2112
	ds_write_b64 v18, v[48:49] offset:4224
	ds_write_b64 v18, v[10:11] offset:6336
	ds_write_b64 v18, v[46:47] offset:8448
	ds_write_b64 v18, v[20:21] offset:10560
	ds_write_b64 v18, v[36:37] offset:12672
	ds_write_b64 v18, v[4:5] offset:14784
	ds_write_b64 v18, v[34:35] offset:16896
	ds_write_b64 v18, v[78:79] offset:19008
	ds_write_b64 v18, v[106:107] offset:21120
	ds_write_b64 v18, v[32:33] offset:23232
	ds_write_b64 v18, v[54:55] offset:25344
	ds_write_b64 v18, v[62:63] offset:27456
	ds_write_b64 v18, v[92:93] offset:29568
	ds_write_b64 v18, v[8:9] offset:31680
	ds_write_b64 v18, v[30:31] offset:33792
	ds_write_b64 v18, v[82:83] offset:35904
	ds_write_b64 v18, v[72:73] offset:38016
	ds_write_b64 v18, v[40:41] offset:40128
	ds_write_b64 v18, v[52:53] offset:42240
	ds_write_b64 v18, v[66:67] offset:44352
	ds_write_b64 v18, v[96:97] offset:46464
	ds_write_b64 v18, v[14:15] offset:48576
	ds_write_b64 v18, v[44:45] offset:50688
	ds_write_b64 v18, v[74:75] offset:52800
	ds_write_b64 v18, v[102:103] offset:54912
	ds_write_b64 v18, v[24:25] offset:57024
	ds_write_b64 v18, v[58:59] offset:59136
	ds_write_b64 v18, v[56:57] offset:61248
	ds_write_b64 v18, v[88:89] offset:63360
	ds_write_b64 v18, v[2:3] offset:65472
	v_mov_b32_e32 v3, v210
	s_waitcnt lgkmcnt(0)
	s_barrier
	s_add_i32 s64, s62, s48
	v_and_b32_e32 v5, 15, v3
	v_cvt_f32_ubyte0_e32 v2, v5
	v_mul_f32_e32 v4, 0x3b800000, v2
	v_sin_f32_e32 v2, v4
	v_cos_f32_e32 v4, v4
	v_lshlrev_b32_e32 v64, 3, v5
	v_lshlrev_b32_e32 v18, 4, v3
	v_xor_b32_e32 v5, 0x80000000, v2
	v_mov_b32_e32 v3, v5
	v_pk_mul_f32 v[6:7], v[4:5], v[2:3] op_sel:[1,0] op_sel_hi:[0,1]
	v_pk_fma_f32 v[6:7], v[4:5], v[4:5], v[6:7] op_sel_hi:[1,0,1]
	s_ashr_i32 s65, s64, 31
	v_xor_b32_e32 v12, 0x80000000, v7
	v_mov_b32_e32 v13, v7
	v_pk_mul_f32 v[10:11], v[6:7], v[12:13] op_sel:[1,0] op_sel_hi:[0,1]
	v_pk_fma_f32 v[10:11], v[6:7], v[6:7], v[10:11] op_sel_hi:[1,0,1]
	v_pk_mul_f32 v[8:9], v[2:3], v[6:7] op_sel:[0,1] op_sel_hi:[1,0]
	v_xor_b32_e32 v14, 0x80000000, v11
	v_mov_b32_e32 v15, v11
	v_pk_mul_f32 v[32:33], v[10:11], v[14:15] op_sel:[1,0] op_sel_hi:[0,1]
	v_pk_fma_f32 v[32:33], v[10:11], v[10:11], v[32:33] op_sel_hi:[1,0,1]
	v_pk_mul_f32 v[16:17], v[2:3], v[10:11] op_sel:[0,1] op_sel_hi:[1,0]
	v_pk_mul_f32 v[48:49], v[14:15], v[32:33] op_sel:[0,1] op_sel_hi:[1,0]
	v_pk_mul_f32 v[36:37], v[2:3], v[32:33] op_sel:[0,1] op_sel_hi:[1,0]
	v_pk_fma_f32 v[48:49], v[10:11], v[32:33], v[48:49] op_sel_hi:[0,1,1]
	v_pk_mul_f32 v[52:53], v[2:3], v[48:49] op_sel:[0,1] op_sel_hi:[1,0]
	v_pk_fma_f32 v[8:9], v[4:5], v[6:7], v[8:9] op_sel_hi:[0,1,1]
	v_pk_fma_f32 v[16:17], v[4:5], v[10:11], v[16:17] op_sel_hi:[0,1,1]
	v_pk_fma_f32 v[36:37], v[4:5], v[32:33], v[36:37] op_sel_hi:[0,1,1]
	v_pk_fma_f32 v[52:53], v[4:5], v[48:49], v[52:53] op_sel_hi:[0,1,1]
	v_and_b32_e32 v5, 0xffffff00, v18
	v_lshlrev_b32_e32 v18, 3, v5
	v_add3_u32 v18, 0, v64, v18
	v_ashrrev_i32_e32 v64, 2, v5
	v_add_u32_e32 v106, v18, v64
	ds_read2_b64 v[64:67], v106 offset1:16
	ds_read2_b64 v[68:71], v106 offset0:33 offset1:49
	ds_read2_b64 v[72:75], v106 offset0:66 offset1:82
	ds_read2_b64 v[76:79], v106 offset0:132 offset1:148
	ds_read2_b64 v[80:83], v106 offset0:99 offset1:115
	ds_read2_b64 v[84:87], v106 offset0:165 offset1:181
	ds_read2_b64 v[88:91], v106 offset0:198 offset1:214
	ds_read2_b64 v[92:95], v106 offset0:231 offset1:247
	s_waitcnt lgkmcnt(4)
	v_pk_add_f32 v[96:97], v[64:65], v[76:77]
	v_pk_add_f32 v[64:65], v[64:65], v[76:77] neg_lo:[0,1] neg_hi:[0,1]
	v_pk_add_f32 v[76:77], v[66:67], v[78:79]
	v_pk_add_f32 v[66:67], v[66:67], v[78:79] neg_lo:[0,1] neg_hi:[0,1]
	s_waitcnt lgkmcnt(1)
	v_pk_add_f32 v[98:99], v[74:75], v[90:91]
	v_pk_mul_f32 v[78:79], v[66:67], s[18:19]
	v_pk_add_f32 v[74:75], v[74:75], v[90:91] neg_lo:[0,1] neg_hi:[0,1]
	v_pk_fma_f32 v[66:67], v[66:67], s[16:17], v[78:79] op_sel:[0,0,1] op_sel_hi:[1,0,0]
	v_pk_add_f32 v[78:79], v[68:69], v[84:85]
	v_pk_add_f32 v[68:69], v[68:69], v[84:85] neg_lo:[0,1] neg_hi:[0,1]
	v_pk_mul_f32 v[90:91], v[74:75], s[40:41]
	v_pk_mul_f32 v[84:85], v[68:69], s[36:37]
	v_pk_fma_f32 v[74:75], v[74:75], s[68:69], v[90:91] op_sel:[0,0,1] op_sel_hi:[1,0,0] neg_lo:[1,0,0] neg_hi:[1,0,0]
	v_pk_fma_f32 v[68:69], v[68:69], s[66:67], v[84:85] op_sel:[0,0,1] op_sel_hi:[1,0,0]
	v_pk_add_f32 v[84:85], v[70:71], v[86:87]
	v_pk_add_f32 v[70:71], v[70:71], v[86:87] neg_lo:[0,1] neg_hi:[0,1]
	s_waitcnt lgkmcnt(0)
	v_pk_add_f32 v[90:91], v[80:81], v[92:93]
	v_pk_add_f32 v[80:81], v[80:81], v[92:93] neg_lo:[0,1] neg_hi:[0,1]
	v_pk_mul_f32 v[86:87], v[70:71], s[40:41]
	v_pk_mul_f32 v[92:93], v[80:81], s[36:37]
	v_pk_fma_f32 v[70:71], v[70:71], s[68:69], v[86:87] op_sel:[0,0,1] op_sel_hi:[1,0,0]
	v_pk_add_f32 v[86:87], v[72:73], v[88:89]
	v_pk_add_f32 v[88:89], v[72:73], v[88:89] neg_lo:[0,1] neg_hi:[0,1]
	v_pk_fma_f32 v[80:81], v[80:81], s[66:67], v[92:93] op_sel:[0,0,1] op_sel_hi:[1,0,0] neg_lo:[1,0,0] neg_hi:[1,0,0]
	v_pk_add_f32 v[92:93], v[82:83], v[94:95]
	v_pk_add_f32 v[82:83], v[82:83], v[94:95] neg_lo:[0,1] neg_hi:[0,1]
	v_pk_mul_f32 v[94:95], v[82:83], s[18:19]
	v_pk_fma_f32 v[82:83], v[82:83], s[16:17], v[94:95] op_sel:[0,0,1] op_sel_hi:[1,0,0] neg_lo:[1,0,0] neg_hi:[1,0,0]
	v_pk_add_f32 v[94:95], v[96:97], v[86:87]
	v_pk_add_f32 v[86:87], v[96:97], v[86:87] neg_lo:[0,1] neg_hi:[0,1]
	v_pk_add_f32 v[96:97], v[76:77], v[98:99]
	v_pk_add_f32 v[76:77], v[76:77], v[98:99] neg_lo:[0,1] neg_hi:[0,1]
	v_pk_add_f32 v[100:101], v[84:85], v[92:93]
	v_pk_add_f32 v[84:85], v[84:85], v[92:93] neg_lo:[0,1] neg_hi:[0,1]
	v_pk_add_f32 v[72:73], v[64:65], v[88:89] op_sel:[0,1] op_sel_hi:[1,0] neg_hi:[0,1]
	v_pk_add_f32 v[64:65], v[64:65], v[88:89] op_sel:[0,1] op_sel_hi:[1,0] neg_lo:[0,1]
	v_pk_add_f32 v[88:89], v[66:67], v[74:75]
	v_pk_add_f32 v[66:67], v[66:67], v[74:75] neg_lo:[0,1] neg_hi:[0,1]
	v_pk_mul_f32 v[98:99], v[76:77], s[36:37]
	v_pk_mul_f32 v[92:93], v[84:85], s[36:37]
	v_pk_mul_f32 v[74:75], v[66:67], s[36:37]
	v_pk_fma_f32 v[76:77], v[76:77], s[66:67], v[98:99] op_sel:[0,0,1] op_sel_hi:[1,0,0]
	v_pk_add_f32 v[98:99], v[78:79], v[90:91]
	v_pk_add_f32 v[90:91], v[78:79], v[90:91] neg_lo:[0,1] neg_hi:[0,1]
	v_pk_fma_f32 v[84:85], v[84:85], s[66:67], v[92:93] op_sel:[0,0,1] op_sel_hi:[1,0,0] neg_lo:[1,0,0] neg_hi:[1,0,0]
	v_pk_fma_f32 v[66:67], v[66:67], s[66:67], v[74:75] op_sel:[0,0,1] op_sel_hi:[1,0,0]
	v_pk_add_f32 v[74:75], v[68:69], v[80:81]
	v_pk_add_f32 v[92:93], v[70:71], v[82:83]
	v_pk_add_f32 v[70:71], v[70:71], v[82:83] neg_lo:[0,1] neg_hi:[0,1]
	v_pk_add_f32 v[68:69], v[68:69], v[80:81] neg_lo:[0,1] neg_hi:[0,1]
	v_pk_mul_f32 v[82:83], v[70:71], s[36:37]
	v_pk_add_f32 v[102:103], v[72:73], v[74:75]
	v_pk_add_f32 v[72:73], v[72:73], v[74:75] neg_lo:[0,1] neg_hi:[0,1]
	v_pk_add_f32 v[74:75], v[88:89], v[92:93]
	v_pk_add_f32 v[92:93], v[88:89], v[92:93] neg_lo:[0,1] neg_hi:[0,1]
	v_xor_b32_e32 v20, 0x80000000, v9
	v_mov_b32_e32 v21, v9
	v_pk_mul_f32 v[24:25], v[12:13], v[10:11] op_sel:[0,1] op_sel_hi:[1,0]
	v_xor_b32_e32 v81, 0x80000000, v68
	v_pk_fma_f32 v[70:71], v[70:71], s[66:67], v[82:83] op_sel:[0,0,1] op_sel_hi:[1,0,0] neg_lo:[1,0,0] neg_hi:[1,0,0]
	v_pk_add_f32 v[78:79], v[86:87], v[90:91] op_sel:[0,1] op_sel_hi:[1,0] neg_hi:[0,1]
	v_pk_add_f32 v[86:87], v[86:87], v[90:91] op_sel:[0,1] op_sel_hi:[1,0] neg_lo:[0,1]
	v_pk_add_f32 v[90:91], v[76:77], v[84:85]
	v_pk_add_f32 v[84:85], v[76:77], v[84:85] neg_lo:[0,1] neg_hi:[0,1]
	v_mov_b32_e32 v80, v69
	v_xor_b32_e32 v22, 0x80000000, v17
	v_mov_b32_e32 v23, v17
	v_pk_fma_f32 v[24:25], v[6:7], v[10:11], v[24:25] op_sel_hi:[0,1,1]
	v_pk_mul_f32 v[28:29], v[10:11], v[20:21] op_sel:[1,0] op_sel_hi:[0,1]
	v_pk_add_f32 v[68:69], v[64:65], v[80:81]
	v_pk_add_f32 v[64:65], v[64:65], v[80:81] neg_lo:[0,1] neg_hi:[0,1]
	v_pk_add_f32 v[80:81], v[66:67], v[70:71]
	v_pk_add_f32 v[70:71], v[66:67], v[70:71] neg_lo:[0,1] neg_hi:[0,1]
	v_pk_add_f32 v[88:89], v[72:73], v[92:93] op_sel:[0,1] op_sel_hi:[1,0] neg_hi:[0,1]
	v_xor_b32_e32 v26, 0x80000000, v25
	v_mov_b32_e32 v27, v25
	v_pk_fma_f32 v[28:29], v[10:11], v[8:9], v[28:29] op_sel_hi:[1,0,1]
	v_pk_add_f32 v[76:77], v[86:87], v[84:85] op_sel:[0,1] op_sel_hi:[1,0] neg_hi:[0,1]
	v_pk_add_f32 v[72:73], v[72:73], v[92:93] op_sel:[0,1] op_sel_hi:[1,0] neg_lo:[0,1]
	v_pk_mul_f32 v[92:93], v[22:23], v[88:89] op_sel:[0,1] op_sel_hi:[1,0]
	v_xor_b32_e32 v30, 0x80000000, v29
	v_mov_b32_e32 v31, v29
	v_pk_add_f32 v[82:83], v[94:95], v[98:99]
	v_pk_add_f32 v[94:95], v[94:95], v[98:99] neg_lo:[0,1] neg_hi:[0,1]
	v_pk_add_f32 v[98:99], v[96:97], v[100:101]
	v_pk_add_f32 v[66:67], v[64:65], v[70:71] op_sel:[0,1] op_sel_hi:[1,0] neg_hi:[0,1]
	v_pk_fma_f32 v[88:89], v[16:17], v[88:89], v[92:93] op_sel_hi:[0,1,1]
	v_pk_mul_f32 v[92:93], v[26:27], v[76:77] op_sel:[0,1] op_sel_hi:[1,0]
	v_xor_b32_e32 v34, 0x80000000, v33
	v_mov_b32_e32 v35, v33
	v_pk_mul_f32 v[40:41], v[12:13], v[32:33] op_sel:[0,1] op_sel_hi:[1,0]
	v_pk_add_f32 v[104:105], v[82:83], v[98:99]
	v_pk_add_f32 v[82:83], v[82:83], v[98:99] neg_lo:[0,1] neg_hi:[0,1]
	v_pk_fma_f32 v[76:77], v[24:25], v[76:77], v[92:93] op_sel_hi:[0,1,1]
	v_pk_mul_f32 v[92:93], v[30:31], v[66:67] op_sel:[0,1] op_sel_hi:[1,0]
	v_xor_b32_e32 v38, 0x80000000, v37
	v_mov_b32_e32 v39, v37
	v_pk_fma_f32 v[40:41], v[6:7], v[32:33], v[40:41] op_sel_hi:[0,1,1]
	v_pk_mul_f32 v[44:45], v[20:21], v[32:33] op_sel:[0,1] op_sel_hi:[1,0]
	v_pk_add_f32 v[84:85], v[86:87], v[84:85] op_sel:[0,1] op_sel_hi:[1,0] neg_lo:[0,1]
	v_pk_add_f32 v[86:87], v[102:103], v[74:75]
	v_pk_add_f32 v[74:75], v[102:103], v[74:75] neg_lo:[0,1] neg_hi:[0,1]
	v_pk_fma_f32 v[66:67], v[28:29], v[66:67], v[92:93] op_sel_hi:[0,1,1]
	v_pk_mul_f32 v[92:93], v[34:35], v[82:83] op_sel:[0,1] op_sel_hi:[1,0]
	v_xor_b32_e32 v42, 0x80000000, v41
	v_mov_b32_e32 v43, v41
	v_pk_fma_f32 v[44:45], v[8:9], v[32:33], v[44:45] op_sel_hi:[0,1,1]
	v_pk_add_f32 v[100:101], v[96:97], v[100:101] neg_lo:[0,1] neg_hi:[0,1]
	v_pk_add_f32 v[98:99], v[78:79], v[90:91]
	v_pk_add_f32 v[78:79], v[78:79], v[90:91] neg_lo:[0,1] neg_hi:[0,1]
	v_pk_fma_f32 v[82:83], v[32:33], v[82:83], v[92:93] op_sel_hi:[0,1,1]
	v_pk_mul_f32 v[92:93], v[38:39], v[74:75] op_sel:[0,1] op_sel_hi:[1,0]
	v_xor_b32_e32 v46, 0x80000000, v45
	v_mov_b32_e32 v47, v45
	v_pk_add_f32 v[90:91], v[68:69], v[80:81]
	v_pk_add_f32 v[68:69], v[68:69], v[80:81] neg_lo:[0,1] neg_hi:[0,1]
	v_pk_fma_f32 v[74:75], v[36:37], v[74:75], v[92:93] op_sel_hi:[0,1,1]
	v_pk_mul_f32 v[92:93], v[42:43], v[78:79] op_sel:[0,1] op_sel_hi:[1,0]
	v_xor_b32_e32 v50, 0x80000000, v49
	v_mov_b32_e32 v51, v49
	v_pk_mul_f32 v[56:57], v[12:13], v[48:49] op_sel:[0,1] op_sel_hi:[1,0]
	v_pk_add_f32 v[96:97], v[94:95], v[100:101] op_sel:[0,1] op_sel_hi:[1,0] neg_hi:[0,1]
	v_pk_add_f32 v[94:95], v[94:95], v[100:101] op_sel:[0,1] op_sel_hi:[1,0] neg_lo:[0,1]
	v_pk_fma_f32 v[78:79], v[40:41], v[78:79], v[92:93] op_sel_hi:[0,1,1]
	v_pk_mul_f32 v[92:93], v[46:47], v[68:69] op_sel:[0,1] op_sel_hi:[1,0]
	v_xor_b32_e32 v54, 0x80000000, v53
	v_mov_b32_e32 v55, v53
	v_pk_fma_f32 v[56:57], v[6:7], v[48:49], v[56:57] op_sel_hi:[0,1,1]
	v_pk_mul_f32 v[60:61], v[20:21], v[48:49] op_sel:[0,1] op_sel_hi:[1,0]
	v_pk_fma_f32 v[68:69], v[44:45], v[68:69], v[92:93] op_sel_hi:[0,1,1]
	v_pk_mul_f32 v[92:93], v[50:51], v[94:95] op_sel:[0,1] op_sel_hi:[1,0]
	v_xor_b32_e32 v58, 0x80000000, v57
	v_mov_b32_e32 v59, v57
	v_pk_fma_f32 v[60:61], v[8:9], v[48:49], v[60:61] op_sel_hi:[0,1,1]
	v_pk_add_f32 v[64:65], v[64:65], v[70:71] op_sel:[0,1] op_sel_hi:[1,0] neg_lo:[0,1]
	v_pk_mul_f32 v[70:71], v[2:3], v[86:87] op_sel:[0,1] op_sel_hi:[1,0]
	v_pk_fma_f32 v[92:93], v[48:49], v[94:95], v[92:93] op_sel_hi:[0,1,1]
	v_pk_mul_f32 v[94:95], v[54:55], v[72:73] op_sel:[0,1] op_sel_hi:[1,0]
	v_xor_b32_e32 v62, 0x80000000, v61
	v_mov_b32_e32 v63, v61
	v_pk_fma_f32 v[70:71], v[4:5], v[86:87], v[70:71] op_sel_hi:[0,1,1]
	v_pk_mul_f32 v[86:87], v[20:21], v[90:91] op_sel:[0,1] op_sel_hi:[1,0]
	v_pk_fma_f32 v[72:73], v[52:53], v[72:73], v[94:95] op_sel_hi:[0,1,1]
	v_pk_mul_f32 v[94:95], v[58:59], v[84:85] op_sel:[0,1] op_sel_hi:[1,0]
	v_add_u32_e32 v5, 0x2000, v5
	v_pk_mul_f32 v[80:81], v[12:13], v[98:99] op_sel:[0,1] op_sel_hi:[1,0]
	v_pk_fma_f32 v[86:87], v[8:9], v[90:91], v[86:87] op_sel_hi:[0,1,1]
	v_pk_mul_f32 v[90:91], v[14:15], v[96:97] op_sel:[0,1] op_sel_hi:[1,0]
	v_pk_fma_f32 v[84:85], v[56:57], v[84:85], v[94:95] op_sel_hi:[0,1,1]
	v_pk_mul_f32 v[94:95], v[62:63], v[64:65] op_sel:[0,1] op_sel_hi:[1,0]
	v_ashrrev_i32_e32 v5, 2, v5
	v_pk_fma_f32 v[80:81], v[6:7], v[98:99], v[80:81] op_sel_hi:[0,1,1]
	v_pk_fma_f32 v[90:91], v[10:11], v[96:97], v[90:91] op_sel_hi:[0,1,1]
	v_pk_fma_f32 v[64:65], v[60:61], v[64:65], v[94:95] op_sel_hi:[0,1,1]
	ds_write2_b64 v106, v[104:105], v[82:83] offset1:16
	ds_write2_b64 v106, v[90:91], v[92:93] offset0:33 offset1:49
	ds_write2_b64 v106, v[80:81], v[78:79] offset0:66 offset1:82
	ds_write2_b64 v106, v[76:77], v[84:85] offset0:99 offset1:115
	ds_write2_b64 v106, v[70:71], v[74:75] offset0:132 offset1:148
	ds_write2_b64 v106, v[88:89], v[72:73] offset0:165 offset1:181
	ds_write2_b64 v106, v[86:87], v[68:69] offset0:198 offset1:214
	ds_write2_b64 v106, v[66:67], v[64:65] offset0:231 offset1:247
	v_add3_u32 v18, v18, v5, s5
	ds_read2_b64 v[64:67], v18 offset1:16
	ds_read2_b64 v[68:71], v18 offset0:33 offset1:49
	ds_read2_b64 v[72:75], v18 offset0:66 offset1:82
	ds_read2_b64 v[76:79], v18 offset0:132 offset1:148
	ds_read2_b64 v[80:83], v18 offset0:99 offset1:115
	ds_read2_b64 v[84:87], v18 offset0:165 offset1:181
	ds_read2_b64 v[88:91], v18 offset0:198 offset1:214
	ds_read2_b64 v[92:95], v18 offset0:231 offset1:247
	s_waitcnt lgkmcnt(4)
	v_pk_add_f32 v[96:97], v[64:65], v[76:77]
	v_pk_add_f32 v[64:65], v[64:65], v[76:77] neg_lo:[0,1] neg_hi:[0,1]
	v_pk_add_f32 v[76:77], v[66:67], v[78:79]
	v_pk_add_f32 v[66:67], v[66:67], v[78:79] neg_lo:[0,1] neg_hi:[0,1]
	s_waitcnt lgkmcnt(1)
	v_pk_add_f32 v[98:99], v[74:75], v[90:91]
	v_pk_mul_f32 v[78:79], v[66:67], s[18:19]
	v_pk_add_f32 v[74:75], v[74:75], v[90:91] neg_lo:[0,1] neg_hi:[0,1]
	v_pk_fma_f32 v[66:67], v[66:67], s[16:17], v[78:79] op_sel:[0,0,1] op_sel_hi:[1,0,0]
	v_pk_add_f32 v[78:79], v[68:69], v[84:85]
	v_pk_add_f32 v[68:69], v[68:69], v[84:85] neg_lo:[0,1] neg_hi:[0,1]
	v_pk_mul_f32 v[90:91], v[74:75], s[40:41]
	v_pk_mul_f32 v[84:85], v[68:69], s[36:37]
	v_pk_fma_f32 v[74:75], v[74:75], s[68:69], v[90:91] op_sel:[0,0,1] op_sel_hi:[1,0,0] neg_lo:[1,0,0] neg_hi:[1,0,0]
	s_waitcnt lgkmcnt(0)
	v_pk_add_f32 v[90:91], v[80:81], v[92:93]
	v_pk_add_f32 v[80:81], v[80:81], v[92:93] neg_lo:[0,1] neg_hi:[0,1]
	v_pk_fma_f32 v[68:69], v[68:69], s[66:67], v[84:85] op_sel:[0,0,1] op_sel_hi:[1,0,0]
	v_pk_add_f32 v[84:85], v[70:71], v[86:87]
	v_pk_add_f32 v[70:71], v[70:71], v[86:87] neg_lo:[0,1] neg_hi:[0,1]
	v_pk_mul_f32 v[92:93], v[80:81], s[36:37]
	v_pk_mul_f32 v[86:87], v[70:71], s[40:41]
	v_pk_fma_f32 v[80:81], v[80:81], s[66:67], v[92:93] op_sel:[0,0,1] op_sel_hi:[1,0,0] neg_lo:[1,0,0] neg_hi:[1,0,0]
	v_pk_add_f32 v[92:93], v[82:83], v[94:95]
	v_pk_add_f32 v[82:83], v[82:83], v[94:95] neg_lo:[0,1] neg_hi:[0,1]
	v_pk_fma_f32 v[70:71], v[70:71], s[68:69], v[86:87] op_sel:[0,0,1] op_sel_hi:[1,0,0]
	v_pk_add_f32 v[86:87], v[72:73], v[88:89]
	v_pk_mul_f32 v[94:95], v[82:83], s[18:19]
	v_pk_add_f32 v[88:89], v[72:73], v[88:89] neg_lo:[0,1] neg_hi:[0,1]
	v_pk_fma_f32 v[82:83], v[82:83], s[16:17], v[94:95] op_sel:[0,0,1] op_sel_hi:[1,0,0] neg_lo:[1,0,0] neg_hi:[1,0,0]
	v_pk_add_f32 v[94:95], v[96:97], v[86:87]
	v_pk_add_f32 v[86:87], v[96:97], v[86:87] neg_lo:[0,1] neg_hi:[0,1]
	v_pk_add_f32 v[96:97], v[76:77], v[98:99]
	v_pk_add_f32 v[76:77], v[76:77], v[98:99] neg_lo:[0,1] neg_hi:[0,1]
	v_pk_mul_f32 v[98:99], v[76:77], s[36:37]
	v_pk_add_f32 v[100:101], v[84:85], v[92:93]
	v_pk_add_f32 v[84:85], v[84:85], v[92:93] neg_lo:[0,1] neg_hi:[0,1]
	v_pk_fma_f32 v[76:77], v[76:77], s[66:67], v[98:99] op_sel:[0,0,1] op_sel_hi:[1,0,0]
	v_pk_add_f32 v[98:99], v[78:79], v[90:91]
	v_pk_add_f32 v[90:91], v[78:79], v[90:91] neg_lo:[0,1] neg_hi:[0,1]
	v_pk_mul_f32 v[92:93], v[84:85], s[36:37]
	v_pk_add_f32 v[72:73], v[64:65], v[88:89] op_sel:[0,1] op_sel_hi:[1,0] neg_hi:[0,1]
	v_pk_add_f32 v[64:65], v[64:65], v[88:89] op_sel:[0,1] op_sel_hi:[1,0] neg_lo:[0,1]
	v_pk_add_f32 v[88:89], v[66:67], v[74:75]
	v_pk_add_f32 v[66:67], v[66:67], v[74:75] neg_lo:[0,1] neg_hi:[0,1]
	v_pk_fma_f32 v[84:85], v[84:85], s[66:67], v[92:93] op_sel:[0,0,1] op_sel_hi:[1,0,0] neg_lo:[1,0,0] neg_hi:[1,0,0]
	v_pk_mul_f32 v[74:75], v[66:67], s[36:37]
	v_pk_fma_f32 v[66:67], v[66:67], s[66:67], v[74:75] op_sel:[0,0,1] op_sel_hi:[1,0,0]
	v_pk_add_f32 v[74:75], v[68:69], v[80:81]
	v_pk_add_f32 v[92:93], v[70:71], v[82:83]
	v_pk_add_f32 v[70:71], v[70:71], v[82:83] neg_lo:[0,1] neg_hi:[0,1]
	v_pk_add_f32 v[78:79], v[86:87], v[90:91] op_sel:[0,1] op_sel_hi:[1,0] neg_hi:[0,1]
	v_pk_add_f32 v[86:87], v[86:87], v[90:91] op_sel:[0,1] op_sel_hi:[1,0] neg_lo:[0,1]
	v_pk_add_f32 v[90:91], v[76:77], v[84:85]
	v_pk_add_f32 v[84:85], v[76:77], v[84:85] neg_lo:[0,1] neg_hi:[0,1]
	v_pk_add_f32 v[80:81], v[68:69], v[80:81] neg_lo:[0,1] neg_hi:[0,1]
	v_pk_mul_f32 v[82:83], v[70:71], s[36:37]
	v_pk_add_f32 v[102:103], v[72:73], v[74:75]
	v_pk_add_f32 v[72:73], v[72:73], v[74:75] neg_lo:[0,1] neg_hi:[0,1]
	v_pk_add_f32 v[74:75], v[88:89], v[92:93]
	v_pk_fma_f32 v[70:71], v[70:71], s[66:67], v[82:83] op_sel:[0,0,1] op_sel_hi:[1,0,0] neg_lo:[1,0,0] neg_hi:[1,0,0]
	v_pk_add_f32 v[82:83], v[94:95], v[98:99]
	v_pk_add_f32 v[94:95], v[94:95], v[98:99] neg_lo:[0,1] neg_hi:[0,1]
	v_pk_add_f32 v[98:99], v[96:97], v[100:101]
	v_pk_add_f32 v[76:77], v[86:87], v[84:85] op_sel:[0,1] op_sel_hi:[1,0] neg_hi:[0,1]
	v_pk_add_f32 v[84:85], v[86:87], v[84:85] op_sel:[0,1] op_sel_hi:[1,0] neg_lo:[0,1]
	v_pk_add_f32 v[86:87], v[102:103], v[74:75]
	v_pk_add_f32 v[100:101], v[96:97], v[100:101] neg_lo:[0,1] neg_hi:[0,1]
	v_pk_add_f32 v[68:69], v[64:65], v[80:81] op_sel:[0,1] op_sel_hi:[1,0] neg_hi:[0,1]
	v_pk_add_f32 v[64:65], v[64:65], v[80:81] op_sel:[0,1] op_sel_hi:[1,0] neg_lo:[0,1]
	v_pk_add_f32 v[80:81], v[66:67], v[70:71]
	v_pk_add_f32 v[104:105], v[82:83], v[98:99]
	v_pk_add_f32 v[82:83], v[82:83], v[98:99] neg_lo:[0,1] neg_hi:[0,1]
	v_pk_add_f32 v[98:99], v[78:79], v[90:91]
	v_pk_mul_f32 v[2:3], v[2:3], v[86:87] op_sel:[0,1] op_sel_hi:[1,0]
	v_pk_add_f32 v[92:93], v[88:89], v[92:93] neg_lo:[0,1] neg_hi:[0,1]
	v_pk_add_f32 v[78:79], v[78:79], v[90:91] neg_lo:[0,1] neg_hi:[0,1]
	v_pk_add_f32 v[90:91], v[68:69], v[80:81]
	v_pk_fma_f32 v[2:3], v[4:5], v[86:87], v[2:3] op_sel_hi:[0,1,1]
	v_pk_mul_f32 v[4:5], v[12:13], v[98:99] op_sel:[0,1] op_sel_hi:[1,0]
	v_pk_add_f32 v[70:71], v[66:67], v[70:71] neg_lo:[0,1] neg_hi:[0,1]
	v_pk_add_f32 v[96:97], v[94:95], v[100:101] op_sel:[0,1] op_sel_hi:[1,0] neg_hi:[0,1]
	v_pk_fma_f32 v[4:5], v[6:7], v[98:99], v[4:5] op_sel_hi:[0,1,1]
	v_pk_mul_f32 v[6:7], v[20:21], v[90:91] op_sel:[0,1] op_sel_hi:[1,0]
	v_pk_add_f32 v[88:89], v[72:73], v[92:93] op_sel:[0,1] op_sel_hi:[1,0] neg_hi:[0,1]
	v_pk_fma_f32 v[6:7], v[8:9], v[90:91], v[6:7] op_sel_hi:[0,1,1]
	v_pk_mul_f32 v[8:9], v[14:15], v[96:97] op_sel:[0,1] op_sel_hi:[1,0]
	v_pk_add_f32 v[66:67], v[64:65], v[70:71] op_sel:[0,1] op_sel_hi:[1,0] neg_hi:[0,1]
	v_pk_fma_f32 v[8:9], v[10:11], v[96:97], v[8:9] op_sel_hi:[0,1,1]
	v_pk_mul_f32 v[10:11], v[22:23], v[88:89] op_sel:[0,1] op_sel_hi:[1,0]
	v_pk_add_f32 v[94:95], v[94:95], v[100:101] op_sel:[0,1] op_sel_hi:[1,0] neg_lo:[0,1]
	v_pk_add_f32 v[74:75], v[102:103], v[74:75] neg_lo:[0,1] neg_hi:[0,1]
	v_pk_add_f32 v[72:73], v[72:73], v[92:93] op_sel:[0,1] op_sel_hi:[1,0] neg_lo:[0,1]
	v_pk_add_f32 v[68:69], v[68:69], v[80:81] neg_lo:[0,1] neg_hi:[0,1]
	v_pk_add_f32 v[64:65], v[64:65], v[70:71] op_sel:[0,1] op_sel_hi:[1,0] neg_lo:[0,1]
	v_pk_fma_f32 v[10:11], v[16:17], v[88:89], v[10:11] op_sel_hi:[0,1,1]
	v_pk_mul_f32 v[12:13], v[26:27], v[76:77] op_sel:[0,1] op_sel_hi:[1,0]
	v_pk_mul_f32 v[14:15], v[30:31], v[66:67] op_sel:[0,1] op_sel_hi:[1,0]
	v_pk_mul_f32 v[16:17], v[34:35], v[82:83] op_sel:[0,1] op_sel_hi:[1,0]
	v_pk_fma_f32 v[12:13], v[24:25], v[76:77], v[12:13] op_sel_hi:[0,1,1]
	v_pk_fma_f32 v[14:15], v[28:29], v[66:67], v[14:15] op_sel_hi:[0,1,1]
	v_pk_fma_f32 v[16:17], v[32:33], v[82:83], v[16:17] op_sel_hi:[0,1,1]
	v_pk_mul_f32 v[20:21], v[38:39], v[74:75] op_sel:[0,1] op_sel_hi:[1,0]
	v_pk_mul_f32 v[22:23], v[42:43], v[78:79] op_sel:[0,1] op_sel_hi:[1,0]
	v_pk_mul_f32 v[24:25], v[46:47], v[68:69] op_sel:[0,1] op_sel_hi:[1,0]
	v_pk_mul_f32 v[26:27], v[50:51], v[94:95] op_sel:[0,1] op_sel_hi:[1,0]
	v_pk_mul_f32 v[28:29], v[54:55], v[72:73] op_sel:[0,1] op_sel_hi:[1,0]
	v_pk_mul_f32 v[30:31], v[58:59], v[84:85] op_sel:[0,1] op_sel_hi:[1,0]
	v_pk_mul_f32 v[32:33], v[62:63], v[64:65] op_sel:[0,1] op_sel_hi:[1,0]
	v_pk_fma_f32 v[20:21], v[36:37], v[74:75], v[20:21] op_sel_hi:[0,1,1]
	v_pk_fma_f32 v[22:23], v[40:41], v[78:79], v[22:23] op_sel_hi:[0,1,1]
	v_pk_fma_f32 v[24:25], v[44:45], v[68:69], v[24:25] op_sel_hi:[0,1,1]
	v_pk_fma_f32 v[26:27], v[48:49], v[94:95], v[26:27] op_sel_hi:[0,1,1]
	v_pk_fma_f32 v[28:29], v[52:53], v[72:73], v[28:29] op_sel_hi:[0,1,1]
	v_pk_fma_f32 v[30:31], v[56:57], v[84:85], v[30:31] op_sel_hi:[0,1,1]
	v_pk_fma_f32 v[32:33], v[60:61], v[64:65], v[32:33] op_sel_hi:[0,1,1]
	ds_write2_b64 v18, v[104:105], v[16:17] offset1:16
	ds_write2_b64 v18, v[8:9], v[26:27] offset0:33 offset1:49
	ds_write2_b64 v18, v[4:5], v[22:23] offset0:66 offset1:82
	ds_write2_b64 v18, v[12:13], v[30:31] offset0:99 offset1:115
	ds_write2_b64 v18, v[2:3], v[20:21] offset0:132 offset1:148
	ds_write2_b64 v18, v[10:11], v[28:29] offset0:165 offset1:181
	ds_write2_b64 v18, v[6:7], v[24:25] offset0:198 offset1:214
	ds_write2_b64 v18, v[14:15], v[32:33] offset0:231 offset1:247
	v_ashrrev_i32_e32 v2, 31, v210
	v_add_u32_sdwa v2, v210, v2 dst_sel:DWORD dst_unused:UNUSED_PAD src0_sel:DWORD src1_sel:BYTE_3
	s_lshl_b64 s[0:1], s[64:65], 15
	v_and_b32_e32 v2, 0xffffff00, v2
	s_add_u32 s0, s29, s0
	v_sub_u32_e32 v2, v210, v2
	s_addc_u32 s1, s85, s1
	v_ashrrev_i32_e32 v3, 31, v2
	v_lshl_add_u64 v[14:15], v[2:3], 3, s[0:1]
	s_movk_i32 s0, 0x1000
	v_add_co_u32_e32 v16, vcc, s0, v14
	s_movk_i32 s0, 0x3000
	s_nop 0
	v_addc_co_u32_e32 v17, vcc, 0, v15, vcc
	v_add_co_u32_e32 v2, vcc, s92, v14
	s_waitcnt lgkmcnt(0)
	s_nop 0
	v_addc_co_u32_e32 v3, vcc, 0, v15, vcc
	v_add_co_u32_e32 v22, vcc, s0, v14
	s_movk_i32 s0, 0x5000
	s_nop 0
	v_addc_co_u32_e32 v23, vcc, 0, v15, vcc
	v_add_co_u32_e32 v8, vcc, s95, v14
	s_barrier
	s_nop 0
	v_addc_co_u32_e32 v9, vcc, 0, v15, vcc
	v_add_co_u32_e32 v26, vcc, s0, v14
	s_nop 1
	v_addc_co_u32_e32 v27, vcc, 0, v15, vcc
	v_add_co_u32_e32 v10, vcc, s96, v14
	global_load_dwordx2 v[12:13], v[2:3], off nt
	global_load_dwordx2 v[6:7], v[2:3], off offset:2048 nt
	global_load_dwordx2 v[4:5], v[8:9], off offset:-4096 nt
	global_load_dwordx2 v[122:123], v[8:9], off nt
	v_addc_co_u32_e32 v11, vcc, 0, v15, vcc
	v_add_co_u32_e32 v28, vcc, s97, v14
	global_load_dwordx2 v[46:47], v[8:9], off offset:2048 nt
	global_load_dwordx2 v[38:39], v[10:11], off offset:-4096 nt
	global_load_dwordx2 v[20:21], v[10:11], off nt
	s_nop 0
	global_load_dwordx2 v[10:11], v[10:11], off offset:2048 nt
	v_addc_co_u32_e32 v29, vcc, 0, v15, vcc
	global_load_dwordx2 v[24:25], v[2:3], off offset:-4096 nt
	s_nop 0
	global_load_dwordx2 v[26:27], v[26:27], off offset:2048 nt
	s_nop 0
	global_load_dwordx2 v[8:9], v[28:29], off nt
	global_load_dwordx2 v[2:3], v[28:29], off offset:2048 nt
	global_load_dwordx2 v[30:31], v[14:15], off offset:2048 nt
	s_nop 0
	global_load_dwordx2 v[28:29], v[16:17], off offset:2048 nt
	s_nop 0
	global_load_dwordx2 v[16:17], v[22:23], off offset:2048 nt
	global_load_dwordx2 v[32:33], v[14:15], off nt
	v_mov_b32_e32 v14, v210
	s_waitcnt vmcnt(15)
	v_cvt_f32_f16_sdwa v164, v12 dst_sel:DWORD dst_unused:UNUSED_PAD src0_sel:WORD_1
	v_ashrrev_i32_e32 v15, 31, v14
	v_add_u32_sdwa v15, v14, v15 dst_sel:DWORD dst_unused:UNUSED_PAD src0_sel:DWORD src1_sel:BYTE_3
	v_ashrrev_i32_e32 v15, 8, v15
	v_mul_i32_i24_e32 v18, 0x100, v15
	v_sub_u32_e32 v18, v14, v18
	v_lshlrev_b32_e32 v14, 13, v15
	v_lshlrev_b32_e32 v15, 1, v18
	v_bfrev_b32_e32 v15, v15
	v_lshrrev_b32_e32 v15, 23, v15
	v_sub_u32_e32 v15, 0x200, v15
	v_bfrev_b32_e32 v15, v15
	v_lshrrev_b32_e32 v15, 19, v15
	v_and_b32_e32 v15, 0x1ff0, v15
	v_cmp_eq_u32_e64 s[0:1], 0, v18
	v_lshl_add_u32 v22, v18, 5, v14
	v_lshl_add_u32 v23, v22, 3, 0
	v_cndmask_b32_e64 v15, v15, 16, s[0:1]
	v_or_b32_e32 v14, v15, v14
	v_ashrrev_i32_e32 v22, 2, v22
	v_ashrrev_i32_e32 v15, 5, v14
	v_add_u32_e32 v211, v23, v22
	v_lshlrev_b32_e32 v14, 3, v14
	v_lshlrev_b32_e32 v15, 3, v15
	v_add3_u32 v212, 0, v14, v15
	ds_read2_b64 v[34:37], v211 offset1:1
	ds_read2_b64 v[40:43], v211 offset0:2 offset1:3
	ds_read2_b64 v[48:51], v212 offset1:1
	ds_read2_b64 v[52:55], v212 offset0:2 offset1:3
	ds_read2_b64 v[56:59], v211 offset0:4 offset1:5
	ds_read2_b64 v[60:63], v211 offset0:6 offset1:7
	ds_read2_b64 v[68:71], v212 offset0:4 offset1:5
	ds_read2_b64 v[72:75], v212 offset0:6 offset1:7
	ds_read2_b64 v[64:67], v211 offset0:8 offset1:9
	ds_read2_b64 v[76:79], v211 offset0:10 offset1:11
	ds_read2_b64 v[80:83], v212 offset0:8 offset1:9
	ds_read2_b64 v[98:101], v212 offset0:10 offset1:11
	ds_read2_b64 v[84:87], v211 offset0:12 offset1:13
	ds_read2_b64 v[88:91], v211 offset0:14 offset1:15
	ds_read2_b64 v[102:105], v212 offset0:12 offset1:13
	ds_read2_b64 v[106:109], v212 offset0:14 offset1:15
	s_waitcnt lgkmcnt(7)
	v_pk_add_f32 v[14:15], v[34:35], v[64:65]
	v_pk_add_f32 v[22:23], v[34:35], v[64:65] neg_lo:[0,1] neg_hi:[0,1]
	v_pk_add_f32 v[34:35], v[36:37], v[66:67]
	v_pk_add_f32 v[36:37], v[36:37], v[66:67] neg_lo:[0,1] neg_hi:[0,1]
	v_cmp_ne_u32_e32 vcc, 0, v18
	v_pk_mul_f32 v[44:45], v[36:37], s[18:19]
	v_bfrev_b32_e32 v18, v18
	v_pk_fma_f32 v[36:37], v[36:37], s[16:17], v[44:45] op_sel:[0,0,1] op_sel_hi:[1,0,0]
	s_waitcnt lgkmcnt(6)
	v_pk_add_f32 v[44:45], v[40:41], v[76:77]
	v_pk_add_f32 v[40:41], v[40:41], v[76:77] neg_lo:[0,1] neg_hi:[0,1]
	v_cvt_f32_ubyte3_e32 v18, v18
	v_pk_mul_f32 v[64:65], v[40:41], s[36:37]
	v_mul_f32_e32 v18, 0x38800000, v18
	v_pk_fma_f32 v[40:41], v[40:41], s[66:67], v[64:65] op_sel:[0,0,1] op_sel_hi:[1,0,0]
	v_pk_add_f32 v[64:65], v[42:43], v[78:79]
	v_pk_add_f32 v[42:43], v[42:43], v[78:79] neg_lo:[0,1] neg_hi:[0,1]
	s_waitcnt lgkmcnt(3)
	v_pk_add_f32 v[78:79], v[58:59], v[86:87]
	v_pk_mul_f32 v[66:67], v[42:43], s[40:41]
	v_pk_add_f32 v[58:59], v[58:59], v[86:87] neg_lo:[0,1] neg_hi:[0,1]
	v_pk_fma_f32 v[42:43], v[42:43], s[68:69], v[66:67] op_sel:[0,0,1] op_sel_hi:[1,0,0]
	v_pk_add_f32 v[66:67], v[56:57], v[84:85]
	v_pk_add_f32 v[76:77], v[56:57], v[84:85] neg_lo:[0,1] neg_hi:[0,1]
	v_pk_mul_f32 v[84:85], v[58:59], s[40:41]
	v_pk_fma_f32 v[58:59], v[58:59], s[68:69], v[84:85] op_sel:[0,0,1] op_sel_hi:[1,0,0] neg_lo:[1,0,0] neg_hi:[1,0,0]
	s_waitcnt lgkmcnt(2)
	v_pk_add_f32 v[84:85], v[60:61], v[88:89]
	v_pk_add_f32 v[60:61], v[60:61], v[88:89] neg_lo:[0,1] neg_hi:[0,1]
	v_pk_mul_f32 v[86:87], v[60:61], s[36:37]
	v_pk_add_f32 v[56:57], v[22:23], v[76:77] op_sel:[0,1] op_sel_hi:[1,0] neg_hi:[0,1]
	v_pk_fma_f32 v[60:61], v[60:61], s[66:67], v[86:87] op_sel:[0,0,1] op_sel_hi:[1,0,0] neg_lo:[1,0,0] neg_hi:[1,0,0]
	v_pk_add_f32 v[86:87], v[62:63], v[90:91]
	v_pk_add_f32 v[62:63], v[62:63], v[90:91] neg_lo:[0,1] neg_hi:[0,1]
	v_pk_add_f32 v[90:91], v[64:65], v[86:87]
	v_pk_mul_f32 v[88:89], v[62:63], s[18:19]
	v_pk_add_f32 v[64:65], v[64:65], v[86:87] neg_lo:[0,1] neg_hi:[0,1]
	v_pk_fma_f32 v[62:63], v[62:63], s[16:17], v[88:89] op_sel:[0,0,1] op_sel_hi:[1,0,0] neg_lo:[1,0,0] neg_hi:[1,0,0]
	v_pk_add_f32 v[88:89], v[14:15], v[66:67]
	v_pk_add_f32 v[14:15], v[14:15], v[66:67] neg_lo:[0,1] neg_hi:[0,1]
	v_pk_add_f32 v[66:67], v[34:35], v[78:79]
	v_pk_add_f32 v[34:35], v[34:35], v[78:79] neg_lo:[0,1] neg_hi:[0,1]
	v_pk_add_f32 v[22:23], v[22:23], v[76:77] op_sel:[0,1] op_sel_hi:[1,0] neg_lo:[0,1]
	v_pk_mul_f32 v[78:79], v[34:35], s[36:37]
	v_pk_add_f32 v[76:77], v[36:37], v[58:59]
	v_pk_add_f32 v[36:37], v[36:37], v[58:59] neg_lo:[0,1] neg_hi:[0,1]
	v_pk_fma_f32 v[34:35], v[34:35], s[66:67], v[78:79] op_sel:[0,0,1] op_sel_hi:[1,0,0]
	v_pk_add_f32 v[78:79], v[44:45], v[84:85]
	v_pk_add_f32 v[84:85], v[44:45], v[84:85] neg_lo:[0,1] neg_hi:[0,1]
	v_pk_mul_f32 v[86:87], v[64:65], s[36:37]
	v_pk_mul_f32 v[58:59], v[36:37], s[36:37]
	v_pk_fma_f32 v[64:65], v[64:65], s[66:67], v[86:87] op_sel:[0,0,1] op_sel_hi:[1,0,0] neg_lo:[1,0,0] neg_hi:[1,0,0]
	v_pk_fma_f32 v[36:37], v[36:37], s[66:67], v[58:59] op_sel:[0,0,1] op_sel_hi:[1,0,0]
	v_pk_add_f32 v[58:59], v[40:41], v[60:61]
	v_pk_add_f32 v[86:87], v[42:43], v[62:63]
	v_pk_add_f32 v[42:43], v[42:43], v[62:63] neg_lo:[0,1] neg_hi:[0,1]
	v_pk_mul_f32 v[62:63], v[42:43], s[36:37]
	v_pk_add_f32 v[44:45], v[14:15], v[84:85] op_sel:[0,1] op_sel_hi:[1,0] neg_hi:[0,1]
	v_pk_add_f32 v[14:15], v[14:15], v[84:85] op_sel:[0,1] op_sel_hi:[1,0] neg_lo:[0,1]
	v_pk_add_f32 v[84:85], v[34:35], v[64:65]
	v_pk_add_f32 v[64:65], v[34:35], v[64:65] neg_lo:[0,1] neg_hi:[0,1]
	v_pk_add_f32 v[94:95], v[56:57], v[58:59]
	v_pk_add_f32 v[56:57], v[56:57], v[58:59] neg_lo:[0,1] neg_hi:[0,1]
	v_pk_add_f32 v[58:59], v[76:77], v[86:87]
	v_pk_fma_f32 v[42:43], v[42:43], s[66:67], v[62:63] op_sel:[0,0,1] op_sel_hi:[1,0,0] neg_lo:[1,0,0] neg_hi:[1,0,0]
	v_pk_add_f32 v[62:63], v[88:89], v[78:79]
	v_pk_add_f32 v[78:79], v[88:89], v[78:79] neg_lo:[0,1] neg_hi:[0,1]
	v_pk_add_f32 v[88:89], v[66:67], v[90:91]
	v_pk_add_f32 v[110:111], v[76:77], v[86:87] neg_lo:[0,1] neg_hi:[0,1]
	v_pk_add_f32 v[86:87], v[94:95], v[58:59]
	v_pk_add_f32 v[34:35], v[94:95], v[58:59] neg_lo:[0,1] neg_hi:[0,1]
	v_pk_add_f32 v[58:59], v[50:51], v[82:83]
	v_pk_add_f32 v[50:51], v[50:51], v[82:83] neg_lo:[0,1] neg_hi:[0,1]
	v_pk_add_f32 v[60:61], v[40:41], v[60:61] neg_lo:[0,1] neg_hi:[0,1]
	v_pk_add_f32 v[148:149], v[62:63], v[88:89]
	v_pk_add_f32 v[138:139], v[62:63], v[88:89] neg_lo:[0,1] neg_hi:[0,1]
	v_pk_mul_f32 v[62:63], v[50:51], s[18:19]
	v_pk_add_f32 v[90:91], v[66:67], v[90:91] neg_lo:[0,1] neg_hi:[0,1]
	v_pk_fma_f32 v[50:51], v[50:51], s[16:17], v[62:63] op_sel:[0,0,1] op_sel_hi:[1,0,0]
	v_pk_add_f32 v[62:63], v[52:53], v[98:99]
	v_pk_add_f32 v[52:53], v[52:53], v[98:99] neg_lo:[0,1] neg_hi:[0,1]
	v_pk_add_f32 v[112:113], v[22:23], v[60:61] op_sel:[0,1] op_sel_hi:[1,0] neg_hi:[0,1]
	v_pk_add_f32 v[114:115], v[22:23], v[60:61] op_sel:[0,1] op_sel_hi:[1,0] neg_lo:[0,1]
	v_pk_add_f32 v[96:97], v[44:45], v[84:85]
	v_pk_add_f32 v[66:67], v[44:45], v[84:85] neg_lo:[0,1] neg_hi:[0,1]
	v_pk_add_f32 v[60:61], v[14:15], v[64:65] op_sel:[0,1] op_sel_hi:[1,0] neg_hi:[0,1]
	v_pk_add_f32 v[84:85], v[14:15], v[64:65] op_sel:[0,1] op_sel_hi:[1,0] neg_lo:[0,1]
	v_pk_mul_f32 v[64:65], v[52:53], s[36:37]
	v_pk_fma_f32 v[52:53], v[52:53], s[66:67], v[64:65] op_sel:[0,0,1] op_sel_hi:[1,0,0]
	v_pk_add_f32 v[64:65], v[54:55], v[100:101]
	v_pk_add_f32 v[54:55], v[54:55], v[100:101] neg_lo:[0,1] neg_hi:[0,1]
	v_pk_mul_f32 v[76:77], v[54:55], s[40:41]
	v_pk_add_f32 v[92:93], v[78:79], v[90:91] op_sel:[0,1] op_sel_hi:[1,0] neg_hi:[0,1]
	v_pk_fma_f32 v[54:55], v[54:55], s[68:69], v[76:77] op_sel:[0,0,1] op_sel_hi:[1,0,0]
	s_waitcnt lgkmcnt(1)
	v_pk_add_f32 v[76:77], v[68:69], v[102:103]
	v_pk_add_f32 v[68:69], v[68:69], v[102:103] neg_lo:[0,1] neg_hi:[0,1]
	v_pk_add_f32 v[88:89], v[78:79], v[90:91] op_sel:[0,1] op_sel_hi:[1,0] neg_lo:[0,1]
	v_xor_b32_e32 v79, 0x80000000, v68
	v_mov_b32_e32 v78, v69
	v_pk_add_f32 v[68:69], v[70:71], v[104:105]
	v_pk_add_f32 v[70:71], v[70:71], v[104:105] neg_lo:[0,1] neg_hi:[0,1]
	v_pk_add_f32 v[40:41], v[56:57], v[110:111] op_sel:[0,1] op_sel_hi:[1,0] neg_hi:[0,1]
	v_pk_add_f32 v[44:45], v[56:57], v[110:111] op_sel:[0,1] op_sel_hi:[1,0] neg_lo:[0,1]
	v_pk_add_f32 v[56:57], v[48:49], v[80:81]
	v_pk_add_f32 v[48:49], v[48:49], v[80:81] neg_lo:[0,1] neg_hi:[0,1]
	v_pk_mul_f32 v[80:81], v[70:71], s[40:41]
	v_cndmask_b32_e64 v18, v18, v208, s[0:1]
	v_pk_fma_f32 v[70:71], v[70:71], s[68:69], v[80:81] op_sel:[0,0,1] op_sel_hi:[1,0,0] neg_lo:[1,0,0] neg_hi:[1,0,0]
	s_waitcnt lgkmcnt(0)
	v_pk_add_f32 v[80:81], v[72:73], v[106:107]
	v_pk_add_f32 v[72:73], v[72:73], v[106:107] neg_lo:[0,1] neg_hi:[0,1]
	v_pk_add_f32 v[22:23], v[36:37], v[42:43]
	v_pk_mul_f32 v[82:83], v[72:73], s[36:37]
	v_pk_add_f32 v[116:117], v[36:37], v[42:43] neg_lo:[0,1] neg_hi:[0,1]
	v_pk_fma_f32 v[72:73], v[72:73], s[66:67], v[82:83] op_sel:[0,0,1] op_sel_hi:[1,0,0] neg_lo:[1,0,0] neg_hi:[1,0,0]
	v_pk_add_f32 v[82:83], v[74:75], v[108:109]
	v_pk_add_f32 v[74:75], v[74:75], v[108:109] neg_lo:[0,1] neg_hi:[0,1]
	v_pk_mul_f32 v[90:91], v[74:75], s[18:19]
	v_pk_fma_f32 v[74:75], v[74:75], s[16:17], v[90:91] op_sel:[0,0,1] op_sel_hi:[1,0,0] neg_lo:[1,0,0] neg_hi:[1,0,0]
	v_pk_add_f32 v[90:91], v[56:57], v[76:77]
	v_pk_add_f32 v[56:57], v[56:57], v[76:77] neg_lo:[0,1] neg_hi:[0,1]
	v_pk_add_f32 v[76:77], v[58:59], v[68:69]
	v_pk_add_f32 v[58:59], v[58:59], v[68:69] neg_lo:[0,1] neg_hi:[0,1]
	v_pk_add_f32 v[14:15], v[114:115], v[116:117] op_sel:[0,1] op_sel_hi:[1,0] neg_hi:[0,1]
	v_pk_mul_f32 v[68:69], v[58:59], s[36:37]
	v_pk_add_f32 v[36:37], v[114:115], v[116:117] op_sel:[0,1] op_sel_hi:[1,0] neg_lo:[0,1]
	v_pk_fma_f32 v[58:59], v[58:59], s[66:67], v[68:69] op_sel:[0,0,1] op_sel_hi:[1,0,0]
	v_pk_add_f32 v[68:69], v[62:63], v[80:81]
	v_pk_add_f32 v[80:81], v[62:63], v[80:81] neg_lo:[0,1] neg_hi:[0,1]
	s_waitcnt vmcnt(0)
	v_cvt_f32_f16_e32 v193, v33
	s_nop 0
	s_nop 0
	v_pk_add_f32 v[62:63], v[64:65], v[82:83]
	v_pk_add_f32 v[64:65], v[64:65], v[82:83] neg_lo:[0,1] neg_hi:[0,1]
	v_cvt_f32_f16_sdwa v192, v32 dst_sel:DWORD dst_unused:UNUSED_PAD src0_sel:WORD_1
	v_pk_mul_f32 v[82:83], v[64:65], s[36:37]
	v_cvt_f32_f16_e32 v194, v32
	v_pk_fma_f32 v[64:65], v[64:65], s[66:67], v[82:83] op_sel:[0,0,1] op_sel_hi:[1,0,0] neg_lo:[1,0,0] neg_hi:[1,0,0]
	v_pk_add_f32 v[82:83], v[48:49], v[78:79]
	v_pk_add_f32 v[48:49], v[48:49], v[78:79] neg_lo:[0,1] neg_hi:[0,1]
	v_pk_add_f32 v[78:79], v[50:51], v[70:71]
	v_pk_add_f32 v[50:51], v[50:51], v[70:71] neg_lo:[0,1] neg_hi:[0,1]
	v_cvt_f32_f16_sdwa v195, v33 dst_sel:DWORD dst_unused:UNUSED_PAD src0_sel:WORD_1
	v_pk_mul_f32 v[70:71], v[50:51], s[36:37]
	v_cvt_f32_f16_sdwa v170, v30 dst_sel:DWORD dst_unused:UNUSED_PAD src0_sel:WORD_1
	v_pk_fma_f32 v[50:51], v[50:51], s[66:67], v[70:71] op_sel:[0,0,1] op_sel_hi:[1,0,0]
	v_pk_add_f32 v[70:71], v[52:53], v[72:73]
	v_pk_add_f32 v[72:73], v[52:53], v[72:73] neg_lo:[0,1] neg_hi:[0,1]
	v_cvt_f32_f16_e32 v171, v31
	s_nop 0
	s_nop 0
	v_pk_add_f32 v[52:53], v[54:55], v[74:75]
	v_pk_add_f32 v[54:55], v[54:55], v[74:75] neg_lo:[0,1] neg_hi:[0,1]
	v_cvt_f32_f16_sdwa v185, v31 dst_sel:DWORD dst_unused:UNUSED_PAD src0_sel:WORD_1
	v_pk_mul_f32 v[74:75], v[54:55], s[36:37]
	v_cvt_f32_f16_e32 v184, v30
	v_pk_fma_f32 v[54:55], v[54:55], s[66:67], v[74:75] op_sel:[0,0,1] op_sel_hi:[1,0,0] neg_lo:[1,0,0] neg_hi:[1,0,0]
	v_pk_add_f32 v[74:75], v[90:91], v[68:69]
	v_pk_add_f32 v[68:69], v[90:91], v[68:69] neg_lo:[0,1] neg_hi:[0,1]
	v_pk_add_f32 v[90:91], v[76:77], v[62:63]
	v_pk_add_f32 v[62:63], v[76:77], v[62:63] neg_lo:[0,1] neg_hi:[0,1]
	v_cvt_f32_f16_sdwa v172, v24 dst_sel:DWORD dst_unused:UNUSED_PAD src0_sel:WORD_1
	v_xor_b32_e32 v77, 0x80000000, v62
	v_mov_b32_e32 v76, v63
	v_pk_add_f32 v[62:63], v[56:57], v[80:81] op_sel:[0,1] op_sel_hi:[1,0] neg_hi:[0,1]
	v_pk_add_f32 v[56:57], v[56:57], v[80:81] op_sel:[0,1] op_sel_hi:[1,0] neg_lo:[0,1]
	v_pk_add_f32 v[80:81], v[58:59], v[64:65]
	v_pk_add_f32 v[58:59], v[58:59], v[64:65] neg_lo:[0,1] neg_hi:[0,1]
	v_cvt_f32_f16_e32 v173, v25
	v_xor_b32_e32 v65, 0x80000000, v58
	v_mov_b32_e32 v64, v59
	v_pk_add_f32 v[58:59], v[82:83], v[70:71]
	v_pk_add_f32 v[70:71], v[82:83], v[70:71] neg_lo:[0,1] neg_hi:[0,1]
	v_pk_add_f32 v[82:83], v[78:79], v[52:53]
	v_pk_add_f32 v[52:53], v[78:79], v[52:53] neg_lo:[0,1] neg_hi:[0,1]
	v_pk_add_f32 v[118:119], v[58:59], v[82:83]
	v_pk_add_f32 v[134:135], v[58:59], v[82:83] neg_lo:[0,1] neg_hi:[0,1]
	v_cos_f32_e32 v83, v18
	v_sin_f32_e32 v82, v18
	v_cvt_f32_f16_sdwa v181, v25 dst_sel:DWORD dst_unused:UNUSED_PAD src0_sel:WORD_1
	v_cvt_f32_f16_e32 v180, v24
	v_cvt_f32_f16_sdwa v174, v28 dst_sel:DWORD dst_unused:UNUSED_PAD src0_sel:WORD_1
	v_cvt_f32_f16_e32 v175, v29
	v_cvt_f32_f16_sdwa v179, v29 dst_sel:DWORD dst_unused:UNUSED_PAD src0_sel:WORD_1
	v_cvt_f32_f16_e32 v178, v28
	v_cvt_f32_f16_e32 v165, v13
	v_cvt_f32_f16_sdwa v167, v13 dst_sel:DWORD dst_unused:UNUSED_PAD src0_sel:WORD_1
	v_cvt_f32_f16_e32 v166, v12
	v_cvt_f32_f16_e32 v154, v6
	v_cvt_f32_f16_e32 v155, v7
	v_cvt_f32_f16_sdwa v157, v7 dst_sel:DWORD dst_unused:UNUSED_PAD src0_sel:WORD_1
	v_cvt_f32_f16_sdwa v156, v6 dst_sel:DWORD dst_unused:UNUSED_PAD src0_sel:WORD_1
	v_cvt_f32_f16_sdwa v140, v4 dst_sel:DWORD dst_unused:UNUSED_PAD src0_sel:WORD_1
	v_cvt_f32_f16_e32 v141, v5
	v_cvt_f32_f16_sdwa v143, v5 dst_sel:DWORD dst_unused:UNUSED_PAD src0_sel:WORD_1
	v_cvt_f32_f16_e32 v142, v4
	v_cvt_f32_f16_e32 v124, v16
	v_cvt_f32_f16_e32 v125, v17
	v_cvt_f32_f16_sdwa v127, v17 dst_sel:DWORD dst_unused:UNUSED_PAD src0_sel:WORD_1
	v_cvt_f32_f16_sdwa v126, v16 dst_sel:DWORD dst_unused:UNUSED_PAD src0_sel:WORD_1
	v_cvt_f32_f16_sdwa v114, v122 dst_sel:DWORD dst_unused:UNUSED_PAD src0_sel:WORD_1
	v_cvt_f32_f16_e32 v115, v123
	v_cvt_f32_f16_sdwa v117, v123 dst_sel:DWORD dst_unused:UNUSED_PAD src0_sel:WORD_1
	v_cvt_f32_f16_e32 v116, v122
	v_xor_b32_e32 v79, 0x80000000, v52
	v_mov_b32_e32 v78, v53
	v_pk_add_f32 v[52:53], v[48:49], v[72:73] op_sel:[0,1] op_sel_hi:[1,0] neg_hi:[0,1]
	v_pk_add_f32 v[48:49], v[48:49], v[72:73] op_sel:[0,1] op_sel_hi:[1,0] neg_lo:[0,1]
	v_pk_add_f32 v[72:73], v[50:51], v[54:55]
	v_pk_add_f32 v[50:51], v[50:51], v[54:55] neg_lo:[0,1] neg_hi:[0,1]
	v_pk_fma_f32 v[160:161], v[82:83], 0, v[82:83] op_sel:[0,0,1] op_sel_hi:[1,0,0] neg_lo:[1,0,0] neg_hi:[1,0,0]
	v_xor_b32_e32 v55, 0x80000000, v50
	v_mov_b32_e32 v54, v51
	v_pk_fma_f32 v[198:199], v[82:83], 0, v[82:83] op_sel:[0,0,1] op_sel_hi:[1,0,0]
	v_pk_add_f32 v[42:43], v[112:113], v[22:23]
	v_pk_add_f32 v[22:23], v[112:113], v[22:23] neg_lo:[0,1] neg_hi:[0,1]
	v_pk_add_f32 v[98:99], v[74:75], v[90:91]
	v_pk_add_f32 v[100:101], v[74:75], v[90:91] neg_lo:[0,1] neg_hi:[0,1]
	v_pk_add_f32 v[102:103], v[68:69], v[76:77]
	v_pk_add_f32 v[106:107], v[68:69], v[76:77] neg_lo:[0,1] neg_hi:[0,1]
	v_pk_add_f32 v[104:105], v[62:63], v[80:81]
	v_pk_add_f32 v[108:109], v[62:63], v[80:81] neg_lo:[0,1] neg_hi:[0,1]
	v_pk_add_f32 v[110:111], v[56:57], v[64:65]
	v_pk_add_f32 v[112:113], v[56:57], v[64:65] neg_lo:[0,1] neg_hi:[0,1]
	v_pk_add_f32 v[152:153], v[70:71], v[78:79]
	v_pk_add_f32 v[162:163], v[70:71], v[78:79] neg_lo:[0,1] neg_hi:[0,1]
	v_pk_add_f32 v[176:177], v[52:53], v[72:73]
	v_pk_add_f32 v[182:183], v[52:53], v[72:73] neg_lo:[0,1] neg_hi:[0,1]
	v_pk_add_f32 v[188:189], v[48:49], v[54:55]
	v_pk_add_f32 v[196:197], v[48:49], v[54:55] neg_lo:[0,1] neg_hi:[0,1]
	v_pk_mul_f32 v[186:187], v[82:83], 0 op_sel_hi:[1,0]
	v_mov_b32_e32 v190, v160
	v_mov_b32_e32 v191, v199
	v_mul_f32_e32 v18, 0x3f3504f3, v83
	v_mul_f32_e32 v158, 0xbec3ef15, v83
	v_mul_f32_e32 v132, 0xbf6c835e, v83
	s_and_saveexec_b64 s[0:1], vcc
	s_xor_b64 s[0:1], exec, s[0:1]
	s_cbranch_execz .LBB0_536
	v_pk_add_f32 v[4:5], v[148:149], v[196:197]
	v_pk_add_f32 v[6:7], v[148:149], v[196:197] neg_lo:[0,1] neg_hi:[0,1]
	v_mul_f32_e32 v4, 0.5, v4
	v_mul_f32_e32 v12, 0.5, v7
	v_mov_b32_e32 v7, v5
	v_pk_mul_f32 v[6:7], v[6:7], s[44:45]
	v_pk_mov_b32 v[16:17], v[198:199], v[160:161] op_sel:[1,0]
	v_pk_mul_f32 v[24:25], v[190:191], v[6:7] op_sel:[0,1] op_sel_hi:[1,0]
	v_pk_mul_f32 v[6:7], v[190:191], v[6:7]
	v_pk_add_f32 v[24:25], v[24:25], v[24:25] op_sel:[0,1] op_sel_hi:[0,1]
	v_pk_add_f32 v[28:29], v[4:5], v[24:25] op_sel_hi:[0,1] neg_hi:[0,1]
	v_pk_add_f32 v[4:5], v[6:7], v[6:7] op_sel:[0,1] op_sel_hi:[0,1] neg_lo:[0,1] neg_hi:[0,1]
	v_pk_add_f32 v[6:7], v[12:13], v[4:5] op_sel_hi:[0,1] neg_hi:[0,1]
	v_pk_mul_f32 v[4:5], v[6:7], v[194:195]
	v_pk_mul_f32 v[6:7], v[6:7], v[192:193]
	v_pk_fma_f32 v[4:5], v[28:29], v[192:193], v[4:5]
	v_pk_fma_f32 v[6:7], v[28:29], v[194:195], v[6:7] neg_lo:[0,0,1] neg_hi:[0,0,1]
	s_mov_b32 s66, s19
	v_pk_add_f32 v[12:13], v[6:7], v[4:5] op_sel:[0,1] op_sel_hi:[1,0] neg_lo:[0,1]
	v_pk_add_f32 v[28:29], v[6:7], v[4:5] op_sel:[0,1] op_sel_hi:[1,0]
	v_pk_add_f32 v[4:5], v[4:5], v[6:7] op_sel:[1,0] op_sel_hi:[0,1] neg_lo:[0,1] neg_hi:[0,1]
	s_nop 0
	v_pk_mul_f32 v[12:13], v[12:13], 0.5 op_sel_hi:[1,0]
	v_mov_b32_e32 v29, v5
	v_mul_f32_e32 v24, v190, v12
	v_pk_fma_f32 v[30:31], v[190:191], v[12:13], v[24:25] op_sel_hi:[1,1,0] neg_lo:[1,0,0] neg_hi:[1,0,0]
	v_mul_f32_e32 v24, v160, v13
	v_pk_fma_f32 v[12:13], v[16:17], v[12:13], v[24:25] op_sel_hi:[1,1,0]
	v_mov_b32_e32 v16, v83
	v_mov_b32_e32 v30, v12
	v_pk_fma_f32 v[4:5], v[28:29], 0.5, v[12:13] op_sel_hi:[1,0,1] neg_lo:[0,0,1] neg_hi:[0,0,1]
	v_pk_fma_f32 v[122:123], v[28:29], 0.5, v[30:31] op_sel_hi:[1,0,1]
	v_pk_fma_f32 v[6:7], v[28:29], 0.5, v[30:31] op_sel_hi:[1,0,1] neg_lo:[1,0,0] neg_hi:[1,0,0]
	v_mov_b32_e32 v5, v123
	v_pk_mul_f32 v[24:25], v[4:5], s[46:47] op_sel_hi:[1,0]
	v_pk_add_f32 v[4:5], v[138:139], v[188:189]
	v_pk_add_f32 v[12:13], v[138:139], v[188:189] neg_lo:[0,1] neg_hi:[0,1]
	v_mov_b32_e32 v17, v82
	v_mul_f32_e32 v6, 0.5, v13
	v_pk_add_f32 v[28:29], v[186:187], v[16:17] neg_lo:[0,1] neg_hi:[0,1]
	v_pk_add_f32 v[30:31], v[186:187], v[16:17]
	v_mov_b32_e32 v13, v5
	v_pk_mov_b32 v[32:33], v[28:29], v[30:31] op_sel:[1,0]
	v_pk_mul_f32 v[12:13], v[12:13], s[44:45]
	v_mul_f32_e32 v4, 0.5, v4
	v_pk_mul_f32 v[48:49], v[32:33], v[12:13] op_sel:[0,1] op_sel_hi:[1,0]
	v_pk_mul_f32 v[12:13], v[32:33], v[12:13]
	v_pk_add_f32 v[48:49], v[48:49], v[48:49] op_sel:[0,1] op_sel_hi:[0,1]
	v_pk_add_f32 v[50:51], v[4:5], v[48:49] op_sel_hi:[0,1] neg_hi:[0,1]
	v_pk_add_f32 v[4:5], v[12:13], v[12:13] op_sel:[0,1] op_sel_hi:[0,1] neg_lo:[0,1] neg_hi:[0,1]
	v_pk_add_f32 v[12:13], v[6:7], v[4:5] op_sel_hi:[0,1] neg_hi:[0,1]
	v_pk_mul_f32 v[4:5], v[12:13], v[184:185]
	v_pk_mul_f32 v[12:13], v[12:13], v[170:171]
	v_pk_fma_f32 v[4:5], v[50:51], v[170:171], v[4:5]
	v_pk_fma_f32 v[12:13], v[50:51], v[184:185], v[12:13] neg_lo:[0,0,1] neg_hi:[0,0,1]
	v_mov_b32_e32 v31, v29
	v_pk_add_f32 v[48:49], v[12:13], v[4:5] op_sel:[0,1] op_sel_hi:[1,0] neg_lo:[0,1]
	v_pk_add_f32 v[50:51], v[12:13], v[4:5] op_sel:[0,1] op_sel_hi:[1,0]
	v_pk_add_f32 v[4:5], v[4:5], v[12:13] op_sel:[1,0] op_sel_hi:[0,1] neg_lo:[0,1] neg_hi:[0,1]
	v_pk_mul_f32 v[48:49], v[48:49], 0.5 op_sel_hi:[1,0]
	v_mov_b32_e32 v51, v5
	v_mul_f32_e32 v6, v29, v48
	v_pk_fma_f32 v[32:33], v[32:33], v[48:49], v[6:7] op_sel_hi:[1,1,0] neg_lo:[1,0,0] neg_hi:[1,0,0]
	v_mul_f32_e32 v6, v29, v49
	v_pk_fma_f32 v[28:29], v[30:31], v[48:49], v[6:7] op_sel_hi:[1,1,0]
	v_pk_mul_f32 v[12:13], v[16:17], s[36:37]
	v_mov_b32_e32 v32, v28
	v_pk_fma_f32 v[4:5], v[50:51], 0.5, v[28:29] op_sel_hi:[1,0,1] neg_lo:[0,0,1] neg_hi:[0,0,1]
	v_pk_fma_f32 v[138:139], v[50:51], 0.5, v[32:33] op_sel_hi:[1,0,1]
	v_pk_add_f32 v[16:17], v[92:93], v[182:183]
	v_mov_b32_e32 v5, v139
	v_pk_add_f32 v[28:29], v[92:93], v[182:183] neg_lo:[0,1] neg_hi:[0,1]
	v_pk_mul_f32 v[30:31], v[4:5], s[46:47] op_sel_hi:[1,0]
	v_pk_fma_f32 v[4:5], v[50:51], 0.5, v[32:33] op_sel_hi:[1,0,1] neg_lo:[1,0,0] neg_hi:[1,0,0]
	v_mul_f32_e32 v6, 0.5, v29
	v_pk_add_f32 v[32:33], v[18:19], v[12:13] op_sel:[0,1] op_sel_hi:[0,1] neg_lo:[0,1] neg_hi:[0,1]
	v_pk_add_f32 v[48:49], v[18:19], v[12:13] op_sel:[0,1] op_sel_hi:[0,1]
	v_mov_b32_e32 v29, v17
	v_mul_f32_e32 v4, 0.5, v16
	v_mov_b32_e32 v50, v32
	v_mov_b32_e32 v51, v49
	v_pk_mul_f32 v[16:17], v[28:29], s[44:45]
	v_pk_mov_b32 v[48:49], v[48:49], v[32:33] op_sel:[1,0]
	v_pk_mul_f32 v[28:29], v[50:51], v[16:17] op_sel:[0,1] op_sel_hi:[1,0]
	v_pk_mul_f32 v[16:17], v[50:51], v[16:17]
	v_pk_add_f32 v[28:29], v[28:29], v[28:29] op_sel:[0,1] op_sel_hi:[0,1]
	v_pk_add_f32 v[52:53], v[4:5], v[28:29] op_sel_hi:[0,1] neg_hi:[0,1]
	v_pk_add_f32 v[16:17], v[16:17], v[16:17] op_sel:[0,1] op_sel_hi:[0,1] neg_lo:[0,1] neg_hi:[0,1]
	v_pk_add_f32 v[28:29], v[6:7], v[16:17] op_sel_hi:[0,1] neg_hi:[0,1]
	v_pk_mul_f32 v[16:17], v[28:29], v[180:181]
	v_pk_mul_f32 v[28:29], v[28:29], v[172:173]
	v_pk_fma_f32 v[16:17], v[52:53], v[172:173], v[16:17]
	v_pk_fma_f32 v[28:29], v[52:53], v[180:181], v[28:29] neg_lo:[0,0,1] neg_hi:[0,0,1]
	v_sub_f32_e32 v6, v89, v177
	v_pk_add_f32 v[52:53], v[28:29], v[16:17] op_sel:[0,1] op_sel_hi:[1,0] neg_lo:[0,1]
	v_pk_add_f32 v[54:55], v[28:29], v[16:17] op_sel:[0,1] op_sel_hi:[1,0]
	v_pk_add_f32 v[16:17], v[16:17], v[28:29] op_sel:[1,0] op_sel_hi:[0,1] neg_lo:[0,1] neg_hi:[0,1]
	v_pk_mul_f32 v[52:53], v[52:53], 0.5 op_sel_hi:[1,0]
	v_mov_b32_e32 v55, v17
	v_mul_f32_e32 v4, v32, v52
	v_pk_fma_f32 v[56:57], v[50:51], v[52:53], v[4:5] op_sel_hi:[1,1,0] neg_lo:[1,0,0] neg_hi:[1,0,0]
	v_mul_f32_e32 v4, v32, v53
	v_pk_fma_f32 v[48:49], v[48:49], v[52:53], v[4:5] op_sel_hi:[1,1,0]
	v_pk_add_f32 v[28:29], v[88:89], v[176:177]
	v_mov_b32_e32 v56, v48
	v_pk_fma_f32 v[16:17], v[54:55], 0.5, v[48:49] op_sel_hi:[1,0,1] neg_lo:[0,0,1] neg_hi:[0,0,1]
	v_mov_b32_e32 v48, v12
	v_mov_b32_e32 v49, v88
	v_pk_mov_b32 v[12:13], v[12:13], v[176:177] op_sel:[1,0]
	v_mul_f32_e32 v18, 0.5, v29
	v_pk_add_f32 v[12:13], v[48:49], v[12:13] neg_lo:[0,1] neg_hi:[0,1]
	v_mul_f32_e32 v4, 0.5, v28
	v_pk_mul_f32 v[48:49], v[12:13], v[18:19]
	v_mov_b32_e32 v13, v32
	v_pk_fma_f32 v[50:51], v[50:51], v[48:49], v[48:49] op_sel:[0,1,0] op_sel_hi:[1,0,1]
	v_mov_b32_e32 v48, v49
	v_mov_b32_e32 v49, v18
	v_pk_mul_f32 v[48:49], v[12:13], v[48:49]
	v_pk_add_f32 v[52:53], v[4:5], v[50:51]
	v_mul_f32_e32 v6, 0.5, v6
	v_fma_f32 v53, v28, 0.5, -v50
	v_pk_add_f32 v[28:29], v[48:49], v[48:49] op_sel:[0,1] op_sel_hi:[0,1] neg_lo:[0,1] neg_hi:[0,1]
	v_pk_add_f32 v[48:49], v[6:7], v[28:29] op_sel_hi:[0,1] neg_hi:[0,1]
	v_pk_mul_f32 v[28:29], v[48:49], v[178:179]
	v_pk_mul_f32 v[48:49], v[48:49], v[174:175]
	v_pk_fma_f32 v[28:29], v[52:53], v[174:175], v[28:29]
	v_pk_fma_f32 v[48:49], v[52:53], v[178:179], v[48:49] neg_lo:[0,0,1] neg_hi:[0,0,1]
	v_pk_fma_f32 v[92:93], v[54:55], 0.5, v[56:57] op_sel_hi:[1,0,1]
	v_pk_add_f32 v[50:51], v[48:49], v[28:29] op_sel:[0,1] op_sel_hi:[1,0] neg_lo:[0,1]
	v_pk_add_f32 v[52:53], v[48:49], v[28:29] op_sel:[0,1] op_sel_hi:[1,0]
	v_mov_b32_e32 v17, v93
	v_pk_mul_f32 v[50:51], v[50:51], 0.5 op_sel_hi:[1,0]
	v_pk_mul_f32 v[64:65], v[16:17], s[46:47] op_sel_hi:[1,0]
	v_mul_f32_e32 v4, v12, v50
	v_pk_fma_f32 v[16:17], v[54:55], 0.5, v[56:57] op_sel_hi:[1,0,1] neg_lo:[1,0,0] neg_hi:[1,0,0]
	v_pk_fma_f32 v[54:55], v[12:13], v[50:51], v[4:5] op_sel_hi:[1,1,0] neg_lo:[1,0,0] neg_hi:[1,0,0]
	v_mov_b32_e32 v33, v12
	v_mul_f32_e32 v4, v12, v51
	v_pk_fma_f32 v[12:13], v[32:33], v[50:51], v[4:5] op_sel_hi:[1,1,0]
	v_pk_add_f32 v[28:29], v[28:29], v[48:49] op_sel:[1,0] op_sel_hi:[0,1] neg_lo:[0,1] neg_hi:[0,1]
	v_mov_b32_e32 v53, v29
	v_mov_b32_e32 v54, v12
	v_pk_fma_f32 v[12:13], v[52:53], 0.5, v[12:13] op_sel_hi:[1,0,1] neg_lo:[0,0,1] neg_hi:[0,0,1]
	v_pk_fma_f32 v[88:89], v[52:53], 0.5, v[54:55] op_sel_hi:[1,0,1]
	s_mov_b32 s67, s16
	v_mov_b32_e32 v13, v89
	v_pk_mul_f32 v[68:69], v[12:13], s[46:47] op_sel_hi:[1,0]
	v_pk_fma_f32 v[12:13], v[52:53], 0.5, v[54:55] op_sel_hi:[1,0,1] neg_lo:[1,0,0] neg_hi:[1,0,0]
	v_mov_b32_e32 v4, v83
	s_mov_b32 s17, s19
	v_pk_mul_f32 v[48:49], v[82:83], s[66:67] op_sel_hi:[0,1]
	v_pk_add_f32 v[28:29], v[96:97], v[162:163]
	v_pk_add_f32 v[32:33], v[96:97], v[162:163] neg_lo:[0,1] neg_hi:[0,1]
	v_pk_fma_f32 v[52:53], v[4:5], s[16:17], v[48:49] op_sel_hi:[0,1,1] neg_lo:[0,0,1] neg_hi:[0,0,1]
	v_mul_f32_e32 v12, 0.5, v33
	v_pk_fma_f32 v[50:51], v[4:5], s[16:17], v[48:49] op_sel_hi:[0,1,1]
	v_mov_b32_e32 v33, v29
	v_mul_f32_e32 v6, 0.5, v28
	v_mov_b32_e32 v54, v52
	v_mov_b32_e32 v55, v51
	v_pk_mul_f32 v[28:29], v[32:33], s[44:45]
	v_pk_mov_b32 v[56:57], v[50:51], v[52:53] op_sel:[1,0]
	v_pk_mul_f32 v[32:33], v[54:55], v[28:29] op_sel:[0,1] op_sel_hi:[1,0]
	v_pk_mul_f32 v[28:29], v[54:55], v[28:29]
	v_pk_add_f32 v[32:33], v[32:33], v[32:33] op_sel:[0,1] op_sel_hi:[0,1]
	v_pk_add_f32 v[58:59], v[6:7], v[32:33] op_sel_hi:[0,1] neg_hi:[0,1]
	v_pk_add_f32 v[28:29], v[28:29], v[28:29] op_sel:[0,1] op_sel_hi:[0,1] neg_lo:[0,1] neg_hi:[0,1]
	v_pk_add_f32 v[32:33], v[12:13], v[28:29] op_sel_hi:[0,1] neg_hi:[0,1]
	v_pk_mul_f32 v[28:29], v[32:33], v[166:167]
	v_pk_mul_f32 v[32:33], v[32:33], v[164:165]
	v_pk_fma_f32 v[28:29], v[58:59], v[164:165], v[28:29]
	v_pk_fma_f32 v[32:33], v[58:59], v[166:167], v[32:33] neg_lo:[0,0,1] neg_hi:[0,0,1]
	v_mov_b32_e32 v159, v66
	v_pk_add_f32 v[58:59], v[32:33], v[28:29] op_sel:[0,1] op_sel_hi:[1,0] neg_lo:[0,1]
	v_pk_add_f32 v[70:71], v[32:33], v[28:29] op_sel:[0,1] op_sel_hi:[1,0]
	v_pk_add_f32 v[28:29], v[28:29], v[32:33] op_sel:[1,0] op_sel_hi:[0,1] neg_lo:[0,1] neg_hi:[0,1]
	v_pk_mul_f32 v[58:59], v[58:59], 0.5 op_sel_hi:[1,0]
	v_mov_b32_e32 v71, v29
	v_mul_f32_e32 v6, v52, v58
	v_pk_fma_f32 v[72:73], v[54:55], v[58:59], v[6:7] op_sel_hi:[1,1,0] neg_lo:[1,0,0] neg_hi:[1,0,0]
	v_mul_f32_e32 v6, v52, v59
	v_pk_fma_f32 v[56:57], v[56:57], v[58:59], v[6:7] op_sel_hi:[1,1,0]
	v_sub_f32_e32 v12, v67, v153
	v_mov_b32_e32 v72, v56
	v_pk_fma_f32 v[28:29], v[70:71], 0.5, v[56:57] op_sel_hi:[1,0,1] neg_lo:[0,0,1] neg_hi:[0,0,1]
	v_pk_fma_f32 v[96:97], v[70:71], 0.5, v[72:73] op_sel_hi:[1,0,1]
	v_pk_mov_b32 v[56:57], v[48:49], v[152:153] op_sel:[1,0]
	v_mov_b32_e32 v29, v97
	v_pk_mul_f32 v[62:63], v[28:29], s[46:47] op_sel_hi:[1,0]
	v_pk_add_f32 v[28:29], v[66:67], v[152:153]
	v_pk_add_f32 v[56:57], v[158:159], v[56:57] neg_lo:[0,1] neg_hi:[0,1]
	v_mul_f32_e32 v18, 0.5, v29
	v_pk_mul_f32 v[58:59], v[56:57], v[18:19]
	v_mul_f32_e32 v6, 0.5, v28
	v_pk_fma_f32 v[54:55], v[54:55], v[58:59], v[58:59] op_sel:[0,1,0] op_sel_hi:[1,0,1]
	v_mov_b32_e32 v66, v56
	v_mov_b32_e32 v67, v52
	v_mov_b32_e32 v58, v59
	v_mov_b32_e32 v59, v18
	v_pk_mul_f32 v[58:59], v[66:67], v[58:59]
	v_pk_add_f32 v[66:67], v[6:7], v[54:55]
	v_mul_f32_e32 v12, 0.5, v12
	v_fma_f32 v67, v28, 0.5, -v54
	v_pk_add_f32 v[28:29], v[58:59], v[58:59] op_sel:[0,1] op_sel_hi:[0,1] neg_lo:[0,1] neg_hi:[0,1]
	v_pk_add_f32 v[54:55], v[12:13], v[28:29] op_sel_hi:[0,1] neg_hi:[0,1]
	v_pk_mul_f32 v[28:29], v[54:55], v[156:157]
	v_pk_mul_f32 v[54:55], v[54:55], v[154:155]
	v_pk_fma_f32 v[32:33], v[70:71], 0.5, v[72:73] op_sel_hi:[1,0,1] neg_lo:[1,0,0] neg_hi:[1,0,0]
	v_pk_fma_f32 v[58:59], v[66:67], v[154:155], v[28:29] neg_lo:[0,0,1] neg_hi:[0,0,1]
	v_pk_fma_f32 v[28:29], v[66:67], v[154:155], v[28:29]
	v_pk_fma_f32 v[70:71], v[66:67], v[156:157], v[54:55]
	v_pk_fma_f32 v[54:55], v[66:67], v[156:157], v[54:55] neg_lo:[0,0,1] neg_hi:[0,0,1]
	v_pk_add_f32 v[72:73], v[58:59], v[28:29] op_sel:[0,1] op_sel_hi:[1,0]
	v_pk_add_f32 v[66:67], v[70:71], v[54:55] op_sel_hi:[0,1] neg_lo:[0,1] neg_hi:[0,1]
	v_pk_add_f32 v[28:29], v[58:59], v[28:29] op_sel_hi:[0,1] neg_lo:[0,1] neg_hi:[0,1]
	v_pk_add_f32 v[54:55], v[70:71], v[54:55] op_sel:[0,1] op_sel_hi:[1,0]
	v_mov_b32_e32 v73, v67
	v_mov_b32_e32 v55, v29
	v_pk_mul_f32 v[28:29], v[54:55], 0.5 op_sel_hi:[1,0]
	v_mov_b32_e32 v133, v84
	v_pk_mul_f32 v[54:55], v[52:53], v[28:29] op_sel:[0,1] op_sel_hi:[0,0]
	v_pk_fma_f32 v[58:59], v[56:57], v[28:29], v[54:55] op_sel_hi:[0,1,1]
	v_pk_fma_f32 v[28:29], v[56:57], v[28:29], v[54:55] op_sel_hi:[0,1,1] neg_hi:[0,0,1]
	v_pk_fma_f32 v[54:55], v[72:73], 0.5, v[58:59] op_sel_hi:[1,0,1] neg_lo:[0,0,1] neg_hi:[0,0,1]
	v_pk_fma_f32 v[66:67], v[72:73], 0.5, v[28:29] op_sel_hi:[1,0,1]
	v_pk_add_f32 v[56:57], v[60:61], v[134:135] neg_lo:[0,1] neg_hi:[0,1]
	v_mov_b32_e32 v55, v67
	v_pk_mul_f32 v[90:91], v[54:55], s[46:47] op_sel_hi:[1,0]
	v_pk_add_f32 v[54:55], v[134:135], v[60:61]
	v_mul_f32_e32 v12, 0.5, v57
	v_mov_b32_e32 v57, v55
	v_mul_f32_e32 v6, 0.5, v54
	v_pk_mov_b32 v[58:59], v[52:53], v[50:51] op_sel:[1,0]
	v_pk_mul_f32 v[54:55], v[56:57], s[44:45]
	v_pk_fma_f32 v[28:29], v[72:73], 0.5, v[28:29] op_sel_hi:[1,0,1] neg_lo:[1,0,0] neg_hi:[1,0,0]
	v_pk_mul_f32 v[56:57], v[58:59], v[54:55] op_sel:[0,1] op_sel_hi:[1,0]
	v_pk_mul_f32 v[54:55], v[58:59], v[54:55]
	v_pk_add_f32 v[56:57], v[56:57], v[56:57] op_sel:[0,1] op_sel_hi:[0,1]
	v_pk_add_f32 v[60:61], v[6:7], v[56:57] op_sel_hi:[0,1] neg_hi:[0,1]
	v_pk_add_f32 v[54:55], v[54:55], v[54:55] op_sel:[0,1] op_sel_hi:[0,1] neg_lo:[0,1] neg_hi:[0,1]
	v_pk_add_f32 v[56:57], v[12:13], v[54:55] op_sel_hi:[0,1] neg_hi:[0,1]
	v_pk_mul_f32 v[54:55], v[56:57], v[142:143]
	v_pk_mul_f32 v[56:57], v[56:57], v[140:141]
	v_pk_fma_f32 v[54:55], v[60:61], v[140:141], v[54:55]
	v_pk_fma_f32 v[56:57], v[60:61], v[142:143], v[56:57] neg_lo:[0,0,1] neg_hi:[0,0,1]
	v_mov_b32_e32 v51, v53
	v_pk_add_f32 v[60:61], v[56:57], v[54:55] op_sel:[0,1] op_sel_hi:[1,0] neg_lo:[0,1]
	v_pk_add_f32 v[70:71], v[56:57], v[54:55] op_sel:[0,1] op_sel_hi:[1,0]
	v_pk_add_f32 v[54:55], v[54:55], v[56:57] op_sel:[1,0] op_sel_hi:[0,1] neg_lo:[0,1] neg_hi:[0,1]
	v_pk_mul_f32 v[60:61], v[60:61], 0.5 op_sel_hi:[1,0]
	v_mov_b32_e32 v71, v55
	v_mul_f32_e32 v6, v53, v60
	v_pk_fma_f32 v[72:73], v[58:59], v[60:61], v[6:7] op_sel_hi:[1,1,0] neg_lo:[1,0,0] neg_hi:[1,0,0]
	v_mul_f32_e32 v6, v53, v61
	v_pk_fma_f32 v[50:51], v[50:51], v[60:61], v[6:7] op_sel_hi:[1,1,0]
	v_pk_add_f32 v[54:55], v[118:119], v[84:85]
	v_mov_b32_e32 v72, v50
	v_mov_b32_e32 v49, v118
	v_pk_fma_f32 v[50:51], v[70:71], 0.5, v[50:51] op_sel_hi:[1,0,1] neg_lo:[0,0,1] neg_hi:[0,0,1]
	v_pk_fma_f32 v[60:61], v[70:71], 0.5, v[72:73] op_sel_hi:[1,0,1]
	v_mul_f32_e32 v18, 0.5, v55
	v_pk_add_f32 v[48:49], v[132:133], v[48:49] neg_lo:[0,1] neg_hi:[0,1]
	v_mov_b32_e32 v51, v61
	v_pk_mul_f32 v[56:57], v[48:49], v[18:19]
	v_pk_mul_f32 v[94:95], v[50:51], s[46:47] op_sel_hi:[1,0]
	v_pk_fma_f32 v[50:51], v[70:71], 0.5, v[72:73] op_sel_hi:[1,0,1] neg_lo:[1,0,0] neg_hi:[1,0,0]
	v_mul_f32_e32 v6, 0.5, v54
	v_pk_fma_f32 v[58:59], v[58:59], v[56:57], v[56:57] op_sel:[0,1,0] op_sel_hi:[1,0,1]
	v_mov_b32_e32 v70, v48
	v_mov_b32_e32 v71, v53
	v_mov_b32_e32 v56, v57
	v_mov_b32_e32 v57, v18
	v_sub_f32_e32 v12, v85, v119
	v_pk_mul_f32 v[56:57], v[70:71], v[56:57]
	v_pk_add_f32 v[70:71], v[6:7], v[58:59]
	v_mul_f32_e32 v12, 0.5, v12
	v_fma_f32 v71, v54, 0.5, -v58
	v_pk_add_f32 v[54:55], v[56:57], v[56:57] op_sel:[0,1] op_sel_hi:[0,1] neg_lo:[0,1] neg_hi:[0,1]
	v_pk_add_f32 v[56:57], v[12:13], v[54:55] op_sel_hi:[0,1] neg_hi:[0,1]
	v_pk_mul_f32 v[54:55], v[56:57], v[126:127]
	v_pk_mul_f32 v[56:57], v[56:57], v[124:125]
	v_pk_fma_f32 v[58:59], v[70:71], v[124:125], v[54:55] neg_lo:[0,0,1] neg_hi:[0,0,1]
	v_pk_fma_f32 v[54:55], v[70:71], v[124:125], v[54:55]
	v_pk_fma_f32 v[72:73], v[70:71], v[126:127], v[56:57]
	v_pk_fma_f32 v[56:57], v[70:71], v[126:127], v[56:57] neg_lo:[0,0,1] neg_hi:[0,0,1]
	v_pk_add_f32 v[70:71], v[58:59], v[54:55] op_sel:[0,1] op_sel_hi:[1,0]
	v_pk_add_f32 v[74:75], v[72:73], v[56:57] op_sel_hi:[0,1] neg_lo:[0,1] neg_hi:[0,1]
	v_pk_add_f32 v[54:55], v[58:59], v[54:55] op_sel_hi:[0,1] neg_lo:[0,1] neg_hi:[0,1]
	v_pk_add_f32 v[56:57], v[72:73], v[56:57] op_sel:[0,1] op_sel_hi:[1,0]
	v_mov_b32_e32 v71, v75
	v_mov_b32_e32 v57, v55
	v_pk_mul_f32 v[54:55], v[56:57], 0.5 op_sel_hi:[1,0]
	s_mov_b32 s66, s11
	v_pk_mul_f32 v[52:53], v[52:53], v[54:55] op_sel:[1,1] op_sel_hi:[1,0]
	s_mov_b32 s67, s8
	v_pk_fma_f32 v[56:57], v[48:49], v[54:55], v[52:53] op_sel_hi:[0,1,1]
	v_pk_fma_f32 v[48:49], v[48:49], v[54:55], v[52:53] op_sel_hi:[0,1,1] neg_hi:[0,0,1]
	s_nop 0
	v_pk_fma_f32 v[52:53], v[70:71], 0.5, v[56:57] op_sel_hi:[1,0,1] neg_lo:[0,0,1] neg_hi:[0,0,1]
	v_pk_fma_f32 v[84:85], v[70:71], 0.5, v[48:49] op_sel_hi:[1,0,1]
	s_mov_b32 s9, s11
	v_mov_b32_e32 v53, v85
	v_pk_mul_f32 v[80:81], v[52:53], s[46:47] op_sel_hi:[1,0]
	v_pk_mul_f32 v[118:119], v[82:83], s[66:67] op_sel_hi:[0,1]
	v_pk_add_f32 v[52:53], v[86:87], v[112:113]
	v_pk_add_f32 v[54:55], v[86:87], v[112:113] neg_lo:[0,1] neg_hi:[0,1]
	v_pk_fma_f32 v[58:59], v[4:5], s[8:9], v[118:119] op_sel_hi:[0,1,1] neg_lo:[0,0,1] neg_hi:[0,0,1]
	v_mul_f32_e32 v12, 0.5, v55
	v_pk_fma_f32 v[72:73], v[4:5], s[8:9], v[118:119] op_sel_hi:[0,1,1]
	v_mov_b32_e32 v55, v53
	v_mul_f32_e32 v6, 0.5, v52
	v_mov_b32_e32 v56, v58
	v_mov_b32_e32 v57, v73
	v_pk_mul_f32 v[52:53], v[54:55], s[44:45]
	v_pk_fma_f32 v[48:49], v[70:71], 0.5, v[48:49] op_sel_hi:[1,0,1] neg_lo:[1,0,0] neg_hi:[1,0,0]
	v_pk_mul_f32 v[54:55], v[56:57], v[52:53] op_sel:[0,1] op_sel_hi:[1,0]
	v_pk_mul_f32 v[52:53], v[56:57], v[52:53]
	v_pk_add_f32 v[54:55], v[54:55], v[54:55] op_sel:[0,1] op_sel_hi:[0,1]
	v_pk_add_f32 v[74:75], v[6:7], v[54:55] op_sel_hi:[0,1] neg_hi:[0,1]
	v_pk_add_f32 v[52:53], v[52:53], v[52:53] op_sel:[0,1] op_sel_hi:[0,1] neg_lo:[0,1] neg_hi:[0,1]
	v_pk_add_f32 v[54:55], v[12:13], v[52:53] op_sel_hi:[0,1] neg_hi:[0,1]
	v_pk_mul_f32 v[52:53], v[54:55], v[116:117]
	v_pk_mul_f32 v[54:55], v[54:55], v[114:115]
	v_pk_fma_f32 v[52:53], v[74:75], v[114:115], v[52:53]
	v_pk_fma_f32 v[54:55], v[74:75], v[116:117], v[54:55] neg_lo:[0,0,1] neg_hi:[0,0,1]
	v_pk_mov_b32 v[70:71], v[72:73], v[58:59] op_sel:[1,0]
	v_pk_add_f32 v[74:75], v[54:55], v[52:53] op_sel:[0,1] op_sel_hi:[1,0] neg_lo:[0,1]
	v_pk_add_f32 v[76:77], v[54:55], v[52:53] op_sel:[0,1] op_sel_hi:[1,0]
	v_pk_add_f32 v[52:53], v[52:53], v[54:55] op_sel:[1,0] op_sel_hi:[0,1] neg_lo:[0,1] neg_hi:[0,1]
	v_pk_mul_f32 v[74:75], v[74:75], 0.5 op_sel_hi:[1,0]
	v_mov_b32_e32 v77, v53
	v_mul_f32_e32 v6, v58, v74
	v_pk_fma_f32 v[112:113], v[56:57], v[74:75], v[6:7] op_sel_hi:[1,1,0] neg_lo:[1,0,0] neg_hi:[1,0,0]
	v_mul_f32_e32 v6, v58, v75
	v_pk_fma_f32 v[70:71], v[70:71], v[74:75], v[6:7] op_sel_hi:[1,1,0]
	v_pk_add_f32 v[54:55], v[34:35], v[110:111]
	v_mov_b32_e32 v112, v70
	v_pk_fma_f32 v[52:53], v[76:77], 0.5, v[70:71] op_sel_hi:[1,0,1] neg_lo:[0,0,1] neg_hi:[0,0,1]
	v_pk_fma_f32 v[86:87], v[76:77], 0.5, v[112:113] op_sel_hi:[1,0,1]
	v_sub_f32_e32 v12, v35, v111
	v_mov_b32_e32 v53, v87
	v_pk_mul_f32 v[78:79], v[52:53], s[46:47] op_sel_hi:[1,0]
	v_mul_f32_e32 v52, 0xbe47c5c2, v83
	v_mov_b32_e32 v53, v34
	v_pk_mov_b32 v[34:35], v[118:119], v[110:111] op_sel:[1,0]
	v_mul_f32_e32 v18, 0.5, v55
	v_pk_add_f32 v[34:35], v[52:53], v[34:35] neg_lo:[0,1] neg_hi:[0,1]
	v_mov_b32_e32 v71, v58
	v_pk_mul_f32 v[52:53], v[34:35], v[18:19]
	v_mov_b32_e32 v70, v34
	v_pk_fma_f32 v[56:57], v[56:57], v[52:53], v[52:53] op_sel:[0,1,0] op_sel_hi:[1,0,1]
	v_mov_b32_e32 v52, v53
	v_mov_b32_e32 v53, v18
	v_mul_f32_e32 v6, 0.5, v54
	v_pk_mul_f32 v[52:53], v[70:71], v[52:53]
	v_cvt_f32_f16_e32 v70, v46
	v_cvt_f32_f16_e32 v71, v47
	v_cvt_f32_f16_sdwa v47, v47 dst_sel:DWORD dst_unused:UNUSED_PAD src0_sel:WORD_1
	v_cvt_f32_f16_sdwa v46, v46 dst_sel:DWORD dst_unused:UNUSED_PAD src0_sel:WORD_1
	v_pk_fma_f32 v[74:75], v[76:77], 0.5, v[112:113] op_sel_hi:[1,0,1] neg_lo:[1,0,0] neg_hi:[1,0,0]
	v_mul_f32_e32 v12, 0.5, v12
	v_pk_add_f32 v[76:77], v[6:7], v[56:57]
	v_pk_add_f32 v[52:53], v[52:53], v[52:53] op_sel:[0,1] op_sel_hi:[0,1] neg_lo:[0,1] neg_hi:[0,1]
	v_fma_f32 v77, v54, 0.5, -v56
	v_pk_add_f32 v[54:55], v[12:13], v[52:53] op_sel_hi:[0,1] neg_hi:[0,1]
	v_pk_mul_f32 v[52:53], v[54:55], v[46:47]
	v_pk_mul_f32 v[54:55], v[54:55], v[70:71]
	v_pk_fma_f32 v[56:57], v[76:77], v[70:71], v[52:53] neg_lo:[0,0,1] neg_hi:[0,0,1]
	v_pk_fma_f32 v[52:53], v[76:77], v[70:71], v[52:53]
	v_pk_fma_f32 v[70:71], v[76:77], v[46:47], v[54:55]
	v_pk_fma_f32 v[46:47], v[76:77], v[46:47], v[54:55] neg_lo:[0,0,1] neg_hi:[0,0,1]
	v_pk_add_f32 v[54:55], v[56:57], v[52:53] op_sel:[0,1] op_sel_hi:[1,0]
	v_pk_add_f32 v[76:77], v[70:71], v[46:47] op_sel_hi:[0,1] neg_lo:[0,1] neg_hi:[0,1]
	v_pk_add_f32 v[52:53], v[56:57], v[52:53] op_sel_hi:[0,1] neg_lo:[0,1] neg_hi:[0,1]
	v_pk_add_f32 v[46:47], v[70:71], v[46:47] op_sel:[0,1] op_sel_hi:[1,0]
	v_mov_b32_e32 v55, v77
	v_mov_b32_e32 v47, v53
	v_pk_mul_f32 v[46:47], v[46:47], 0.5 op_sel_hi:[1,0]
	s_mov_b32 s25, s27
	v_pk_mul_f32 v[52:53], v[58:59], v[46:47] op_sel:[0,1] op_sel_hi:[0,0]
	v_pk_fma_f32 v[56:57], v[34:35], v[46:47], v[52:53] op_sel_hi:[0,1,1]
	v_pk_fma_f32 v[46:47], v[34:35], v[46:47], v[52:53] op_sel_hi:[0,1,1] neg_hi:[0,0,1]
	s_nop 0
	v_pk_fma_f32 v[52:53], v[54:55], 0.5, v[56:57] op_sel_hi:[1,0,1] neg_lo:[0,0,1] neg_hi:[0,0,1]
	v_pk_fma_f32 v[34:35], v[54:55], 0.5, v[46:47] op_sel_hi:[1,0,1]
	s_mov_b32 s66, s27
	v_mov_b32_e32 v53, v35
	v_pk_mul_f32 v[136:137], v[52:53], s[46:47] op_sel_hi:[1,0]
	v_pk_fma_f32 v[52:53], v[54:55], 0.5, v[46:47] op_sel_hi:[1,0,1] neg_lo:[1,0,0] neg_hi:[1,0,0]
	s_mov_b32 s67, s24
	v_pk_mul_f32 v[46:47], v[82:83], s[24:25] op_sel_hi:[0,1]
	v_pk_add_f32 v[54:55], v[108:109], v[40:41]
	v_pk_add_f32 v[40:41], v[40:41], v[108:109] neg_lo:[0,1] neg_hi:[0,1]
	v_pk_fma_f32 v[108:109], v[4:5], s[66:67], v[46:47] op_sel_hi:[0,1,1] neg_lo:[0,0,1] neg_hi:[0,0,1]
	v_mul_f32_e32 v12, 0.5, v41
	v_pk_fma_f32 v[70:71], v[4:5], s[66:67], v[46:47] op_sel_hi:[0,1,1]
	v_mov_b32_e32 v41, v55
	v_mov_b32_e32 v56, v108
	v_mov_b32_e32 v57, v71
	v_pk_mul_f32 v[40:41], v[40:41], s[44:45]
	v_mul_f32_e32 v6, 0.5, v54
	v_pk_mul_f32 v[54:55], v[56:57], v[40:41] op_sel:[0,1] op_sel_hi:[1,0]
	v_cvt_f32_f16_sdwa v76, v38 dst_sel:DWORD dst_unused:UNUSED_PAD src0_sel:WORD_1
	v_cvt_f32_f16_e32 v77, v39
	v_cvt_f32_f16_sdwa v39, v39 dst_sel:DWORD dst_unused:UNUSED_PAD src0_sel:WORD_1
	v_cvt_f32_f16_e32 v38, v38
	v_pk_mul_f32 v[40:41], v[56:57], v[40:41]
	v_pk_add_f32 v[54:55], v[54:55], v[54:55] op_sel:[0,1] op_sel_hi:[0,1]
	v_pk_add_f32 v[112:113], v[6:7], v[54:55] op_sel_hi:[0,1] neg_hi:[0,1]
	s_nop 0
	v_pk_add_f32 v[40:41], v[40:41], v[40:41] op_sel:[0,1] op_sel_hi:[0,1] neg_lo:[0,1] neg_hi:[0,1]
	v_pk_add_f32 v[54:55], v[12:13], v[40:41] op_sel_hi:[0,1] neg_hi:[0,1]
	v_pk_mul_f32 v[40:41], v[54:55], v[38:39]
	v_pk_mul_f32 v[54:55], v[54:55], v[76:77]
	v_pk_fma_f32 v[40:41], v[112:113], v[76:77], v[40:41]
	v_pk_fma_f32 v[38:39], v[112:113], v[38:39], v[54:55] neg_lo:[0,0,1] neg_hi:[0,0,1]
	v_pk_mov_b32 v[110:111], v[70:71], v[108:109] op_sel:[1,0]
	v_pk_add_f32 v[54:55], v[38:39], v[40:41] op_sel:[0,1] op_sel_hi:[1,0] neg_lo:[0,1]
	v_pk_add_f32 v[76:77], v[38:39], v[40:41] op_sel:[0,1] op_sel_hi:[1,0]
	v_pk_add_f32 v[38:39], v[40:41], v[38:39] op_sel:[1,0] op_sel_hi:[0,1] neg_lo:[0,1] neg_hi:[0,1]
	v_pk_mul_f32 v[54:55], v[54:55], 0.5 op_sel_hi:[1,0]
	v_mov_b32_e32 v77, v39
	v_mul_f32_e32 v4, v108, v54
	v_pk_fma_f32 v[112:113], v[56:57], v[54:55], v[4:5] op_sel_hi:[1,1,0] neg_lo:[1,0,0] neg_hi:[1,0,0]
	v_mul_f32_e32 v4, v108, v55
	v_pk_fma_f32 v[54:55], v[110:111], v[54:55], v[4:5] op_sel_hi:[1,1,0]
	v_sub_f32_e32 v6, v45, v105
	v_mov_b32_e32 v112, v54
	v_pk_fma_f32 v[40:41], v[76:77], 0.5, v[54:55] op_sel_hi:[1,0,1] neg_lo:[0,0,1] neg_hi:[0,0,1]
	v_pk_fma_f32 v[38:39], v[76:77], 0.5, v[112:113] op_sel_hi:[1,0,1]
	v_pk_add_f32 v[54:55], v[104:105], v[44:45]
	v_mov_b32_e32 v41, v39
	v_pk_mul_f32 v[130:131], v[40:41], s[46:47] op_sel_hi:[1,0]
	v_mul_f32_e32 v40, 0xbf54db31, v83
	v_mov_b32_e32 v41, v44
	v_pk_mov_b32 v[44:45], v[46:47], v[104:105] op_sel:[1,0]
	v_mul_f32_e32 v18, 0.5, v55
	v_pk_add_f32 v[40:41], v[40:41], v[44:45] neg_lo:[0,1] neg_hi:[0,1]
	v_mov_b32_e32 v105, v108
	v_pk_mul_f32 v[44:45], v[40:41], v[18:19]
	v_mov_b32_e32 v104, v40
	v_pk_fma_f32 v[56:57], v[56:57], v[44:45], v[44:45] op_sel:[0,1,0] op_sel_hi:[1,0,1]
	v_mov_b32_e32 v44, v45
	v_mov_b32_e32 v45, v18
	v_mul_f32_e32 v4, 0.5, v54
	v_pk_mul_f32 v[44:45], v[104:105], v[44:45]
	v_cvt_f32_f16_e32 v104, v26
	v_cvt_f32_f16_e32 v105, v27
	v_cvt_f32_f16_sdwa v27, v27 dst_sel:DWORD dst_unused:UNUSED_PAD src0_sel:WORD_1
	v_cvt_f32_f16_sdwa v26, v26 dst_sel:DWORD dst_unused:UNUSED_PAD src0_sel:WORD_1
	v_mul_f32_e32 v6, 0.5, v6
	v_pk_add_f32 v[110:111], v[4:5], v[56:57]
	v_pk_add_f32 v[44:45], v[44:45], v[44:45] op_sel:[0,1] op_sel_hi:[0,1] neg_lo:[0,1] neg_hi:[0,1]
	v_fma_f32 v111, v54, 0.5, -v56
	v_pk_add_f32 v[54:55], v[6:7], v[44:45] op_sel_hi:[0,1] neg_hi:[0,1]
	v_pk_mul_f32 v[44:45], v[54:55], v[26:27]
	v_pk_mul_f32 v[54:55], v[54:55], v[104:105]
	v_pk_fma_f32 v[56:57], v[110:111], v[104:105], v[44:45] neg_lo:[0,0,1] neg_hi:[0,0,1]
	v_pk_fma_f32 v[44:45], v[110:111], v[104:105], v[44:45]
	v_pk_fma_f32 v[104:105], v[110:111], v[26:27], v[54:55]
	v_pk_fma_f32 v[26:27], v[110:111], v[26:27], v[54:55] neg_lo:[0,0,1] neg_hi:[0,0,1]
	v_pk_add_f32 v[54:55], v[56:57], v[44:45] op_sel:[0,1] op_sel_hi:[1,0]
	v_pk_add_f32 v[110:111], v[104:105], v[26:27] op_sel_hi:[0,1] neg_lo:[0,1] neg_hi:[0,1]
	v_pk_add_f32 v[44:45], v[56:57], v[44:45] op_sel_hi:[0,1] neg_lo:[0,1] neg_hi:[0,1]
	v_pk_add_f32 v[26:27], v[104:105], v[26:27] op_sel:[0,1] op_sel_hi:[1,0]
	v_mov_b32_e32 v55, v111
	v_mov_b32_e32 v27, v45
	v_pk_mul_f32 v[26:27], v[26:27], 0.5 op_sel_hi:[1,0]
	v_mov_b32_e32 v47, v102
	v_pk_mul_f32 v[44:45], v[108:109], v[26:27] op_sel:[0,1] op_sel_hi:[0,0]
	v_pk_fma_f32 v[56:57], v[40:41], v[26:27], v[44:45] op_sel_hi:[0,1,1]
	v_pk_fma_f32 v[40:41], v[40:41], v[26:27], v[44:45] op_sel_hi:[0,1,1] neg_hi:[0,0,1]
	v_pk_fma_f32 v[44:45], v[54:55], 0.5, v[56:57] op_sel_hi:[1,0,1] neg_lo:[0,0,1] neg_hi:[0,0,1]
	v_pk_fma_f32 v[26:27], v[54:55], 0.5, v[40:41] op_sel_hi:[1,0,1]
	v_pk_fma_f32 v[56:57], v[54:55], 0.5, v[40:41] op_sel_hi:[1,0,1] neg_lo:[1,0,0] neg_hi:[1,0,0]
	v_pk_add_f32 v[40:41], v[106:107], v[42:43]
	v_pk_add_f32 v[42:43], v[42:43], v[106:107] neg_lo:[0,1] neg_hi:[0,1]
	v_mov_b32_e32 v45, v27
	v_mul_f32_e32 v6, 0.5, v43
	v_mov_b32_e32 v43, v41
	v_pk_mul_f32 v[120:121], v[44:45], s[46:47] op_sel_hi:[1,0]
	v_mul_f32_e32 v4, 0.5, v40
	v_pk_mov_b32 v[44:45], v[108:109], v[70:71] op_sel:[1,0]
	v_pk_mul_f32 v[40:41], v[42:43], s[44:45]
	v_cvt_f32_f16_sdwa v54, v20 dst_sel:DWORD dst_unused:UNUSED_PAD src0_sel:WORD_1
	v_pk_mul_f32 v[42:43], v[44:45], v[40:41] op_sel:[0,1] op_sel_hi:[1,0]
	v_cvt_f32_f16_e32 v55, v21
	v_cvt_f32_f16_sdwa v21, v21 dst_sel:DWORD dst_unused:UNUSED_PAD src0_sel:WORD_1
	v_cvt_f32_f16_e32 v20, v20
	v_pk_mul_f32 v[40:41], v[44:45], v[40:41]
	v_pk_add_f32 v[42:43], v[42:43], v[42:43] op_sel:[0,1] op_sel_hi:[0,1]
	v_pk_add_f32 v[104:105], v[4:5], v[42:43] op_sel_hi:[0,1] neg_hi:[0,1]
	s_nop 0
	v_pk_add_f32 v[40:41], v[40:41], v[40:41] op_sel:[0,1] op_sel_hi:[0,1] neg_lo:[0,1] neg_hi:[0,1]
	v_pk_add_f32 v[42:43], v[6:7], v[40:41] op_sel_hi:[0,1] neg_hi:[0,1]
	v_pk_mul_f32 v[40:41], v[42:43], v[20:21]
	v_pk_mul_f32 v[42:43], v[42:43], v[54:55]
	v_pk_fma_f32 v[40:41], v[104:105], v[54:55], v[40:41]
	v_pk_fma_f32 v[20:21], v[104:105], v[20:21], v[42:43] neg_lo:[0,0,1] neg_hi:[0,0,1]
	v_mov_b32_e32 v71, v109
	v_pk_add_f32 v[42:43], v[20:21], v[40:41] op_sel:[0,1] op_sel_hi:[1,0] neg_lo:[0,1]
	v_pk_add_f32 v[54:55], v[20:21], v[40:41] op_sel:[0,1] op_sel_hi:[1,0]
	v_pk_add_f32 v[20:21], v[40:41], v[20:21] op_sel:[1,0] op_sel_hi:[0,1] neg_lo:[0,1] neg_hi:[0,1]
	v_pk_mul_f32 v[42:43], v[42:43], 0.5 op_sel_hi:[1,0]
	v_mov_b32_e32 v55, v21
	v_mul_f32_e32 v4, v109, v42
	v_pk_fma_f32 v[104:105], v[44:45], v[42:43], v[4:5] op_sel_hi:[1,1,0] neg_lo:[1,0,0] neg_hi:[1,0,0]
	v_mul_f32_e32 v4, v109, v43
	v_pk_fma_f32 v[42:43], v[70:71], v[42:43], v[4:5] op_sel_hi:[1,1,0]
	v_sub_f32_e32 v6, v23, v103
	v_mov_b32_e32 v104, v42
	v_pk_fma_f32 v[40:41], v[54:55], 0.5, v[42:43] op_sel_hi:[1,0,1] neg_lo:[0,0,1] neg_hi:[0,0,1]
	v_pk_fma_f32 v[20:21], v[54:55], 0.5, v[104:105] op_sel_hi:[1,0,1]
	v_pk_add_f32 v[42:43], v[102:103], v[22:23]
	v_mov_b32_e32 v41, v21
	v_pk_mul_f32 v[128:129], v[40:41], s[46:47] op_sel_hi:[1,0]
	v_mul_f32_e32 v40, 0xbf0e39da, v83
	v_mov_b32_e32 v41, v22
	v_mul_f32_e32 v18, 0.5, v43
	v_pk_add_f32 v[22:23], v[40:41], v[46:47] neg_lo:[0,1] neg_hi:[0,1]
	v_mov_b32_e32 v47, v109
	v_pk_mul_f32 v[40:41], v[22:23], v[18:19]
	v_mov_b32_e32 v46, v22
	v_pk_fma_f32 v[44:45], v[44:45], v[40:41], v[40:41] op_sel:[0,1,0] op_sel_hi:[1,0,1]
	v_mov_b32_e32 v40, v41
	v_mov_b32_e32 v41, v18
	v_mul_f32_e32 v4, 0.5, v42
	v_pk_mul_f32 v[40:41], v[46:47], v[40:41]
	v_cvt_f32_f16_e32 v46, v10
	v_cvt_f32_f16_e32 v47, v11
	v_cvt_f32_f16_sdwa v11, v11 dst_sel:DWORD dst_unused:UNUSED_PAD src0_sel:WORD_1
	v_cvt_f32_f16_sdwa v10, v10 dst_sel:DWORD dst_unused:UNUSED_PAD src0_sel:WORD_1
	v_pk_fma_f32 v[70:71], v[54:55], 0.5, v[104:105] op_sel_hi:[1,0,1] neg_lo:[1,0,0] neg_hi:[1,0,0]
	v_mul_f32_e32 v6, 0.5, v6
	v_pk_add_f32 v[54:55], v[4:5], v[44:45]
	v_pk_add_f32 v[40:41], v[40:41], v[40:41] op_sel:[0,1] op_sel_hi:[0,1] neg_lo:[0,1] neg_hi:[0,1]
	v_fma_f32 v55, v42, 0.5, -v44
	v_pk_add_f32 v[42:43], v[6:7], v[40:41] op_sel_hi:[0,1] neg_hi:[0,1]
	v_pk_mul_f32 v[40:41], v[42:43], v[10:11]
	v_pk_mul_f32 v[42:43], v[42:43], v[46:47]
	v_pk_fma_f32 v[44:45], v[54:55], v[46:47], v[40:41] neg_lo:[0,0,1] neg_hi:[0,0,1]
	v_pk_fma_f32 v[40:41], v[54:55], v[46:47], v[40:41]
	v_pk_fma_f32 v[46:47], v[54:55], v[10:11], v[42:43]
	v_pk_fma_f32 v[10:11], v[54:55], v[10:11], v[42:43] neg_lo:[0,0,1] neg_hi:[0,0,1]
	v_pk_add_f32 v[42:43], v[44:45], v[40:41] op_sel:[0,1] op_sel_hi:[1,0]
	v_pk_add_f32 v[54:55], v[46:47], v[10:11] op_sel_hi:[0,1] neg_lo:[0,1] neg_hi:[0,1]
	v_pk_add_f32 v[40:41], v[44:45], v[40:41] op_sel_hi:[0,1] neg_lo:[0,1] neg_hi:[0,1]
	v_pk_add_f32 v[10:11], v[46:47], v[10:11] op_sel:[0,1] op_sel_hi:[1,0]
	v_mov_b32_e32 v43, v55
	v_mov_b32_e32 v11, v41
	v_pk_mul_f32 v[10:11], v[10:11], 0.5 op_sel_hi:[1,0]
	v_mov_b32_e32 v119, v98
	v_pk_mul_f32 v[40:41], v[108:109], v[10:11] op_sel:[1,1] op_sel_hi:[1,0]
	v_pk_fma_f32 v[76:77], v[76:77], 0.5, v[112:113] op_sel_hi:[1,0,1] neg_lo:[1,0,0] neg_hi:[1,0,0]
	v_pk_fma_f32 v[44:45], v[22:23], v[10:11], v[40:41] op_sel_hi:[0,1,1]
	v_pk_fma_f32 v[10:11], v[22:23], v[10:11], v[40:41] op_sel_hi:[0,1,1] neg_hi:[0,0,1]
	v_pk_fma_f32 v[22:23], v[42:43], 0.5, v[44:45] op_sel_hi:[1,0,1] neg_lo:[0,0,1] neg_hi:[0,0,1]
	v_pk_fma_f32 v[40:41], v[42:43], 0.5, v[10:11] op_sel_hi:[1,0,1]
	v_pk_fma_f32 v[54:55], v[42:43], 0.5, v[10:11] op_sel_hi:[1,0,1] neg_lo:[1,0,0] neg_hi:[1,0,0]
	v_pk_add_f32 v[10:11], v[100:101], v[14:15]
	v_pk_add_f32 v[14:15], v[14:15], v[100:101] neg_lo:[0,1] neg_hi:[0,1]
	v_mov_b32_e32 v23, v41
	v_mul_f32_e32 v6, 0.5, v15
	v_mov_b32_e32 v15, v11
	v_pk_mul_f32 v[150:151], v[22:23], s[46:47] op_sel_hi:[1,0]
	v_mul_f32_e32 v4, 0.5, v10
	v_pk_mov_b32 v[22:23], v[58:59], v[72:73] op_sel:[1,0]
	v_pk_mul_f32 v[10:11], v[14:15], s[44:45]
	v_cvt_f32_f16_sdwa v42, v8 dst_sel:DWORD dst_unused:UNUSED_PAD src0_sel:WORD_1
	v_pk_mul_f32 v[14:15], v[22:23], v[10:11] op_sel:[0,1] op_sel_hi:[1,0]
	v_cvt_f32_f16_e32 v43, v9
	v_cvt_f32_f16_sdwa v9, v9 dst_sel:DWORD dst_unused:UNUSED_PAD src0_sel:WORD_1
	v_cvt_f32_f16_e32 v8, v8
	v_pk_mul_f32 v[10:11], v[22:23], v[10:11]
	v_pk_add_f32 v[14:15], v[14:15], v[14:15] op_sel:[0,1] op_sel_hi:[0,1]
	v_pk_add_f32 v[44:45], v[4:5], v[14:15] op_sel_hi:[0,1] neg_hi:[0,1]
	s_nop 0
	v_pk_add_f32 v[10:11], v[10:11], v[10:11] op_sel:[0,1] op_sel_hi:[0,1] neg_lo:[0,1] neg_hi:[0,1]
	v_pk_add_f32 v[14:15], v[6:7], v[10:11] op_sel_hi:[0,1] neg_hi:[0,1]
	v_pk_mul_f32 v[10:11], v[14:15], v[8:9]
	v_pk_mul_f32 v[14:15], v[14:15], v[42:43]
	v_pk_fma_f32 v[10:11], v[44:45], v[42:43], v[10:11]
	v_pk_fma_f32 v[8:9], v[44:45], v[8:9], v[14:15] neg_lo:[0,0,1] neg_hi:[0,0,1]
	v_mov_b32_e32 v73, v59
	v_pk_add_f32 v[14:15], v[8:9], v[10:11] op_sel:[0,1] op_sel_hi:[1,0] neg_lo:[0,1]
	v_pk_add_f32 v[42:43], v[8:9], v[10:11] op_sel:[0,1] op_sel_hi:[1,0]
	v_pk_add_f32 v[8:9], v[10:11], v[8:9] op_sel:[1,0] op_sel_hi:[0,1] neg_lo:[0,1] neg_hi:[0,1]
	v_pk_mul_f32 v[14:15], v[14:15], 0.5 op_sel_hi:[1,0]
	v_mov_b32_e32 v43, v9
	v_mul_f32_e32 v4, v59, v14
	v_pk_fma_f32 v[44:45], v[22:23], v[14:15], v[4:5] op_sel_hi:[1,1,0] neg_lo:[1,0,0] neg_hi:[1,0,0]
	v_mul_f32_e32 v4, v59, v15
	v_pk_fma_f32 v[14:15], v[72:73], v[14:15], v[4:5] op_sel_hi:[1,1,0]
	v_sub_f32_e32 v6, v37, v99
	v_mov_b32_e32 v44, v14
	v_pk_fma_f32 v[8:9], v[42:43], 0.5, v[14:15] op_sel_hi:[1,0,1] neg_lo:[0,0,1] neg_hi:[0,0,1]
	v_pk_fma_f32 v[10:11], v[42:43], 0.5, v[44:45] op_sel_hi:[1,0,1]
	v_pk_add_f32 v[14:15], v[98:99], v[36:37]
	v_mov_b32_e32 v9, v11
	v_pk_mul_f32 v[168:169], v[8:9], s[46:47] op_sel_hi:[1,0]
	v_mul_f32_e32 v8, 0xbf7b14be, v83
	v_mov_b32_e32 v9, v36
	v_mul_f32_e32 v18, 0.5, v15
	v_pk_add_f32 v[8:9], v[8:9], v[118:119] neg_lo:[0,1] neg_hi:[0,1]
	v_pk_fma_f32 v[72:73], v[42:43], 0.5, v[44:45] op_sel_hi:[1,0,1] neg_lo:[1,0,0] neg_hi:[1,0,0]
	v_pk_mul_f32 v[36:37], v[8:9], v[18:19]
	v_mov_b32_e32 v42, v8
	v_pk_fma_f32 v[22:23], v[22:23], v[36:37], v[36:37] op_sel:[0,1,0] op_sel_hi:[1,0,1]
	v_mov_b32_e32 v43, v59
	v_mov_b32_e32 v36, v37
	v_mov_b32_e32 v37, v18
	v_mul_f32_e32 v4, 0.5, v14
	v_pk_mul_f32 v[36:37], v[42:43], v[36:37]
	v_cvt_f32_f16_e32 v44, v2
	v_cvt_f32_f16_e32 v45, v3
	v_cvt_f32_f16_sdwa v3, v3 dst_sel:DWORD dst_unused:UNUSED_PAD src0_sel:WORD_1
	v_cvt_f32_f16_sdwa v2, v2 dst_sel:DWORD dst_unused:UNUSED_PAD src0_sel:WORD_1
	v_mul_f32_e32 v6, 0.5, v6
	v_pk_add_f32 v[46:47], v[4:5], v[22:23]
	v_fma_f32 v4, v14, 0.5, -v22
	v_pk_add_f32 v[22:23], v[36:37], v[36:37] op_sel:[0,1] op_sel_hi:[0,1] neg_lo:[0,1] neg_hi:[0,1]
	v_pk_add_f32 v[36:37], v[6:7], v[22:23] op_sel_hi:[0,1] neg_hi:[0,1]
	v_mov_b32_e32 v14, v46
	v_mov_b32_e32 v15, v4
	v_pk_mul_f32 v[22:23], v[4:5], v[44:45] op_sel_hi:[0,1]
	v_pk_mul_f32 v[82:83], v[36:37], v[2:3]
	v_pk_mul_f32 v[46:47], v[46:47], v[2:3]
	v_pk_mul_f32 v[36:37], v[36:37], v[44:45]
	v_pk_fma_f32 v[98:99], v[14:15], v[44:45], v[82:83] neg_lo:[0,0,1] neg_hi:[0,0,1]
	v_pk_fma_f32 v[2:3], v[14:15], v[2:3], v[36:37] neg_lo:[0,0,1] neg_hi:[0,0,1]
	v_add_f32_e32 v4, v23, v83
	v_add_f32_e32 v6, v46, v36
	v_pk_add_f32 v[22:23], v[6:7], v[2:3] op_sel_hi:[0,1] neg_lo:[0,1] neg_hi:[0,1]
	v_pk_add_f32 v[36:37], v[98:99], v[4:5] op_sel_hi:[1,0] neg_lo:[0,1] neg_hi:[0,1]
	v_pk_add_f32 v[2:3], v[6:7], v[2:3] op_sel_hi:[0,1]
	v_mov_b32_e32 v37, v3
	v_pk_mul_f32 v[2:3], v[36:37], 0.5 op_sel_hi:[1,0]
	v_pk_add_f32 v[14:15], v[98:99], v[4:5] op_sel_hi:[1,0]
	v_mul_f32_e32 v4, v59, v3
	v_pk_fma_f32 v[36:37], v[42:43], v[2:3], v[4:5] op_sel_hi:[1,1,0] neg_lo:[0,0,1] neg_hi:[0,0,1]
	v_pk_mov_b32 v[42:43], v[58:59], v[8:9] op_sel:[1,0]
	v_mul_f32_e32 v4, v8, v3
	v_pk_fma_f32 v[2:3], v[42:43], v[2:3], v[4:5] op_sel_hi:[1,1,0]
	v_mov_b32_e32 v15, v23
	v_pk_fma_f32 v[8:9], v[14:15], 0.5, v[2:3] op_sel_hi:[1,0,1] neg_lo:[0,0,1] neg_hi:[0,0,1]
	v_pk_fma_f32 v[42:43], v[14:15], 0.5, v[36:37] op_sel_hi:[1,0,0]
	v_pk_fma_f32 v[2:3], v[14:15], 0.5, v[2:3] op_sel_hi:[1,0,1]
	v_mov_b32_e32 v9, v43
	v_pk_fma_f32 v[58:59], v[22:23], 0.5, v[36:37] op_sel_hi:[1,0,0] neg_lo:[1,0,0] neg_hi:[1,0,0]
	v_pk_mul_f32 v[144:145], v[8:9], s[46:47] op_sel_hi:[1,0]
	v_mov_b32_e32 v58, v2
	v_mov_b32_e32 v72, v10
	v_mov_b32_e32 v54, v40
	v_mov_b32_e32 v70, v20
	v_mov_b32_e32 v56, v26
	v_mov_b32_e32 v76, v38
	v_mov_b32_e32 v52, v34
	v_mov_b32_e32 v74, v86
	v_mov_b32_e32 v48, v84
	v_mov_b32_e32 v50, v60
	v_mov_b32_e32 v28, v66
	v_mov_b32_e32 v32, v96
	v_mov_b32_e32 v12, v88
	v_mov_b32_e32 v16, v92
	v_mov_b32_e32 v4, v138
	v_mov_b32_e32 v6, v122
.LBB0_536:
	s_andn2_saveexec_b64 s[0:1], s[0:1]
	s_cbranch_execz .LBB0_538
	v_pk_add_f32 v[4:5], v[98:99], v[196:197]
	v_pk_add_f32 v[6:7], v[98:99], v[196:197] neg_lo:[0,1] neg_hi:[0,1]
	v_mul_f32_e32 v4, 0.5, v4
	v_mul_f32_e32 v12, 0.5, v7
	v_mov_b32_e32 v7, v5
	v_pk_mul_f32 v[6:7], v[6:7], s[44:45]
	v_pk_mov_b32 v[16:17], v[198:199], v[160:161] op_sel:[1,0]
	v_pk_mul_f32 v[24:25], v[190:191], v[6:7] op_sel:[0,1] op_sel_hi:[1,0]
	v_pk_mul_f32 v[6:7], v[190:191], v[6:7]
	v_pk_add_f32 v[24:25], v[24:25], v[24:25] op_sel:[0,1] op_sel_hi:[0,1]
	v_pk_add_f32 v[28:29], v[4:5], v[24:25] op_sel_hi:[0,1] neg_hi:[0,1]
	v_pk_add_f32 v[4:5], v[6:7], v[6:7] op_sel:[0,1] op_sel_hi:[0,1] neg_lo:[0,1] neg_hi:[0,1]
	v_pk_add_f32 v[6:7], v[12:13], v[4:5] op_sel_hi:[0,1] neg_hi:[0,1]
	v_pk_mul_f32 v[4:5], v[6:7], v[194:195]
	v_pk_mul_f32 v[6:7], v[6:7], v[192:193]
	v_pk_fma_f32 v[4:5], v[28:29], v[192:193], v[4:5]
	v_pk_fma_f32 v[6:7], v[28:29], v[194:195], v[6:7] neg_lo:[0,0,1] neg_hi:[0,0,1]
	s_mov_b32 s66, s19
	v_pk_add_f32 v[12:13], v[6:7], v[4:5] op_sel:[0,1] op_sel_hi:[1,0] neg_lo:[0,1]
	v_pk_add_f32 v[24:25], v[6:7], v[4:5] op_sel:[0,1] op_sel_hi:[1,0]
	v_pk_add_f32 v[4:5], v[4:5], v[6:7] op_sel:[1,0] op_sel_hi:[0,1] neg_lo:[0,1] neg_hi:[0,1]
	s_nop 0
	v_pk_mul_f32 v[12:13], v[12:13], 0.5 op_sel_hi:[1,0]
	v_mov_b32_e32 v25, v5
	v_mul_f32_e32 v28, v191, v13
	v_mul_f32_e32 v30, v160, v13
	v_pk_fma_f32 v[28:29], v[190:191], v[12:13], v[28:29] op_sel_hi:[1,1,0] neg_lo:[0,0,1] neg_hi:[0,0,1]
	v_pk_fma_f32 v[12:13], v[16:17], v[12:13], v[30:31] op_sel_hi:[1,1,0]
	v_mov_b32_e32 v7, v28
	v_mov_b32_e32 v6, v12
	v_pk_fma_f32 v[58:59], v[24:25], 0.5, v[12:13] op_sel_hi:[1,0,1] neg_lo:[0,0,1] neg_hi:[0,0,1]
	v_pk_fma_f32 v[98:99], v[24:25], 0.5, v[6:7] op_sel_hi:[1,0,1]
	v_pk_fma_f32 v[6:7], v[24:25], 0.5, v[12:13] op_sel_hi:[1,0,1]
	v_pk_fma_f32 v[160:161], v[4:5], 0.5, v[28:29] op_sel_hi:[1,0,0] neg_lo:[1,0,0] neg_hi:[1,0,0]
	v_pk_add_f32 v[4:5], v[100:101], v[188:189]
	v_pk_add_f32 v[12:13], v[100:101], v[188:189] neg_lo:[0,1] neg_hi:[0,1]
	v_mov_b32_e32 v24, v83
	v_mov_b32_e32 v25, v82
	v_mul_f32_e32 v16, 0.5, v13
	v_pk_add_f32 v[28:29], v[186:187], v[24:25] neg_lo:[0,1] neg_hi:[0,1]
	v_pk_add_f32 v[30:31], v[186:187], v[24:25]
	v_mov_b32_e32 v13, v5
	v_pk_mov_b32 v[32:33], v[28:29], v[30:31] op_sel:[1,0]
	v_pk_mul_f32 v[12:13], v[12:13], s[44:45]
	v_mul_f32_e32 v4, 0.5, v4
	v_pk_mul_f32 v[48:49], v[32:33], v[12:13] op_sel:[0,1] op_sel_hi:[1,0]
	v_pk_mul_f32 v[12:13], v[32:33], v[12:13]
	v_pk_add_f32 v[48:49], v[48:49], v[48:49] op_sel:[0,1] op_sel_hi:[0,1]
	v_pk_add_f32 v[50:51], v[4:5], v[48:49] op_sel_hi:[0,1] neg_hi:[0,1]
	v_pk_add_f32 v[4:5], v[12:13], v[12:13] op_sel:[0,1] op_sel_hi:[0,1] neg_lo:[0,1] neg_hi:[0,1]
	v_pk_add_f32 v[12:13], v[16:17], v[4:5] op_sel_hi:[0,1] neg_hi:[0,1]
	v_pk_mul_f32 v[4:5], v[12:13], v[184:185]
	v_pk_mul_f32 v[12:13], v[12:13], v[170:171]
	v_pk_fma_f32 v[4:5], v[50:51], v[170:171], v[4:5]
	v_pk_fma_f32 v[12:13], v[50:51], v[184:185], v[12:13] neg_lo:[0,0,1] neg_hi:[0,0,1]
	v_mov_b32_e32 v31, v29
	v_pk_add_f32 v[16:17], v[12:13], v[4:5] op_sel:[0,1] op_sel_hi:[1,0] neg_lo:[0,1]
	v_pk_add_f32 v[48:49], v[12:13], v[4:5] op_sel:[0,1] op_sel_hi:[1,0]
	v_pk_add_f32 v[12:13], v[4:5], v[12:13] op_sel:[1,0] op_sel_hi:[0,1] neg_lo:[0,1] neg_hi:[0,1]
	v_pk_mul_f32 v[16:17], v[16:17], 0.5 op_sel_hi:[1,0]
	v_mov_b32_e32 v49, v13
	v_mul_f32_e32 v28, v30, v17
	v_pk_fma_f32 v[32:33], v[32:33], v[16:17], v[28:29] op_sel_hi:[1,1,0] neg_lo:[0,0,1] neg_hi:[0,0,1]
	v_mul_f32_e32 v28, v29, v17
	v_pk_fma_f32 v[16:17], v[30:31], v[16:17], v[28:29] op_sel_hi:[1,1,0]
	v_mov_b32_e32 v5, v32
	v_mov_b32_e32 v4, v16
	v_pk_fma_f32 v[72:73], v[48:49], 0.5, v[16:17] op_sel_hi:[1,0,1] neg_lo:[0,0,1] neg_hi:[0,0,1]
	v_pk_fma_f32 v[100:101], v[48:49], 0.5, v[4:5] op_sel_hi:[1,0,1]
	v_pk_fma_f32 v[4:5], v[48:49], 0.5, v[16:17] op_sel_hi:[1,0,1]
	v_pk_fma_f32 v[170:171], v[12:13], 0.5, v[32:33] op_sel_hi:[1,0,0] neg_lo:[1,0,0] neg_hi:[1,0,0]
	v_pk_mul_f32 v[12:13], v[24:25], s[36:37]
	v_pk_add_f32 v[16:17], v[102:103], v[182:183]
	v_pk_add_f32 v[24:25], v[102:103], v[182:183] neg_lo:[0,1] neg_hi:[0,1]
	v_pk_add_f32 v[30:31], v[18:19], v[12:13] op_sel:[0,1] op_sel_hi:[0,1] neg_lo:[0,1] neg_hi:[0,1]
	v_mul_f32_e32 v28, 0.5, v25
	v_pk_add_f32 v[32:33], v[18:19], v[12:13] op_sel:[0,1] op_sel_hi:[0,1]
	v_mov_b32_e32 v25, v17
	v_mov_b32_e32 v48, v30
	v_mov_b32_e32 v49, v33
	v_pk_mul_f32 v[24:25], v[24:25], s[44:45]
	v_mul_f32_e32 v16, 0.5, v16
	v_pk_mul_f32 v[52:53], v[48:49], v[24:25] op_sel:[0,1] op_sel_hi:[1,0]
	v_pk_mul_f32 v[24:25], v[48:49], v[24:25]
	v_pk_add_f32 v[52:53], v[52:53], v[52:53] op_sel:[0,1] op_sel_hi:[0,1]
	v_pk_add_f32 v[54:55], v[16:17], v[52:53] op_sel_hi:[0,1] neg_hi:[0,1]
	v_pk_add_f32 v[16:17], v[24:25], v[24:25] op_sel:[0,1] op_sel_hi:[0,1] neg_lo:[0,1] neg_hi:[0,1]
	v_pk_add_f32 v[24:25], v[28:29], v[16:17] op_sel_hi:[0,1] neg_hi:[0,1]
	v_pk_mul_f32 v[16:17], v[24:25], v[180:181]
	v_pk_mul_f32 v[24:25], v[24:25], v[172:173]
	v_pk_fma_f32 v[16:17], v[54:55], v[172:173], v[16:17]
	v_pk_fma_f32 v[24:25], v[54:55], v[180:181], v[24:25] neg_lo:[0,0,1] neg_hi:[0,0,1]
	v_pk_mov_b32 v[50:51], v[32:33], v[30:31] op_sel:[1,0]
	v_pk_add_f32 v[28:29], v[24:25], v[16:17] op_sel:[0,1] op_sel_hi:[1,0] neg_lo:[0,1]
	v_pk_add_f32 v[52:53], v[24:25], v[16:17] op_sel:[0,1] op_sel_hi:[1,0]
	v_pk_add_f32 v[24:25], v[16:17], v[24:25] op_sel:[1,0] op_sel_hi:[0,1] neg_lo:[0,1] neg_hi:[0,1]
	v_pk_mul_f32 v[28:29], v[28:29], 0.5 op_sel_hi:[1,0]
	v_mov_b32_e32 v53, v25
	v_mul_f32_e32 v18, v33, v29
	v_pk_fma_f32 v[32:33], v[48:49], v[28:29], v[18:19] op_sel_hi:[1,1,0] neg_lo:[0,0,1] neg_hi:[0,0,1]
	v_mul_f32_e32 v18, v30, v29
	v_pk_fma_f32 v[28:29], v[50:51], v[28:29], v[18:19] op_sel_hi:[1,1,0]
	v_pk_fma_f32 v[172:173], v[24:25], 0.5, v[32:33] op_sel_hi:[1,0,0] neg_lo:[1,0,0] neg_hi:[1,0,0]
	v_pk_add_f32 v[24:25], v[106:107], v[176:177]
	v_mov_b32_e32 v50, v12
	v_mov_b32_e32 v51, v106
	v_pk_mov_b32 v[12:13], v[12:13], v[176:177] op_sel:[1,0]
	v_mul_f32_e32 v18, 0.5, v25
	v_pk_add_f32 v[12:13], v[50:51], v[12:13] neg_lo:[0,1] neg_hi:[0,1]
	v_mov_b32_e32 v16, v28
	v_mov_b32_e32 v17, v32
	v_pk_mul_f32 v[50:51], v[12:13], v[18:19]
	v_pk_fma_f32 v[54:55], v[52:53], 0.5, v[28:29] op_sel_hi:[1,0,1] neg_lo:[0,0,1] neg_hi:[0,0,1]
	v_pk_fma_f32 v[102:103], v[52:53], 0.5, v[16:17] op_sel_hi:[1,0,1]
	v_pk_fma_f32 v[16:17], v[52:53], 0.5, v[28:29] op_sel_hi:[1,0,1]
	v_mul_f32_e32 v28, 0.5, v24
	v_pk_fma_f32 v[48:49], v[48:49], v[50:51], v[50:51] op_sel:[0,1,0] op_sel_hi:[1,0,1]
	v_mov_b32_e32 v13, v30
	v_mov_b32_e32 v50, v51
	v_mov_b32_e32 v51, v18
	v_sub_f32_e32 v5, v107, v177
	v_pk_mul_f32 v[50:51], v[12:13], v[50:51]
	v_pk_add_f32 v[28:29], v[28:29], v[48:49]
	v_mul_f32_e32 v32, 0.5, v5
	v_fma_f32 v29, v24, 0.5, -v48
	v_pk_add_f32 v[24:25], v[50:51], v[50:51] op_sel:[0,1] op_sel_hi:[0,1] neg_lo:[0,1] neg_hi:[0,1]
	v_pk_add_f32 v[48:49], v[32:33], v[24:25] op_sel_hi:[0,1] neg_hi:[0,1]
	v_pk_mul_f32 v[24:25], v[48:49], v[178:179]
	v_pk_mul_f32 v[32:33], v[48:49], v[174:175]
	v_pk_fma_f32 v[24:25], v[28:29], v[174:175], v[24:25]
	v_pk_fma_f32 v[28:29], v[28:29], v[178:179], v[32:33] neg_lo:[0,0,1] neg_hi:[0,0,1]
	v_mov_b32_e32 v31, v12
	v_pk_add_f32 v[32:33], v[28:29], v[24:25] op_sel:[0,1] op_sel_hi:[1,0] neg_lo:[0,1]
	v_pk_add_f32 v[48:49], v[28:29], v[24:25] op_sel:[0,1] op_sel_hi:[1,0]
	v_pk_add_f32 v[24:25], v[24:25], v[28:29] op_sel:[1,0] op_sel_hi:[0,1] neg_lo:[0,1] neg_hi:[0,1]
	v_pk_mul_f32 v[32:33], v[32:33], 0.5 op_sel_hi:[1,0]
	v_mov_b32_e32 v49, v25
	v_mul_f32_e32 v18, v30, v33
	v_pk_fma_f32 v[50:51], v[12:13], v[32:33], v[18:19] op_sel_hi:[1,1,0] neg_lo:[0,0,1] neg_hi:[0,0,1]
	v_mul_f32_e32 v12, v12, v33
	v_pk_fma_f32 v[12:13], v[30:31], v[32:33], v[12:13] op_sel_hi:[1,1,0]
	v_mov_b32_e32 v29, v50
	v_mov_b32_e32 v28, v12
	s_mov_b32 s67, s16
	v_pk_fma_f32 v[106:107], v[48:49], 0.5, v[28:29] op_sel_hi:[1,0,1]
	v_pk_fma_f32 v[174:175], v[24:25], 0.5, v[50:51] op_sel_hi:[1,0,0] neg_lo:[1,0,0] neg_hi:[1,0,0]
	v_mov_b32_e32 v18, v83
	s_mov_b32 s17, s19
	v_pk_mul_f32 v[24:25], v[82:83], s[66:67] op_sel_hi:[0,1]
	v_pk_add_f32 v[28:29], v[104:105], v[162:163]
	v_pk_add_f32 v[30:31], v[104:105], v[162:163] neg_lo:[0,1] neg_hi:[0,1]
	v_pk_fma_f32 v[70:71], v[48:49], 0.5, v[12:13] op_sel_hi:[1,0,1] neg_lo:[0,0,1] neg_hi:[0,0,1]
	v_pk_fma_f32 v[12:13], v[48:49], 0.5, v[12:13] op_sel_hi:[1,0,1]
	v_mul_f32_e32 v32, 0.5, v31
	v_pk_fma_f32 v[48:49], v[18:19], s[16:17], v[24:25] op_sel_hi:[0,1,1] neg_lo:[0,0,1] neg_hi:[0,0,1]
	v_pk_fma_f32 v[50:51], v[18:19], s[16:17], v[24:25] op_sel_hi:[0,1,1]
	v_mov_b32_e32 v31, v29
	v_mov_b32_e32 v52, v48
	v_mov_b32_e32 v53, v51
	v_pk_mul_f32 v[30:31], v[30:31], s[44:45]
	v_mul_f32_e32 v28, 0.5, v28
	v_pk_mul_f32 v[62:63], v[52:53], v[30:31] op_sel:[0,1] op_sel_hi:[1,0]
	v_pk_mul_f32 v[30:31], v[52:53], v[30:31]
	v_pk_add_f32 v[62:63], v[62:63], v[62:63] op_sel:[0,1] op_sel_hi:[0,1]
	v_pk_add_f32 v[64:65], v[28:29], v[62:63] op_sel_hi:[0,1] neg_hi:[0,1]
	v_pk_add_f32 v[28:29], v[30:31], v[30:31] op_sel:[0,1] op_sel_hi:[0,1] neg_lo:[0,1] neg_hi:[0,1]
	v_pk_add_f32 v[30:31], v[32:33], v[28:29] op_sel_hi:[0,1] neg_hi:[0,1]
	v_pk_mul_f32 v[28:29], v[30:31], v[166:167]
	v_pk_mul_f32 v[30:31], v[30:31], v[164:165]
	v_pk_fma_f32 v[28:29], v[64:65], v[164:165], v[28:29]
	v_pk_fma_f32 v[30:31], v[64:65], v[166:167], v[30:31] neg_lo:[0,0,1] neg_hi:[0,0,1]
	v_pk_mov_b32 v[56:57], v[50:51], v[48:49] op_sel:[1,0]
	v_pk_add_f32 v[32:33], v[30:31], v[28:29] op_sel:[0,1] op_sel_hi:[1,0] neg_lo:[0,1]
	v_pk_add_f32 v[62:63], v[30:31], v[28:29] op_sel:[0,1] op_sel_hi:[1,0]
	v_pk_add_f32 v[28:29], v[28:29], v[30:31] op_sel:[1,0] op_sel_hi:[0,1] neg_lo:[0,1] neg_hi:[0,1]
	v_pk_mul_f32 v[32:33], v[32:33], 0.5 op_sel_hi:[1,0]
	v_mov_b32_e32 v63, v29
	v_mul_f32_e32 v18, v51, v33
	v_pk_fma_f32 v[52:53], v[52:53], v[32:33], v[18:19] op_sel_hi:[1,1,0] neg_lo:[0,0,1] neg_hi:[0,0,1]
	v_mul_f32_e32 v18, v48, v33
	v_pk_fma_f32 v[32:33], v[56:57], v[32:33], v[18:19] op_sel_hi:[1,1,0]
	v_mov_b32_e32 v31, v52
	v_mov_b32_e32 v30, v32
	v_pk_fma_f32 v[56:57], v[62:63], 0.5, v[32:33] op_sel_hi:[1,0,1] neg_lo:[0,0,1] neg_hi:[0,0,1]
	v_pk_fma_f32 v[82:83], v[62:63], 0.5, v[30:31] op_sel_hi:[1,0,1]
	v_pk_fma_f32 v[32:33], v[62:63], 0.5, v[32:33] op_sel_hi:[1,0,1]
	v_pk_fma_f32 v[104:105], v[28:29], 0.5, v[52:53] op_sel_hi:[1,0,0] neg_lo:[1,0,0] neg_hi:[1,0,0]
	v_pk_add_f32 v[28:29], v[108:109], v[152:153]
	v_mov_b32_e32 v159, v108
	v_pk_mov_b32 v[62:63], v[24:25], v[152:153] op_sel:[1,0]
	v_mul_f32_e32 v18, 0.5, v29
	v_pk_add_f32 v[62:63], v[158:159], v[62:63] neg_lo:[0,1] neg_hi:[0,1]
	v_sub_f32_e32 v5, v109, v153
	v_pk_mul_f32 v[64:65], v[62:63], v[18:19]
	v_mov_b32_e32 v63, v48
	v_pk_fma_f32 v[68:69], v[48:49], v[64:65], v[64:65] op_sel:[0,1,0] op_sel_hi:[1,0,1]
	v_mov_b32_e32 v64, v65
	v_mov_b32_e32 v65, v18
	v_pk_mul_f32 v[64:65], v[62:63], v[64:65]
	v_mul_f32_e32 v30, 0.5, v28
	v_mul_f32_e32 v52, 0.5, v5
	v_pk_add_f32 v[64:65], v[64:65], v[64:65] op_sel:[0,1] op_sel_hi:[0,1] neg_lo:[0,1] neg_hi:[0,1]
	v_pk_add_f32 v[30:31], v[30:31], v[68:69]
	v_fma_f32 v18, v28, 0.5, -v68
	v_pk_add_f32 v[68:69], v[52:53], v[64:65] op_sel_hi:[0,1] neg_hi:[0,1]
	v_mov_b32_e32 v28, v30
	v_mov_b32_e32 v29, v18
	v_pk_mul_f32 v[52:53], v[18:19], v[154:155] op_sel_hi:[0,1]
	v_pk_mul_f32 v[64:65], v[68:69], v[156:157]
	v_pk_mul_f32 v[30:31], v[30:31], v[156:157]
	v_pk_mul_f32 v[68:69], v[68:69], v[154:155]
	v_pk_fma_f32 v[74:75], v[28:29], v[154:155], v[64:65] neg_lo:[0,0,1] neg_hi:[0,0,1]
	v_pk_fma_f32 v[28:29], v[28:29], v[156:157], v[68:69] neg_lo:[0,0,1] neg_hi:[0,0,1]
	v_add_f32_e32 v18, v53, v65
	v_add_f32_e32 v30, v30, v68
	v_pk_add_f32 v[64:65], v[30:31], v[28:29] op_sel_hi:[0,1] neg_lo:[0,1] neg_hi:[0,1]
	v_pk_add_f32 v[68:69], v[74:75], v[18:19] op_sel_hi:[1,0] neg_lo:[0,1] neg_hi:[0,1]
	v_pk_add_f32 v[28:29], v[30:31], v[28:29] op_sel_hi:[0,1]
	v_mov_b32_e32 v69, v29
	v_pk_mul_f32 v[28:29], v[68:69], 0.5 op_sel_hi:[1,0]
	v_pk_add_f32 v[52:53], v[74:75], v[18:19] op_sel_hi:[1,0]
	v_mul_f32_e32 v18, v48, v29
	v_pk_fma_f32 v[30:31], v[62:63], v[28:29], v[18:19] op_sel_hi:[1,1,0] neg_lo:[0,0,1] neg_hi:[0,0,1]
	v_mov_b32_e32 v68, v48
	v_mov_b32_e32 v69, v62
	v_mul_f32_e32 v18, v62, v29
	v_pk_fma_f32 v[28:29], v[68:69], v[28:29], v[18:19] op_sel_hi:[1,1,0]
	v_mov_b32_e32 v53, v65
	v_mov_b32_e32 v62, v28
	v_mov_b32_e32 v63, v30
	v_pk_fma_f32 v[76:77], v[52:53], 0.5, v[28:29] op_sel_hi:[1,0,1] neg_lo:[0,0,1] neg_hi:[0,0,1]
	v_pk_fma_f32 v[108:109], v[52:53], 0.5, v[62:63] op_sel_hi:[1,0,1]
	v_pk_fma_f32 v[28:29], v[52:53], 0.5, v[28:29] op_sel_hi:[1,0,1]
	v_pk_fma_f32 v[152:153], v[64:65], 0.5, v[30:31] op_sel_hi:[1,0,0] neg_lo:[1,0,0] neg_hi:[1,0,0]
	v_pk_add_f32 v[30:31], v[134:135], v[110:111]
	v_pk_add_f32 v[52:53], v[110:111], v[134:135] neg_lo:[0,1] neg_hi:[0,1]
	v_mul_f32_e32 v18, 0.5, v30
	v_mul_f32_e32 v30, 0.5, v53
	v_mov_b32_e32 v53, v31
	v_pk_mov_b32 v[62:63], v[48:49], v[50:51] op_sel:[1,0]
	v_pk_mul_f32 v[52:53], v[52:53], s[44:45]
	v_mov_b32_e32 v51, v49
	v_pk_mul_f32 v[64:65], v[62:63], v[52:53] op_sel:[0,1] op_sel_hi:[1,0]
	v_pk_mul_f32 v[52:53], v[62:63], v[52:53]
	v_pk_add_f32 v[64:65], v[64:65], v[64:65] op_sel:[0,1] op_sel_hi:[0,1]
	v_pk_add_f32 v[68:69], v[18:19], v[64:65] op_sel_hi:[0,1] neg_hi:[0,1]
	v_pk_add_f32 v[52:53], v[52:53], v[52:53] op_sel:[0,1] op_sel_hi:[0,1] neg_lo:[0,1] neg_hi:[0,1]
	v_pk_add_f32 v[64:65], v[30:31], v[52:53] op_sel_hi:[0,1] neg_hi:[0,1]
	v_pk_mul_f32 v[30:31], v[64:65], v[142:143]
	v_pk_mul_f32 v[52:53], v[64:65], v[140:141]
	v_pk_fma_f32 v[30:31], v[68:69], v[140:141], v[30:31]
	v_pk_fma_f32 v[52:53], v[68:69], v[142:143], v[52:53] neg_lo:[0,0,1] neg_hi:[0,0,1]
	v_mov_b32_e32 v133, v112
	v_pk_add_f32 v[64:65], v[52:53], v[30:31] op_sel:[0,1] op_sel_hi:[1,0] neg_lo:[0,1]
	v_pk_add_f32 v[68:69], v[52:53], v[30:31] op_sel:[0,1] op_sel_hi:[1,0]
	v_pk_add_f32 v[30:31], v[30:31], v[52:53] op_sel:[1,0] op_sel_hi:[0,1] neg_lo:[0,1] neg_hi:[0,1]
	v_pk_mul_f32 v[64:65], v[64:65], 0.5 op_sel_hi:[1,0]
	v_mov_b32_e32 v69, v31
	v_mul_f32_e32 v18, v50, v65
	v_pk_fma_f32 v[74:75], v[62:63], v[64:65], v[18:19] op_sel_hi:[1,1,0] neg_lo:[0,0,1] neg_hi:[0,0,1]
	v_mul_f32_e32 v18, v49, v65
	v_pk_fma_f32 v[134:135], v[30:31], 0.5, v[74:75] op_sel_hi:[1,0,0] neg_lo:[1,0,0] neg_hi:[1,0,0]
	v_pk_add_f32 v[30:31], v[118:119], v[112:113]
	v_mov_b32_e32 v25, v118
	v_pk_fma_f32 v[50:51], v[50:51], v[64:65], v[18:19] op_sel_hi:[1,1,0]
	v_mul_f32_e32 v18, 0.5, v31
	v_pk_add_f32 v[24:25], v[132:133], v[24:25] neg_lo:[0,1] neg_hi:[0,1]
	v_mov_b32_e32 v65, v74
	v_pk_mul_f32 v[74:75], v[24:25], v[18:19]
	v_mov_b32_e32 v64, v50
	v_pk_fma_f32 v[62:63], v[62:63], v[74:75], v[74:75] op_sel:[0,1,0] op_sel_hi:[1,0,1]
	v_mov_b32_e32 v78, v24
	v_mov_b32_e32 v79, v49
	v_mov_b32_e32 v74, v75
	v_mov_b32_e32 v75, v18
	v_pk_fma_f32 v[110:111], v[68:69], 0.5, v[64:65] op_sel_hi:[1,0,1]
	v_mul_f32_e32 v64, 0.5, v30
	v_sub_f32_e32 v5, v113, v119
	v_pk_mul_f32 v[74:75], v[78:79], v[74:75]
	v_pk_fma_f32 v[52:53], v[68:69], 0.5, v[50:51] op_sel_hi:[1,0,1] neg_lo:[0,0,1] neg_hi:[0,0,1]
	v_pk_fma_f32 v[50:51], v[68:69], 0.5, v[50:51] op_sel_hi:[1,0,1]
	v_mul_f32_e32 v68, 0.5, v5
	v_pk_add_f32 v[64:65], v[64:65], v[62:63]
	v_fma_f32 v18, v30, 0.5, -v62
	v_pk_add_f32 v[62:63], v[74:75], v[74:75] op_sel:[0,1] op_sel_hi:[0,1] neg_lo:[0,1] neg_hi:[0,1]
	v_pk_add_f32 v[74:75], v[68:69], v[62:63] op_sel_hi:[0,1] neg_hi:[0,1]
	v_mov_b32_e32 v30, v64
	v_mov_b32_e32 v31, v18
	v_pk_mul_f32 v[62:63], v[18:19], v[124:125] op_sel_hi:[0,1]
	v_pk_mul_f32 v[68:69], v[74:75], v[126:127]
	v_pk_mul_f32 v[64:65], v[64:65], v[126:127]
	v_pk_mul_f32 v[74:75], v[74:75], v[124:125]
	v_pk_fma_f32 v[80:81], v[30:31], v[124:125], v[68:69] neg_lo:[0,0,1] neg_hi:[0,0,1]
	v_pk_fma_f32 v[30:31], v[30:31], v[126:127], v[74:75] neg_lo:[0,0,1] neg_hi:[0,0,1]
	v_add_f32_e32 v18, v63, v69
	v_add_f32_e32 v64, v64, v74
	v_pk_add_f32 v[68:69], v[64:65], v[30:31] op_sel_hi:[0,1] neg_lo:[0,1] neg_hi:[0,1]
	v_pk_add_f32 v[74:75], v[80:81], v[18:19] op_sel_hi:[1,0] neg_lo:[0,1] neg_hi:[0,1]
	v_pk_add_f32 v[30:31], v[64:65], v[30:31] op_sel_hi:[0,1]
	v_mov_b32_e32 v75, v31
	v_pk_mul_f32 v[30:31], v[74:75], 0.5 op_sel_hi:[1,0]
	v_pk_add_f32 v[62:63], v[80:81], v[18:19] op_sel_hi:[1,0]
	v_mul_f32_e32 v18, v49, v31
	v_pk_fma_f32 v[64:65], v[78:79], v[30:31], v[18:19] op_sel_hi:[1,1,0] neg_lo:[0,0,1] neg_hi:[0,0,1]
	v_pk_mov_b32 v[48:49], v[48:49], v[24:25] op_sel:[1,0]
	v_mul_f32_e32 v18, v24, v31
	v_pk_fma_f32 v[24:25], v[48:49], v[30:31], v[18:19] op_sel_hi:[1,1,0]
	v_mov_b32_e32 v63, v69
	v_mov_b32_e32 v30, v24
	v_mov_b32_e32 v31, v64
	v_pk_fma_f32 v[74:75], v[62:63], 0.5, v[24:25] op_sel_hi:[1,0,1] neg_lo:[0,0,1] neg_hi:[0,0,1]
	v_pk_fma_f32 v[112:113], v[62:63], 0.5, v[30:31] op_sel_hi:[1,0,1]
	v_pk_fma_f32 v[48:49], v[62:63], 0.5, v[24:25] op_sel_hi:[1,0,1]
	v_mov_b32_e32 v62, v115
	v_mov_b32_e32 v18, v117
	v_mov_b32_e32 v30, v117
	v_pk_mul_f32 v[62:63], v[138:139], v[62:63] op_sel_hi:[1,0]
	v_pk_fma_f32 v[118:119], v[68:69], 0.5, v[64:65] op_sel_hi:[1,0,0] neg_lo:[1,0,0] neg_hi:[1,0,0]
	v_pk_fma_f32 v[64:65], v[138:139], v[18:19], v[62:63] op_sel:[1,0,0] op_sel_hi:[0,1,1]
	v_pk_fma_f32 v[30:31], v[138:139], v[30:31], v[62:63] op_sel:[1,0,0] op_sel_hi:[0,0,1] neg_lo:[0,0,1] neg_hi:[0,0,1]
	v_pk_add_f32 v[62:63], v[86:87], v[36:37]
	v_pk_add_f32 v[36:37], v[86:87], v[36:37] neg_lo:[0,1] neg_hi:[0,1]
	v_mul_f32_e32 v18, 0.5, v62
	v_mul_f32_e32 v62, 0.5, v37
	v_mov_b32_e32 v37, v63
	v_mov_b32_e32 v65, v31
	v_pk_mul_f32 v[36:37], v[36:37], s[44:45]
	s_mov_b32 s68, s11
	s_mov_b32 s69, s8
	s_mov_b32 s9, s11
	v_cvt_f32_f16_sdwa v69, v47 dst_sel:DWORD dst_unused:UNUSED_PAD src0_sel:WORD_1
	v_cvt_f32_f16_sdwa v78, v46 dst_sel:DWORD dst_unused:UNUSED_PAD src0_sel:WORD_1
	v_pk_mul_f32 v[30:31], v[64:65], s[46:47]
	v_pk_mul_f32 v[64:65], v[36:37], s[68:69]
	v_pk_mul_f32 v[36:37], v[36:37], s[8:9]
	v_cvt_f32_f16_e32 v68, v46
	v_cvt_f32_f16_e32 v79, v47
	v_pk_add_f32 v[64:65], v[64:65], v[64:65] op_sel:[1,0] op_sel_hi:[1,0]
	v_pk_add_f32 v[36:37], v[36:37], v[36:37] op_sel:[0,1] op_sel_hi:[0,1] neg_lo:[0,1] neg_hi:[0,1]
	v_pk_add_f32 v[80:81], v[18:19], v[64:65] op_sel_hi:[0,1]
	v_pk_add_f32 v[90:91], v[62:63], v[36:37] op_sel_hi:[0,1]
	v_pk_add_f32 v[36:37], v[62:63], v[36:37] op_sel_hi:[0,1] neg_lo:[0,1] neg_hi:[0,1]
	v_mov_b32_e32 v46, v69
	v_mov_b32_e32 v47, v78
	v_pk_add_f32 v[64:65], v[18:19], v[64:65] op_sel_hi:[0,1] neg_lo:[0,1] neg_hi:[0,1]
	v_mov_b32_e32 v62, v90
	v_mov_b32_e32 v63, v37
	v_pk_mov_b32 v[36:37], v[36:37], v[80:81] op_sel:[1,0]
	v_mov_b32_e32 v86, v80
	v_mov_b32_e32 v87, v65
	v_pk_mov_b32 v[64:65], v[64:65], v[90:91] op_sel:[1,0]
	v_mov_b32_e32 v90, v79
	v_mov_b32_e32 v91, v68
	v_pk_mul_f32 v[36:37], v[36:37], v[46:47]
	v_pk_mul_f32 v[46:47], v[62:63], v[78:79]
	v_pk_fma_f32 v[36:37], v[64:65], v[90:91], v[36:37]
	v_pk_fma_f32 v[46:47], v[86:87], v[68:69], v[46:47] neg_lo:[0,0,1] neg_hi:[0,0,1]
	s_mov_b32 s72, s45
	v_pk_add_f32 v[62:63], v[46:47], v[36:37] neg_lo:[0,1]
	v_pk_add_f32 v[64:65], v[46:47], v[36:37]
	v_pk_add_f32 v[36:37], v[36:37], v[46:47] neg_lo:[0,1] neg_hi:[0,1]
	s_nop 0
	v_pk_mul_f32 v[62:63], v[62:63], 0.5 op_sel_hi:[1,0]
	v_mov_b32_e32 v65, v37
	v_mul_f32_e32 v18, 0x3f7b14be, v62
	v_pk_fma_f32 v[68:69], v[62:63], s[8:9], v[18:19] op_sel_hi:[1,1,0] neg_lo:[1,0,0] neg_hi:[1,0,0]
	v_mul_f32_e32 v18, 0x3f7b14be, v63
	v_pk_fma_f32 v[62:63], v[62:63], s[68:69], v[18:19] op_sel_hi:[1,1,0]
	v_mov_b32_e32 v37, v69
	v_mov_b32_e32 v36, v62
	v_pk_fma_f32 v[46:47], v[64:65], 0.5, v[62:63] op_sel_hi:[1,0,1] neg_lo:[0,0,1] neg_hi:[0,0,1]
	v_pk_fma_f32 v[36:37], v[64:65], 0.5, v[36:37] op_sel_hi:[1,0,1]
	s_mov_b32 s73, s44
	v_mov_b32_e32 v47, v37
	v_pk_mul_f32 v[78:79], v[46:47], s[46:47] op_sel_hi:[1,0]
	v_pk_fma_f32 v[46:47], v[64:65], 0.5, v[68:69] op_sel_hi:[1,0,1] neg_lo:[1,0,0] neg_hi:[1,0,0]
	s_mov_b32 s74, s19
	v_mov_b32_e32 v37, v47
	v_pk_mul_f32 v[144:145], v[36:37], s[46:47] op_sel_hi:[1,0]
	v_pk_add_f32 v[36:37], v[96:97], v[84:85]
	v_pk_add_f32 v[46:47], v[96:97], v[84:85] neg_lo:[0,1] neg_hi:[0,1]
	v_mov_b32_e32 v80, v36
	v_pk_mov_b32 v[36:37], v[36:37], v[46:47] op_sel:[1,0]
	v_cvt_f32_f16_sdwa v62, v38 dst_sel:DWORD dst_unused:UNUSED_PAD src0_sel:WORD_1
	v_pk_mul_f32 v[36:37], v[36:37], s[72:73]
	v_mov_b32_e32 v81, v47
	v_pk_mul_f32 v[46:47], v[36:37], s[74:75] op_sel_hi:[1,0]
	v_cvt_f32_f16_e32 v63, v39
	v_cvt_f32_f16_e32 v65, v38
	v_cvt_f32_f16_sdwa v38, v39 dst_sel:DWORD dst_unused:UNUSED_PAD src0_sel:WORD_1
	v_pk_fma_f32 v[84:85], v[36:37], s[16:17], v[46:47] op_sel:[0,0,1] op_sel_hi:[1,0,0] neg_hi:[0,0,1]
	s_nop 0
	v_mov_b32_e32 v39, v62
	s_nop 0
	v_pk_fma_f32 v[36:37], v[80:81], 0.5, v[84:85] op_sel_hi:[1,0,1] neg_lo:[0,0,1] neg_hi:[0,0,1]
	v_pk_fma_f32 v[46:47], v[80:81], 0.5, v[84:85] op_sel_hi:[1,0,1]
	v_mov_b32_e32 v64, v63
	v_pk_mov_b32 v[84:85], v[36:37], v[46:47] op_sel:[1,0]
	v_mov_b32_e32 v69, v38
	v_mov_b32_e32 v80, v36
	v_mov_b32_e32 v81, v47
	v_pk_mul_f32 v[38:39], v[84:85], v[38:39]
	v_mov_b32_e32 v68, v65
	v_pk_fma_f32 v[38:39], v[80:81], v[64:65], v[38:39]
	v_mov_b32_e32 v65, v36
	v_mov_b32_e32 v36, v47
	v_mov_b32_e32 v64, v46
	v_pk_mul_f32 v[36:37], v[36:37], v[62:63]
	v_sub_f32_e32 v13, v148, v149
	v_pk_fma_f32 v[36:37], v[64:65], v[68:69], v[36:37] neg_lo:[0,0,1] neg_hi:[0,0,1]
	v_add_f32_e32 v5, v148, v149
	v_mul_f32_e32 v13, v13, v114
	v_pk_add_f32 v[46:47], v[38:39], v[36:37]
	v_mul_f32_e32 v7, v5, v116
	v_fma_mix_f32 v25, v5, v122, -v13 op_sel_hi:[0,1,0]
	v_pk_add_f32 v[64:65], v[38:39], v[36:37] neg_hi:[0,1]
	v_sub_f32_e32 v5, v36, v38
	v_mul_f32_e32 v36, 0.5, v47
	v_mul_f32_e32 v18, 0.5, v5
	v_pk_mul_f32 v[36:37], v[36:37], s[16:17] op_sel_hi:[0,1]
	v_pk_fma_f32 v[38:39], v[18:19], s[66:67], v[36:37] op_sel_hi:[0,1,1]
	v_pk_fma_f32 v[36:37], v[18:19], s[66:67], v[36:37] op_sel_hi:[0,1,1] neg_lo:[0,0,1] neg_hi:[0,0,1]
	v_mov_b32_e32 v46, v38
	v_mov_b32_e32 v47, v37
	v_pk_fma_f32 v[38:39], v[64:65], 0.5, v[38:39] op_sel_hi:[1,0,1] neg_lo:[0,0,1] neg_hi:[0,0,1]
	v_pk_fma_f32 v[46:47], v[64:65], 0.5, v[46:47] op_sel_hi:[1,0,1]
	v_pk_fma_f32 v[36:37], v[64:65], 0.5, v[36:37] op_sel_hi:[1,0,1] neg_lo:[1,0,0] neg_hi:[1,0,0]
	v_mov_b32_e32 v39, v47
	v_pk_mul_f32 v[62:63], v[38:39], s[46:47] op_sel_hi:[1,0]
	v_mov_b32_e32 v47, v37
	v_pk_add_f32 v[36:37], v[42:43], v[44:45]
	v_pk_add_f32 v[38:39], v[42:43], v[44:45] neg_lo:[0,1] neg_hi:[0,1]
	v_mov_b32_e32 v64, v36
	v_pk_mov_b32 v[36:37], v[36:37], v[38:39] op_sel:[1,0]
	s_mov_b32 s76, s27
	v_pk_mul_f32 v[36:37], v[36:37], s[72:73]
	v_cvt_f32_f16_sdwa v42, v26 dst_sel:DWORD dst_unused:UNUSED_PAD src0_sel:WORD_1
	v_mov_b32_e32 v65, v39
	v_pk_mul_f32 v[38:39], v[36:37], s[76:77] op_sel_hi:[1,0]
	v_cvt_f32_f16_e32 v43, v27
	v_cvt_f32_f16_e32 v45, v26
	v_cvt_f32_f16_sdwa v26, v27 dst_sel:DWORD dst_unused:UNUSED_PAD src0_sel:WORD_1
	v_pk_fma_f32 v[68:69], v[36:37], s[24:25], v[38:39] op_sel:[0,0,1] op_sel_hi:[1,0,0] neg_hi:[0,0,1]
	s_nop 0
	v_mov_b32_e32 v27, v42
	s_nop 0
	v_pk_fma_f32 v[36:37], v[64:65], 0.5, v[68:69] op_sel_hi:[1,0,1] neg_lo:[0,0,1] neg_hi:[0,0,1]
	v_pk_fma_f32 v[38:39], v[64:65], 0.5, v[68:69] op_sel_hi:[1,0,1]
	v_pk_mul_f32 v[80:81], v[46:47], s[46:47] op_sel_hi:[1,0]
	v_pk_mov_b32 v[68:69], v[36:37], v[38:39] op_sel:[1,0]
	v_mov_b32_e32 v44, v43
	v_mov_b32_e32 v47, v26
	v_mov_b32_e32 v64, v36
	v_mov_b32_e32 v65, v39
	v_pk_mul_f32 v[26:27], v[68:69], v[26:27]
	v_mov_b32_e32 v46, v45
	v_pk_fma_f32 v[26:27], v[64:65], v[44:45], v[26:27]
	v_mov_b32_e32 v45, v36
	v_mov_b32_e32 v36, v39
	v_mov_b32_e32 v44, v38
	v_pk_mul_f32 v[36:37], v[36:37], v[42:43]
	s_mov_b32 s25, s27
	v_pk_fma_f32 v[36:37], v[44:45], v[46:47], v[36:37] neg_lo:[0,0,1] neg_hi:[0,0,1]
	s_mov_b32 s78, s27
	v_pk_add_f32 v[38:39], v[26:27], v[36:37]
	v_pk_add_f32 v[42:43], v[26:27], v[36:37] neg_hi:[0,1]
	v_sub_f32_e32 v5, v36, v26
	v_mul_f32_e32 v26, 0.5, v39
	v_mul_f32_e32 v18, 0.5, v5
	s_mov_b32 s79, s24
	v_pk_mul_f32 v[26:27], v[26:27], s[24:25] op_sel_hi:[0,1]
	v_pk_fma_f32 v[36:37], v[18:19], s[78:79], v[26:27] op_sel_hi:[0,1,1]
	v_pk_fma_f32 v[26:27], v[18:19], s[78:79], v[26:27] op_sel_hi:[0,1,1] neg_lo:[0,0,1] neg_hi:[0,0,1]
	s_nop 0
	v_mov_b32_e32 v38, v36
	v_mov_b32_e32 v39, v27
	v_pk_fma_f32 v[36:37], v[42:43], 0.5, v[36:37] op_sel_hi:[1,0,1] neg_lo:[0,0,1] neg_hi:[0,0,1]
	v_pk_fma_f32 v[38:39], v[42:43], 0.5, v[38:39] op_sel_hi:[1,0,1]
	v_pk_fma_f32 v[26:27], v[42:43], 0.5, v[26:27] op_sel_hi:[1,0,1] neg_lo:[1,0,0] neg_hi:[1,0,0]
	v_mov_b32_e32 v37, v39
	v_pk_mul_f32 v[128:129], v[36:37], s[46:47] op_sel_hi:[1,0]
	v_mov_b32_e32 v39, v27
	v_pk_add_f32 v[26:27], v[92:93], v[88:89]
	v_pk_add_f32 v[36:37], v[92:93], v[88:89] neg_lo:[0,1] neg_hi:[0,1]
	v_add_f32_e32 v24, v7, v13
	v_pk_mul_f32 v[120:121], v[38:39], s[46:47] op_sel_hi:[1,0]
	v_mul_f32_e32 v5, 0.5, v27
	v_mul_f32_e32 v7, -0.5, v36
	v_cvt_f32_f16_sdwa v38, v20 dst_sel:DWORD dst_unused:UNUSED_PAD src0_sel:WORD_1
	v_mul_f32_e32 v5, 0x3f3504f3, v5
	v_mul_f32_e32 v13, 0x3f3504f3, v7
	v_cvt_f32_f16_e32 v39, v21
	v_cvt_f32_f16_e32 v43, v20
	v_cvt_f32_f16_sdwa v20, v21 dst_sel:DWORD dst_unused:UNUSED_PAD src0_sel:WORD_1
	v_mov_b32_e32 v27, v37
	v_add_f32_e32 v36, v13, v5
	v_fma_f32 v37, v7, s37, -v5
	v_pk_fma_f32 v[46:47], v[26:27], 0.5, v[36:37] op_sel_hi:[1,0,1] neg_lo:[0,0,1] neg_hi:[0,0,1]
	v_pk_fma_f32 v[26:27], v[26:27], 0.5, v[36:37] op_sel_hi:[1,0,1]
	v_mov_b32_e32 v21, v38
	v_pk_mov_b32 v[64:65], v[46:47], v[26:27] op_sel:[1,0]
	v_mov_b32_e32 v42, v39
	v_mov_b32_e32 v45, v20
	v_mov_b32_e32 v36, v46
	v_mov_b32_e32 v37, v27
	v_pk_mul_f32 v[20:21], v[64:65], v[20:21]
	v_mov_b32_e32 v44, v43
	v_pk_fma_f32 v[20:21], v[36:37], v[42:43], v[20:21]
	v_mov_b32_e32 v37, v46
	v_mov_b32_e32 v46, v27
	v_mov_b32_e32 v36, v26
	v_pk_mul_f32 v[26:27], v[46:47], v[38:39]
	v_pk_mul_f32 v[24:25], v[24:25], 0.5 op_sel_hi:[1,0]
	v_pk_fma_f32 v[26:27], v[36:37], v[44:45], v[26:27] neg_lo:[0,0,1] neg_hi:[0,0,1]
	v_pk_mul_f32 v[24:25], v[24:25], s[46:47] op_sel_hi:[1,0]
	v_pk_add_f32 v[36:37], v[20:21], v[26:27]
	v_sub_f32_e32 v5, v26, v20
	v_mul_f32_e32 v7, 0.5, v37
	v_mul_f32_e32 v5, 0.5, v5
	v_mul_f32_e32 v7, 0x3f3504f3, v7
	v_pk_add_f32 v[38:39], v[20:21], v[26:27] neg_hi:[0,1]
	v_mul_f32_e32 v13, 0x3f3504f3, v5
	v_fma_f32 v18, v5, s37, -v7
	v_add_f32_e32 v20, v13, v7
	v_mov_b32_e32 v21, v18
	v_pk_fma_f32 v[26:27], v[38:39], 0.5, v[20:21] op_sel_hi:[1,0,1] neg_lo:[0,0,1]
	v_pk_fma_f32 v[20:21], v[38:39], 0.5, v[20:21] op_sel_hi:[1,0,1]
	v_cvt_f32_f16_e32 v37, v10
	v_pk_mul_f32 v[64:65], v[26:27], s[46:47] op_sel_hi:[1,0]
	v_pk_fma_f32 v[26:27], v[38:39], 0.5, v[18:19] op_sel_hi:[1,0,0] neg_lo:[1,0,0] neg_hi:[1,0,0]
	v_mov_b32_e32 v38, v37
	v_mov_b32_e32 v21, v27
	v_pk_mul_f32 v[68:69], v[20:21], s[46:47] op_sel_hi:[1,0]
	v_pk_add_f32 v[20:21], v[40:41], v[22:23]
	v_pk_add_f32 v[22:23], v[40:41], v[22:23] neg_lo:[0,1] neg_hi:[0,1]
	v_mov_b32_e32 v40, v20
	v_pk_mov_b32 v[20:21], v[20:21], v[22:23] op_sel:[1,0]
	v_cvt_f32_f16_sdwa v26, v10 dst_sel:DWORD dst_unused:UNUSED_PAD src0_sel:WORD_1
	v_pk_mul_f32 v[20:21], v[20:21], s[72:73]
	v_mov_b32_e32 v41, v23
	v_pk_mul_f32 v[22:23], v[20:21], s[24:25] op_sel_hi:[1,0]
	v_cvt_f32_f16_e32 v27, v11
	v_cvt_f32_f16_sdwa v10, v11 dst_sel:DWORD dst_unused:UNUSED_PAD src0_sel:WORD_1
	v_pk_fma_f32 v[42:43], v[20:21], s[76:77], v[22:23] op_sel:[0,0,1] op_sel_hi:[1,0,0] neg_hi:[0,0,1]
	s_nop 0
	v_mov_b32_e32 v11, v26
	s_nop 0
	v_pk_fma_f32 v[20:21], v[40:41], 0.5, v[42:43] op_sel_hi:[1,0,1] neg_lo:[0,0,1] neg_hi:[0,0,1]
	v_pk_fma_f32 v[22:23], v[40:41], 0.5, v[42:43] op_sel_hi:[1,0,1]
	v_mov_b32_e32 v36, v27
	v_pk_mov_b32 v[42:43], v[20:21], v[22:23] op_sel:[1,0]
	v_mov_b32_e32 v39, v10
	v_mov_b32_e32 v40, v20
	v_mov_b32_e32 v41, v23
	v_pk_mul_f32 v[10:11], v[42:43], v[10:11]
	v_mov_b32_e32 v7, v161
	v_pk_fma_f32 v[10:11], v[40:41], v[36:37], v[10:11]
	v_mov_b32_e32 v37, v20
	v_mov_b32_e32 v20, v23
	v_mov_b32_e32 v36, v22
	v_pk_mul_f32 v[20:21], v[20:21], v[26:27]
	v_mov_b32_e32 v17, v173
	v_pk_fma_f32 v[20:21], v[36:37], v[38:39], v[20:21] neg_lo:[0,0,1] neg_hi:[0,0,1]
	v_mov_b32_e32 v13, v175
	v_pk_add_f32 v[22:23], v[10:11], v[20:21]
	v_sub_f32_e32 v5, v20, v10
	v_mul_f32_e32 v18, 0.5, v23
	v_pk_add_f32 v[26:27], v[10:11], v[20:21] neg_hi:[0,1]
	v_mul_f32_e32 v10, 0.5, v5
	v_pk_mul_f32 v[20:21], v[18:19], s[78:79] op_sel_hi:[0,1]
	v_pk_fma_f32 v[22:23], v[10:11], s[24:25], v[20:21] op_sel_hi:[0,1,1]
	v_pk_fma_f32 v[10:11], v[10:11], s[24:25], v[20:21] op_sel_hi:[0,1,1] neg_lo:[0,0,1] neg_hi:[0,0,1]
	v_mov_b32_e32 v20, v22
	v_mov_b32_e32 v21, v11
	v_pk_fma_f32 v[22:23], v[26:27], 0.5, v[22:23] op_sel_hi:[1,0,1] neg_lo:[0,0,1] neg_hi:[0,0,1]
	v_pk_fma_f32 v[20:21], v[26:27], 0.5, v[20:21] op_sel_hi:[1,0,1]
	v_pk_fma_f32 v[10:11], v[26:27], 0.5, v[10:11] op_sel_hi:[1,0,1] neg_lo:[1,0,0] neg_hi:[1,0,0]
	v_mov_b32_e32 v23, v21
	v_mov_b32_e32 v21, v11
	v_pk_mul_f32 v[150:151], v[20:21], s[46:47] op_sel_hi:[1,0]
	v_pk_add_f32 v[10:11], v[66:67], v[60:61]
	v_pk_add_f32 v[20:21], v[60:61], v[66:67] neg_lo:[0,1] neg_hi:[0,1]
	v_mov_b32_e32 v38, v10
	v_pk_mov_b32 v[10:11], v[10:11], v[20:21] op_sel:[1,0]
	v_pk_mul_f32 v[130:131], v[22:23], s[46:47] op_sel_hi:[1,0]
	v_pk_mul_f32 v[10:11], v[10:11], s[72:73]
	v_cvt_f32_f16_sdwa v22, v8 dst_sel:DWORD dst_unused:UNUSED_PAD src0_sel:WORD_1
	v_mov_b32_e32 v39, v21
	v_pk_mul_f32 v[20:21], v[10:11], s[16:17] op_sel_hi:[1,0]
	v_cvt_f32_f16_e32 v23, v9
	v_cvt_f32_f16_e32 v27, v8
	v_cvt_f32_f16_sdwa v8, v9 dst_sel:DWORD dst_unused:UNUSED_PAD src0_sel:WORD_1
	v_pk_fma_f32 v[40:41], v[10:11], s[74:75], v[20:21] op_sel:[0,0,1] op_sel_hi:[1,0,0] neg_hi:[0,0,1]
	s_nop 0
	v_mov_b32_e32 v9, v22
	s_nop 0
	v_pk_fma_f32 v[10:11], v[38:39], 0.5, v[40:41] op_sel_hi:[1,0,1] neg_lo:[0,0,1] neg_hi:[0,0,1]
	v_pk_fma_f32 v[20:21], v[38:39], 0.5, v[40:41] op_sel_hi:[1,0,1]
	v_mov_b32_e32 v26, v23
	v_pk_mov_b32 v[40:41], v[10:11], v[20:21] op_sel:[1,0]
	v_mov_b32_e32 v37, v8
	v_mov_b32_e32 v38, v10
	v_mov_b32_e32 v39, v21
	v_pk_mul_f32 v[8:9], v[40:41], v[8:9]
	v_mov_b32_e32 v36, v27
	v_pk_fma_f32 v[8:9], v[38:39], v[26:27], v[8:9]
	v_mov_b32_e32 v27, v10
	v_mov_b32_e32 v10, v21
	v_mov_b32_e32 v26, v20
	v_pk_mul_f32 v[10:11], v[10:11], v[22:23]
	v_mov_b32_e32 v33, v105
	v_pk_fma_f32 v[10:11], v[26:27], v[36:37], v[10:11] neg_lo:[0,0,1] neg_hi:[0,0,1]
	v_mov_b32_e32 v29, v153
	v_pk_add_f32 v[20:21], v[8:9], v[10:11]
	v_pk_add_f32 v[22:23], v[8:9], v[10:11] neg_hi:[0,1]
	v_sub_f32_e32 v5, v10, v8
	v_mul_f32_e32 v10, 0.5, v21
	v_mul_f32_e32 v8, 0.5, v5
	v_pk_mul_f32 v[10:11], v[10:11], s[66:67] op_sel_hi:[0,1]
	v_pk_fma_f32 v[20:21], v[8:9], s[16:17], v[10:11] op_sel_hi:[0,1,1]
	v_pk_fma_f32 v[8:9], v[8:9], s[16:17], v[10:11] op_sel_hi:[0,1,1] neg_lo:[0,0,1] neg_hi:[0,0,1]
	v_mov_b32_e32 v10, v20
	v_mov_b32_e32 v11, v9
	v_pk_fma_f32 v[20:21], v[22:23], 0.5, v[20:21] op_sel_hi:[1,0,1] neg_lo:[0,0,1] neg_hi:[0,0,1]
	v_pk_fma_f32 v[10:11], v[22:23], 0.5, v[10:11] op_sel_hi:[1,0,1]
	v_pk_fma_f32 v[8:9], v[22:23], 0.5, v[8:9] op_sel_hi:[1,0,1] neg_lo:[1,0,0] neg_hi:[1,0,0]
	v_mov_b32_e32 v21, v11
	v_mov_b32_e32 v11, v9
	v_pk_mul_f32 v[90:91], v[10:11], s[46:47] op_sel_hi:[1,0]
	v_pk_add_f32 v[8:9], v[34:35], v[14:15]
	v_pk_add_f32 v[10:11], v[14:15], v[34:35] neg_lo:[0,1] neg_hi:[0,1]
	v_mov_b32_e32 v26, v8
	v_pk_mov_b32 v[8:9], v[8:9], v[10:11] op_sel:[1,0]
	v_cvt_f32_f16_sdwa v14, v2 dst_sel:DWORD dst_unused:UNUSED_PAD src0_sel:WORD_1
	v_pk_mul_f32 v[8:9], v[8:9], s[72:73]
	v_mov_b32_e32 v27, v11
	s_mov_b32 s66, s11
	v_pk_mul_f32 v[10:11], v[8:9], s[8:9] op_sel_hi:[1,0]
	v_pk_mul_f32 v[94:95], v[20:21], s[46:47] op_sel_hi:[1,0]
	v_cvt_f32_f16_e32 v15, v3
	v_cvt_f32_f16_e32 v21, v2
	v_cvt_f32_f16_sdwa v2, v3 dst_sel:DWORD dst_unused:UNUSED_PAD src0_sel:WORD_1
	v_pk_fma_f32 v[34:35], v[8:9], s[66:67], v[10:11] op_sel:[0,0,1] op_sel_hi:[1,0,0] neg_hi:[0,0,1]
	s_nop 0
	v_mov_b32_e32 v3, v14
	s_nop 0
	v_pk_fma_f32 v[8:9], v[26:27], 0.5, v[34:35] op_sel_hi:[1,0,1] neg_lo:[0,0,1] neg_hi:[0,0,1]
	v_pk_fma_f32 v[10:11], v[26:27], 0.5, v[34:35] op_sel_hi:[1,0,1]
	v_mov_b32_e32 v20, v15
	v_pk_mov_b32 v[34:35], v[8:9], v[10:11] op_sel:[1,0]
	v_mov_b32_e32 v23, v2
	v_mov_b32_e32 v26, v8
	v_mov_b32_e32 v27, v11
	v_pk_mul_f32 v[2:3], v[34:35], v[2:3]
	v_mov_b32_e32 v22, v21
	v_pk_fma_f32 v[2:3], v[26:27], v[20:21], v[2:3]
	v_mov_b32_e32 v21, v8
	v_mov_b32_e32 v8, v11
	v_mov_b32_e32 v20, v10
	v_pk_mul_f32 v[8:9], v[8:9], v[14:15]
	v_mov_b32_e32 v5, v171
	v_pk_fma_f32 v[8:9], v[20:21], v[22:23], v[8:9] neg_lo:[0,0,1] neg_hi:[0,0,1]
	v_mov_b32_e32 v51, v135
	v_pk_add_f32 v[10:11], v[2:3], v[8:9]
	v_pk_add_f32 v[14:15], v[2:3], v[8:9] neg_hi:[0,1]
	v_sub_f32_e32 v2, v8, v2
	v_mul_f32_e32 v8, 0.5, v11
	v_mul_f32_e32 v2, 0.5, v2
	v_pk_mul_f32 v[8:9], v[8:9], s[68:69] op_sel_hi:[0,1]
	v_pk_fma_f32 v[10:11], v[2:3], s[8:9], v[8:9] op_sel_hi:[0,1,1]
	v_pk_fma_f32 v[2:3], v[2:3], s[8:9], v[8:9] op_sel_hi:[0,1,1] neg_lo:[0,0,1] neg_hi:[0,0,1]
	v_mov_b32_e32 v8, v10
	v_mov_b32_e32 v9, v3
	v_pk_fma_f32 v[10:11], v[14:15], 0.5, v[10:11] op_sel_hi:[1,0,1] neg_lo:[0,0,1] neg_hi:[0,0,1]
	v_pk_fma_f32 v[8:9], v[14:15], 0.5, v[8:9] op_sel_hi:[1,0,1]
	v_pk_fma_f32 v[2:3], v[14:15], 0.5, v[2:3] op_sel_hi:[1,0,1] neg_lo:[1,0,0] neg_hi:[1,0,0]
	v_mov_b32_e32 v11, v9
	v_mov_b32_e32 v9, v3
	v_pk_mul_f32 v[168:169], v[10:11], s[46:47] op_sel_hi:[1,0]
	v_pk_mul_f32 v[136:137], v[8:9], s[46:47] op_sel_hi:[1,0]
	v_mov_b32_e32 v49, v119
	v_mov_b32_e32 v75, v113
	v_mov_b32_e32 v53, v111
	v_mov_b32_e32 v77, v109
	v_mov_b32_e32 v57, v83
	v_mov_b32_e32 v71, v107
	v_mov_b32_e32 v55, v103
	v_mov_b32_e32 v73, v101
	v_mov_b32_e32 v59, v99
